# IEEE f32 division expansions (div_scale..div_fixup) replaced by v_rcp_f32 (+v_mul): sigmoid/gelu/tanh epilogues, 429 sites
# speedup vs baseline: 1.0332x; 1.0332x over previous
.LBB0_29:
	s_or_b64 exec, exec, s[0:1]
	s_waitcnt vmcnt(0)
	v_max_f32_e32 v17, v17, v17
	v_min_f32_e32 v24, 0xb8d1b717, v17
	v_mul_f32_e32 v17, v24, v18
	v_mul_f32_e32 v18, 0x3fb8aa3b, v17
	v_fma_f32 v20, v17, s23, -v18
	v_rndne_f32_e32 v21, v18
	v_fmac_f32_e32 v20, 0x32a5705f, v17
	v_sub_f32_e32 v18, v18, v21
	v_add_f32_e32 v18, v18, v20
	v_cvt_i32_f32_e32 v20, v21
	v_exp_f32_e32 v18, v18
	v_cmp_ngt_f32_e32 vcc, s25, v17
	v_xor_b32_e32 v16, v16, v5
	s_brev_b32 s0, 1
	v_ldexp_f32 v18, v18, v20
	v_cndmask_b32_e32 v18, 0, v18, vcc
	v_cmp_nlt_f32_e32 vcc, s26, v17
	v_mul_f32_e32 v17, v6, v6
	v_readlane_b32 s56, v252, 18
	v_cndmask_b32_e32 v25, v10, v18, vcc
	v_fmamk_f32 v18, v17, 0xb94c1982, v11
	v_fmaak_f32 v18, v17, v18, 0xbe2aaa9d
	v_mul_f32_e32 v18, v17, v18
	v_fmac_f32_e32 v6, v6, v18
	v_fmamk_f32 v18, v17, 0x37d75334, v12
	v_fmaak_f32 v18, v17, v18, 0x3d2aabf7
	v_fmaak_f32 v18, v17, v18, 0xbf000004
	v_fma_f32 v17, v17, v18, 1.0
	v_lshlrev_b32_e32 v18, 30, v19
	v_and_b32_e32 v19, 1, v19
	v_cmp_eq_u32_e32 vcc, 0, v19
	v_and_b32_e32 v20, 0x80000000, v18
	v_readlane_b32 s58, v252, 20
	v_cndmask_b32_e32 v19, v17, v6, vcc
	v_xor_b32_e32 v6, 0x80000000, v6
	v_cndmask_b32_e32 v6, v6, v17, vcc
	v_xor_b32_e32 v16, v16, v19
	v_bitop3_b32 v6, v6, v18, s0 bitop3:0x78
	s_movk_i32 s0, 0x1f8
	v_xor_b32_e32 v16, v16, v20
	v_cmp_class_f32_e64 vcc, v5, s0
	v_readlane_b32 s59, v252, 21
	v_readlane_b32 s57, v252, 19
	v_cndmask_b32_e32 v5, v15, v16, vcc
	v_cndmask_b32_e32 v34, v15, v6, vcc
	v_mul_f32_e32 v26, v25, v5
	v_ashrrev_i32_e32 v5, 31, v4
	v_mul_f32_e32 v16, v25, v34
	v_lshl_add_u64 v[18:19], v[4:5], 2, s[14:15]
	v_mov_b32_e32 v17, v26
	global_store_dwordx2 v[18:19], v[16:17], off
	v_lshlrev_b64 v[16:17], 6, v[2:3]
	v_lshl_add_u64 v[30:31], s[58:59], 0, v[16:17]
	v_lshl_add_u64 v[28:29], s[56:57], 0, v[16:17]
	global_load_dwordx4 v[16:19], v[30:31], off
	global_load_dwordx4 v[20:23], v[28:29], off
	v_mov_b32_e32 v27, v8
	v_ashrrev_i32_e32 v32, 6, v2
	v_ashrrev_i32_e32 v33, 31, v32
	v_mov_b32_e32 v35, v24
	v_fma_f32 v34, v25, v34, -1.0
	v_pk_mul_f32 v[36:37], v[8:9], v[26:27] op_sel_hi:[0,1]
	v_and_b32_e32 v3, 0x7e0, v9
	v_lshlrev_b64 v[32:33], 12, v[32:33]
	v_mov_b32_e32 v27, v34
	v_pk_fma_f32 v[34:35], v[24:25], v[34:35], v[36:37] op_sel_hi:[0,1,1]
	v_mov_b32_e32 v25, v8
	v_lshlrev_b32_e32 v6, 1, v3
	v_lshl_add_u64 v[32:33], s[16:17], 0, v[32:33]
	v_pk_mul_f32 v[24:25], v[24:25], v[26:27]
	v_lshl_add_u64 v[32:33], v[32:33], 0, v[6:7]
	v_sub_f32_e32 v8, v24, v25
	v_div_scale_f32 v24, s[0:1], v35, v35, v8
	v_rcp_f32_e32 v26, v24
	s_nop 0
	v_fma_f32 v36, -v24, v26, 1.0
	v_div_scale_f32 v25, s[0:1], v8, v35, v8
	v_fmac_f32_e32 v26, v36, v26
	v_mul_f32_e32 v36, v25, v26
	v_fma_f32 v5, -v24, v36, v25
	v_fmac_f32_e32 v36, v5, v26
	v_rcp_f32_e32 v6, v35
	s_nop 0
	v_mul_f32_e32 v6, v34, v6
	v_fma_f32 v3, -v24, v36, v25
	s_mov_b64 vcc, s[0:1]
	v_div_fmas_f32 v3, v3, v26, v36
	v_div_fixup_f32 v8, v3, v35, v8
	v_add_u32_e32 v2, s20, v2
	s_movk_i32 s0, 0xfff
	v_cmp_lt_i32_e32 vcc, s0, v2
	s_or_b64 s[18:19], vcc, s[18:19]
	v_add_u32_e32 v4, s22, v4
	v_readlane_b32 s60, v252, 22
	v_readlane_b32 s61, v252, 23
	v_readlane_b32 s62, v252, 24
	v_readlane_b32 s63, v252, 25
	v_readlane_b32 s64, v252, 26
	v_readlane_b32 s65, v252, 27
	v_readlane_b32 s66, v252, 28
	v_readlane_b32 s67, v252, 29
	v_readlane_b32 s68, v252, 30
	v_readlane_b32 s69, v252, 31
	v_readlane_b32 s70, v252, 32
	v_readlane_b32 s71, v252, 33
	s_waitcnt vmcnt(1)
	v_pk_mul_f32 v[24:25], v[16:17], v[8:9] op_sel_hi:[1,0]
	v_pk_mul_f32 v[34:35], v[18:19], v[8:9] op_sel_hi:[1,0]
	s_waitcnt vmcnt(0)
	v_pk_mul_f32 v[26:27], v[20:21], v[8:9] op_sel_hi:[1,0]
	v_pk_fma_f32 v[20:21], v[20:21], v[6:7], v[24:25] op_sel_hi:[1,0,1] neg_lo:[0,0,1] neg_hi:[0,0,1]
	v_pk_fma_f32 v[24:25], v[22:23], v[6:7], v[34:35] op_sel_hi:[1,0,1] neg_lo:[0,0,1] neg_hi:[0,0,1]
	v_pk_mul_f32 v[22:23], v[22:23], v[8:9] op_sel_hi:[1,0]
	v_pk_fma_f32 v[16:17], v[16:17], v[6:7], v[26:27] op_sel_hi:[1,0,1]
	v_pk_fma_f32 v[18:19], v[18:19], v[6:7], v[22:23] op_sel_hi:[1,0,1]
	v_cvt_pk_bf16_f32 v20, v20, v21
	v_cvt_pk_bf16_f32 v21, v24, v25
	v_cvt_pk_bf16_f32 v16, v16, v17
	v_cvt_pk_bf16_f32 v17, v18, v19
	global_store_dwordx2 v[32:33], v[20:21], off
	global_store_dwordx2 v[32:33], v[16:17], off offset:32
	global_load_dwordx4 v[16:19], v[30:31], off offset:16
	s_nop 0
	global_load_dwordx4 v[20:23], v[28:29], off offset:16
	s_waitcnt vmcnt(1)
	v_pk_mul_f32 v[24:25], v[16:17], v[8:9] op_sel_hi:[1,0]
	v_pk_mul_f32 v[34:35], v[18:19], v[8:9] op_sel_hi:[1,0]
	s_waitcnt vmcnt(0)
	v_pk_mul_f32 v[26:27], v[20:21], v[8:9] op_sel_hi:[1,0]
	v_pk_mul_f32 v[36:37], v[22:23], v[8:9] op_sel_hi:[1,0]
	v_pk_fma_f32 v[20:21], v[20:21], v[6:7], v[24:25] op_sel_hi:[1,0,1] neg_lo:[0,0,1] neg_hi:[0,0,1]
	v_pk_fma_f32 v[22:23], v[22:23], v[6:7], v[34:35] op_sel_hi:[1,0,1] neg_lo:[0,0,1] neg_hi:[0,0,1]
	v_pk_fma_f32 v[16:17], v[16:17], v[6:7], v[26:27] op_sel_hi:[1,0,1]
	v_pk_fma_f32 v[18:19], v[18:19], v[6:7], v[36:37] op_sel_hi:[1,0,1]
	v_cvt_pk_bf16_f32 v20, v20, v21
	v_cvt_pk_bf16_f32 v21, v22, v23
	v_cvt_pk_bf16_f32 v16, v16, v17
	v_cvt_pk_bf16_f32 v17, v18, v19
	global_store_dwordx2 v[32:33], v[20:21], off offset:8
	global_store_dwordx2 v[32:33], v[16:17], off offset:40
	global_load_dwordx4 v[16:19], v[30:31], off offset:32
	s_nop 0
	global_load_dwordx4 v[20:23], v[28:29], off offset:32
	s_waitcnt vmcnt(1)
	v_pk_mul_f32 v[24:25], v[16:17], v[8:9] op_sel_hi:[1,0]
	v_pk_mul_f32 v[34:35], v[18:19], v[8:9] op_sel_hi:[1,0]
	s_waitcnt vmcnt(0)
	v_pk_mul_f32 v[26:27], v[20:21], v[8:9] op_sel_hi:[1,0]
	v_pk_mul_f32 v[36:37], v[22:23], v[8:9] op_sel_hi:[1,0]
	v_pk_fma_f32 v[20:21], v[20:21], v[6:7], v[24:25] op_sel_hi:[1,0,1] neg_lo:[0,0,1] neg_hi:[0,0,1]
	v_pk_fma_f32 v[22:23], v[22:23], v[6:7], v[34:35] op_sel_hi:[1,0,1] neg_lo:[0,0,1] neg_hi:[0,0,1]
	v_pk_fma_f32 v[16:17], v[16:17], v[6:7], v[26:27] op_sel_hi:[1,0,1]
	v_pk_fma_f32 v[18:19], v[18:19], v[6:7], v[36:37] op_sel_hi:[1,0,1]
	v_cvt_pk_bf16_f32 v20, v20, v21
	v_cvt_pk_bf16_f32 v21, v22, v23
	v_cvt_pk_bf16_f32 v16, v16, v17
	v_cvt_pk_bf16_f32 v17, v18, v19
	global_store_dwordx2 v[32:33], v[20:21], off offset:16
	global_store_dwordx2 v[32:33], v[16:17], off offset:48
	global_load_dwordx4 v[16:19], v[30:31], off offset:48
	s_nop 0
	global_load_dwordx4 v[20:23], v[28:29], off offset:48
	v_add_u32_e32 v9, s21, v9
	s_waitcnt vmcnt(1)
	v_pk_mul_f32 v[24:25], v[8:9], v[16:17] op_sel_hi:[0,1]
	v_pk_mul_f32 v[16:17], v[6:7], v[16:17] op_sel_hi:[0,1]
	v_pk_mul_f32 v[26:27], v[8:9], v[18:19] op_sel_hi:[0,1]
	v_pk_mul_f32 v[18:19], v[6:7], v[18:19] op_sel_hi:[0,1]
	s_waitcnt vmcnt(0)
	v_pk_fma_f32 v[24:25], v[6:7], v[20:21], v[24:25] op_sel_hi:[0,1,1] neg_lo:[0,0,1] neg_hi:[0,0,1]
	v_pk_fma_f32 v[16:17], v[8:9], v[20:21], v[16:17] op_sel_hi:[0,1,1]
	v_pk_fma_f32 v[20:21], v[6:7], v[22:23], v[26:27] op_sel_hi:[0,1,1] neg_lo:[0,0,1] neg_hi:[0,0,1]
	v_pk_fma_f32 v[18:19], v[8:9], v[22:23], v[18:19] op_sel_hi:[0,1,1]
	v_cvt_pk_bf16_f32 v22, v24, v25
	v_cvt_pk_bf16_f32 v23, v20, v21
	v_cvt_pk_bf16_f32 v16, v16, v17
	v_cvt_pk_bf16_f32 v17, v18, v19
	global_store_dwordx2 v[32:33], v[22:23], off offset:24
	global_store_dwordx2 v[32:33], v[16:17], off offset:56
	s_andn2_b64 exec, exec, s[18:19]
	s_cbranch_execz .LBB0_34

.LBB0_342:
	v_or_b32_e32 v176, s0, v221
	s_waitcnt lgkmcnt(0)
	v_mov_b64_e32 v[0:1], s[10:11]
	v_mad_i64_i32 v[0:1], s[4:5], v176, s86, v[0:1]
	s_mov_b64 s[4:5], 0x2040c00
	s_nop 0
	v_lshl_add_u64 v[180:181], v[0:1], 0, s[4:5]
	v_bitop3_b32 v0, s0, v241, v221 bitop3:0xc8
	v_cmp_eq_u32_e32 vcc, 0, v0
	v_mov_b32_e32 v0, 0xffffec00
	v_mov_b32_e32 v159, v195
	v_cndmask_b32_e64 v185, -1, 0, vcc
	v_cndmask_b32_e64 v184, v0, 0, vcc
	v_lshl_add_u64 v[0:1], v[180:181], 0, v[194:195]
	flat_load_dwordx4 v[116:119], v[0:1]
	v_lshl_add_u64 v[182:183], v[180:181], 0, v[184:185]
	v_lshl_add_u64 v[0:1], v[182:183], 0, v[194:195]
	flat_load_dwordx4 v[186:189], v[0:1]
	global_load_dwordx4 v[80:83], v[122:123], off offset:3072
	global_load_dwordx4 v[206:209], v[122:123], off offset:3088
	v_lshl_add_u64 v[0:1], v[180:181], 0, v[158:159]
	flat_load_dwordx4 v[104:107], v[0:1]
	v_lshl_add_u64 v[0:1], v[182:183], 0, v[158:159]
	v_mov_b32_e32 v161, v195
	flat_load_dwordx4 v[84:87], v[0:1]
	global_load_dwordx4 v[108:111], v[122:123], off offset:3216
	global_load_dwordx4 v[112:115], v[122:123], off offset:3200
	v_lshl_add_u64 v[0:1], v[180:181], 0, v[160:161]
	flat_load_dwordx4 v[88:91], v[0:1]
	v_lshl_add_u64 v[0:1], v[182:183], 0, v[160:161]
	v_mov_b32_e32 v163, v195
	flat_load_dwordx4 v[92:95], v[0:1]
	global_load_dwordx4 v[96:99], v[122:123], off offset:3328
	global_load_dwordx4 v[100:103], v[122:123], off offset:3344
	v_lshl_add_u64 v[0:1], v[180:181], 0, v[162:163]
	v_cndmask_b32_e64 v178, 1.0, 0, vcc
	flat_load_dwordx4 v[64:67], v[0:1]
	v_lshl_add_u64 v[0:1], v[182:183], 0, v[162:163]
	flat_load_dwordx4 v[68:71], v[0:1]
	global_load_dwordx4 v[72:75], v[122:123], off offset:3456
	global_load_dwordx4 v[76:79], v[122:123], off offset:3472
	flat_load_dwordx4 v[60:63], v[124:125]
	flat_load_dwordx4 v[56:59], v[124:125] offset:64
	flat_load_dwordx4 v[52:55], v[124:125] offset:128
	flat_load_dwordx4 v[48:51], v[124:125] offset:192
	flat_load_dwordx4 v[44:47], v[124:125] offset:1024
	flat_load_dwordx4 v[40:43], v[124:125] offset:1088
	flat_load_dwordx4 v[28:31], v[124:125] offset:1152
	flat_load_dwordx4 v[24:27], v[124:125] offset:1216
	flat_load_dwordx4 v[20:23], v[126:127]
	flat_load_dwordx4 v[0:3], v[128:129]
	flat_load_dwordx4 v[4:7], v[130:131]
	flat_load_dwordx4 v[8:11], v[132:133]
	flat_load_dwordx4 v[12:15], v[134:135]
	flat_load_dwordx4 v[16:19], v[136:137]
	flat_load_dwordx4 v[32:35], v[138:139]
	flat_load_dwordx4 v[36:39], v[140:141]
	v_ashrrev_i32_e32 v177, 31, v176
	v_lshlrev_b64 v[212:213], 9, v[176:177]
	v_lshl_add_u64 v[212:213], v[156:157], 0, v[212:213]
	s_waitcnt vmcnt(0) lgkmcnt(0)
	v_and_b32_e32 v163, 0xffff0000, v116
	v_lshlrev_b32_e32 v165, 16, v117
	v_and_b32_e32 v167, 0xffff0000, v117
	v_lshlrev_b32_e32 v161, 16, v118
	v_and_b32_e32 v159, 0xffff0000, v118
	v_lshlrev_b32_e32 v118, 16, v119
	v_and_b32_e32 v117, 0xffff0000, v119
	v_and_b32_e32 v119, 0xffff0000, v186
	v_lshlrev_b32_e32 v169, 16, v187
	v_fma_f32 v119, v178, v119, -v163
	v_and_b32_e32 v171, 0xffff0000, v187
	v_fmac_f32_e32 v163, v81, v119
	v_fma_f32 v81, v178, v169, -v165
	v_lshlrev_b32_e32 v173, 16, v188
	v_fmac_f32_e32 v165, v82, v81
	v_fma_f32 v81, v178, v171, -v167
	v_and_b32_e32 v175, 0xffff0000, v188
	v_fmac_f32_e32 v167, v83, v81
	v_fma_f32 v81, v178, v173, -v161
	v_lshlrev_b32_e32 v187, 16, v189
	v_fmac_f32_e32 v161, v206, v81
	v_fma_f32 v81, v178, v175, -v159
	v_and_b32_e32 v188, 0xffff0000, v189
	v_fmac_f32_e32 v159, v207, v81
	v_fma_f32 v81, v178, v187, -v118
	v_fmac_f32_e32 v118, v208, v81
	v_fma_f32 v81, v178, v188, -v117
	v_fmac_f32_e32 v117, v209, v81
	v_lshlrev_b32_e32 v81, 16, v186
	v_lshlrev_b32_e32 v82, 16, v116
	v_fma_f32 v81, v178, v81, -v82
	v_fmac_f32_e32 v82, v80, v81
	v_add_f32_e32 v80, v82, v82
	v_add_f32_e32 v81, v163, v163
	v_mul_f32_e32 v80, 0x3fb8aa3b, v80
	v_mul_f32_e32 v81, 0x3fb8aa3b, v81
	v_exp_f32_e32 v80, v80
	v_exp_f32_e32 v81, v81
	v_add_f32_e32 v117, v117, v117
	v_mul_f32_e32 v117, 0x3fb8aa3b, v117
	v_exp_f32_e32 v117, v117
	v_pk_add_f32 v[80:81], v[80:81], 1.0 op_sel_hi:[1,0]
	v_mov_b32_e32 v169, v195
	v_mov_b32_e32 v171, v195
	v_mov_b32_e32 v173, v195
	v_mov_b32_e32 v175, v195
	v_rcp_f32_e32 v81, v81
	s_nop 0
	v_mul_f32_e32 v81, 2.0, v81
	v_rcp_f32_e32 v80, v80
	s_nop 0
	v_mul_f32_e32 v80, 2.0, v80
	v_add_f32_e32 v82, v165, v165
	v_add_f32_e32 v83, v167, v167
	v_mul_f32_e32 v82, 0x3fb8aa3b, v82
	v_mul_f32_e32 v83, 0x3fb8aa3b, v83
	v_exp_f32_e32 v82, v82
	v_exp_f32_e32 v83, v83
	v_pk_add_f32 v[80:81], v[80:81], 1.0 op_sel_hi:[1,0] neg_lo:[1,0] neg_hi:[1,0]
	v_pk_add_f32 v[82:83], v[82:83], 1.0 op_sel_hi:[1,0]
	s_nop 0
	v_cvt_pk_bf16_f32 v80, v80, v81
	v_rcp_f32_e32 v83, v83
	s_nop 0
	v_mul_f32_e32 v83, 2.0, v83
	v_rcp_f32_e32 v82, v82
	s_nop 0
	v_mul_f32_e32 v82, 2.0, v82
	v_add_f32_e32 v116, v161, v161
	v_mul_f32_e32 v116, 0x3fb8aa3b, v116
	v_exp_f32_e32 v186, v116
	v_add_f32_e32 v116, v159, v159
	v_mul_f32_e32 v116, 0x3fb8aa3b, v116
	v_exp_f32_e32 v187, v116
	v_pk_add_f32 v[82:83], v[82:83], 1.0 op_sel_hi:[1,0] neg_lo:[1,0] neg_hi:[1,0]
	v_mov_b32_e32 v165, v195
	v_cvt_pk_bf16_f32 v81, v82, v83
	v_pk_add_f32 v[186:187], v[186:187], 1.0 op_sel_hi:[1,0]
	v_mov_b32_e32 v167, v195
	v_rcp_f32_e32 v187, v187
	s_nop 0
	v_mul_f32_e32 v187, 2.0, v187
	v_rcp_f32_e32 v186, v186
	s_nop 0
	v_mul_f32_e32 v186, 2.0, v186
	v_add_f32_e32 v116, v118, v118
	v_mul_f32_e32 v116, 0x3fb8aa3b, v116
	v_exp_f32_e32 v116, v116
	v_pk_add_f32 v[186:187], v[186:187], 1.0 op_sel_hi:[1,0] neg_lo:[1,0] neg_hi:[1,0]
	v_pk_add_f32 v[116:117], v[116:117], 1.0 op_sel_hi:[1,0]
	s_nop 0
	v_cvt_pk_bf16_f32 v82, v186, v187
	v_rcp_f32_e32 v117, v117
	s_nop 0
	v_mul_f32_e32 v117, 2.0, v117
	v_rcp_f32_e32 v116, v116
	s_nop 0
	v_mul_f32_e32 v116, 2.0, v116
	v_pk_add_f32 v[116:117], v[116:117], 1.0 op_sel_hi:[1,0] neg_lo:[1,0] neg_hi:[1,0]
	v_lshlrev_b32_e32 v118, 16, v84
	v_cvt_pk_bf16_f32 v83, v116, v117
	v_lshlrev_b32_e32 v116, 16, v104
	v_and_b32_e32 v117, 0xffff0000, v104
	v_and_b32_e32 v119, 0xffff0000, v84
	v_lshlrev_b32_e32 v104, 16, v105
	v_and_b32_e32 v105, 0xffff0000, v105
	v_lshlrev_b32_e32 v84, 16, v85
	v_and_b32_e32 v85, 0xffff0000, v85
	v_pk_fma_f32 v[84:85], v[178:179], v[84:85], v[104:105] op_sel_hi:[0,1,1] neg_lo:[0,0,1] neg_hi:[0,0,1]
	v_pk_fma_f32 v[104:105], v[114:115], v[84:85], v[104:105]
	v_lshlrev_b32_e32 v84, 16, v106
	v_and_b32_e32 v85, 0xffff0000, v106
	v_lshlrev_b32_e32 v114, 16, v86
	v_and_b32_e32 v115, 0xffff0000, v86
	v_pk_fma_f32 v[114:115], v[178:179], v[114:115], v[84:85] op_sel_hi:[0,1,1] neg_lo:[0,0,1] neg_hi:[0,0,1]
	v_pk_fma_f32 v[108:109], v[108:109], v[114:115], v[84:85]
	v_lshlrev_b32_e32 v84, 16, v107
	v_and_b32_e32 v85, 0xffff0000, v107
	v_lshlrev_b32_e32 v86, 16, v87
	v_and_b32_e32 v87, 0xffff0000, v87
	v_pk_fma_f32 v[86:87], v[178:179], v[86:87], v[84:85] op_sel_hi:[0,1,1] neg_lo:[0,0,1] neg_hi:[0,0,1]
	v_pk_fma_f32 v[106:107], v[110:111], v[86:87], v[84:85]
	v_cvt_pk_bf16_f32 v85, v104, v105
	v_cvt_pk_bf16_f32 v87, v106, v107
	v_and_b32_e32 v104, 0xffff0000, v88
	v_lshlrev_b32_e32 v105, 16, v89
	v_and_b32_e32 v106, 0xffff0000, v89
	v_and_b32_e32 v89, 0xffff0000, v92
	v_cvt_pk_bf16_f32 v86, v108, v109
	v_lshlrev_b32_e32 v109, 16, v93
	v_fma_f32 v89, v178, v89, -v104
	v_and_b32_e32 v93, 0xffff0000, v93
	v_fmac_f32_e32 v104, v97, v89
	v_fma_f32 v89, v178, v109, -v105
	v_lshlrev_b32_e32 v107, 16, v90
	v_lshlrev_b32_e32 v110, 16, v94
	v_fmac_f32_e32 v105, v98, v89
	v_fma_f32 v89, v178, v93, -v106
	v_and_b32_e32 v90, 0xffff0000, v90
	v_and_b32_e32 v94, 0xffff0000, v94
	v_fmac_f32_e32 v106, v99, v89
	v_fma_f32 v89, v178, v110, -v107
	v_lshlrev_b32_e32 v108, 16, v91
	v_lshlrev_b32_e32 v111, 16, v95
	v_fmac_f32_e32 v107, v100, v89
	v_fma_f32 v89, v178, v94, -v90
	v_and_b32_e32 v91, 0xffff0000, v91
	v_and_b32_e32 v95, 0xffff0000, v95
	v_fmac_f32_e32 v90, v101, v89
	v_fma_f32 v89, v178, v111, -v108
	v_fmac_f32_e32 v108, v102, v89
	v_fma_f32 v89, v178, v95, -v91
	v_fmac_f32_e32 v91, v103, v89
	v_lshlrev_b32_e32 v89, 16, v92
	v_lshlrev_b32_e32 v88, 16, v88
	v_fma_f32 v89, v178, v89, -v88
	v_fmac_f32_e32 v88, v96, v89
	v_mul_f32_e32 v88, 0xbfb8aa3b, v88
	v_mul_f32_e32 v89, 0xbfb8aa3b, v104
	v_exp_f32_e32 v88, v88
	v_exp_f32_e32 v89, v89
	v_pk_fma_f32 v[118:119], v[178:179], v[118:119], v[116:117] op_sel_hi:[0,1,1] neg_lo:[0,0,1] neg_hi:[0,0,1]
	v_pk_fma_f32 v[112:113], v[112:113], v[118:119], v[116:117]
	v_pk_add_f32 v[88:89], v[88:89], 1.0 op_sel_hi:[1,0]
	s_nop 0
	v_cvt_pk_bf16_f32 v84, v112, v113
	v_rcp_f32_e32 v92, v89
	s_nop 0
	v_mfma_f32_16x16x32_bf16 v[16:19], v[16:19], v[84:87], 0
	v_rcp_f32_e32 v93, v88
	v_mul_f32_e32 v88, 0xbfb8aa3b, v105
	v_mul_f32_e32 v89, 0xbfb8aa3b, v106
	v_exp_f32_e32 v88, v88
	v_exp_f32_e32 v89, v89
	s_nop 0
	v_pk_add_f32 v[88:89], v[88:89], 1.0 op_sel_hi:[1,0]
	s_nop 0
	v_rcp_f32_e32 v94, v89
	v_rcp_f32_e32 v95, v88
	v_mul_f32_e32 v88, 0xbfb8aa3b, v107
	v_mul_f32_e32 v89, 0xbfb8aa3b, v90
	v_exp_f32_e32 v88, v88
	v_exp_f32_e32 v89, v89
	s_nop 0
	v_pk_add_f32 v[88:89], v[88:89], 1.0 op_sel_hi:[1,0]
	s_nop 0
	v_rcp_f32_e32 v90, v89
	v_rcp_f32_e32 v96, v88
	v_mul_f32_e32 v88, 0xbfb8aa3b, v108
	v_mul_f32_e32 v89, 0xbfb8aa3b, v91
	v_exp_f32_e32 v88, v88
	v_exp_f32_e32 v89, v89
	v_cvt_pk_bf16_f32 v90, v96, v90
	v_lshlrev_b32_e32 v96, 16, v67
	v_and_b32_e32 v67, 0xffff0000, v67
	v_pk_add_f32 v[88:89], v[88:89], 1.0 op_sel_hi:[1,0]
	s_nop 0
	v_rcp_f32_e32 v91, v89
	v_rcp_f32_e32 v97, v88
	v_cvt_pk_bf16_f32 v88, v93, v92
	v_cvt_pk_bf16_f32 v89, v95, v94
	v_and_b32_e32 v92, 0xffff0000, v64
	v_lshlrev_b32_e32 v93, 16, v65
	v_and_b32_e32 v94, 0xffff0000, v65
	v_and_b32_e32 v65, 0xffff0000, v68
	v_cvt_pk_bf16_f32 v91, v97, v91
	v_lshlrev_b32_e32 v97, 16, v69
	v_fma_f32 v65, v178, v65, -v92
	v_and_b32_e32 v69, 0xffff0000, v69
	v_fmac_f32_e32 v92, v73, v65
	v_fma_f32 v65, v178, v97, -v93
	v_lshlrev_b32_e32 v95, 16, v66
	v_lshlrev_b32_e32 v98, 16, v70
	v_fmac_f32_e32 v93, v74, v65
	v_fma_f32 v65, v178, v69, -v94
	v_and_b32_e32 v66, 0xffff0000, v66
	v_and_b32_e32 v70, 0xffff0000, v70
	v_fmac_f32_e32 v94, v75, v65
	v_fma_f32 v65, v178, v98, -v95
	v_lshlrev_b32_e32 v99, 16, v71
	v_fmac_f32_e32 v95, v76, v65
	v_fma_f32 v65, v178, v70, -v66
	v_and_b32_e32 v71, 0xffff0000, v71
	v_fmac_f32_e32 v66, v77, v65
	v_fma_f32 v65, v178, v99, -v96
	v_fmac_f32_e32 v96, v78, v65
	v_fma_f32 v65, v178, v71, -v67
	v_fmac_f32_e32 v67, v79, v65
	v_lshlrev_b32_e32 v65, 16, v68
	v_lshlrev_b32_e32 v64, 16, v64
	v_fma_f32 v65, v178, v65, -v64
	v_fmac_f32_e32 v64, v72, v65
	v_mul_f32_e32 v64, 0xbfb8aa3b, v64
	v_mul_f32_e32 v65, 0xbfb8aa3b, v92
	v_exp_f32_e32 v64, v64
	v_exp_f32_e32 v65, v65
	v_mfma_f32_16x16x32_bf16 v[28:31], v[28:31], v[88:91], 0
	v_add_f32_e64 v64, v64, 1.0
	v_add_f32_e64 v65, v65, 1.0
	v_mfma_f32_16x16x32_bf16 v[52:55], v[52:55], v[88:91], 0
	v_rcp_f32_e32 v68, v65
	v_rcp_f32_e32 v69, v64
	v_mul_f32_e32 v64, 0xbfb8aa3b, v93
	v_mul_f32_e32 v65, 0xbfb8aa3b, v94
	v_exp_f32_e32 v64, v64
	v_exp_f32_e32 v65, v65
	s_nop 0
	v_pk_add_f32 v[64:65], v[64:65], 1.0 op_sel_hi:[1,0]
	s_nop 0
	v_rcp_f32_e32 v70, v65
	v_rcp_f32_e32 v71, v64
	v_mul_f32_e32 v64, 0xbfb8aa3b, v95
	v_mul_f32_e32 v65, 0xbfb8aa3b, v66
	v_exp_f32_e32 v64, v64
	v_exp_f32_e32 v65, v65
	v_mfma_f32_16x16x32_bf16 v[92:95], v[56:59], v[84:87], 0
	v_add_f32_e64 v64, v64, 1.0
	v_add_f32_e64 v65, v65, 1.0
	v_mfma_f32_16x16x32_bf16 v[56:59], v[40:43], v[84:87], 0
	v_rcp_f32_e32 v66, v65
	v_rcp_f32_e32 v72, v64
	v_mul_f32_e32 v64, 0xbfb8aa3b, v96
	v_mul_f32_e32 v65, 0xbfb8aa3b, v67
	v_exp_f32_e32 v64, v64
	v_exp_f32_e32 v65, v65
	v_cvt_pk_bf16_f32 v66, v72, v66
	v_mfma_f32_16x16x32_bf16 v[96:99], v[60:63], v[80:83], 0
	v_add_f32_e64 v64, v64, 1.0
	v_add_f32_e64 v65, v65, 1.0
	v_mfma_f32_16x16x32_bf16 v[60:63], v[44:47], v[80:83], 0
	v_rcp_f32_e32 v67, v65
	v_rcp_f32_e32 v73, v64
	v_cvt_pk_bf16_f32 v64, v69, v68
	v_cvt_pk_bf16_f32 v65, v71, v70
	v_cvt_pk_bf16_f32 v67, v73, v67
	s_nop 1
	v_mfma_f32_16x16x32_bf16 v[40:43], v[24:27], v[64:67], v[28:31]
	v_mfma_f32_16x16x32_bf16 v[24:27], v[0:3], v[84:87], 0
	v_mfma_f32_16x16x32_bf16 v[0:3], v[4:7], v[88:91], 0
	v_mfma_f32_16x16x32_bf16 v[0:3], v[8:11], v[64:67], v[0:3]
	v_lshl_add_u64 v[8:9], v[180:181], 0, v[164:165]
	flat_load_dwordx4 v[186:189], v[8:9]
	v_lshl_add_u64 v[8:9], v[8:9], 0, v[184:185]
	v_mfma_f32_16x16x32_bf16 v[4:7], v[32:35], v[88:91], 0
	flat_load_dwordx4 v[216:219], v[8:9]
	global_load_dwordx4 v[222:225], v[142:143], off offset:16
	global_load_dwordx4 v[208:211], v[142:143], off
	v_lshl_add_u64 v[8:9], v[180:181], 0, v[166:167]
	flat_load_dwordx4 v[72:75], v[8:9]
	v_lshl_add_u64 v[8:9], v[182:183], 0, v[166:167]
	v_mfma_f32_16x16x32_bf16 v[48:51], v[48:51], v[64:67], v[52:55]
	v_cvt_pk_bf16_f32 v0, v0, v1
	v_cvt_pk_bf16_f32 v1, v2, v3
	s_waitcnt vmcnt(0) lgkmcnt(0)
	v_lshlrev_b32_e32 v184, 16, v186
	v_mfma_f32_16x16x32_bf16 v[4:7], v[36:39], v[64:67], v[4:7]
	flat_load_dwordx4 v[68:71], v[8:9]
	global_load_dwordx4 v[64:67], v[142:143], off offset:1040
	global_load_dwordx4 v[100:103], v[142:143], off offset:1024
	v_lshl_add_u64 v[8:9], v[180:181], 0, v[168:169]
	flat_load_dwordx4 v[44:47], v[8:9]
	v_lshl_add_u64 v[8:9], v[182:183], 0, v[168:169]
	v_mfma_f32_16x16x32_bf16 v[28:31], v[20:23], v[80:83], 0
	v_and_b32_e32 v185, 0xffff0000, v186
	v_lshlrev_b32_e32 v190, 16, v216
	v_and_b32_e32 v191, 0xffff0000, v216
	v_mfma_f32_16x16x32_bf16 v[20:23], v[12:15], v[80:83], 0
	flat_load_dwordx4 v[36:39], v[8:9]
	global_load_dwordx4 v[32:35], v[142:143], off offset:2064
	global_load_dwordx4 v[52:55], v[142:143], off offset:2048
	global_load_dwordx4 v[84:87], v[144:145], off offset:16
	global_load_dwordx4 v[116:119], v[144:145], off
	global_load_dwordx4 v[88:91], v[146:147], off offset:16
	global_load_dwordx4 v[112:115], v[146:147], off
	global_load_dwordx4 v[8:11], v[148:149], off
	global_load_dwordx4 v[12:15], v[148:149], off offset:16
	global_load_dwordx4 v[80:83], v[150:151], off offset:16
	global_load_dwordx4 v[108:111], v[150:151], off
	global_load_dwordx4 v[76:79], v[152:153], off offset:16
	global_load_dwordx4 v[104:107], v[152:153], off
	v_pk_fma_f32 v[190:191], v[178:179], v[190:191], v[184:185] op_sel_hi:[0,1,1] neg_lo:[0,0,1] neg_hi:[0,0,1]
	v_pk_fma_f32 v[208:209], v[208:209], v[190:191], v[184:185]
	v_lshlrev_b32_e32 v184, 16, v187
	v_and_b32_e32 v185, 0xffff0000, v187
	v_lshlrev_b32_e32 v186, 16, v217
	v_and_b32_e32 v187, 0xffff0000, v217
	v_pk_fma_f32 v[186:187], v[178:179], v[186:187], v[184:185] op_sel_hi:[0,1,1] neg_lo:[0,0,1] neg_hi:[0,0,1]
	v_pk_fma_f32 v[214:215], v[210:211], v[186:187], v[184:185]
	v_lshlrev_b32_e32 v184, 16, v188
	v_and_b32_e32 v185, 0xffff0000, v188
	v_lshlrev_b32_e32 v186, 16, v218
	v_and_b32_e32 v187, 0xffff0000, v218
	v_pk_fma_f32 v[186:187], v[178:179], v[186:187], v[184:185] op_sel_hi:[0,1,1] neg_lo:[0,0,1] neg_hi:[0,0,1]
	v_pk_fma_f32 v[216:217], v[222:223], v[186:187], v[184:185]
	v_lshlrev_b32_e32 v184, 16, v189
	v_and_b32_e32 v185, 0xffff0000, v189
	v_lshlrev_b32_e32 v186, 16, v219
	v_and_b32_e32 v187, 0xffff0000, v219
	v_pk_fma_f32 v[186:187], v[178:179], v[186:187], v[184:185] op_sel_hi:[0,1,1] neg_lo:[0,0,1] neg_hi:[0,0,1]
	v_pk_fma_f32 v[218:219], v[224:225], v[186:187], v[184:185]
	v_cvt_pk_bf16_f32 v2, v4, v5
	v_cvt_pk_bf16_f32 v3, v6, v7
	s_waitcnt vmcnt(0)
	v_add_f32_e32 v60, v60, v84
	v_add_f32_e32 v96, v96, v116
	v_max_f32_e64 v116, -v96, 0
	v_mul_f32_e64 v96, |v96|, s26
	v_exp_f32_e32 v96, v96
	v_add_f32_e32 v97, v97, v117
	v_add_f32_e32 v92, v92, v112
	v_max_f32_e64 v112, -v97, 0
	v_add_f32_e32 v96, 1.0, v96
	v_cmp_gt_f32_e32 vcc, s6, v96
	v_mul_f32_e64 v97, |v97|, s26
	v_exp_f32_e32 v97, v97
	v_cndmask_b32_e64 v159, 0, 32, vcc
	v_ldexp_f32 v96, v96, v159
	v_log_f32_e32 v96, v96
	v_add_f32_e32 v97, 1.0, v97
	v_add_f32_e32 v93, v93, v113
	v_mul_f32_e32 v92, 0xbfb8aa3b, v92
	v_mul_f32_e32 v159, 0x3f317217, v96
	v_fma_f32 v159, v96, s34, -v159
	v_fmac_f32_e32 v159, 0x3377d1cf, v96
	v_fmac_f32_e32 v159, 0x3f317217, v96
	v_cmp_lt_f32_e64 s[0:1], |v96|, s35
	v_mul_f32_e32 v93, 0xbfb8aa3b, v93
	v_exp_f32_e32 v92, v92
	v_cndmask_b32_e64 v96, v96, v159, s[0:1]
	v_cndmask_b32_e32 v159, 0, v242, vcc
	v_sub_f32_e32 v96, v96, v159
	v_cmp_gt_f32_e32 vcc, s6, v97
	v_add_f32_e32 v96, v116, v96
	v_exp_f32_e32 v93, v93
	v_cndmask_b32_e64 v116, 0, 32, vcc
	v_ldexp_f32 v97, v97, v116
	v_log_f32_e32 v97, v97
	v_pk_add_f32 v[92:93], v[92:93], 1.0 op_sel_hi:[1,0]
	s_waitcnt lgkmcnt(0)
	v_and_b32_e32 v117, 0xffff0000, v68
	v_and_b32_e32 v113, 0xffff0000, v72
	v_mul_f32_e32 v116, 0x3f317217, v97
	v_fma_f32 v116, v97, s34, -v116
	v_fmac_f32_e32 v116, 0x3377d1cf, v97
	v_fmac_f32_e32 v116, 0x3f317217, v97
	v_cmp_lt_f32_e64 s[0:1], |v97|, s35
	v_add_f32_e32 v61, v61, v85
	v_add_f32_e32 v56, v56, v88
	v_cndmask_b32_e64 v97, v97, v116, s[0:1]
	v_cndmask_b32_e32 v116, 0, v242, vcc
	v_sub_f32_e32 v97, v97, v116
	v_lshlrev_b32_e32 v116, 16, v68
	v_add_f32_e32 v97, v112, v97
	v_lshlrev_b32_e32 v112, 16, v72
	v_pk_fma_f32 v[116:117], v[178:179], v[116:117], v[112:113] op_sel_hi:[0,1,1] neg_lo:[0,0,1] neg_hi:[0,0,1]
	v_pk_fma_f32 v[184:185], v[100:101], v[116:117], v[112:113]
	v_add_f32_e32 v57, v57, v89
	v_rcp_f32_e32 v117, v93
	v_mul_f32_e32 v56, 0xbfb8aa3b, v56
	v_mul_f32_e32 v57, 0xbfb8aa3b, v57
	v_exp_f32_e32 v56, v56
	v_rcp_f32_e32 v116, v92
	v_add_f32_e32 v68, v98, v118
	v_max_f32_e64 v72, -v68, 0
	v_mul_f32_e64 v68, |v68|, s26
	v_exp_f32_e32 v68, v68
	v_pk_add_f32 v[92:93], v[116:117], -1.0 op_sel_hi:[1,0]
	v_exp_f32_e32 v57, v57
	v_pk_fma_f32 v[92:93], v[108:109], v[92:93], 1.0 op_sel_hi:[1,1,0]
	v_add_f32_e32 v68, 1.0, v68
	v_cmp_gt_f32_e32 vcc, s6, v68
	v_pk_mul_f32 v[92:93], v[184:185], v[92:93]
	v_and_b32_e32 v85, 0xffff0000, v74
	v_cndmask_b32_e64 v98, 0, 32, vcc
	v_ldexp_f32 v68, v68, v98
	v_log_f32_e32 v68, v68
	v_pk_mul_f32 v[100:101], v[208:209], v[92:93]
	v_lshlrev_b32_e32 v88, 16, v70
	v_fma_f32 v159, v104, v100, 0
	v_mul_f32_e32 v98, 0x3f317217, v68
	v_fma_f32 v98, v68, s34, -v98
	v_fmac_f32_e32 v98, 0x3377d1cf, v68
	v_fmac_f32_e32 v98, 0x3f317217, v68
	v_cmp_lt_f32_e64 s[0:1], |v68|, s35
	v_fmac_f32_e32 v159, v105, v101
	v_lshlrev_b32_e32 v100, 16, v73
	v_cndmask_b32_e64 v68, v68, v98, s[0:1]
	v_cndmask_b32_e32 v98, 0, v242, vcc
	v_sub_f32_e32 v68, v68, v98
	v_add_f32_e32 v68, v72, v68
	v_sub_f32_e32 v68, -0.5, v68
	v_mul_f32_e32 v68, 0x3fb8aa3b, v68
	v_exp_f32_e32 v68, v68
	v_and_b32_e32 v101, 0xffff0000, v73
	v_and_b32_e32 v89, 0xffff0000, v70
	v_pk_add_f32 v[56:57], v[56:57], 1.0 op_sel_hi:[1,0]
	v_xor_b32_e32 v72, 0x80000000, v68
	v_add_f32_e32 v68, v94, v114
	v_mul_f32_e32 v68, 0xbfb8aa3b, v68
	v_exp_f32_e32 v98, v68
	v_add_f32_e32 v68, v99, v119
	v_max_f32_e64 v94, -v68, 0
	v_mul_f32_e64 v68, |v68|, s26
	v_exp_f32_e32 v68, v68
	v_add_f32_e32 v62, v62, v86
	v_add_f32_e32 v58, v58, v90
	v_add_f32_e32 v59, v59, v91
	v_add_f32_e32 v68, 1.0, v68
	v_cmp_gt_f32_e32 vcc, s6, v68
	v_mul_f32_e32 v58, 0xbfb8aa3b, v58
	v_mul_f32_e32 v59, 0xbfb8aa3b, v59
	v_cndmask_b32_e64 v99, 0, 32, vcc
	v_ldexp_f32 v68, v68, v99
	v_log_f32_e32 v68, v68
	v_exp_f32_e32 v58, v58
	v_exp_f32_e32 v59, v59
	v_sub_f32_e32 v96, -0.5, v96
	v_mul_f32_e32 v99, 0x3f317217, v68
	v_fma_f32 v99, v68, s34, -v99
	v_fmac_f32_e32 v99, 0x3377d1cf, v68
	v_fmac_f32_e32 v99, 0x3f317217, v68
	v_cmp_lt_f32_e64 s[0:1], |v68|, s35
	v_pk_add_f32 v[58:59], v[58:59], 1.0 op_sel_hi:[1,0]
	v_sub_f32_e32 v97, -0.5, v97
	v_cndmask_b32_e64 v68, v68, v99, s[0:1]
	v_cndmask_b32_e32 v99, 0, v242, vcc
	v_sub_f32_e32 v68, v68, v99
	v_add_f32_e32 v68, v94, v68
	v_sub_f32_e32 v68, -0.5, v68
	v_mul_f32_e32 v68, 0x3fb8aa3b, v68
	v_exp_f32_e32 v68, v68
	v_mul_f32_e32 v96, 0x3fb8aa3b, v96
	v_mul_f32_e32 v97, 0x3fb8aa3b, v97
	v_exp_f32_e32 v96, v96
	v_xor_b32_e32 v94, 0x80000000, v68
	v_add_f32_e32 v68, v95, v115
	v_mul_f32_e32 v68, 0xbfb8aa3b, v68
	v_exp_f32_e32 v99, v68
	v_lshlrev_b32_e32 v68, 16, v69
	v_and_b32_e32 v69, 0xffff0000, v69
	v_pk_fma_f32 v[68:69], v[178:179], v[68:69], v[100:101] op_sel_hi:[0,1,1] neg_lo:[0,0,1] neg_hi:[0,0,1]
	v_pk_fma_f32 v[186:187], v[102:103], v[68:69], v[100:101]
	v_pk_add_f32 v[68:69], v[98:99], 1.0 op_sel_hi:[1,0]
	v_exp_f32_e32 v97, v97
	v_xor_b32_e32 v96, 0x80000000, v96
	v_xor_b32_e32 v97, 0x80000000, v97
	v_pk_mul_f32 v[8:9], v[184:185], v[8:9]
	v_rcp_f32_e32 v119, v69
	v_pk_mul_f32 v[10:11], v[186:187], v[10:11]
	v_max_f32_e64 v73, -v60, 0
	v_mul_f32_e64 v60, |v60|, s26
	v_exp_f32_e32 v60, v60
	v_rcp_f32_e32 v118, v68
	s_nop 0
	v_pk_add_f32 v[68:69], v[118:119], -1.0 op_sel_hi:[1,0]
	v_add_f32_e32 v60, 1.0, v60
	v_cmp_gt_f32_e32 vcc, s6, v60
	v_pk_fma_f32 v[68:69], v[110:111], v[68:69], 1.0 op_sel_hi:[1,1,0]
	s_nop 0
	v_cndmask_b32_e64 v84, 0, 32, vcc
	v_ldexp_f32 v60, v60, v84
	v_log_f32_e32 v60, v60
	v_pk_mul_f32 v[68:69], v[186:187], v[68:69]
	v_mul_f32_e32 v84, 0x3f317217, v60
	v_fma_f32 v84, v60, s34, -v84
	v_fmac_f32_e32 v84, 0x3377d1cf, v60
	v_fmac_f32_e32 v84, 0x3f317217, v60
	v_cmp_lt_f32_e64 s[0:1], |v60|, s35
	v_pk_mul_f32 v[98:99], v[214:215], v[68:69]
	s_nop 0
	v_cndmask_b32_e64 v60, v60, v84, s[0:1]
	v_cndmask_b32_e32 v84, 0, v242, vcc
	v_sub_f32_e32 v60, v60, v84
	v_add_f32_e32 v60, v73, v60
	v_max_f32_e64 v73, -v61, 0
	v_mul_f32_e64 v61, |v61|, s26
	v_exp_f32_e32 v61, v61
	v_fmac_f32_e32 v159, v106, v98
	v_fmac_f32_e32 v159, v107, v99
	v_sub_f32_e32 v60, -0.5, v60
	v_add_f32_e32 v61, 1.0, v61
	v_cmp_gt_f32_e32 vcc, s6, v61
	v_mul_f32_e32 v60, 0x3fb8aa3b, v60
	v_exp_f32_e32 v60, v60
	v_cndmask_b32_e64 v84, 0, 32, vcc
	v_ldexp_f32 v61, v61, v84
	v_log_f32_e32 v61, v61
	v_xor_b32_e32 v60, 0x80000000, v60
	v_mul_f32_e32 v84, 0x3f317217, v61
	v_fma_f32 v84, v61, s34, -v84
	v_fmac_f32_e32 v84, 0x3377d1cf, v61
	v_fmac_f32_e32 v84, 0x3f317217, v61
	v_cmp_lt_f32_e64 s[0:1], |v61|, s35
	s_nop 1
	v_cndmask_b32_e64 v61, v61, v84, s[0:1]
	v_cndmask_b32_e32 v84, 0, v242, vcc
	v_sub_f32_e32 v61, v61, v84
	v_lshlrev_b32_e32 v84, 16, v74
	v_pk_fma_f32 v[88:89], v[178:179], v[88:89], v[84:85] op_sel_hi:[0,1,1] neg_lo:[0,0,1] neg_hi:[0,0,1]
	v_pk_fma_f32 v[190:191], v[64:65], v[88:89], v[84:85]
	v_add_f32_e32 v61, v73, v61
	v_sub_f32_e32 v61, -0.5, v61
	v_mul_f32_e32 v61, 0x3fb8aa3b, v61
	v_rcp_f32_e32 v189, v57
	v_exp_f32_e32 v61, v61
	v_pk_mul_f32 v[6:7], v[190:191], v[12:13]
	v_rcp_f32_e32 v188, v56
	s_nop 0
	v_pk_add_f32 v[56:57], v[188:189], -1.0 op_sel_hi:[1,0]
	v_xor_b32_e32 v61, 0x80000000, v61
	v_pk_fma_f32 v[56:57], v[80:81], v[56:57], 1.0 op_sel_hi:[1,1,0]
	v_pk_mul_f32 v[12:13], v[6:7], v[6:7]
	v_pk_mul_f32 v[56:57], v[190:191], v[56:57]
	s_nop 0
	v_pk_mul_f32 v[64:65], v[216:217], v[56:57]
	s_nop 0
	v_fmac_f32_e32 v159, v76, v64
	v_max_f32_e64 v64, -v62, 0
	v_mul_f32_e64 v62, |v62|, s26
	v_exp_f32_e32 v62, v62
	v_fmac_f32_e32 v159, v77, v65
	v_add_f32_e32 v62, 1.0, v62
	v_cmp_gt_f32_e32 vcc, s6, v62
	s_nop 1
	v_cndmask_b32_e64 v65, 0, 32, vcc
	v_ldexp_f32 v62, v62, v65
	v_log_f32_e32 v62, v62
	s_nop 0
	v_mul_f32_e32 v65, 0x3f317217, v62
	v_fma_f32 v65, v62, s34, -v65
	v_fmac_f32_e32 v65, 0x3377d1cf, v62
	v_fmac_f32_e32 v65, 0x3f317217, v62
	v_cmp_lt_f32_e64 s[0:1], |v62|, s35
	s_nop 1
	v_cndmask_b32_e64 v62, v62, v65, s[0:1]
	v_cndmask_b32_e32 v65, 0, v242, vcc
	v_sub_f32_e32 v62, v62, v65
	v_add_f32_e32 v62, v64, v62
	v_sub_f32_e32 v62, -0.5, v62
	v_mul_f32_e32 v62, 0x3fb8aa3b, v62
	v_exp_f32_e32 v62, v62
	v_and_b32_e32 v65, 0xffff0000, v71
	v_xor_b32_e32 v70, 0x80000000, v62
	v_add_f32_e32 v62, v63, v87
	v_max_f32_e64 v63, -v62, 0
	v_mul_f32_e64 v62, |v62|, s26
	v_exp_f32_e32 v62, v62
	s_nop 0
	v_add_f32_e32 v62, 1.0, v62
	v_cmp_gt_f32_e32 vcc, s6, v62
	s_nop 1
	v_cndmask_b32_e64 v64, 0, 32, vcc
	v_ldexp_f32 v62, v62, v64
	v_log_f32_e32 v62, v62
	s_nop 0
	v_mul_f32_e32 v64, 0x3f317217, v62
	v_fma_f32 v64, v62, s34, -v64
	v_fmac_f32_e32 v64, 0x3377d1cf, v62
	v_fmac_f32_e32 v64, 0x3f317217, v62
	v_cmp_lt_f32_e64 s[0:1], |v62|, s35
	s_nop 1
	v_cndmask_b32_e64 v62, v62, v64, s[0:1]
	v_cndmask_b32_e32 v64, 0, v242, vcc
	v_sub_f32_e32 v62, v62, v64
	v_add_f32_e32 v62, v63, v62
	v_sub_f32_e32 v62, -0.5, v62
	v_mul_f32_e32 v62, 0x3fb8aa3b, v62
	v_exp_f32_e32 v62, v62
	v_and_b32_e32 v63, 0xffff0000, v75
	v_lshlrev_b32_e32 v64, 16, v71
	v_xor_b32_e32 v73, 0x80000000, v62
	v_lshlrev_b32_e32 v62, 16, v75
	v_pk_fma_f32 v[64:65], v[178:179], v[64:65], v[62:63] op_sel_hi:[0,1,1] neg_lo:[0,0,1] neg_hi:[0,0,1]
	v_pk_fma_f32 v[210:211], v[66:67], v[64:65], v[62:63]
	v_rcp_f32_e32 v207, v59
	v_rcp_f32_e32 v206, v58
	s_nop 0
	v_pk_add_f32 v[58:59], v[206:207], -1.0 op_sel_hi:[1,0]
	v_lshlrev_b32_e32 v64, 16, v36
	v_pk_fma_f32 v[58:59], v[82:83], v[58:59], 1.0 op_sel_hi:[1,1,0]
	v_and_b32_e32 v65, 0xffff0000, v36
	v_pk_mul_f32 v[58:59], v[210:211], v[58:59]
	v_lshlrev_b32_e32 v36, 16, v37
	v_pk_mul_f32 v[62:63], v[218:219], v[58:59]
	v_and_b32_e32 v37, 0xffff0000, v37
	v_fmac_f32_e32 v159, v78, v62
	v_fmac_f32_e32 v159, v79, v63
	v_lshlrev_b32_e32 v62, 16, v44
	v_and_b32_e32 v63, 0xffff0000, v44
	v_lshlrev_b32_e32 v44, 16, v45
	v_and_b32_e32 v45, 0xffff0000, v45
	v_pk_fma_f32 v[36:37], v[178:179], v[36:37], v[44:45] op_sel_hi:[0,1,1] neg_lo:[0,0,1] neg_hi:[0,0,1]
	v_pk_fma_f32 v[36:37], v[54:55], v[36:37], v[44:45]
	v_lshlrev_b32_e32 v44, 16, v46
	v_and_b32_e32 v45, 0xffff0000, v46
	v_lshlrev_b32_e32 v54, 16, v38
	v_and_b32_e32 v55, 0xffff0000, v38
	v_pk_fma_f32 v[54:55], v[178:179], v[54:55], v[44:45] op_sel_hi:[0,1,1] neg_lo:[0,0,1] neg_hi:[0,0,1]
	v_pk_fma_f32 v[44:45], v[32:33], v[54:55], v[44:45]
	v_lshlrev_b32_e32 v32, 16, v47
	v_and_b32_e32 v33, 0xffff0000, v47
	v_lshlrev_b32_e32 v38, 16, v39
	v_and_b32_e32 v39, 0xffff0000, v39
	v_pk_fma_f32 v[38:39], v[178:179], v[38:39], v[32:33] op_sel_hi:[0,1,1] neg_lo:[0,0,1] neg_hi:[0,0,1]
	v_pk_fma_f32 v[64:65], v[178:179], v[64:65], v[62:63] op_sel_hi:[0,1,1] neg_lo:[0,0,1] neg_hi:[0,0,1]
	v_pk_fma_f32 v[38:39], v[34:35], v[38:39], v[32:33]
	v_cvt_pk_bf16_f32 v32, v208, v209
	v_cvt_pk_bf16_f32 v33, v214, v215
	v_cvt_pk_bf16_f32 v34, v216, v217
	v_cvt_pk_bf16_f32 v35, v218, v219
	v_mad_i64_i32 v[208:209], s[0:1], v176, s23, v[154:155]
	v_pk_fma_f32 v[52:53], v[52:53], v[64:65], v[62:63]
	flat_store_dwordx4 v[208:209], v[32:35]
	s_nop 1
	v_cvt_pk_bf16_f32 v32, v92, v93
	v_cvt_pk_bf16_f32 v33, v68, v69
	v_cvt_pk_bf16_f32 v34, v56, v57
	v_cvt_pk_bf16_f32 v35, v58, v59
	flat_store_dwordx4 v[208:209], v[32:35] offset:512
	s_nop 1
	v_cvt_pk_bf16_f32 v32, v52, v53
	v_cvt_pk_bf16_f32 v33, v36, v37
	v_cvt_pk_bf16_f32 v34, v44, v45
	v_cvt_pk_bf16_f32 v35, v38, v39
	flat_store_dwordx4 v[208:209], v[32:35] offset:1024
	s_nop 1
	v_cvt_pk_bf16_f32 v32, v96, v97
	v_cvt_pk_bf16_f32 v33, v72, v94
	v_cvt_pk_bf16_f32 v34, v60, v61
	v_cvt_pk_bf16_f32 v35, v70, v73
	flat_store_dwordx4 v[208:209], v[32:35] offset:2560
	s_nop 1
	v_cvt_pk_bf16_f32 v32, v48, v49
	v_cvt_pk_bf16_f32 v33, v50, v51
	v_cvt_pk_bf16_f32 v34, v40, v41
	v_cvt_pk_bf16_f32 v35, v42, v43
	flat_store_dwordx4 v[212:213], v[32:35]
	s_nop 1
	v_lshl_add_u64 v[32:33], v[180:181], 0, v[170:171]
	flat_load_dwordx4 v[108:111], v[32:33]
	v_lshl_add_u64 v[32:33], v[182:183], 0, v[170:171]
	flat_load_dwordx4 v[112:115], v[32:33]
	global_load_dwordx4 v[104:107], v[142:143], off offset:144
	global_load_dwordx4 v[214:217], v[142:143], off offset:128
	v_lshl_add_u64 v[32:33], v[180:181], 0, v[172:173]
	flat_load_dwordx4 v[60:63], v[32:33]
	v_lshl_add_u64 v[32:33], v[182:183], 0, v[172:173]
	flat_load_dwordx4 v[56:59], v[32:33]
	global_load_dwordx4 v[52:55], v[142:143], off offset:1168
	global_load_dwordx4 v[84:87], v[142:143], off offset:1152
	v_lshl_add_u64 v[32:33], v[180:181], 0, v[174:175]
	flat_load_dwordx4 v[40:43], v[32:33]
	v_lshl_add_u64 v[32:33], v[182:183], 0, v[174:175]
	flat_load_dwordx4 v[36:39], v[32:33]
	s_nop 0
	global_load_dwordx4 v[32:35], v[142:143], off offset:2192
	global_load_dwordx4 v[44:47], v[142:143], off offset:2176
	global_load_dwordx4 v[64:67], v[144:145], off offset:144
	global_load_dwordx4 v[96:99], v[144:145], off offset:128
	global_load_dwordx4 v[80:83], v[146:147], off offset:144
	global_load_dwordx4 v[100:103], v[146:147], off offset:128
	global_load_dwordx4 v[68:71], v[148:149], off offset:144
	global_load_dwordx4 v[48:51], v[148:149], off offset:128
	global_load_dwordx4 v[76:79], v[150:151], off offset:144
	global_load_dwordx4 v[92:95], v[150:151], off offset:128
	global_load_dwordx4 v[72:75], v[152:153], off offset:144
	global_load_dwordx4 v[88:91], v[152:153], off offset:128
	s_waitcnt vmcnt(0) lgkmcnt(0)
	v_lshlrev_b32_e32 v180, 16, v108
	v_and_b32_e32 v181, 0xffff0000, v108
	v_add_f32_e32 v28, v28, v96
	v_max_f32_e64 v96, -v28, 0
	v_mul_f32_e64 v28, |v28|, s26
	v_lshlrev_b32_e32 v182, 16, v112
	v_and_b32_e32 v183, 0xffff0000, v112
	v_lshlrev_b32_e32 v108, 16, v109
	v_and_b32_e32 v109, 0xffff0000, v109
	v_lshlrev_b32_e32 v112, 16, v113
	v_and_b32_e32 v113, 0xffff0000, v113
	v_exp_f32_e32 v28, v28
	v_pk_fma_f32 v[182:183], v[178:179], v[182:183], v[180:181] op_sel_hi:[0,1,1] neg_lo:[0,0,1] neg_hi:[0,0,1]
	v_pk_fma_f32 v[112:113], v[178:179], v[112:113], v[108:109] op_sel_hi:[0,1,1] neg_lo:[0,0,1] neg_hi:[0,0,1]
	v_pk_fma_f32 v[180:181], v[214:215], v[182:183], v[180:181]
	v_pk_fma_f32 v[108:109], v[216:217], v[112:113], v[108:109]
	v_lshlrev_b32_e32 v112, 16, v110
	v_and_b32_e32 v113, 0xffff0000, v110
	v_lshlrev_b32_e32 v182, 16, v114
	v_and_b32_e32 v183, 0xffff0000, v114
	v_pk_fma_f32 v[182:183], v[178:179], v[182:183], v[112:113] op_sel_hi:[0,1,1] neg_lo:[0,0,1] neg_hi:[0,0,1]
	v_pk_fma_f32 v[104:105], v[104:105], v[182:183], v[112:113]
	v_lshlrev_b32_e32 v110, 16, v111
	v_and_b32_e32 v111, 0xffff0000, v111
	v_lshlrev_b32_e32 v112, 16, v115
	v_and_b32_e32 v113, 0xffff0000, v115
	v_add_f32_e32 v28, 1.0, v28
	v_pk_fma_f32 v[112:113], v[178:179], v[112:113], v[110:111] op_sel_hi:[0,1,1] neg_lo:[0,0,1] neg_hi:[0,0,1]
	v_cmp_gt_f32_e32 vcc, s6, v28
	v_pk_fma_f32 v[106:107], v[106:107], v[112:113], v[110:111]
	v_add_f32_e32 v24, v24, v100
	v_cndmask_b32_e64 v110, 0, 32, vcc
	v_ldexp_f32 v28, v28, v110
	v_log_f32_e32 v28, v28
	v_add_f32_e32 v25, v25, v101
	v_mul_f32_e32 v24, 0xbfb8aa3b, v24
	v_mul_f32_e32 v25, 0xbfb8aa3b, v25
	v_mul_f32_e32 v110, 0x3f317217, v28
	v_fma_f32 v110, v28, s34, -v110
	v_fmac_f32_e32 v110, 0x3377d1cf, v28
	v_fmac_f32_e32 v110, 0x3f317217, v28
	v_cmp_lt_f32_e64 s[0:1], |v28|, s35
	v_exp_f32_e32 v24, v24
	v_exp_f32_e32 v25, v25
	v_cndmask_b32_e64 v28, v28, v110, s[0:1]
	v_cndmask_b32_e32 v110, 0, v242, vcc
	v_sub_f32_e32 v28, v28, v110
	v_add_f32_e32 v28, v96, v28
	v_sub_f32_e32 v28, -0.5, v28
	v_mul_f32_e32 v28, 0x3fb8aa3b, v28
	v_exp_f32_e32 v28, v28
	v_pk_add_f32 v[24:25], v[24:25], 1.0 op_sel_hi:[1,0]
	v_lshlrev_b32_e32 v100, 16, v56
	v_and_b32_e32 v101, 0xffff0000, v56
	v_xor_b32_e32 v96, 0x80000000, v28
	v_add_f32_e32 v28, v29, v97
	v_max_f32_e64 v29, -v28, 0
	v_mul_f32_e64 v28, |v28|, s26
	v_exp_f32_e32 v28, v28
	v_add_f32_e32 v30, v30, v98
	v_add_f32_e32 v26, v26, v102
	v_add_f32_e32 v27, v27, v103
	v_add_f32_e32 v28, 1.0, v28
	v_cmp_gt_f32_e32 vcc, s6, v28
	v_mul_f32_e32 v26, 0xbfb8aa3b, v26
	v_mul_f32_e32 v27, 0xbfb8aa3b, v27
	v_cndmask_b32_e64 v97, 0, 32, vcc
	v_ldexp_f32 v28, v28, v97
	v_log_f32_e32 v28, v28
	v_exp_f32_e32 v26, v26
	v_exp_f32_e32 v27, v27
	v_add_f32_e32 v20, v20, v64
	v_mul_f32_e32 v97, 0x3f317217, v28
	v_fma_f32 v97, v28, s34, -v97
	v_fmac_f32_e32 v97, 0x3377d1cf, v28
	v_fmac_f32_e32 v97, 0x3f317217, v28
	v_cmp_lt_f32_e64 s[0:1], |v28|, s35
	v_pk_add_f32 v[26:27], v[26:27], 1.0 op_sel_hi:[1,0]
	v_add_f32_e32 v16, v16, v80
	v_cndmask_b32_e64 v28, v28, v97, s[0:1]
	v_cndmask_b32_e32 v97, 0, v242, vcc
	v_sub_f32_e32 v28, v28, v97
	v_add_f32_e32 v28, v29, v28
	v_sub_f32_e32 v28, -0.5, v28
	v_mul_f32_e32 v28, 0x3fb8aa3b, v28
	v_exp_f32_e32 v28, v28
	v_and_b32_e32 v29, 0xffff0000, v60
	v_xor_b32_e32 v97, 0x80000000, v28
	v_lshlrev_b32_e32 v28, 16, v60
	v_pk_fma_f32 v[100:101], v[178:179], v[100:101], v[28:29] op_sel_hi:[0,1,1] neg_lo:[0,0,1] neg_hi:[0,0,1]
	v_pk_fma_f32 v[28:29], v[84:85], v[100:101], v[28:29]
	v_add_f32_e32 v17, v17, v81
	v_rcp_f32_e32 v25, v25
	v_mul_f32_e32 v16, 0xbfb8aa3b, v16
	v_mul_f32_e32 v17, 0xbfb8aa3b, v17
	v_exp_f32_e32 v16, v16
	v_rcp_f32_e32 v24, v24
	v_max_f32_e64 v56, -v30, 0
	v_mul_f32_e64 v30, |v30|, s26
	v_exp_f32_e32 v30, v30
	v_pk_add_f32 v[84:85], v[24:25], -1.0 op_sel_hi:[1,0]
	v_exp_f32_e32 v17, v17
	v_pk_fma_f32 v[84:85], v[92:93], v[84:85], 1.0 op_sel_hi:[1,1,0]
	v_add_f32_e32 v30, 1.0, v30
	v_cmp_gt_f32_e32 vcc, s6, v30
	v_pk_mul_f32 v[84:85], v[28:29], v[84:85]
	v_pk_add_f32 v[16:17], v[16:17], 1.0 op_sel_hi:[1,0]
	v_cndmask_b32_e64 v60, 0, 32, vcc
	v_ldexp_f32 v30, v30, v60
	v_log_f32_e32 v30, v30
	v_pk_mul_f32 v[92:93], v[180:181], v[84:85]
	v_add_f32_e32 v22, v22, v66
	v_fmac_f32_e32 v159, v88, v92
	v_mul_f32_e32 v60, 0x3f317217, v30
	v_fma_f32 v60, v30, s34, -v60
	v_fmac_f32_e32 v60, 0x3377d1cf, v30
	v_fmac_f32_e32 v60, 0x3f317217, v30
	v_cmp_lt_f32_e64 s[0:1], |v30|, s35
	v_fmac_f32_e32 v159, v89, v93
	v_add_f32_e32 v18, v18, v82
	v_cndmask_b32_e64 v30, v30, v60, s[0:1]
	v_cndmask_b32_e32 v60, 0, v242, vcc
	v_sub_f32_e32 v30, v30, v60
	v_add_f32_e32 v30, v56, v30
	v_sub_f32_e32 v30, -0.5, v30
	v_mul_f32_e32 v30, 0x3fb8aa3b, v30
	v_exp_f32_e32 v30, v30
	v_add_f32_e32 v19, v19, v83
	v_mul_f32_e32 v18, 0xbfb8aa3b, v18
	v_mul_f32_e32 v19, 0xbfb8aa3b, v19
	v_xor_b32_e32 v88, 0x80000000, v30
	v_add_f32_e32 v30, v31, v99
	v_max_f32_e64 v31, -v30, 0
	v_mul_f32_e64 v30, |v30|, s26
	v_exp_f32_e32 v30, v30
	v_exp_f32_e32 v18, v18
	v_exp_f32_e32 v19, v19
	v_lshlrev_b32_e32 v66, 16, v36
	v_add_f32_e32 v30, 1.0, v30
	v_cmp_gt_f32_e32 vcc, s6, v30
	v_pk_add_f32 v[18:19], v[18:19], 1.0 op_sel_hi:[1,0]
	v_pk_mul_f32 v[28:29], v[28:29], v[48:49]
	v_cndmask_b32_e64 v56, 0, 32, vcc
	v_ldexp_f32 v30, v30, v56
	v_log_f32_e32 v30, v30
	s_nop 0
	v_mul_f32_e32 v56, 0x3f317217, v30
	v_fma_f32 v56, v30, s34, -v56
	v_fmac_f32_e32 v56, 0x3377d1cf, v30
	v_fmac_f32_e32 v56, 0x3f317217, v30
	v_cmp_lt_f32_e64 s[0:1], |v30|, s35
	s_nop 1
	v_cndmask_b32_e64 v30, v30, v56, s[0:1]
	v_cndmask_b32_e32 v56, 0, v242, vcc
	v_sub_f32_e32 v30, v30, v56
	v_add_f32_e32 v30, v31, v30
	v_sub_f32_e32 v30, -0.5, v30
	v_mul_f32_e32 v30, 0x3fb8aa3b, v30
	v_exp_f32_e32 v30, v30
	v_and_b32_e32 v31, 0xffff0000, v61
	v_lshlrev_b32_e32 v56, 16, v57
	v_and_b32_e32 v57, 0xffff0000, v57
	v_xor_b32_e32 v89, 0x80000000, v30
	v_lshlrev_b32_e32 v30, 16, v61
	v_pk_fma_f32 v[56:57], v[178:179], v[56:57], v[30:31] op_sel_hi:[0,1,1] neg_lo:[0,0,1] neg_hi:[0,0,1]
	v_pk_fma_f32 v[30:31], v[86:87], v[56:57], v[30:31]
	v_rcp_f32_e32 v27, v27
	v_rcp_f32_e32 v26, v26
	s_nop 0
	v_pk_add_f32 v[56:57], v[26:27], -1.0 op_sel_hi:[1,0]
	s_nop 0
	v_pk_fma_f32 v[56:57], v[94:95], v[56:57], 1.0 op_sel_hi:[1,1,0]
	s_nop 0
	v_pk_mul_f32 v[56:57], v[30:31], v[56:57]
	v_pk_mul_f32 v[30:31], v[30:31], v[50:51]
	v_pk_mul_f32 v[60:61], v[108:109], v[56:57]
	v_pk_mul_f32 v[50:51], v[30:31], v[30:31]
	v_fmac_f32_e32 v159, v90, v60
	v_max_f32_e64 v60, -v20, 0
	v_mul_f32_e64 v20, |v20|, s26
	v_exp_f32_e32 v20, v20
	v_fmac_f32_e32 v159, v91, v61
	v_add_f32_e32 v20, 1.0, v20
	v_cmp_gt_f32_e32 vcc, s6, v20
	s_nop 1
	v_cndmask_b32_e64 v61, 0, 32, vcc
	v_ldexp_f32 v20, v20, v61
	v_log_f32_e32 v20, v20
	s_nop 0
	v_mul_f32_e32 v61, 0x3f317217, v20
	v_fma_f32 v61, v20, s34, -v61
	v_fmac_f32_e32 v61, 0x3377d1cf, v20
	v_fmac_f32_e32 v61, 0x3f317217, v20
	v_cmp_lt_f32_e64 s[0:1], |v20|, s35
	s_nop 1
	v_cndmask_b32_e64 v20, v20, v61, s[0:1]
	v_cndmask_b32_e32 v61, 0, v242, vcc
	v_sub_f32_e32 v20, v20, v61
	v_add_f32_e32 v20, v60, v20
	v_sub_f32_e32 v20, -0.5, v20
	v_mul_f32_e32 v20, 0x3fb8aa3b, v20
	v_exp_f32_e32 v20, v20
	v_and_b32_e32 v61, 0xffff0000, v58
	v_xor_b32_e32 v64, 0x80000000, v20
	v_add_f32_e32 v20, v21, v65
	v_max_f32_e64 v21, -v20, 0
	v_mul_f32_e64 v20, |v20|, s26
	v_exp_f32_e32 v20, v20
	s_nop 0
	v_add_f32_e32 v20, 1.0, v20
	v_cmp_gt_f32_e32 vcc, s6, v20
	s_nop 1
	v_cndmask_b32_e64 v60, 0, 32, vcc
	v_ldexp_f32 v20, v20, v60
	v_log_f32_e32 v20, v20
	s_nop 0
	v_mul_f32_e32 v60, 0x3f317217, v20
	v_fma_f32 v60, v20, s34, -v60
	v_fmac_f32_e32 v60, 0x3377d1cf, v20
	v_fmac_f32_e32 v60, 0x3f317217, v20
	v_cmp_lt_f32_e64 s[0:1], |v20|, s35
	s_nop 1
	v_cndmask_b32_e64 v20, v20, v60, s[0:1]
	v_cndmask_b32_e32 v60, 0, v242, vcc
	v_sub_f32_e32 v20, v20, v60
	v_add_f32_e32 v20, v21, v20
	v_sub_f32_e32 v20, -0.5, v20
	v_mul_f32_e32 v20, 0x3fb8aa3b, v20
	v_exp_f32_e32 v20, v20
	v_and_b32_e32 v21, 0xffff0000, v62
	v_lshlrev_b32_e32 v60, 16, v58
	v_xor_b32_e32 v65, 0x80000000, v20
	v_lshlrev_b32_e32 v20, 16, v62
	v_pk_fma_f32 v[60:61], v[178:179], v[60:61], v[20:21] op_sel_hi:[0,1,1] neg_lo:[0,0,1] neg_hi:[0,0,1]
	v_pk_fma_f32 v[20:21], v[52:53], v[60:61], v[20:21]
	v_rcp_f32_e32 v17, v17
	v_max_f32_e64 v58, -v22, 0
	v_mul_f32_e64 v22, |v22|, s26
	v_exp_f32_e32 v22, v22
	v_rcp_f32_e32 v16, v16
	s_nop 0
	v_pk_add_f32 v[52:53], v[16:17], -1.0 op_sel_hi:[1,0]
	v_add_f32_e32 v22, 1.0, v22
	v_cmp_gt_f32_e32 vcc, s6, v22
	v_pk_fma_f32 v[52:53], v[76:77], v[52:53], 1.0 op_sel_hi:[1,1,0]
	s_nop 0
	v_cndmask_b32_e64 v62, 0, 32, vcc
	v_ldexp_f32 v22, v22, v62
	v_log_f32_e32 v22, v22
	v_pk_mul_f32 v[60:61], v[20:21], v[52:53]
	v_pk_mul_f32 v[20:21], v[20:21], v[68:69]
	v_pk_mul_f32 v[76:77], v[104:105], v[60:61]
	v_mul_f32_e32 v62, 0x3f317217, v22
	v_fma_f32 v62, v22, s34, -v62
	v_fmac_f32_e32 v62, 0x3377d1cf, v22
	v_fmac_f32_e32 v62, 0x3f317217, v22
	v_cmp_lt_f32_e64 s[0:1], |v22|, s35
	v_fmac_f32_e32 v159, v72, v76
	v_fmac_f32_e32 v159, v73, v77
	v_cndmask_b32_e64 v22, v22, v62, s[0:1]
	v_cndmask_b32_e32 v62, 0, v242, vcc
	v_sub_f32_e32 v22, v22, v62
	v_add_f32_e32 v22, v58, v22
	v_sub_f32_e32 v22, -0.5, v22
	v_mul_f32_e32 v22, 0x3fb8aa3b, v22
	v_exp_f32_e32 v22, v22
	v_pk_mul_f32 v[52:53], v[20:21], v[20:21]
	v_xor_b32_e32 v68, 0x80000000, v22
	v_add_f32_e32 v22, v23, v67
	v_max_f32_e64 v23, -v22, 0
	v_mul_f32_e64 v22, |v22|, s26
	v_exp_f32_e32 v22, v22
	v_and_b32_e32 v67, 0xffff0000, v36
	v_lshlrev_b32_e32 v36, 16, v37
	v_and_b32_e32 v37, 0xffff0000, v37
	v_add_f32_e32 v22, 1.0, v22
	v_cmp_gt_f32_e32 vcc, s6, v22
	s_nop 1
	v_cndmask_b32_e64 v58, 0, 32, vcc
	v_ldexp_f32 v22, v22, v58
	v_log_f32_e32 v22, v22
	s_nop 0
	v_mul_f32_e32 v58, 0x3f317217, v22
	v_fma_f32 v58, v22, s34, -v58
	v_fmac_f32_e32 v58, 0x3377d1cf, v22
	v_fmac_f32_e32 v58, 0x3f317217, v22
	v_cmp_lt_f32_e64 s[0:1], |v22|, s35
	s_nop 1
	v_cndmask_b32_e64 v22, v22, v58, s[0:1]
	v_cndmask_b32_e32 v58, 0, v242, vcc
	v_sub_f32_e32 v22, v22, v58
	v_add_f32_e32 v22, v23, v22
	v_sub_f32_e32 v22, -0.5, v22
	v_mul_f32_e32 v22, 0x3fb8aa3b, v22
	v_exp_f32_e32 v22, v22
	v_and_b32_e32 v23, 0xffff0000, v63
	v_lshlrev_b32_e32 v58, 16, v59
	v_and_b32_e32 v59, 0xffff0000, v59
	v_xor_b32_e32 v69, 0x80000000, v22
	v_lshlrev_b32_e32 v22, 16, v63
	v_pk_fma_f32 v[58:59], v[178:179], v[58:59], v[22:23] op_sel_hi:[0,1,1] neg_lo:[0,0,1] neg_hi:[0,0,1]
	v_pk_fma_f32 v[22:23], v[54:55], v[58:59], v[22:23]
	v_rcp_f32_e32 v19, v19
	v_rcp_f32_e32 v18, v18
	s_nop 0
	v_pk_add_f32 v[54:55], v[18:19], -1.0 op_sel_hi:[1,0]
	s_nop 0
	v_pk_fma_f32 v[54:55], v[78:79], v[54:55], 1.0 op_sel_hi:[1,1,0]
	s_nop 0
	v_pk_mul_f32 v[54:55], v[22:23], v[54:55]
	v_pk_mul_f32 v[22:23], v[22:23], v[70:71]
	v_pk_mul_f32 v[58:59], v[106:107], v[54:55]
	v_pk_mul_f32 v[62:63], v[22:23], v[22:23]
	v_fmac_f32_e32 v159, v74, v58
	v_fmac_f32_e32 v159, v75, v59
	v_lshlrev_b32_e32 v58, 16, v40
	v_and_b32_e32 v59, 0xffff0000, v40
	v_lshlrev_b32_e32 v40, 16, v41
	v_and_b32_e32 v41, 0xffff0000, v41
	v_pk_fma_f32 v[36:37], v[178:179], v[36:37], v[40:41] op_sel_hi:[0,1,1] neg_lo:[0,0,1] neg_hi:[0,0,1]
	v_pk_fma_f32 v[36:37], v[46:47], v[36:37], v[40:41]
	v_lshlrev_b32_e32 v40, 16, v42
	v_and_b32_e32 v41, 0xffff0000, v42
	v_lshlrev_b32_e32 v46, 16, v38
	v_and_b32_e32 v47, 0xffff0000, v38
	v_pk_fma_f32 v[46:47], v[178:179], v[46:47], v[40:41] op_sel_hi:[0,1,1] neg_lo:[0,0,1] neg_hi:[0,0,1]
	v_pk_fma_f32 v[40:41], v[32:33], v[46:47], v[40:41]
	v_lshlrev_b32_e32 v32, 16, v43
	v_and_b32_e32 v33, 0xffff0000, v43
	v_lshlrev_b32_e32 v38, 16, v39
	v_and_b32_e32 v39, 0xffff0000, v39
	v_pk_fma_f32 v[38:39], v[178:179], v[38:39], v[32:33] op_sel_hi:[0,1,1] neg_lo:[0,0,1] neg_hi:[0,0,1]
	v_pk_fma_f32 v[66:67], v[178:179], v[66:67], v[58:59] op_sel_hi:[0,1,1] neg_lo:[0,0,1] neg_hi:[0,0,1]
	v_pk_fma_f32 v[38:39], v[34:35], v[38:39], v[32:33]
	v_cvt_pk_bf16_f32 v32, v180, v181
	v_cvt_pk_bf16_f32 v33, v108, v109
	v_cvt_pk_bf16_f32 v34, v104, v105
	v_cvt_pk_bf16_f32 v35, v106, v107
	v_pk_fma_f32 v[44:45], v[44:45], v[66:67], v[58:59]
	flat_store_dwordx4 v[208:209], v[32:35] offset:64
	s_nop 1
	v_cvt_pk_bf16_f32 v32, v84, v85
	v_cvt_pk_bf16_f32 v33, v56, v57
	v_cvt_pk_bf16_f32 v34, v60, v61
	v_cvt_pk_bf16_f32 v35, v54, v55
	flat_store_dwordx4 v[208:209], v[32:35] offset:576
	s_nop 1
	v_cvt_pk_bf16_f32 v32, v44, v45
	v_cvt_pk_bf16_f32 v33, v36, v37
	v_cvt_pk_bf16_f32 v34, v40, v41
	v_cvt_pk_bf16_f32 v35, v38, v39
	flat_store_dwordx4 v[208:209], v[32:35] offset:1088
	s_nop 1
	v_cvt_pk_bf16_f32 v32, v96, v97
	v_cvt_pk_bf16_f32 v33, v88, v89
	v_cvt_pk_bf16_f32 v34, v64, v65
	v_cvt_pk_bf16_f32 v35, v68, v69
	flat_store_dwordx4 v[208:209], v[32:35] offset:2624
	flat_store_dwordx4 v[212:213], v[0:3] offset:64
	s_nop 0
	v_pk_mul_f32 v[32:33], v[8:9], v[8:9]
	v_pk_mul_f32 v[2:3], v[210:211], v[14:15]
	v_pk_mul_f32 v[14:15], v[10:11], v[10:11]
	v_add_f32_e32 v32, v32, v33
	v_add_f32_e32 v14, v14, v32
	v_add_f32_e32 v14, v15, v14
	v_add_f32_e32 v12, v14, v12
	v_pk_mul_f32 v[4:5], v[2:3], v[2:3]
	v_add_f32_e32 v12, v13, v12
	v_add_f32_e32 v4, v4, v12
	v_pk_mul_f32 v[34:35], v[28:29], v[28:29]
	v_add_f32_e32 v4, v5, v4
	v_add_f32_e32 v4, v4, v34
	v_add_f32_e32 v4, v35, v4
	v_add_f32_e32 v4, v50, v4
	v_and_b32_e32 v1, 64, v243
	v_add_f32_e32 v4, v51, v4
	v_xor_b32_e32 v0, 16, v243
	v_add_u32_e32 v1, 64, v1
	v_add_f32_e32 v4, v4, v52
	v_cmp_lt_i32_e32 vcc, v0, v1
	v_add_f32_e32 v4, v53, v4
	v_add_f32_e32 v4, v62, v4
	v_cndmask_b32_e32 v0, v243, v0, vcc
	v_lshlrev_b32_e32 v36, 2, v0
	v_add_f32_e32 v4, v63, v4
	ds_bpermute_b32 v5, v36, v4
	v_xor_b32_e32 v0, 32, v243
	v_cmp_lt_i32_e32 vcc, v0, v1
	s_waitcnt lgkmcnt(0)
	v_add_f32_e32 v4, v4, v5
	v_cndmask_b32_e32 v0, v243, v0, vcc
	v_lshlrev_b32_e32 v37, 2, v0
	ds_bpermute_b32 v5, v37, v4
	ds_bpermute_b32 v0, v36, v159
	s_waitcnt lgkmcnt(0)
	v_add_f32_e32 v4, v4, v5
	v_cmp_gt_f32_e32 vcc, s36, v4
	v_mul_f32_e32 v5, 0x4f800000, v4
	v_add_f32_e32 v0, v159, v0
	v_cndmask_b32_e32 v4, v4, v5, vcc
	v_sqrt_f32_e32 v5, v4
	ds_bpermute_b32 v1, v37, v0
	v_add_u32_e32 v12, -1, v5
	v_fma_f32 v13, -v12, v5, v4
	v_cmp_ge_f32_e64 s[0:1], 0, v13
	v_add_u32_e32 v13, 1, v5
	s_nop 0
	v_cndmask_b32_e64 v12, v5, v12, s[0:1]
	v_fma_f32 v5, -v13, v5, v4
	v_cmp_lt_f32_e64 s[0:1], 0, v5
	s_nop 1
	v_cndmask_b32_e64 v5, v12, v13, s[0:1]
	v_mul_f32_e32 v12, 0x37800000, v5
	v_cndmask_b32_e32 v5, v5, v12, vcc
	v_cmp_class_f32_e32 vcc, v4, v237
	s_nop 1
	v_cndmask_b32_e32 v4, v5, v4, vcc
	v_max_f32_e32 v4, 0x2b8cbccc, v4
	v_rcp_f32_e32 v12, v4
	s_nop 0
	v_pk_mul_f32 v[4:5], v[8:9], v[12:13] op_sel_hi:[1,0]
	v_pk_mul_f32 v[10:11], v[10:11], v[12:13] op_sel_hi:[1,0]
	v_pk_mul_f32 v[6:7], v[6:7], v[12:13] op_sel_hi:[1,0]
	v_pk_mul_f32 v[34:35], v[2:3], v[12:13] op_sel_hi:[1,0]
	v_pk_mul_f32 v[8:9], v[116:117], v[4:5]
	v_pk_mul_f32 v[14:15], v[118:119], v[10:11]
	v_pk_mul_f32 v[32:33], v[188:189], v[6:7]
	v_pk_mul_f32 v[36:37], v[206:207], v[34:35]
	v_cvt_pk_bf16_f32 v2, v4, v5
	v_cvt_pk_bf16_f32 v3, v10, v11
	v_cvt_pk_bf16_f32 v4, v6, v7
	v_cvt_pk_bf16_f32 v5, v34, v35
	flat_store_dwordx4 v[208:209], v[2:5] offset:1536
	v_pk_mul_f32 v[10:11], v[20:21], v[12:13] op_sel_hi:[1,0]
	s_nop 0
	v_cvt_pk_bf16_f32 v2, v8, v9
	v_cvt_pk_bf16_f32 v3, v14, v15
	v_cvt_pk_bf16_f32 v4, v32, v33
	v_cvt_pk_bf16_f32 v5, v36, v37
	flat_store_dwordx4 v[208:209], v[2:5] offset:2048
	v_pk_mul_f32 v[14:15], v[16:17], v[10:11]
	s_nop 0
	v_pk_mul_f32 v[2:3], v[28:29], v[12:13] op_sel_hi:[1,0]
	v_pk_mul_f32 v[4:5], v[30:31], v[12:13] op_sel_hi:[1,0]
	v_pk_mul_f32 v[12:13], v[22:23], v[12:13] op_sel_hi:[1,0]
	v_pk_mul_f32 v[6:7], v[24:25], v[2:3]
	v_pk_mul_f32 v[8:9], v[26:27], v[4:5]
	v_pk_mul_f32 v[16:17], v[18:19], v[12:13]
	v_cvt_pk_bf16_f32 v2, v2, v3
	v_cvt_pk_bf16_f32 v3, v4, v5
	v_cvt_pk_bf16_f32 v4, v10, v11
	v_cvt_pk_bf16_f32 v5, v12, v13
	flat_store_dwordx4 v[208:209], v[2:5] offset:1600
	s_nop 1
	v_cvt_pk_bf16_f32 v2, v6, v7
	v_cvt_pk_bf16_f32 v3, v8, v9
	v_cvt_pk_bf16_f32 v4, v14, v15
	v_cvt_pk_bf16_f32 v5, v16, v17
	flat_store_dwordx4 v[208:209], v[2:5] offset:2112
	s_and_saveexec_b64 s[0:1], s[8:9]
	s_cbranch_execz .LBB0_341
	v_lshl_add_u64 v[2:3], v[176:177], 4, s[16:17]
	s_waitcnt lgkmcnt(0)
	v_add_f32_e32 v0, v0, v1
	flat_store_dword v[2:3], v0
	s_branch .LBB0_341

.LBB0_347:
	s_and_b32 s0, s3, -16
	s_addk_i32 s0, 0x4000
	v_or_b32_e32 v206, s0, v193
	s_waitcnt lgkmcnt(0)
	v_mov_b64_e32 v[0:1], s[10:11]
	v_mad_i64_i32 v[0:1], s[0:1], v206, s86, v[0:1]
	s_mov_b64 s[0:1], 0x2040c00
	s_nop 0
	v_lshl_add_u64 v[208:209], v[0:1], 0, s[0:1]
	v_add_u32_e32 v0, 0xffffc000, v206
	v_ashrrev_i32_e32 v1, 31, v0
	v_lshl_add_u64 v[0:1], v[0:1], 0, s[42:43]
	v_mov_b64_e32 v[2:3], s[46:47]
	s_movk_i32 s4, 0xe00
	v_mad_u64_u32 v[210:211], s[0:1], v0, s4, v[2:3]
	v_mad_i32_i24 v211, v1, s4, v211
	v_lshl_add_u64 v[0:1], v[208:209], 0, v[194:195]
	flat_load_dwordx4 v[132:135], v[0:1]
	v_mov_b32_e32 v175, v195
	v_lshl_add_u64 v[0:1], v[210:211], 0, v[174:175]
	global_load_dwordx4 v[128:131], v[0:1], off offset:3072
	global_load_dwordx4 v[212:215], v[0:1], off offset:3088
	global_load_dwordx4 v[84:87], v[136:137], off offset:3072
	global_load_dwordx4 v[216:219], v[136:137], off offset:3088
	v_mov_b32_e32 v177, v195
	v_lshl_add_u64 v[2:3], v[208:209], 0, v[176:177]
	v_mov_b32_e32 v179, v195
	flat_load_dwordx4 v[108:111], v[2:3]
	global_load_dwordx4 v[88:91], v[0:1], off offset:3216
	global_load_dwordx4 v[120:123], v[0:1], off offset:3200
	global_load_dwordx4 v[116:119], v[136:137], off offset:3216
	global_load_dwordx4 v[124:127], v[136:137], off offset:3200
	v_lshl_add_u64 v[2:3], v[208:209], 0, v[178:179]
	v_mov_b32_e32 v181, v195
	flat_load_dwordx4 v[92:95], v[2:3]
	global_load_dwordx4 v[96:99], v[0:1], off offset:3328
	global_load_dwordx4 v[104:107], v[0:1], off offset:3344
	global_load_dwordx4 v[100:103], v[136:137], off offset:3328
	global_load_dwordx4 v[112:115], v[136:137], off offset:3344
	v_lshl_add_u64 v[2:3], v[208:209], 0, v[180:181]
	flat_load_dwordx4 v[64:67], v[2:3]
	global_load_dwordx4 v[68:71], v[0:1], off offset:3456
	global_load_dwordx4 v[76:79], v[0:1], off offset:3472
	global_load_dwordx4 v[72:75], v[136:137], off offset:3456
	global_load_dwordx4 v[80:83], v[136:137], off offset:3472
	flat_load_dwordx4 v[60:63], v[140:141]
	flat_load_dwordx4 v[56:59], v[140:141] offset:64
	flat_load_dwordx4 v[52:55], v[140:141] offset:128
	flat_load_dwordx4 v[28:31], v[140:141] offset:192
	flat_load_dwordx4 v[24:27], v[140:141] offset:1024
	flat_load_dwordx4 v[0:3], v[140:141] offset:1088
	flat_load_dwordx4 v[4:7], v[140:141] offset:1152
	flat_load_dwordx4 v[8:11], v[140:141] offset:1216
	flat_load_dwordx4 v[12:15], v[142:143]
	flat_load_dwordx4 v[16:19], v[144:145]
	flat_load_dwordx4 v[20:23], v[146:147]
	flat_load_dwordx4 v[32:35], v[148:149]
	flat_load_dwordx4 v[36:39], v[150:151]
	flat_load_dwordx4 v[40:43], v[152:153]
	flat_load_dwordx4 v[44:47], v[154:155]
	flat_load_dwordx4 v[48:51], v[156:157]
	v_mov_b32_e32 v183, v195
	v_mov_b32_e32 v185, v195
	s_mov_b32 s4, 0x800000
	s_mov_b32 s5, 0x3f317217
	s_mov_b32 s6, 0x7f800000
	v_ashrrev_i32_e32 v207, 31, v206
	v_mov_b32_e32 v187, v195
	v_mov_b32_e32 v189, v195
	v_mov_b32_e32 v191, v195
	s_waitcnt vmcnt(0) lgkmcnt(0)
	v_and_b32_e32 v177, 0xffff0000, v132
	v_lshlrev_b32_e32 v179, 16, v133
	v_sub_f32_e32 v129, v129, v177
	v_and_b32_e32 v181, 0xffff0000, v133
	v_fmac_f32_e32 v177, v85, v129
	v_sub_f32_e32 v85, v130, v179
	v_lshlrev_b32_e32 v175, 16, v134
	v_fmac_f32_e32 v179, v86, v85
	v_sub_f32_e32 v85, v131, v181
	v_and_b32_e32 v139, 0xffff0000, v134
	v_fmac_f32_e32 v181, v87, v85
	v_sub_f32_e32 v85, v212, v175
	v_lshlrev_b32_e32 v134, 16, v135
	v_fmac_f32_e32 v175, v85, v216
	v_sub_f32_e32 v85, v213, v139
	v_and_b32_e32 v133, 0xffff0000, v135
	v_fmac_f32_e32 v139, v85, v217
	v_sub_f32_e32 v85, v214, v134
	v_fmac_f32_e32 v134, v85, v218
	v_sub_f32_e32 v85, v215, v133
	v_fmac_f32_e32 v133, v85, v219
	v_lshlrev_b32_e32 v85, 16, v132
	v_sub_f32_e32 v86, v128, v85
	v_fmac_f32_e32 v85, v84, v86
	v_add_f32_e32 v84, v85, v85
	v_add_f32_e32 v85, v177, v177
	v_mul_f32_e32 v84, 0x3fb8aa3b, v84
	v_mul_f32_e32 v85, 0x3fb8aa3b, v85
	v_exp_f32_e32 v84, v84
	v_exp_f32_e32 v85, v85
	v_lshlrev_b64 v[216:217], 9, v[206:207]
	v_lshl_add_u64 v[216:217], v[172:173], 0, v[216:217]
	v_pk_add_f32 v[84:85], v[84:85], 1.0 op_sel_hi:[1,0]
	s_nop 0
	v_rcp_f32_e32 v85, v85
	s_nop 0
	v_mul_f32_e32 v85, 2.0, v85
	v_rcp_f32_e32 v84, v84
	s_nop 0
	v_mul_f32_e32 v84, 2.0, v84
	v_add_f32_e32 v86, v179, v179
	v_add_f32_e32 v87, v181, v181
	v_mul_f32_e32 v86, 0x3fb8aa3b, v86
	v_mul_f32_e32 v87, 0x3fb8aa3b, v87
	v_exp_f32_e32 v86, v86
	v_exp_f32_e32 v87, v87
	v_pk_add_f32 v[84:85], v[84:85], 1.0 op_sel_hi:[1,0] neg_lo:[1,0] neg_hi:[1,0]
	v_pk_add_f32 v[86:87], v[86:87], 1.0 op_sel_hi:[1,0]
	s_nop 0
	v_cvt_pk_bf16_f32 v84, v84, v85
	v_rcp_f32_e32 v87, v87
	s_nop 0
	v_mul_f32_e32 v87, 2.0, v87
	v_rcp_f32_e32 v86, v86
	s_nop 0
	v_mul_f32_e32 v86, 2.0, v86
	v_add_f32_e32 v128, v175, v175
	v_add_f32_e32 v129, v139, v139
	v_mul_f32_e32 v128, 0x3fb8aa3b, v128
	v_mul_f32_e32 v129, 0x3fb8aa3b, v129
	v_exp_f32_e32 v128, v128
	v_exp_f32_e32 v129, v129
	v_pk_add_f32 v[86:87], v[86:87], 1.0 op_sel_hi:[1,0] neg_lo:[1,0] neg_hi:[1,0]
	v_pk_add_f32 v[128:129], v[128:129], 1.0 op_sel_hi:[1,0]
	s_nop 0
	v_cvt_pk_bf16_f32 v85, v86, v87
	v_rcp_f32_e32 v129, v129
	s_nop 0
	v_mul_f32_e32 v129, 2.0, v129
	v_rcp_f32_e32 v128, v128
	s_nop 0
	v_mul_f32_e32 v128, 2.0, v128
	v_add_f32_e32 v130, v134, v134
	v_add_f32_e32 v131, v133, v133
	v_pk_add_f32 v[128:129], v[128:129], 1.0 op_sel_hi:[1,0] neg_lo:[1,0] neg_hi:[1,0]
	v_mul_f32_e32 v130, 0x3fb8aa3b, v130
	v_mul_f32_e32 v131, 0x3fb8aa3b, v131
	v_exp_f32_e32 v130, v130
	v_exp_f32_e32 v131, v131
	v_cvt_pk_bf16_f32 v86, v128, v129
	v_lshlrev_b32_e32 v128, 16, v108
	v_and_b32_e32 v129, 0xffff0000, v108
	v_lshlrev_b32_e32 v108, 16, v109
	v_and_b32_e32 v109, 0xffff0000, v109
	v_pk_add_f32 v[122:123], v[122:123], v[108:109] neg_lo:[0,1] neg_hi:[0,1]
	v_pk_add_f32 v[130:131], v[130:131], 1.0 op_sel_hi:[1,0]
	v_pk_fma_f32 v[108:109], v[126:127], v[122:123], v[108:109]
	v_lshlrev_b32_e32 v122, 16, v110
	v_and_b32_e32 v123, 0xffff0000, v110
	v_pk_add_f32 v[88:89], v[88:89], v[122:123] neg_lo:[0,1] neg_hi:[0,1]
	s_nop 0
	v_pk_fma_f32 v[116:117], v[88:89], v[116:117], v[122:123]
	v_lshlrev_b32_e32 v88, 16, v111
	v_and_b32_e32 v89, 0xffff0000, v111
	v_pk_add_f32 v[90:91], v[90:91], v[88:89] neg_lo:[0,1] neg_hi:[0,1]
	s_nop 0
	v_pk_fma_f32 v[110:111], v[90:91], v[118:119], v[88:89]
	v_cvt_pk_bf16_f32 v89, v108, v109
	v_and_b32_e32 v108, 0xffff0000, v92
	v_cvt_pk_bf16_f32 v91, v110, v111
	v_lshlrev_b32_e32 v109, 16, v93
	v_and_b32_e32 v110, 0xffff0000, v93
	v_sub_f32_e32 v93, v97, v108
	v_fmac_f32_e32 v108, v101, v93
	v_sub_f32_e32 v93, v98, v109
	v_lshlrev_b32_e32 v111, 16, v94
	v_fmac_f32_e32 v109, v102, v93
	v_sub_f32_e32 v93, v99, v110
	v_and_b32_e32 v94, 0xffff0000, v94
	v_fmac_f32_e32 v110, v103, v93
	v_sub_f32_e32 v93, v104, v111
	v_cvt_pk_bf16_f32 v90, v116, v117
	v_lshlrev_b32_e32 v116, 16, v95
	v_fmac_f32_e32 v111, v93, v112
	v_sub_f32_e32 v93, v105, v94
	v_and_b32_e32 v95, 0xffff0000, v95
	v_fmac_f32_e32 v94, v93, v113
	v_sub_f32_e32 v93, v106, v116
	v_fmac_f32_e32 v116, v93, v114
	v_sub_f32_e32 v93, v107, v95
	v_lshlrev_b32_e32 v92, 16, v92
	v_fmac_f32_e32 v95, v93, v115
	v_sub_f32_e32 v93, v96, v92
	v_fmac_f32_e32 v92, v100, v93
	v_mul_f32_e32 v92, 0xbfb8aa3b, v92
	v_mul_f32_e32 v93, 0xbfb8aa3b, v108
	v_rcp_f32_e32 v131, v131
	s_nop 0
	v_mul_f32_e32 v131, 2.0, v131
	v_exp_f32_e32 v92, v92
	v_exp_f32_e32 v93, v93
	v_pk_add_f32 v[120:121], v[120:121], v[128:129] neg_lo:[0,1] neg_hi:[0,1]
	v_pk_add_f32 v[92:93], v[92:93], 1.0 op_sel_hi:[1,0]
	s_nop 0
	v_rcp_f32_e32 v96, v93
	v_rcp_f32_e32 v130, v130
	s_nop 0
	v_mul_f32_e32 v130, 2.0, v130
	v_pk_add_f32 v[130:131], v[130:131], 1.0 op_sel_hi:[1,0] neg_lo:[1,0] neg_hi:[1,0]
	v_pk_fma_f32 v[120:121], v[124:125], v[120:121], v[128:129]
	v_rcp_f32_e32 v97, v92
	v_mul_f32_e32 v92, 0xbfb8aa3b, v109
	v_mul_f32_e32 v93, 0xbfb8aa3b, v110
	v_exp_f32_e32 v92, v92
	v_exp_f32_e32 v93, v93
	v_cvt_pk_bf16_f32 v87, v130, v131
	v_cvt_pk_bf16_f32 v88, v120, v121
	v_pk_add_f32 v[92:93], v[92:93], 1.0 op_sel_hi:[1,0]
	s_nop 0
	v_rcp_f32_e32 v98, v93
	v_rcp_f32_e32 v99, v92
	v_mul_f32_e32 v92, 0xbfb8aa3b, v111
	v_mul_f32_e32 v93, 0xbfb8aa3b, v94
	v_exp_f32_e32 v92, v92
	v_exp_f32_e32 v93, v93
	s_nop 0
	v_pk_add_f32 v[92:93], v[92:93], 1.0 op_sel_hi:[1,0]
	s_nop 0
	v_rcp_f32_e32 v94, v93
	v_rcp_f32_e32 v100, v92
	v_mul_f32_e32 v92, 0xbfb8aa3b, v116
	v_mul_f32_e32 v93, 0xbfb8aa3b, v95
	v_exp_f32_e32 v92, v92
	v_exp_f32_e32 v93, v93
	v_cvt_pk_bf16_f32 v94, v100, v94
	v_lshlrev_b32_e32 v100, 16, v67
	v_and_b32_e32 v67, 0xffff0000, v67
	v_pk_add_f32 v[92:93], v[92:93], 1.0 op_sel_hi:[1,0]
	s_nop 0
	v_rcp_f32_e32 v95, v93
	v_rcp_f32_e32 v101, v92
	v_cvt_pk_bf16_f32 v92, v97, v96
	v_and_b32_e32 v96, 0xffff0000, v64
	v_cvt_pk_bf16_f32 v93, v99, v98
	v_lshlrev_b32_e32 v97, 16, v65
	v_and_b32_e32 v98, 0xffff0000, v65
	v_sub_f32_e32 v65, v69, v96
	v_fmac_f32_e32 v96, v73, v65
	v_sub_f32_e32 v65, v70, v97
	v_lshlrev_b32_e32 v99, 16, v66
	v_fmac_f32_e32 v97, v74, v65
	v_sub_f32_e32 v65, v71, v98
	v_and_b32_e32 v66, 0xffff0000, v66
	v_fmac_f32_e32 v98, v75, v65
	v_sub_f32_e32 v65, v76, v99
	v_fmac_f32_e32 v99, v65, v80
	v_sub_f32_e32 v65, v77, v66
	v_fmac_f32_e32 v66, v65, v81
	v_sub_f32_e32 v65, v78, v100
	v_fmac_f32_e32 v100, v65, v82
	v_sub_f32_e32 v65, v79, v67
	v_lshlrev_b32_e32 v64, 16, v64
	v_fmac_f32_e32 v67, v65, v83
	v_sub_f32_e32 v65, v68, v64
	v_fmac_f32_e32 v64, v72, v65
	v_mul_f32_e32 v64, 0xbfb8aa3b, v64
	v_mul_f32_e32 v65, 0xbfb8aa3b, v96
	v_exp_f32_e32 v64, v64
	v_exp_f32_e32 v65, v65
	v_cvt_pk_bf16_f32 v95, v101, v95
	v_pk_add_f32 v[64:65], v[64:65], 1.0 op_sel_hi:[1,0]
	s_nop 0
	v_mfma_f32_16x16x32_bf16 v[52:55], v[52:55], v[92:95], 0
	v_rcp_f32_e32 v68, v65
	v_rcp_f32_e32 v69, v64
	v_mul_f32_e32 v64, 0xbfb8aa3b, v97
	v_mul_f32_e32 v65, 0xbfb8aa3b, v98
	v_exp_f32_e32 v64, v64
	v_exp_f32_e32 v65, v65
	v_cvt_pk_bf16_f32 v68, v69, v68
	v_pk_add_f32 v[64:65], v[64:65], 1.0 op_sel_hi:[1,0]
	s_nop 0
	v_rcp_f32_e32 v70, v65
	v_rcp_f32_e32 v71, v64
	v_mul_f32_e32 v64, 0xbfb8aa3b, v99
	v_mul_f32_e32 v65, 0xbfb8aa3b, v66
	v_exp_f32_e32 v64, v64
	v_exp_f32_e32 v65, v65
	v_cvt_pk_bf16_f32 v69, v71, v70
	v_mfma_f32_16x16x32_bf16 v[96:99], v[56:59], v[88:91], 0
	v_add_f32_e64 v64, v64, 1.0
	v_add_f32_e64 v65, v65, 1.0
	v_rcp_f32_e32 v66, v65
	v_rcp_f32_e32 v72, v64
	v_mul_f32_e32 v64, 0xbfb8aa3b, v100
	v_mul_f32_e32 v65, 0xbfb8aa3b, v67
	v_exp_f32_e32 v64, v64
	v_exp_f32_e32 v65, v65
	v_mfma_f32_16x16x32_bf16 v[100:103], v[60:63], v[84:87], 0
	v_cvt_pk_bf16_f32 v70, v72, v66
	v_pk_add_f32 v[64:65], v[64:65], 1.0 op_sel_hi:[1,0]
	s_nop 0
	v_mfma_f32_16x16x32_bf16 v[60:63], v[0:3], v[88:91], 0
	v_rcp_f32_e32 v65, v65
	v_mfma_f32_16x16x32_bf16 v[0:3], v[4:7], v[92:95], 0
	v_rcp_f32_e32 v64, v64
	s_nop 0
	v_cvt_pk_bf16_f32 v71, v64, v65
	v_mfma_f32_16x16x32_bf16 v[4:7], v[44:47], v[92:95], 0
	s_nop 0
	v_mfma_f32_16x16x32_bf16 v[56:59], v[8:11], v[68:71], v[0:3]
	v_lshlrev_b32_e32 v8, 1, v138
	v_mov_b32_e32 v9, v195
	v_lshl_add_u64 v[8:9], v[208:209], 0, v[8:9]
	flat_load_dwordx4 v[128:131], v[8:9]
	v_lshlrev_b32_e32 v8, 2, v138
	v_mov_b32_e32 v9, v195
	v_lshl_add_u64 v[218:219], v[210:211], 0, v[8:9]
	v_mfma_f32_16x16x32_bf16 v[0:3], v[20:23], v[92:95], 0
	global_load_dwordx4 v[132:135], v[218:219], off offset:16
	global_load_dwordx4 v[212:215], v[218:219], off
	global_load_dwordx4 v[222:225], v[158:159], off offset:16
	global_load_dwordx4 v[226:229], v[158:159], off
	v_lshl_add_u64 v[8:9], v[208:209], 0, v[182:183]
	s_waitcnt vmcnt(0) lgkmcnt(0)
	v_lshlrev_b32_e32 v210, 16, v128
	v_mfma_f32_16x16x32_bf16 v[52:55], v[28:31], v[68:71], v[52:55]
	v_and_b32_e32 v211, 0xffff0000, v128
	v_pk_add_f32 v[212:213], v[212:213], v[210:211] neg_lo:[0,1] neg_hi:[0,1]
	v_lshlrev_b32_e32 v128, 16, v129
	v_mfma_f32_16x16x32_bf16 v[0:3], v[32:35], v[68:71], v[0:3]
	v_and_b32_e32 v129, 0xffff0000, v129
	v_pk_fma_f32 v[212:213], v[212:213], v[226:227], v[210:211]
	v_pk_add_f32 v[210:211], v[214:215], v[128:129] neg_lo:[0,1] neg_hi:[0,1]
	v_mfma_f32_16x16x32_bf16 v[4:7], v[48:51], v[68:71], v[4:7]
	flat_load_dwordx4 v[68:71], v[8:9]
	global_load_dwordx4 v[72:75], v[218:219], off offset:1040
	global_load_dwordx4 v[104:107], v[218:219], off offset:1024
	global_load_dwordx4 v[76:79], v[158:159], off offset:1040
	global_load_dwordx4 v[108:111], v[158:159], off offset:1024
	v_lshl_add_u64 v[8:9], v[208:209], 0, v[184:185]
	v_pk_fma_f32 v[220:221], v[210:211], v[228:229], v[128:129]
	v_mfma_f32_16x16x32_bf16 v[64:67], v[24:27], v[84:87], 0
	v_lshlrev_b32_e32 v128, 16, v130
	v_and_b32_e32 v129, 0xffff0000, v130
	v_pk_add_f32 v[132:133], v[132:133], v[128:129] neg_lo:[0,1] neg_hi:[0,1]
	v_mfma_f32_16x16x32_bf16 v[28:31], v[12:15], v[84:87], 0
	v_fma_f32 v222, v132, v222, v128
	v_fma_f32 v223, v133, v223, v129
	v_lshlrev_b32_e32 v128, 16, v131
	v_and_b32_e32 v129, 0xffff0000, v131
	v_mfma_f32_16x16x32_bf16 v[24:27], v[16:19], v[88:91], 0
	v_add_f32_e64 v130, v134, -v128
	v_add_f32_e64 v131, v135, -v129
	v_cvt_pk_bf16_f32 v0, v0, v1
	v_pk_fma_f32 v[224:225], v[130:131], v[224:225], v[128:129]
	v_mfma_f32_16x16x32_bf16 v[20:23], v[36:39], v[84:87], 0
	v_cvt_pk_bf16_f32 v1, v2, v3
	v_cvt_pk_bf16_f32 v2, v4, v5
	v_cvt_pk_bf16_f32 v3, v6, v7
	v_mfma_f32_16x16x32_bf16 v[16:19], v[40:43], v[88:91], 0
	flat_load_dwordx4 v[40:43], v[8:9]
	global_load_dwordx4 v[36:39], v[218:219], off offset:2064
	global_load_dwordx4 v[48:51], v[218:219], off offset:2048
	global_load_dwordx4 v[32:35], v[158:159], off offset:2064
	global_load_dwordx4 v[44:47], v[158:159], off offset:2048
	global_load_dwordx4 v[80:83], v[160:161], off offset:16
	global_load_dwordx4 v[124:127], v[160:161], off
	global_load_dwordx4 v[92:95], v[162:163], off offset:16
	global_load_dwordx4 v[120:123], v[162:163], off
	global_load_dwordx4 v[8:11], v[164:165], off
	global_load_dwordx4 v[12:15], v[164:165], off offset:16
	global_load_dwordx4 v[88:91], v[166:167], off offset:16
	global_load_dwordx4 v[116:119], v[166:167], off
	global_load_dwordx4 v[84:87], v[168:169], off offset:16
	global_load_dwordx4 v[112:115], v[168:169], off
	s_waitcnt vmcnt(0)
	v_add_f32_e32 v64, v64, v80
	v_add_f32_e32 v100, v100, v124
	v_max_f32_e64 v124, -v100, 0
	v_mul_f32_e64 v100, |v100|, s21
	v_exp_f32_e32 v100, v100
	v_add_f32_e32 v101, v101, v125
	v_add_f32_e32 v96, v96, v120
	v_max_f32_e64 v120, -v101, 0
	v_add_f32_e32 v100, 1.0, v100
	v_cmp_gt_f32_e32 vcc, s4, v100
	v_mul_f32_e64 v101, |v101|, s21
	v_exp_f32_e32 v101, v101
	v_cndmask_b32_e64 v128, 0, 32, vcc
	v_ldexp_f32 v100, v100, v128
	v_log_f32_e32 v100, v100
	v_add_f32_e32 v101, 1.0, v101
	v_add_f32_e32 v97, v97, v121
	v_mul_f32_e32 v96, 0xbfb8aa3b, v96
	v_mul_f32_e32 v128, 0x3f317217, v100
	v_fma_f32 v128, v100, s5, -v128
	v_fmac_f32_e32 v128, 0x3377d1cf, v100
	v_fmac_f32_e32 v128, 0x3f317217, v100
	v_cmp_lt_f32_e64 s[0:1], |v100|, s6
	v_mul_f32_e32 v97, 0xbfb8aa3b, v97
	v_exp_f32_e32 v96, v96
	v_cndmask_b32_e64 v100, v100, v128, s[0:1]
	v_cndmask_b32_e32 v128, 0, v242, vcc
	v_sub_f32_e32 v100, v100, v128
	v_cmp_gt_f32_e32 vcc, s4, v101
	v_add_f32_e32 v100, v124, v100
	v_exp_f32_e32 v97, v97
	v_cndmask_b32_e64 v124, 0, 32, vcc
	v_ldexp_f32 v101, v101, v124
	v_log_f32_e32 v101, v101
	s_waitcnt lgkmcnt(0)
	v_and_b32_e32 v121, 0xffff0000, v68
	v_pk_add_f32 v[96:97], v[96:97], 1.0 op_sel_hi:[1,0]
	v_max_f32_e64 v80, -v64, 0
	v_mul_f32_e32 v124, 0x3f317217, v101
	v_fma_f32 v124, v101, s5, -v124
	v_fmac_f32_e32 v124, 0x3377d1cf, v101
	v_fmac_f32_e32 v124, 0x3f317217, v101
	v_cmp_lt_f32_e64 s[0:1], |v101|, s6
	v_mul_f32_e64 v64, |v64|, s21
	v_exp_f32_e32 v64, v64
	v_cndmask_b32_e64 v101, v101, v124, s[0:1]
	v_cndmask_b32_e32 v124, 0, v242, vcc
	v_sub_f32_e32 v101, v101, v124
	v_add_f32_e32 v101, v120, v101
	v_lshlrev_b32_e32 v120, 16, v68
	v_pk_add_f32 v[104:105], v[104:105], v[120:121] neg_lo:[0,1] neg_hi:[0,1]
	s_nop 0
	v_pk_fma_f32 v[128:129], v[108:109], v[104:105], v[120:121]
	v_add_f32_e32 v64, 1.0, v64
	v_add_f32_e32 v65, v65, v81
	v_add_f32_e32 v60, v60, v92
	v_rcp_f32_e32 v125, v97
	v_add_f32_e32 v61, v61, v93
	v_mul_f32_e32 v60, 0xbfb8aa3b, v60
	v_mul_f32_e32 v61, 0xbfb8aa3b, v61
	v_rcp_f32_e32 v124, v96
	v_add_f32_e32 v68, v102, v126
	v_max_f32_e64 v102, -v68, 0
	v_mul_f32_e64 v68, |v68|, s21
	v_exp_f32_e32 v68, v68
	v_pk_add_f32 v[96:97], v[124:125], -1.0 op_sel_hi:[1,0]
	v_exp_f32_e32 v60, v60
	v_pk_fma_f32 v[96:97], v[116:117], v[96:97], 1.0 op_sel_hi:[1,1,0]
	v_add_f32_e32 v68, 1.0, v68
	v_pk_mul_f32 v[96:97], v[128:129], v[96:97]
	v_cmp_gt_f32_e32 vcc, s4, v68
	v_pk_mul_f32 v[104:105], v[212:213], v[96:97]
	v_exp_f32_e32 v61, v61
	v_fma_f32 v139, v112, v104, 0
	v_cndmask_b32_e64 v104, 0, 32, vcc
	v_ldexp_f32 v68, v68, v104
	v_log_f32_e32 v68, v68
	v_fmac_f32_e32 v139, v113, v105
	v_pk_add_f32 v[60:61], v[60:61], 1.0 op_sel_hi:[1,0]
	v_add_f32_e32 v66, v66, v82
	v_mul_f32_e32 v104, 0x3f317217, v68
	v_fma_f32 v104, v68, s5, -v104
	v_fmac_f32_e32 v104, 0x3377d1cf, v68
	v_fmac_f32_e32 v104, 0x3f317217, v68
	v_cmp_lt_f32_e64 s[0:1], |v68|, s6
	v_add_f32_e32 v62, v62, v94
	v_add_f32_e32 v63, v63, v95
	v_cndmask_b32_e64 v68, v68, v104, s[0:1]
	v_cndmask_b32_e32 v104, 0, v242, vcc
	v_sub_f32_e32 v68, v68, v104
	v_add_f32_e32 v68, v102, v68
	v_sub_f32_e32 v68, -0.5, v68
	v_mul_f32_e32 v68, 0x3fb8aa3b, v68
	v_exp_f32_e32 v68, v68
	v_mul_f32_e32 v62, 0xbfb8aa3b, v62
	v_mul_f32_e32 v63, 0xbfb8aa3b, v63
	v_exp_f32_e32 v62, v62
	v_xor_b32_e32 v102, 0x80000000, v68
	v_add_f32_e32 v68, v98, v122
	v_mul_f32_e32 v68, 0xbfb8aa3b, v68
	v_exp_f32_e32 v104, v68
	v_add_f32_e32 v68, v103, v127
	v_max_f32_e64 v98, -v68, 0
	v_mul_f32_e64 v68, |v68|, s21
	v_exp_f32_e32 v68, v68
	v_exp_f32_e32 v63, v63
	v_sub_f32_e32 v100, -0.5, v100
	v_sub_f32_e32 v101, -0.5, v101
	v_add_f32_e32 v68, 1.0, v68
	v_cmp_gt_f32_e32 vcc, s4, v68
	v_pk_add_f32 v[62:63], v[62:63], 1.0 op_sel_hi:[1,0]
	v_mul_f32_e32 v100, 0x3fb8aa3b, v100
	v_cndmask_b32_e64 v103, 0, 32, vcc
	v_ldexp_f32 v68, v68, v103
	v_log_f32_e32 v68, v68
	v_mul_f32_e32 v101, 0x3fb8aa3b, v101
	v_exp_f32_e32 v100, v100
	v_exp_f32_e32 v101, v101
	v_mul_f32_e32 v103, 0x3f317217, v68
	v_fma_f32 v103, v68, s5, -v103
	v_fmac_f32_e32 v103, 0x3377d1cf, v68
	v_fmac_f32_e32 v103, 0x3f317217, v68
	v_cmp_lt_f32_e64 s[0:1], |v68|, s6
	v_xor_b32_e32 v100, 0x80000000, v100
	v_xor_b32_e32 v101, 0x80000000, v101
	v_cndmask_b32_e64 v68, v68, v103, s[0:1]
	v_cndmask_b32_e32 v103, 0, v242, vcc
	v_sub_f32_e32 v68, v68, v103
	v_add_f32_e32 v68, v98, v68
	v_sub_f32_e32 v68, -0.5, v68
	v_mul_f32_e32 v68, 0x3fb8aa3b, v68
	v_exp_f32_e32 v68, v68
	v_pk_mul_f32 v[8:9], v[128:129], v[8:9]
	v_xor_b32_e32 v98, 0x80000000, v68
	v_add_f32_e32 v68, v99, v123
	v_mul_f32_e32 v68, 0xbfb8aa3b, v68
	v_exp_f32_e32 v105, v68
	v_lshlrev_b32_e32 v68, 16, v69
	v_and_b32_e32 v69, 0xffff0000, v69
	v_pk_add_f32 v[106:107], v[106:107], v[68:69] neg_lo:[0,1] neg_hi:[0,1]
	s_nop 0
	v_pk_fma_f32 v[130:131], v[110:111], v[106:107], v[68:69]
	v_pk_add_f32 v[68:69], v[104:105], 1.0 op_sel_hi:[1,0]
	v_pk_mul_f32 v[10:11], v[130:131], v[10:11]
	v_rcp_f32_e32 v127, v69
	v_cmp_gt_f32_e32 vcc, s4, v64
	v_rcp_f32_e32 v126, v68
	s_nop 0
	v_pk_add_f32 v[68:69], v[126:127], -1.0 op_sel_hi:[1,0]
	v_cndmask_b32_e64 v99, 0, 32, vcc
	v_ldexp_f32 v64, v64, v99
	v_log_f32_e32 v64, v64
	v_pk_fma_f32 v[68:69], v[118:119], v[68:69], 1.0 op_sel_hi:[1,1,0]
	v_mul_f32_e32 v99, 0x3f317217, v64
	v_fma_f32 v99, v64, s5, -v99
	v_fmac_f32_e32 v99, 0x3377d1cf, v64
	v_fmac_f32_e32 v99, 0x3f317217, v64
	v_cmp_lt_f32_e64 s[0:1], |v64|, s6
	v_pk_mul_f32 v[68:69], v[130:131], v[68:69]
	s_nop 0
	v_cndmask_b32_e64 v64, v64, v99, s[0:1]
	v_cndmask_b32_e32 v99, 0, v242, vcc
	v_sub_f32_e32 v64, v64, v99
	v_add_f32_e32 v64, v80, v64
	v_max_f32_e64 v80, -v65, 0
	v_mul_f32_e64 v65, |v65|, s21
	v_exp_f32_e32 v65, v65
	v_pk_mul_f32 v[104:105], v[220:221], v[68:69]
	v_sub_f32_e32 v64, -0.5, v64
	v_fmac_f32_e32 v139, v114, v104
	v_add_f32_e32 v65, 1.0, v65
	v_cmp_gt_f32_e32 vcc, s4, v65
	v_fmac_f32_e32 v139, v115, v105
	v_mul_f32_e32 v64, 0x3fb8aa3b, v64
	v_cndmask_b32_e64 v81, 0, 32, vcc
	v_ldexp_f32 v65, v65, v81
	v_log_f32_e32 v65, v65
	v_exp_f32_e32 v64, v64
	v_mul_f32_e32 v81, 0x3f317217, v65
	v_fma_f32 v81, v65, s5, -v81
	v_fmac_f32_e32 v81, 0x3377d1cf, v65
	v_fmac_f32_e32 v81, 0x3f317217, v65
	v_cmp_lt_f32_e64 s[0:1], |v65|, s6
	v_xor_b32_e32 v64, 0x80000000, v64
	s_nop 0
	v_cndmask_b32_e64 v65, v65, v81, s[0:1]
	v_cndmask_b32_e32 v81, 0, v242, vcc
	v_sub_f32_e32 v65, v65, v81
	v_add_f32_e32 v65, v80, v65
	v_lshlrev_b32_e32 v80, 16, v70
	v_and_b32_e32 v81, 0xffff0000, v70
	v_pk_add_f32 v[72:73], v[72:73], v[80:81] neg_lo:[0,1] neg_hi:[0,1]
	s_nop 0
	v_pk_fma_f32 v[134:135], v[72:73], v[76:77], v[80:81]
	v_sub_f32_e32 v65, -0.5, v65
	v_mul_f32_e32 v65, 0x3fb8aa3b, v65
	v_exp_f32_e32 v65, v65
	v_rcp_f32_e32 v133, v61
	v_xor_b32_e32 v65, 0x80000000, v65
	v_pk_mul_f32 v[6:7], v[134:135], v[12:13]
	v_max_f32_e64 v70, -v66, 0
	v_mul_f32_e64 v66, |v66|, s21
	v_exp_f32_e32 v66, v66
	v_rcp_f32_e32 v132, v60
	s_nop 0
	v_pk_add_f32 v[60:61], v[132:133], -1.0 op_sel_hi:[1,0]
	v_pk_mul_f32 v[12:13], v[6:7], v[6:7]
	v_pk_fma_f32 v[60:61], v[88:89], v[60:61], 1.0 op_sel_hi:[1,1,0]
	v_add_f32_e32 v66, 1.0, v66
	v_pk_mul_f32 v[60:61], v[134:135], v[60:61]
	v_cmp_gt_f32_e32 vcc, s4, v66
	v_pk_mul_f32 v[72:73], v[222:223], v[60:61]
	s_nop 0
	v_fmac_f32_e32 v139, v84, v72
	v_cndmask_b32_e64 v72, 0, 32, vcc
	v_ldexp_f32 v66, v66, v72
	v_log_f32_e32 v66, v66
	v_fmac_f32_e32 v139, v85, v73
	v_mul_f32_e32 v72, 0x3f317217, v66
	v_fma_f32 v72, v66, s5, -v72
	v_fmac_f32_e32 v72, 0x3377d1cf, v66
	v_fmac_f32_e32 v72, 0x3f317217, v66
	v_cmp_lt_f32_e64 s[0:1], |v66|, s6
	s_nop 1
	v_cndmask_b32_e64 v66, v66, v72, s[0:1]
	v_cndmask_b32_e32 v72, 0, v242, vcc
	v_sub_f32_e32 v66, v66, v72
	v_add_f32_e32 v66, v70, v66
	v_sub_f32_e32 v66, -0.5, v66
	v_mul_f32_e32 v66, 0x3fb8aa3b, v66
	v_exp_f32_e32 v66, v66
	s_nop 0
	v_xor_b32_e32 v72, 0x80000000, v66
	v_add_f32_e32 v66, v67, v83
	v_max_f32_e64 v67, -v66, 0
	v_mul_f32_e64 v66, |v66|, s21
	v_exp_f32_e32 v66, v66
	s_nop 0
	v_add_f32_e32 v66, 1.0, v66
	v_cmp_gt_f32_e32 vcc, s4, v66
	s_nop 1
	v_cndmask_b32_e64 v70, 0, 32, vcc
	v_ldexp_f32 v66, v66, v70
	v_log_f32_e32 v66, v66
	s_nop 0
	v_mul_f32_e32 v70, 0x3f317217, v66
	v_fma_f32 v70, v66, s5, -v70
	v_fmac_f32_e32 v70, 0x3377d1cf, v66
	v_fmac_f32_e32 v70, 0x3f317217, v66
	v_cmp_lt_f32_e64 s[0:1], |v66|, s6
	s_nop 1
	v_cndmask_b32_e64 v66, v66, v70, s[0:1]
	v_cndmask_b32_e32 v70, 0, v242, vcc
	v_sub_f32_e32 v66, v66, v70
	v_add_f32_e32 v66, v67, v66
	v_sub_f32_e32 v66, -0.5, v66
	v_mul_f32_e32 v66, 0x3fb8aa3b, v66
	v_exp_f32_e32 v66, v66
	v_and_b32_e32 v67, 0xffff0000, v71
	v_xor_b32_e32 v73, 0x80000000, v66
	v_lshlrev_b32_e32 v66, 16, v71
	v_pk_add_f32 v[70:71], v[74:75], v[66:67] neg_lo:[0,1] neg_hi:[0,1]
	s_nop 0
	v_pk_fma_f32 v[214:215], v[70:71], v[78:79], v[66:67]
	v_rcp_f32_e32 v211, v63
	v_rcp_f32_e32 v210, v62
	s_nop 0
	v_pk_add_f32 v[62:63], v[210:211], -1.0 op_sel_hi:[1,0]
	s_nop 0
	v_pk_fma_f32 v[62:63], v[90:91], v[62:63], 1.0 op_sel_hi:[1,1,0]
	s_nop 0
	v_pk_mul_f32 v[62:63], v[214:215], v[62:63]
	s_nop 0
	v_pk_mul_f32 v[66:67], v[224:225], v[62:63]
	s_nop 0
	v_fmac_f32_e32 v139, v86, v66
	v_fmac_f32_e32 v139, v87, v67
	v_lshlrev_b32_e32 v66, 16, v40
	v_and_b32_e32 v67, 0xffff0000, v40
	v_pk_add_f32 v[48:49], v[48:49], v[66:67] neg_lo:[0,1] neg_hi:[0,1]
	v_lshlrev_b32_e32 v40, 16, v41
	v_and_b32_e32 v41, 0xffff0000, v41
	v_pk_fma_f32 v[44:45], v[44:45], v[48:49], v[66:67]
	v_pk_add_f32 v[48:49], v[50:51], v[40:41] neg_lo:[0,1] neg_hi:[0,1]
	s_nop 0
	v_pk_fma_f32 v[40:41], v[46:47], v[48:49], v[40:41]
	v_lshlrev_b32_e32 v46, 16, v42
	v_and_b32_e32 v47, 0xffff0000, v42
	v_pk_add_f32 v[36:37], v[36:37], v[46:47] neg_lo:[0,1] neg_hi:[0,1]
	s_nop 0
	v_pk_fma_f32 v[36:37], v[36:37], v[32:33], v[46:47]
	v_lshlrev_b32_e32 v32, 16, v43
	v_and_b32_e32 v33, 0xffff0000, v43
	v_pk_add_f32 v[38:39], v[38:39], v[32:33] neg_lo:[0,1] neg_hi:[0,1]
	s_nop 0
	v_pk_fma_f32 v[38:39], v[38:39], v[34:35], v[32:33]
	v_cvt_pk_bf16_f32 v32, v212, v213
	v_cvt_pk_bf16_f32 v33, v220, v221
	v_cvt_pk_bf16_f32 v34, v222, v223
	v_cvt_pk_bf16_f32 v35, v224, v225
	v_mad_i64_i32 v[212:213], s[0:1], v206, s20, v[170:171]
	flat_store_dwordx4 v[212:213], v[32:35]
	s_nop 1
	v_cvt_pk_bf16_f32 v32, v96, v97
	v_cvt_pk_bf16_f32 v33, v68, v69
	v_cvt_pk_bf16_f32 v34, v60, v61
	v_cvt_pk_bf16_f32 v35, v62, v63
	flat_store_dwordx4 v[212:213], v[32:35] offset:512
	s_nop 1
	v_cvt_pk_bf16_f32 v32, v44, v45
	v_cvt_pk_bf16_f32 v33, v40, v41
	v_cvt_pk_bf16_f32 v34, v36, v37
	v_cvt_pk_bf16_f32 v35, v38, v39
	flat_store_dwordx4 v[212:213], v[32:35] offset:1024
	s_nop 1
	v_cvt_pk_bf16_f32 v32, v100, v101
	v_cvt_pk_bf16_f32 v33, v102, v98
	v_cvt_pk_bf16_f32 v34, v64, v65
	v_cvt_pk_bf16_f32 v35, v72, v73
	flat_store_dwordx4 v[212:213], v[32:35] offset:2560
	s_nop 1
	v_cvt_pk_bf16_f32 v32, v52, v53
	v_cvt_pk_bf16_f32 v33, v54, v55
	v_cvt_pk_bf16_f32 v34, v56, v57
	v_cvt_pk_bf16_f32 v35, v58, v59
	flat_store_dwordx4 v[216:217], v[32:35]
	s_nop 1
	v_lshl_add_u64 v[32:33], v[208:209], 0, v[186:187]
	flat_load_dwordx4 v[112:115], v[32:33]
	global_load_dwordx4 v[116:119], v[218:219], off offset:144
	global_load_dwordx4 v[220:223], v[218:219], off offset:128
	global_load_dwordx4 v[120:123], v[158:159], off offset:144
	global_load_dwordx4 v[224:227], v[158:159], off offset:128
	v_lshl_add_u64 v[32:33], v[208:209], 0, v[188:189]
	flat_load_dwordx4 v[56:59], v[32:33]
	global_load_dwordx4 v[60:63], v[218:219], off offset:1168
	global_load_dwordx4 v[88:91], v[218:219], off offset:1152
	global_load_dwordx4 v[64:67], v[158:159], off offset:1168
	global_load_dwordx4 v[92:95], v[158:159], off offset:1152
	v_lshl_add_u64 v[32:33], v[208:209], 0, v[190:191]
	flat_load_dwordx4 v[40:43], v[32:33]
	global_load_dwordx4 v[36:39], v[218:219], off offset:2192
	global_load_dwordx4 v[48:51], v[218:219], off offset:2176
	s_nop 0
	global_load_dwordx4 v[32:35], v[158:159], off offset:2192
	global_load_dwordx4 v[44:47], v[158:159], off offset:2176
	global_load_dwordx4 v[68:71], v[160:161], off offset:144
	global_load_dwordx4 v[108:111], v[160:161], off offset:128
	global_load_dwordx4 v[72:75], v[162:163], off offset:144
	global_load_dwordx4 v[96:99], v[162:163], off offset:128
	global_load_dwordx4 v[76:79], v[164:165], off offset:144
	global_load_dwordx4 v[52:55], v[164:165], off offset:128
	global_load_dwordx4 v[84:87], v[166:167], off offset:144
	global_load_dwordx4 v[104:107], v[166:167], off offset:128
	global_load_dwordx4 v[80:83], v[168:169], off offset:144
	global_load_dwordx4 v[100:103], v[168:169], off offset:128
	s_waitcnt vmcnt(0)
	v_add_f32_e32 v20, v20, v68
	v_add_f32_e32 v28, v28, v108
	v_max_f32_e64 v108, -v28, 0
	v_mul_f32_e64 v28, |v28|, s21
	v_exp_f32_e32 v28, v28
	s_waitcnt lgkmcnt(0)
	v_lshlrev_b32_e32 v208, 16, v112
	v_and_b32_e32 v209, 0xffff0000, v112
	v_pk_add_f32 v[218:219], v[220:221], v[208:209] neg_lo:[0,1] neg_hi:[0,1]
	v_lshlrev_b32_e32 v112, 16, v113
	v_and_b32_e32 v113, 0xffff0000, v113
	v_pk_fma_f32 v[208:209], v[218:219], v[224:225], v[208:209]
	v_pk_add_f32 v[218:219], v[222:223], v[112:113] neg_lo:[0,1] neg_hi:[0,1]
	v_add_f32_e32 v28, 1.0, v28
	v_pk_fma_f32 v[112:113], v[218:219], v[226:227], v[112:113]
	v_lshlrev_b32_e32 v218, 16, v114
	v_and_b32_e32 v219, 0xffff0000, v114
	v_lshlrev_b32_e32 v114, 16, v115
	v_and_b32_e32 v115, 0xffff0000, v115
	v_pk_add_f32 v[118:119], v[118:119], v[114:115] neg_lo:[0,1] neg_hi:[0,1]
	v_cmp_gt_f32_e32 vcc, s4, v28
	v_pk_fma_f32 v[114:115], v[118:119], v[122:123], v[114:115]
	v_add_f32_e32 v24, v24, v96
	v_cndmask_b32_e64 v118, 0, 32, vcc
	v_ldexp_f32 v28, v28, v118
	v_log_f32_e32 v28, v28
	v_add_f32_e32 v25, v25, v97
	v_mul_f32_e32 v24, 0xbfb8aa3b, v24
	v_mul_f32_e32 v25, 0xbfb8aa3b, v25
	v_mul_f32_e32 v118, 0x3f317217, v28
	v_fma_f32 v118, v28, s5, -v118
	v_fmac_f32_e32 v118, 0x3377d1cf, v28
	v_fmac_f32_e32 v118, 0x3f317217, v28
	v_cmp_lt_f32_e64 s[0:1], |v28|, s6
	v_exp_f32_e32 v24, v24
	v_exp_f32_e32 v25, v25
	v_cndmask_b32_e64 v28, v28, v118, s[0:1]
	v_cndmask_b32_e32 v118, 0, v242, vcc
	v_sub_f32_e32 v28, v28, v118
	v_add_f32_e32 v28, v108, v28
	v_sub_f32_e32 v28, -0.5, v28
	v_mul_f32_e32 v28, 0x3fb8aa3b, v28
	v_exp_f32_e32 v28, v28
	v_pk_add_f32 v[24:25], v[24:25], 1.0 op_sel_hi:[1,0]
	v_add_f32_e32 v30, v30, v110
	v_add_f32_e32 v26, v26, v98
	v_xor_b32_e32 v108, 0x80000000, v28
	v_add_f32_e32 v28, v29, v109
	v_max_f32_e64 v29, -v28, 0
	v_mul_f32_e64 v28, |v28|, s21
	v_exp_f32_e32 v28, v28
	v_add_f32_e32 v27, v27, v99
	v_mul_f32_e32 v26, 0xbfb8aa3b, v26
	v_mul_f32_e32 v27, 0xbfb8aa3b, v27
	v_add_f32_e32 v28, 1.0, v28
	v_cmp_gt_f32_e32 vcc, s4, v28
	v_exp_f32_e32 v26, v26
	v_exp_f32_e32 v27, v27
	v_cndmask_b32_e64 v96, 0, 32, vcc
	v_ldexp_f32 v28, v28, v96
	v_log_f32_e32 v28, v28
	v_pk_add_f32 v[26:27], v[26:27], 1.0 op_sel_hi:[1,0]
	v_max_f32_e64 v68, -v20, 0
	v_mul_f32_e64 v20, |v20|, s21
	v_mul_f32_e32 v96, 0x3f317217, v28
	v_fma_f32 v96, v28, s5, -v96
	v_fmac_f32_e32 v96, 0x3377d1cf, v28
	v_fmac_f32_e32 v96, 0x3f317217, v28
	v_cmp_lt_f32_e64 s[0:1], |v28|, s6
	v_exp_f32_e32 v20, v20
	v_add_f32_e32 v16, v16, v72
	v_cndmask_b32_e64 v28, v28, v96, s[0:1]
	v_cndmask_b32_e32 v96, 0, v242, vcc
	v_sub_f32_e32 v28, v28, v96
	v_add_f32_e32 v28, v29, v28
	v_sub_f32_e32 v28, -0.5, v28
	v_mul_f32_e32 v28, 0x3fb8aa3b, v28
	v_exp_f32_e32 v28, v28
	v_and_b32_e32 v29, 0xffff0000, v56
	v_add_f32_e32 v20, 1.0, v20
	v_add_f32_e32 v17, v17, v73
	v_xor_b32_e32 v96, 0x80000000, v28
	v_lshlrev_b32_e32 v28, 16, v56
	v_pk_add_f32 v[88:89], v[88:89], v[28:29] neg_lo:[0,1] neg_hi:[0,1]
	s_nop 0
	v_pk_fma_f32 v[28:29], v[92:93], v[88:89], v[28:29]
	v_mul_f32_e32 v16, 0xbfb8aa3b, v16
	v_mul_f32_e32 v17, 0xbfb8aa3b, v17
	v_exp_f32_e32 v16, v16
	v_rcp_f32_e32 v25, v25
	v_exp_f32_e32 v17, v17
	v_add_f32_e32 v22, v22, v70
	v_add_f32_e32 v18, v18, v74
	v_rcp_f32_e32 v24, v24
	v_max_f32_e64 v56, -v30, 0
	v_mul_f32_e64 v30, |v30|, s21
	v_exp_f32_e32 v30, v30
	v_pk_add_f32 v[88:89], v[24:25], -1.0 op_sel_hi:[1,0]
	v_pk_add_f32 v[16:17], v[16:17], 1.0 op_sel_hi:[1,0]
	v_pk_fma_f32 v[88:89], v[104:105], v[88:89], 1.0 op_sel_hi:[1,1,0]
	v_add_f32_e32 v30, 1.0, v30
	v_pk_mul_f32 v[88:89], v[28:29], v[88:89]
	v_cmp_gt_f32_e32 vcc, s4, v30
	v_pk_mul_f32 v[92:93], v[208:209], v[88:89]
	v_add_f32_e32 v19, v19, v75
	v_fmac_f32_e32 v139, v100, v92
	v_cndmask_b32_e64 v92, 0, 32, vcc
	v_ldexp_f32 v30, v30, v92
	v_log_f32_e32 v30, v30
	v_fmac_f32_e32 v139, v101, v93
	v_mul_f32_e32 v18, 0xbfb8aa3b, v18
	v_mul_f32_e32 v19, 0xbfb8aa3b, v19
	v_mul_f32_e32 v92, 0x3f317217, v30
	v_fma_f32 v92, v30, s5, -v92
	v_fmac_f32_e32 v92, 0x3377d1cf, v30
	v_fmac_f32_e32 v92, 0x3f317217, v30
	v_cmp_lt_f32_e64 s[0:1], |v30|, s6
	v_exp_f32_e32 v18, v18
	v_exp_f32_e32 v19, v19
	v_cndmask_b32_e64 v30, v30, v92, s[0:1]
	v_cndmask_b32_e32 v92, 0, v242, vcc
	v_sub_f32_e32 v30, v30, v92
	v_add_f32_e32 v30, v56, v30
	v_sub_f32_e32 v30, -0.5, v30
	v_mul_f32_e32 v30, 0x3fb8aa3b, v30
	v_exp_f32_e32 v30, v30
	v_pk_add_f32 v[18:19], v[18:19], 1.0 op_sel_hi:[1,0]
	v_pk_add_f32 v[116:117], v[116:117], v[218:219] neg_lo:[0,1] neg_hi:[0,1]
	v_pk_mul_f32 v[28:29], v[28:29], v[52:53]
	v_xor_b32_e32 v92, 0x80000000, v30
	v_add_f32_e32 v30, v31, v111
	v_max_f32_e64 v31, -v30, 0
	v_mul_f32_e64 v30, |v30|, s21
	v_exp_f32_e32 v30, v30
	v_pk_fma_f32 v[116:117], v[116:117], v[120:121], v[218:219]
	v_add_f32_e32 v30, 1.0, v30
	v_cmp_gt_f32_e32 vcc, s4, v30
	s_nop 1
	v_cndmask_b32_e64 v56, 0, 32, vcc
	v_ldexp_f32 v30, v30, v56
	v_log_f32_e32 v30, v30
	s_nop 0
	v_mul_f32_e32 v56, 0x3f317217, v30
	v_fma_f32 v56, v30, s5, -v56
	v_fmac_f32_e32 v56, 0x3377d1cf, v30
	v_fmac_f32_e32 v56, 0x3f317217, v30
	v_cmp_lt_f32_e64 s[0:1], |v30|, s6
	s_nop 1
	v_cndmask_b32_e64 v30, v30, v56, s[0:1]
	v_cndmask_b32_e32 v56, 0, v242, vcc
	v_sub_f32_e32 v30, v30, v56
	v_add_f32_e32 v30, v31, v30
	v_sub_f32_e32 v30, -0.5, v30
	v_mul_f32_e32 v30, 0x3fb8aa3b, v30
	v_exp_f32_e32 v30, v30
	v_and_b32_e32 v31, 0xffff0000, v57
	v_xor_b32_e32 v93, 0x80000000, v30
	v_lshlrev_b32_e32 v30, 16, v57
	v_pk_add_f32 v[56:57], v[90:91], v[30:31] neg_lo:[0,1] neg_hi:[0,1]
	s_nop 0
	v_pk_fma_f32 v[30:31], v[94:95], v[56:57], v[30:31]
	v_rcp_f32_e32 v27, v27
	v_rcp_f32_e32 v26, v26
	s_nop 0
	v_pk_add_f32 v[56:57], v[26:27], -1.0 op_sel_hi:[1,0]
	v_cmp_gt_f32_e32 vcc, s4, v20
	v_pk_fma_f32 v[56:57], v[106:107], v[56:57], 1.0 op_sel_hi:[1,1,0]
	s_nop 0
	v_pk_mul_f32 v[56:57], v[30:31], v[56:57]
	v_pk_mul_f32 v[30:31], v[30:31], v[54:55]
	v_pk_mul_f32 v[90:91], v[112:113], v[56:57]
	v_pk_mul_f32 v[54:55], v[30:31], v[30:31]
	v_fmac_f32_e32 v139, v102, v90
	v_cndmask_b32_e64 v90, 0, 32, vcc
	v_ldexp_f32 v20, v20, v90
	v_log_f32_e32 v20, v20
	v_fmac_f32_e32 v139, v103, v91
	v_mul_f32_e32 v90, 0x3f317217, v20
	v_fma_f32 v90, v20, s5, -v90
	v_fmac_f32_e32 v90, 0x3377d1cf, v20
	v_fmac_f32_e32 v90, 0x3f317217, v20
	v_cmp_lt_f32_e64 s[0:1], |v20|, s6
	s_nop 1
	v_cndmask_b32_e64 v20, v20, v90, s[0:1]
	v_cndmask_b32_e32 v90, 0, v242, vcc
	v_sub_f32_e32 v20, v20, v90
	v_add_f32_e32 v20, v68, v20
	v_sub_f32_e32 v20, -0.5, v20
	v_mul_f32_e32 v20, 0x3fb8aa3b, v20
	v_exp_f32_e32 v20, v20
	s_nop 0
	v_xor_b32_e32 v68, 0x80000000, v20
	v_add_f32_e32 v20, v21, v69
	v_max_f32_e64 v21, -v20, 0
	v_mul_f32_e64 v20, |v20|, s21
	v_exp_f32_e32 v20, v20
	s_nop 0
	v_add_f32_e32 v20, 1.0, v20
	v_cmp_gt_f32_e32 vcc, s4, v20
	s_nop 1
	v_cndmask_b32_e64 v69, 0, 32, vcc
	v_ldexp_f32 v20, v20, v69
	v_log_f32_e32 v20, v20
	s_nop 0
	v_mul_f32_e32 v69, 0x3f317217, v20
	v_fma_f32 v69, v20, s5, -v69
	v_fmac_f32_e32 v69, 0x3377d1cf, v20
	v_fmac_f32_e32 v69, 0x3f317217, v20
	v_cmp_lt_f32_e64 s[0:1], |v20|, s6
	s_nop 1
	v_cndmask_b32_e64 v20, v20, v69, s[0:1]
	v_cndmask_b32_e32 v69, 0, v242, vcc
	v_sub_f32_e32 v20, v20, v69
	v_add_f32_e32 v20, v21, v20
	v_sub_f32_e32 v20, -0.5, v20
	v_mul_f32_e32 v20, 0x3fb8aa3b, v20
	v_exp_f32_e32 v20, v20
	v_and_b32_e32 v21, 0xffff0000, v58
	v_xor_b32_e32 v69, 0x80000000, v20
	v_lshlrev_b32_e32 v20, 16, v58
	v_pk_add_f32 v[60:61], v[60:61], v[20:21] neg_lo:[0,1] neg_hi:[0,1]
	s_nop 0
	v_pk_fma_f32 v[20:21], v[60:61], v[64:65], v[20:21]
	v_rcp_f32_e32 v17, v17
	v_rcp_f32_e32 v16, v16
	v_max_f32_e64 v58, -v22, 0
	v_mul_f32_e64 v22, |v22|, s21
	v_exp_f32_e32 v22, v22
	v_pk_add_f32 v[60:61], v[16:17], -1.0 op_sel_hi:[1,0]
	v_add_f32_e32 v22, 1.0, v22
	v_cmp_gt_f32_e32 vcc, s4, v22
	v_pk_fma_f32 v[60:61], v[84:85], v[60:61], 1.0 op_sel_hi:[1,1,0]
	s_nop 0
	v_cndmask_b32_e64 v70, 0, 32, vcc
	v_ldexp_f32 v22, v22, v70
	v_log_f32_e32 v22, v22
	v_pk_mul_f32 v[64:65], v[20:21], v[60:61]
	v_pk_mul_f32 v[20:21], v[20:21], v[76:77]
	v_pk_mul_f32 v[72:73], v[116:117], v[64:65]
	v_mul_f32_e32 v70, 0x3f317217, v22
	v_fma_f32 v70, v22, s5, -v70
	v_fmac_f32_e32 v70, 0x3377d1cf, v22
	v_fmac_f32_e32 v70, 0x3f317217, v22
	v_cmp_lt_f32_e64 s[0:1], |v22|, s6
	v_fmac_f32_e32 v139, v80, v72
	v_fmac_f32_e32 v139, v81, v73
	v_cndmask_b32_e64 v22, v22, v70, s[0:1]
	v_cndmask_b32_e32 v70, 0, v242, vcc
	v_sub_f32_e32 v22, v22, v70
	v_add_f32_e32 v22, v58, v22
	v_sub_f32_e32 v22, -0.5, v22
	v_mul_f32_e32 v22, 0x3fb8aa3b, v22
	v_exp_f32_e32 v22, v22
	v_pk_mul_f32 v[60:61], v[20:21], v[20:21]
	v_xor_b32_e32 v70, 0x80000000, v22
	v_add_f32_e32 v22, v23, v71
	v_max_f32_e64 v23, -v22, 0
	v_mul_f32_e64 v22, |v22|, s21
	v_exp_f32_e32 v22, v22
	s_nop 0
	v_add_f32_e32 v22, 1.0, v22
	v_cmp_gt_f32_e32 vcc, s4, v22
	s_nop 1
	v_cndmask_b32_e64 v58, 0, 32, vcc
	v_ldexp_f32 v22, v22, v58
	v_log_f32_e32 v22, v22
	s_nop 0
	v_mul_f32_e32 v58, 0x3f317217, v22
	v_fma_f32 v58, v22, s5, -v58
	v_fmac_f32_e32 v58, 0x3377d1cf, v22
	v_fmac_f32_e32 v58, 0x3f317217, v22
	v_cmp_lt_f32_e64 s[0:1], |v22|, s6
	s_nop 1
	v_cndmask_b32_e64 v22, v22, v58, s[0:1]
	v_cndmask_b32_e32 v58, 0, v242, vcc
	v_sub_f32_e32 v22, v22, v58
	v_add_f32_e32 v22, v23, v22
	v_sub_f32_e32 v22, -0.5, v22
	v_mul_f32_e32 v22, 0x3fb8aa3b, v22
	v_exp_f32_e32 v22, v22
	v_and_b32_e32 v23, 0xffff0000, v59
	v_xor_b32_e32 v71, 0x80000000, v22
	v_lshlrev_b32_e32 v22, 16, v59
	v_pk_add_f32 v[58:59], v[62:63], v[22:23] neg_lo:[0,1] neg_hi:[0,1]
	s_nop 0
	v_pk_fma_f32 v[22:23], v[58:59], v[66:67], v[22:23]
	v_rcp_f32_e32 v19, v19
	v_rcp_f32_e32 v18, v18
	s_nop 0
	v_pk_add_f32 v[58:59], v[18:19], -1.0 op_sel_hi:[1,0]
	s_nop 0
	v_pk_fma_f32 v[58:59], v[86:87], v[58:59], 1.0 op_sel_hi:[1,1,0]
	s_nop 0
	v_pk_mul_f32 v[58:59], v[22:23], v[58:59]
	v_pk_mul_f32 v[22:23], v[22:23], v[78:79]
	v_pk_mul_f32 v[62:63], v[114:115], v[58:59]
	v_pk_mul_f32 v[66:67], v[22:23], v[22:23]
	v_fmac_f32_e32 v139, v82, v62
	v_fmac_f32_e32 v139, v83, v63
	v_lshlrev_b32_e32 v62, 16, v40
	v_and_b32_e32 v63, 0xffff0000, v40
	v_pk_add_f32 v[48:49], v[48:49], v[62:63] neg_lo:[0,1] neg_hi:[0,1]
	v_lshlrev_b32_e32 v40, 16, v41
	v_and_b32_e32 v41, 0xffff0000, v41
	v_pk_fma_f32 v[44:45], v[44:45], v[48:49], v[62:63]
	v_pk_add_f32 v[48:49], v[50:51], v[40:41] neg_lo:[0,1] neg_hi:[0,1]
	s_nop 0
	v_pk_fma_f32 v[40:41], v[46:47], v[48:49], v[40:41]
	v_lshlrev_b32_e32 v46, 16, v42
	v_and_b32_e32 v47, 0xffff0000, v42
	v_pk_add_f32 v[36:37], v[36:37], v[46:47] neg_lo:[0,1] neg_hi:[0,1]
	s_nop 0
	v_pk_fma_f32 v[36:37], v[36:37], v[32:33], v[46:47]
	v_lshlrev_b32_e32 v32, 16, v43
	v_and_b32_e32 v33, 0xffff0000, v43
	v_pk_add_f32 v[38:39], v[38:39], v[32:33] neg_lo:[0,1] neg_hi:[0,1]
	s_nop 0
	v_pk_fma_f32 v[38:39], v[38:39], v[34:35], v[32:33]
	v_cvt_pk_bf16_f32 v32, v208, v209
	v_cvt_pk_bf16_f32 v33, v112, v113
	v_cvt_pk_bf16_f32 v34, v116, v117
	v_cvt_pk_bf16_f32 v35, v114, v115
	flat_store_dwordx4 v[212:213], v[32:35] offset:64
	s_nop 1
	v_cvt_pk_bf16_f32 v32, v88, v89
	v_cvt_pk_bf16_f32 v33, v56, v57
	v_cvt_pk_bf16_f32 v34, v64, v65
	v_cvt_pk_bf16_f32 v35, v58, v59
	flat_store_dwordx4 v[212:213], v[32:35] offset:576
	s_nop 1
	v_cvt_pk_bf16_f32 v32, v44, v45
	v_cvt_pk_bf16_f32 v33, v40, v41
	v_cvt_pk_bf16_f32 v34, v36, v37
	v_cvt_pk_bf16_f32 v35, v38, v39
	flat_store_dwordx4 v[212:213], v[32:35] offset:1088
	s_nop 1
	v_cvt_pk_bf16_f32 v32, v108, v96
	v_cvt_pk_bf16_f32 v33, v92, v93
	v_cvt_pk_bf16_f32 v34, v68, v69
	v_cvt_pk_bf16_f32 v35, v70, v71
	flat_store_dwordx4 v[212:213], v[32:35] offset:2624
	flat_store_dwordx4 v[216:217], v[0:3] offset:64
	s_nop 0
	v_pk_mul_f32 v[32:33], v[8:9], v[8:9]
	v_pk_mul_f32 v[2:3], v[214:215], v[14:15]
	v_pk_mul_f32 v[14:15], v[10:11], v[10:11]
	v_add_f32_e32 v32, v32, v33
	v_add_f32_e32 v14, v14, v32
	v_add_f32_e32 v14, v15, v14
	v_add_f32_e32 v12, v14, v12
	v_pk_mul_f32 v[4:5], v[2:3], v[2:3]
	v_add_f32_e32 v12, v13, v12
	v_add_f32_e32 v4, v4, v12
	v_pk_mul_f32 v[34:35], v[28:29], v[28:29]
	v_add_f32_e32 v4, v5, v4
	v_add_f32_e32 v4, v4, v34
	v_add_f32_e32 v4, v35, v4
	v_add_f32_e32 v4, v54, v4
	v_and_b32_e32 v1, 64, v243
	v_add_f32_e32 v4, v55, v4
	v_xor_b32_e32 v0, 16, v243
	v_add_u32_e32 v1, 64, v1
	v_add_f32_e32 v4, v4, v60
	v_cmp_lt_i32_e32 vcc, v0, v1
	v_add_f32_e32 v4, v61, v4
	v_add_f32_e32 v4, v66, v4
	v_cndmask_b32_e32 v0, v243, v0, vcc
	v_lshlrev_b32_e32 v36, 2, v0
	v_add_f32_e32 v4, v67, v4
	ds_bpermute_b32 v5, v36, v4
	v_xor_b32_e32 v0, 32, v243
	v_cmp_lt_i32_e32 vcc, v0, v1
	s_waitcnt lgkmcnt(0)
	v_add_f32_e32 v4, v4, v5
	v_cndmask_b32_e32 v0, v243, v0, vcc
	v_lshlrev_b32_e32 v37, 2, v0
	ds_bpermute_b32 v5, v37, v4
	ds_bpermute_b32 v0, v36, v139
	s_waitcnt lgkmcnt(0)
	v_add_f32_e32 v4, v4, v5
	v_cmp_gt_f32_e32 vcc, s34, v4
	v_mul_f32_e32 v5, 0x4f800000, v4
	v_add_f32_e32 v0, v139, v0
	v_cndmask_b32_e32 v4, v4, v5, vcc
	v_sqrt_f32_e32 v5, v4
	ds_bpermute_b32 v1, v37, v0
	v_add_u32_e32 v12, -1, v5
	v_fma_f32 v13, -v12, v5, v4
	v_cmp_ge_f32_e64 s[0:1], 0, v13
	v_add_u32_e32 v13, 1, v5
	s_nop 0
	v_cndmask_b32_e64 v12, v5, v12, s[0:1]
	v_fma_f32 v5, -v13, v5, v4
	v_cmp_lt_f32_e64 s[0:1], 0, v5
	s_nop 1
	v_cndmask_b32_e64 v5, v12, v13, s[0:1]
	v_mul_f32_e32 v12, 0x37800000, v5
	v_cndmask_b32_e32 v5, v5, v12, vcc
	v_cmp_class_f32_e32 vcc, v4, v237
	s_nop 1
	v_cndmask_b32_e32 v4, v5, v4, vcc
	v_max_f32_e32 v4, 0x2b8cbccc, v4
	v_rcp_f32_e32 v12, v4
	s_nop 0
	v_pk_mul_f32 v[4:5], v[8:9], v[12:13] op_sel_hi:[1,0]
	v_pk_mul_f32 v[10:11], v[10:11], v[12:13] op_sel_hi:[1,0]
	v_pk_mul_f32 v[6:7], v[6:7], v[12:13] op_sel_hi:[1,0]
	v_pk_mul_f32 v[34:35], v[2:3], v[12:13] op_sel_hi:[1,0]
	v_pk_mul_f32 v[8:9], v[124:125], v[4:5]
	v_pk_mul_f32 v[14:15], v[126:127], v[10:11]
	v_pk_mul_f32 v[32:33], v[132:133], v[6:7]
	v_pk_mul_f32 v[36:37], v[210:211], v[34:35]
	v_cvt_pk_bf16_f32 v2, v4, v5
	v_cvt_pk_bf16_f32 v3, v10, v11
	v_cvt_pk_bf16_f32 v4, v6, v7
	v_cvt_pk_bf16_f32 v5, v34, v35
	flat_store_dwordx4 v[212:213], v[2:5] offset:1536
	v_pk_mul_f32 v[10:11], v[20:21], v[12:13] op_sel_hi:[1,0]
	s_nop 0
	v_cvt_pk_bf16_f32 v2, v8, v9
	v_cvt_pk_bf16_f32 v3, v14, v15
	v_cvt_pk_bf16_f32 v4, v32, v33
	v_cvt_pk_bf16_f32 v5, v36, v37
	flat_store_dwordx4 v[212:213], v[2:5] offset:2048
	v_pk_mul_f32 v[14:15], v[16:17], v[10:11]
	s_nop 0
	v_pk_mul_f32 v[2:3], v[28:29], v[12:13] op_sel_hi:[1,0]
	v_pk_mul_f32 v[4:5], v[30:31], v[12:13] op_sel_hi:[1,0]
	v_pk_mul_f32 v[12:13], v[22:23], v[12:13] op_sel_hi:[1,0]
	v_pk_mul_f32 v[6:7], v[24:25], v[2:3]
	v_pk_mul_f32 v[8:9], v[26:27], v[4:5]
	v_pk_mul_f32 v[16:17], v[18:19], v[12:13]
	v_cvt_pk_bf16_f32 v2, v2, v3
	v_cvt_pk_bf16_f32 v3, v4, v5
	v_cvt_pk_bf16_f32 v4, v10, v11
	v_cvt_pk_bf16_f32 v5, v12, v13
	flat_store_dwordx4 v[212:213], v[2:5] offset:1600
	s_nop 1
	v_cvt_pk_bf16_f32 v2, v6, v7
	v_cvt_pk_bf16_f32 v3, v8, v9
	v_cvt_pk_bf16_f32 v4, v14, v15
	v_cvt_pk_bf16_f32 v5, v16, v17
	flat_store_dwordx4 v[212:213], v[2:5] offset:2112
	s_and_saveexec_b64 s[0:1], s[8:9]
	s_cbranch_execz .LBB0_346
	v_lshl_add_u64 v[2:3], v[206:207], 4, s[12:13]
	s_waitcnt lgkmcnt(0)
	v_add_f32_e32 v0, v0, v1
	flat_store_dword v[2:3], v0
	s_branch .LBB0_346

.LBB0_430:
	v_mov_b32_e32 v0, v192
	v_mov_b32_e32 v4, v192
	v_mov_b32_e32 v8, v192
	v_mov_b32_e32 v12, v192
	v_mov_b32_e32 v16, v192
	v_mov_b32_e32 v20, v192
	v_mov_b32_e32 v24, v192
	v_mov_b32_e32 v28, v195
	s_waitcnt lgkmcnt(0)
	s_barrier
	flat_load_dwordx4 v[32:35], v[70:71]
	flat_load_dwordx4 v[36:39], v[72:73]
	ds_read_b128 v[40:43], v118
	v_mov_b32_e32 v1, v0
	v_mov_b32_e32 v2, v0
	v_mov_b32_e32 v3, v0
	v_mov_b32_e32 v5, v4
	v_mov_b32_e32 v6, v4
	v_mov_b32_e32 v7, v4
	v_mov_b32_e32 v9, v8
	v_mov_b32_e32 v10, v8
	v_mov_b32_e32 v11, v8
	v_mov_b32_e32 v13, v12
	v_mov_b32_e32 v14, v12
	v_mov_b32_e32 v15, v12
	v_mov_b32_e32 v17, v16
	v_mov_b32_e32 v18, v16
	v_mov_b32_e32 v19, v16
	v_mov_b32_e32 v21, v20
	v_mov_b32_e32 v22, v20
	v_mov_b32_e32 v23, v20
	v_mov_b32_e32 v25, v24
	v_mov_b32_e32 v26, v24
	v_mov_b32_e32 v27, v24
	v_mov_b32_e32 v29, v28
	v_mov_b32_e32 v30, v28
	v_mov_b32_e32 v31, v28
	s_add_i32 s39, s39, s81
	s_cmpk_gt_i32 s39, 0xff
	s_waitcnt vmcnt(0) lgkmcnt(0)
	v_mfma_f32_16x16x32_bf16 v[0:3], v[32:35], v[40:43], v[0:3]
	v_mfma_f32_16x16x32_bf16 v[4:7], v[36:39], v[40:43], v[4:7]
	ds_read_b128 v[40:43], v118 offset:8448
	s_waitcnt lgkmcnt(0)
	v_mfma_f32_16x16x32_bf16 v[8:11], v[32:35], v[40:43], v[8:11]
	v_mfma_f32_16x16x32_bf16 v[12:15], v[36:39], v[40:43], v[12:15]
	ds_read_b128 v[40:43], v118 offset:16896
	s_waitcnt lgkmcnt(0)
	v_mfma_f32_16x16x32_bf16 v[16:19], v[32:35], v[40:43], v[16:19]
	v_mfma_f32_16x16x32_bf16 v[20:23], v[36:39], v[40:43], v[20:23]
	ds_read_b128 v[40:43], v118 offset:25344
	s_waitcnt lgkmcnt(0)
	v_mfma_f32_16x16x32_bf16 v[24:27], v[32:35], v[40:43], v[24:27]
	v_mfma_f32_16x16x32_bf16 v[28:31], v[36:39], v[40:43], v[28:31]
	flat_load_dwordx4 v[32:35], v[70:71] offset:64
	flat_load_dwordx4 v[36:39], v[72:73] offset:64
	ds_read_b128 v[40:43], v118 offset:64
	s_waitcnt vmcnt(0) lgkmcnt(0)
	v_mfma_f32_16x16x32_bf16 v[0:3], v[32:35], v[40:43], v[0:3]
	v_mfma_f32_16x16x32_bf16 v[4:7], v[36:39], v[40:43], v[4:7]
	ds_read_b128 v[40:43], v118 offset:8512
	s_waitcnt lgkmcnt(0)
	v_mfma_f32_16x16x32_bf16 v[8:11], v[32:35], v[40:43], v[8:11]
	v_mfma_f32_16x16x32_bf16 v[12:15], v[36:39], v[40:43], v[12:15]
	ds_read_b128 v[40:43], v118 offset:16960
	s_waitcnt lgkmcnt(0)
	v_mfma_f32_16x16x32_bf16 v[16:19], v[32:35], v[40:43], v[16:19]
	v_mfma_f32_16x16x32_bf16 v[20:23], v[36:39], v[40:43], v[20:23]
	ds_read_b128 v[40:43], v118 offset:25408
	s_waitcnt lgkmcnt(0)
	v_mfma_f32_16x16x32_bf16 v[24:27], v[32:35], v[40:43], v[24:27]
	v_mfma_f32_16x16x32_bf16 v[28:31], v[36:39], v[40:43], v[28:31]
	flat_load_dwordx4 v[32:35], v[70:71] offset:128
	flat_load_dwordx4 v[36:39], v[72:73] offset:128
	ds_read_b128 v[40:43], v118 offset:128
	s_waitcnt vmcnt(0) lgkmcnt(0)
	v_mfma_f32_16x16x32_bf16 v[0:3], v[32:35], v[40:43], v[0:3]
	v_mfma_f32_16x16x32_bf16 v[4:7], v[36:39], v[40:43], v[4:7]
	ds_read_b128 v[40:43], v118 offset:8576
	s_waitcnt lgkmcnt(0)
	v_mfma_f32_16x16x32_bf16 v[8:11], v[32:35], v[40:43], v[8:11]
	v_mfma_f32_16x16x32_bf16 v[12:15], v[36:39], v[40:43], v[12:15]
	ds_read_b128 v[40:43], v118 offset:17024
	s_waitcnt lgkmcnt(0)
	v_mfma_f32_16x16x32_bf16 v[16:19], v[32:35], v[40:43], v[16:19]
	v_mfma_f32_16x16x32_bf16 v[20:23], v[36:39], v[40:43], v[20:23]
	ds_read_b128 v[40:43], v118 offset:25472
	s_waitcnt lgkmcnt(0)
	v_mfma_f32_16x16x32_bf16 v[24:27], v[32:35], v[40:43], v[24:27]
	v_mfma_f32_16x16x32_bf16 v[28:31], v[36:39], v[40:43], v[28:31]
	flat_load_dwordx4 v[32:35], v[70:71] offset:192
	flat_load_dwordx4 v[36:39], v[72:73] offset:192
	ds_read_b128 v[40:43], v118 offset:192
	s_waitcnt vmcnt(0) lgkmcnt(0)
	v_mfma_f32_16x16x32_bf16 v[0:3], v[32:35], v[40:43], v[0:3]
	v_mfma_f32_16x16x32_bf16 v[4:7], v[36:39], v[40:43], v[4:7]
	ds_read_b128 v[40:43], v118 offset:8640
	s_waitcnt lgkmcnt(0)
	v_mfma_f32_16x16x32_bf16 v[8:11], v[32:35], v[40:43], v[8:11]
	v_mfma_f32_16x16x32_bf16 v[12:15], v[36:39], v[40:43], v[12:15]
	ds_read_b128 v[40:43], v118 offset:17088
	s_waitcnt lgkmcnt(0)
	v_mfma_f32_16x16x32_bf16 v[16:19], v[32:35], v[40:43], v[16:19]
	v_mfma_f32_16x16x32_bf16 v[20:23], v[36:39], v[40:43], v[20:23]
	ds_read_b128 v[40:43], v118 offset:25536
	s_waitcnt lgkmcnt(0)
	v_mfma_f32_16x16x32_bf16 v[24:27], v[32:35], v[40:43], v[24:27]
	v_mfma_f32_16x16x32_bf16 v[28:31], v[36:39], v[40:43], v[28:31]
	flat_load_dwordx4 v[32:35], v[70:71] offset:256
	flat_load_dwordx4 v[36:39], v[72:73] offset:256
	ds_read_b128 v[40:43], v118 offset:256
	s_waitcnt vmcnt(0) lgkmcnt(0)
	v_mfma_f32_16x16x32_bf16 v[0:3], v[32:35], v[40:43], v[0:3]
	v_mfma_f32_16x16x32_bf16 v[4:7], v[36:39], v[40:43], v[4:7]
	ds_read_b128 v[40:43], v118 offset:8704
	s_waitcnt lgkmcnt(0)
	v_mfma_f32_16x16x32_bf16 v[8:11], v[32:35], v[40:43], v[8:11]
	v_mfma_f32_16x16x32_bf16 v[12:15], v[36:39], v[40:43], v[12:15]
	ds_read_b128 v[40:43], v118 offset:17152
	s_waitcnt lgkmcnt(0)
	v_mfma_f32_16x16x32_bf16 v[16:19], v[32:35], v[40:43], v[16:19]
	v_mfma_f32_16x16x32_bf16 v[20:23], v[36:39], v[40:43], v[20:23]
	ds_read_b128 v[40:43], v118 offset:25600
	s_waitcnt lgkmcnt(0)
	v_mfma_f32_16x16x32_bf16 v[24:27], v[32:35], v[40:43], v[24:27]
	v_mfma_f32_16x16x32_bf16 v[28:31], v[36:39], v[40:43], v[28:31]
	flat_load_dwordx4 v[32:35], v[70:71] offset:320
	flat_load_dwordx4 v[36:39], v[72:73] offset:320
	ds_read_b128 v[40:43], v118 offset:320
	s_waitcnt vmcnt(0) lgkmcnt(0)
	v_mfma_f32_16x16x32_bf16 v[0:3], v[32:35], v[40:43], v[0:3]
	v_mfma_f32_16x16x32_bf16 v[4:7], v[36:39], v[40:43], v[4:7]
	ds_read_b128 v[40:43], v118 offset:8768
	s_waitcnt lgkmcnt(0)
	v_mfma_f32_16x16x32_bf16 v[8:11], v[32:35], v[40:43], v[8:11]
	v_mfma_f32_16x16x32_bf16 v[12:15], v[36:39], v[40:43], v[12:15]
	ds_read_b128 v[40:43], v118 offset:17216
	s_waitcnt lgkmcnt(0)
	v_mfma_f32_16x16x32_bf16 v[44:47], v[32:35], v[40:43], v[16:19]
	s_nop 2
	ds_read_b128 v[16:19], v118 offset:25664
	flat_load_dwordx4 v[48:51], v[70:71] offset:384
	flat_load_dwordx4 v[52:55], v[72:73] offset:384
	v_mfma_f32_16x16x32_bf16 v[40:43], v[36:39], v[40:43], v[20:23]
	s_waitcnt lgkmcnt(0)
	v_mfma_f32_16x16x32_bf16 v[32:35], v[32:35], v[16:19], v[24:27]
	v_mfma_f32_16x16x32_bf16 v[36:39], v[36:39], v[16:19], v[28:31]
	ds_read_b128 v[16:19], v118 offset:384
	s_waitcnt vmcnt(0) lgkmcnt(0)
	v_mfma_f32_16x16x32_bf16 v[24:27], v[48:51], v[16:19], v[0:3]
	s_nop 2
	ds_read_b128 v[0:3], v118 offset:8832
	v_mfma_f32_16x16x32_bf16 v[28:31], v[52:55], v[16:19], v[4:7]
	s_nop 2
	ds_read_b128 v[4:7], v118 offset:17280
	s_waitcnt lgkmcnt(1)
	v_mfma_f32_16x16x32_bf16 v[16:19], v[48:51], v[0:3], v[8:11]
	v_mfma_f32_16x16x32_bf16 v[20:23], v[52:55], v[0:3], v[12:15]
	s_waitcnt lgkmcnt(0)
	v_mfma_f32_16x16x32_bf16 v[0:3], v[48:51], v[4:7], v[44:47]
	s_nop 0
	ds_read_b128 v[12:15], v118 offset:25728
	v_mfma_f32_16x16x32_bf16 v[4:7], v[52:55], v[4:7], v[40:43]
	s_nop 2
	flat_load_dwordx4 v[40:43], v[70:71] offset:448
	flat_load_dwordx4 v[44:47], v[72:73] offset:448
	s_waitcnt lgkmcnt(0)
	v_mfma_f32_16x16x32_bf16 v[8:11], v[48:51], v[12:15], v[32:35]
	s_nop 2
	ds_read_b128 v[32:35], v118 offset:448
	v_mfma_f32_16x16x32_bf16 v[12:15], v[52:55], v[12:15], v[36:39]
	s_waitcnt vmcnt(0) lgkmcnt(0)
	v_mfma_f32_16x16x32_bf16 v[36:39], v[40:43], v[32:35], v[24:27]
	s_nop 2
	ds_read_b128 v[24:27], v118 offset:8896
	v_mfma_f32_16x16x32_bf16 v[32:35], v[44:47], v[32:35], v[28:31]
	s_waitcnt lgkmcnt(0)
	v_mfma_f32_16x16x32_bf16 v[28:31], v[40:43], v[24:27], v[16:19]
	s_nop 2
	ds_read_b128 v[16:19], v118 offset:17344
	v_mfma_f32_16x16x32_bf16 v[24:27], v[44:47], v[24:27], v[20:23]
	s_waitcnt lgkmcnt(0)
	v_mfma_f32_16x16x32_bf16 v[20:23], v[40:43], v[16:19], v[0:3]
	s_nop 2
	ds_read_b128 v[0:3], v118 offset:25792
	v_mfma_f32_16x16x32_bf16 v[16:19], v[44:47], v[16:19], v[4:7]
	s_waitcnt lgkmcnt(0)
	v_mfma_f32_16x16x32_bf16 v[8:11], v[40:43], v[0:3], v[8:11]
	v_mfma_f32_16x16x32_bf16 v[0:3], v[44:47], v[0:3], v[12:15]
	s_nop 2
	global_load_dwordx4 v[12:15], v[74:75], off
	global_load_dwordx4 v[4:7], v[74:75], off offset:64
	ds_read_b64 v[40:41], v59
	s_waitcnt lgkmcnt(0)
	v_lshlrev_b32_e32 v42, 16, v40
	v_and_b32_e32 v43, 0xffff0000, v40
	s_waitcnt vmcnt(1)
	v_add_f32_e32 v36, v36, v12
	v_add_f32_e32 v37, v37, v13
	v_mul_f32_e32 v36, 0xbfb8aa3b, v36
	v_mul_f32_e32 v37, 0xbfb8aa3b, v37
	v_exp_f32_e32 v36, v36
	v_exp_f32_e32 v37, v37
	v_add_f32_e32 v38, v38, v14
	v_add_f32_e32 v39, v39, v15
	v_mul_f32_e32 v38, 0xbfb8aa3b, v38
	v_pk_add_f32 v[36:37], v[36:37], 1.0 op_sel_hi:[1,0]
	v_mul_f32_e32 v39, 0xbfb8aa3b, v39
	v_exp_f32_e32 v38, v38
	v_exp_f32_e32 v39, v39
	s_waitcnt vmcnt(0)
	v_add_f32_e32 v32, v32, v4
	v_rcp_f32_e32 v37, v37
	v_pk_add_f32 v[38:39], v[38:39], 1.0 op_sel_hi:[1,0]
	v_add_f32_e32 v33, v33, v5
	v_mul_f32_e32 v32, 0xbfb8aa3b, v32
	v_rcp_f32_e32 v36, v36
	s_nop 0
	v_pk_mul_f32 v[36:37], v[36:37], v[42:43]
	v_lshlrev_b32_e32 v40, 16, v41
	v_and_b32_e32 v41, 0xffff0000, v41
	v_mul_f32_e32 v33, 0xbfb8aa3b, v33
	v_rcp_f32_e32 v39, v39
	v_exp_f32_e32 v32, v32
	v_exp_f32_e32 v33, v33
	v_add_f32_e32 v34, v34, v6
	v_rcp_f32_e32 v38, v38
	s_nop 0
	v_pk_mul_f32 v[38:39], v[38:39], v[40:41]
	v_cvt_pk_bf16_f32 v40, v36, v37
	v_mov_b64_e32 v[36:37], s[26:27]
	v_cvt_pk_bf16_f32 v41, v38, v39
	v_mad_i64_i32 v[38:39], s[0:1], v119, s86, v[36:37]
	v_lshl_add_u64 v[38:39], v[38:39], 0, s[74:75]
	v_lshl_add_u64 v[42:43], v[38:39], 0, v[84:85]
	flat_store_dwordx2 v[42:43], v[40:41]
	ds_read_b64 v[40:41], v59 offset:32
	v_pk_add_f32 v[32:33], v[32:33], 1.0 op_sel_hi:[1,0]
	v_add_f32_e32 v35, v35, v7
	v_mul_f32_e32 v34, 0xbfb8aa3b, v34
	v_mul_f32_e32 v35, 0xbfb8aa3b, v35
	s_waitcnt lgkmcnt(0)
	v_lshlrev_b32_e32 v42, 16, v40
	v_and_b32_e32 v43, 0xffff0000, v40
	v_exp_f32_e32 v34, v34
	v_exp_f32_e32 v35, v35
	v_add_f32_e32 v28, v28, v12
	v_rcp_f32_e32 v33, v33
	v_pk_add_f32 v[34:35], v[34:35], 1.0 op_sel_hi:[1,0]
	v_add_f32_e32 v29, v29, v13
	v_mul_f32_e32 v28, 0xbfb8aa3b, v28
	v_rcp_f32_e32 v32, v32
	s_nop 0
	v_pk_mul_f32 v[32:33], v[32:33], v[42:43]
	v_lshlrev_b32_e32 v40, 16, v41
	v_and_b32_e32 v41, 0xffff0000, v41
	v_cvt_pk_bf16_f32 v32, v32, v33
	v_rcp_f32_e32 v35, v35
	v_mul_f32_e32 v29, 0xbfb8aa3b, v29
	v_exp_f32_e32 v28, v28
	v_exp_f32_e32 v29, v29
	v_rcp_f32_e32 v34, v34
	s_nop 0
	v_pk_mul_f32 v[34:35], v[34:35], v[40:41]
	v_pk_add_f32 v[28:29], v[28:29], 1.0 op_sel_hi:[1,0]
	v_cvt_pk_bf16_f32 v33, v34, v35
	v_lshl_add_u64 v[34:35], v[38:39], 0, v[86:87]
	flat_store_dwordx2 v[34:35], v[32:33]
	ds_read_b64 v[32:33], v112
	v_add_f32_e32 v30, v30, v14
	v_add_f32_e32 v31, v31, v15
	v_mul_f32_e32 v30, 0xbfb8aa3b, v30
	v_mul_f32_e32 v31, 0xbfb8aa3b, v31
	s_waitcnt lgkmcnt(0)
	v_lshlrev_b32_e32 v34, 16, v32
	v_and_b32_e32 v35, 0xffff0000, v32
	v_exp_f32_e32 v30, v30
	v_exp_f32_e32 v31, v31
	v_or_b32_e32 v38, s40, v61
	v_rcp_f32_e32 v29, v29
	v_pk_add_f32 v[30:31], v[30:31], 1.0 op_sel_hi:[1,0]
	v_add_f32_e32 v24, v24, v4
	v_add_f32_e32 v25, v25, v5
	v_rcp_f32_e32 v28, v28
	s_nop 0
	v_pk_mul_f32 v[28:29], v[28:29], v[34:35]
	v_lshlrev_b32_e32 v32, 16, v33
	v_and_b32_e32 v33, 0xffff0000, v33
	v_cvt_pk_bf16_f32 v28, v28, v29
	v_rcp_f32_e32 v31, v31
	v_mul_f32_e32 v24, 0xbfb8aa3b, v24
	v_mul_f32_e32 v25, 0xbfb8aa3b, v25
	v_exp_f32_e32 v24, v24
	v_rcp_f32_e32 v30, v30
	s_nop 0
	v_pk_mul_f32 v[30:31], v[30:31], v[32:33]
	v_exp_f32_e32 v25, v25
	v_cvt_pk_bf16_f32 v29, v30, v31
	v_mad_i64_i32 v[30:31], s[0:1], v38, s86, v[36:37]
	v_lshl_add_u64 v[30:31], v[30:31], 0, s[74:75]
	v_lshl_add_u64 v[32:33], v[30:31], 0, v[84:85]
	flat_store_dwordx2 v[32:33], v[28:29]
	ds_read_b64 v[28:29], v112 offset:32
	v_pk_add_f32 v[24:25], v[24:25], 1.0 op_sel_hi:[1,0]
	v_add_f32_e32 v26, v26, v6
	v_add_f32_e32 v27, v27, v7
	v_mul_f32_e32 v26, 0xbfb8aa3b, v26
	s_waitcnt lgkmcnt(0)
	v_lshlrev_b32_e32 v32, 16, v28
	v_and_b32_e32 v33, 0xffff0000, v28
	v_mul_f32_e32 v27, 0xbfb8aa3b, v27
	v_exp_f32_e32 v26, v26
	v_exp_f32_e32 v27, v27
	v_rcp_f32_e32 v25, v25
	v_pk_add_f32 v[26:27], v[26:27], 1.0 op_sel_hi:[1,0]
	v_add_f32_e32 v20, v20, v12
	v_add_f32_e32 v21, v21, v13
	v_rcp_f32_e32 v24, v24
	s_nop 0
	v_pk_mul_f32 v[24:25], v[24:25], v[32:33]
	v_lshlrev_b32_e32 v28, 16, v29
	v_and_b32_e32 v29, 0xffff0000, v29
	v_cvt_pk_bf16_f32 v24, v24, v25
	v_rcp_f32_e32 v27, v27
	v_mul_f32_e32 v20, 0xbfb8aa3b, v20
	v_mul_f32_e32 v21, 0xbfb8aa3b, v21
	v_exp_f32_e32 v20, v20
	v_rcp_f32_e32 v26, v26
	s_nop 0
	v_pk_mul_f32 v[26:27], v[26:27], v[28:29]
	v_exp_f32_e32 v21, v21
	v_cvt_pk_bf16_f32 v25, v26, v27
	v_lshl_add_u64 v[26:27], v[30:31], 0, v[86:87]
	flat_store_dwordx2 v[26:27], v[24:25]
	ds_read_b64 v[24:25], v113
	v_pk_add_f32 v[20:21], v[20:21], 1.0 op_sel_hi:[1,0]
	v_add_f32_e32 v22, v22, v14
	v_add_f32_e32 v23, v23, v15
	v_mul_f32_e32 v22, 0xbfb8aa3b, v22
	s_waitcnt lgkmcnt(0)
	v_lshlrev_b32_e32 v26, 16, v24
	v_and_b32_e32 v27, 0xffff0000, v24
	v_mul_f32_e32 v23, 0xbfb8aa3b, v23
	v_exp_f32_e32 v22, v22
	v_exp_f32_e32 v23, v23
	v_rcp_f32_e32 v21, v21
	v_pk_add_f32 v[22:23], v[22:23], 1.0 op_sel_hi:[1,0]
	v_or_b32_e32 v28, s40, v81
	v_add_f32_e32 v16, v16, v4
	v_rcp_f32_e32 v20, v20
	s_nop 0
	v_pk_mul_f32 v[20:21], v[20:21], v[26:27]
	v_lshlrev_b32_e32 v24, 16, v25
	v_and_b32_e32 v25, 0xffff0000, v25
	v_cvt_pk_bf16_f32 v20, v20, v21
	v_rcp_f32_e32 v23, v23
	v_add_f32_e32 v17, v17, v5
	v_mul_f32_e32 v16, 0xbfb8aa3b, v16
	v_mul_f32_e32 v17, 0xbfb8aa3b, v17
	v_rcp_f32_e32 v22, v22
	s_nop 0
	v_pk_mul_f32 v[22:23], v[22:23], v[24:25]
	v_exp_f32_e32 v16, v16
	v_cvt_pk_bf16_f32 v21, v22, v23
	v_mad_i64_i32 v[22:23], s[0:1], v28, s86, v[36:37]
	v_lshl_add_u64 v[22:23], v[22:23], 0, s[74:75]
	v_lshl_add_u64 v[24:25], v[22:23], 0, v[84:85]
	flat_store_dwordx2 v[24:25], v[20:21]
	ds_read_b64 v[20:21], v113 offset:32
	v_exp_f32_e32 v17, v17
	v_add_f32_e32 v18, v18, v6
	v_add_f32_e32 v19, v19, v7
	v_mul_f32_e32 v18, 0xbfb8aa3b, v18
	v_pk_add_f32 v[16:17], v[16:17], 1.0 op_sel_hi:[1,0]
	s_waitcnt lgkmcnt(0)
	v_lshlrev_b32_e32 v24, 16, v20
	v_and_b32_e32 v25, 0xffff0000, v20
	v_mul_f32_e32 v19, 0xbfb8aa3b, v19
	v_exp_f32_e32 v18, v18
	v_exp_f32_e32 v19, v19
	v_rcp_f32_e32 v17, v17
	v_pk_add_f32 v[18:19], v[18:19], 1.0 op_sel_hi:[1,0]
	v_add_f32_e32 v8, v8, v12
	v_add_f32_e32 v9, v9, v13
	v_rcp_f32_e32 v16, v16
	s_nop 0
	v_pk_mul_f32 v[16:17], v[16:17], v[24:25]
	v_lshlrev_b32_e32 v20, 16, v21
	v_and_b32_e32 v21, 0xffff0000, v21
	v_cvt_pk_bf16_f32 v16, v16, v17
	v_rcp_f32_e32 v19, v19
	v_mul_f32_e32 v8, 0xbfb8aa3b, v8
	v_mul_f32_e32 v9, 0xbfb8aa3b, v9
	v_exp_f32_e32 v8, v8
	v_rcp_f32_e32 v18, v18
	s_nop 0
	v_pk_mul_f32 v[18:19], v[18:19], v[20:21]
	v_exp_f32_e32 v9, v9
	v_cvt_pk_bf16_f32 v17, v18, v19
	v_lshl_add_u64 v[18:19], v[22:23], 0, v[86:87]
	flat_store_dwordx2 v[18:19], v[16:17]
	ds_read_b64 v[16:17], v114
	v_pk_add_f32 v[8:9], v[8:9], 1.0 op_sel_hi:[1,0]
	v_add_f32_e32 v10, v10, v14
	v_add_f32_e32 v11, v11, v15
	v_mul_f32_e32 v10, 0xbfb8aa3b, v10
	s_waitcnt lgkmcnt(0)
	v_lshlrev_b32_e32 v12, 16, v16
	v_and_b32_e32 v13, 0xffff0000, v16
	v_mul_f32_e32 v11, 0xbfb8aa3b, v11
	v_exp_f32_e32 v10, v10
	v_exp_f32_e32 v11, v11
	v_rcp_f32_e32 v9, v9
	v_pk_add_f32 v[10:11], v[10:11], 1.0 op_sel_hi:[1,0]
	v_or_b32_e32 v18, s40, v110
	v_rcp_f32_e32 v8, v8
	s_nop 0
	v_pk_mul_f32 v[8:9], v[8:9], v[12:13]
	v_lshlrev_b32_e32 v12, 16, v17
	v_and_b32_e32 v13, 0xffff0000, v17
	v_rcp_f32_e32 v11, v11
	v_cvt_pk_bf16_f32 v8, v8, v9
	v_add_f32_e32 v0, v0, v4
	v_add_f32_e32 v1, v1, v5
	v_rcp_f32_e32 v10, v10
	s_nop 0
	v_pk_mul_f32 v[10:11], v[10:11], v[12:13]
	v_mul_f32_e32 v0, 0xbfb8aa3b, v0
	v_cvt_pk_bf16_f32 v9, v10, v11
	v_mad_i64_i32 v[10:11], s[0:1], v18, s86, v[36:37]
	v_lshl_add_u64 v[10:11], v[10:11], 0, s[74:75]
	v_lshl_add_u64 v[12:13], v[10:11], 0, v[84:85]
	flat_store_dwordx2 v[12:13], v[8:9]
	v_mul_f32_e32 v1, 0xbfb8aa3b, v1
	ds_read_b64 v[8:9], v114 offset:32
	v_exp_f32_e32 v0, v0
	v_exp_f32_e32 v1, v1
	v_add_f32_e32 v2, v2, v6
	v_add_f32_e32 v3, v3, v7
	s_waitcnt lgkmcnt(0)
	v_lshlrev_b32_e32 v4, 16, v8
	v_pk_add_f32 v[0:1], v[0:1], 1.0 op_sel_hi:[1,0]
	v_and_b32_e32 v5, 0xffff0000, v8
	v_mul_f32_e32 v2, 0xbfb8aa3b, v2
	v_mul_f32_e32 v3, 0xbfb8aa3b, v3
	v_exp_f32_e32 v2, v2
	v_rcp_f32_e32 v1, v1
	v_exp_f32_e32 v3, v3
	s_nop 0
	v_pk_add_f32 v[2:3], v[2:3], 1.0 op_sel_hi:[1,0]
	v_rcp_f32_e32 v0, v0
	s_nop 0
	v_pk_mul_f32 v[0:1], v[0:1], v[4:5]
	v_lshlrev_b32_e32 v4, 16, v9
	v_and_b32_e32 v5, 0xffff0000, v9
	v_rcp_f32_e32 v3, v3
	v_cvt_pk_bf16_f32 v0, v0, v1
	v_rcp_f32_e32 v2, v2
	s_nop 0
	v_pk_mul_f32 v[2:3], v[2:3], v[4:5]
	s_nop 0
	v_cvt_pk_bf16_f32 v1, v2, v3
	v_lshl_add_u64 v[2:3], v[10:11], 0, v[86:87]
	flat_store_dwordx2 v[2:3], v[0:1]
	s_waitcnt lgkmcnt(0)
	s_barrier
	s_cbranch_scc1 .LBB0_443

.LBB0_439:
	ds_read2_b32 v[122:123], v83 offset1:68
	ds_read2_b32 v[124:125], v83 offset0:136 offset1:204
	v_mov_b32_e32 v130, v93
	v_pk_mul_f32 v[130:131], v[98:99], v[130:131] op_sel_hi:[1,0]
	v_add_u32_e32 v121, 0x400, v83
	v_pk_fma_f32 v[134:135], v[90:91], v[92:93], v[130:131] neg_lo:[0,0,1] neg_hi:[0,0,1]
	v_pk_fma_f32 v[92:93], v[90:91], v[92:93], v[130:131] op_sel_hi:[1,0,1]
	s_waitcnt lgkmcnt(1)
	v_lshlrev_b32_e32 v132, 16, v122
	v_and_b32_e32 v133, 0xffff0000, v122
	v_mov_b32_e32 v135, v93
	v_pk_add_f32 v[92:93], v[134:135], v[132:133]
	v_lshlrev_b32_e32 v122, 16, v123
	v_pk_mul_f32 v[130:131], v[96:97], v[92:93]
	v_cvt_pk_bf16_f32 v134, v92, v93
	v_pk_fma_f32 v[132:133], v[94:95], v[92:93], v[130:131] op_sel:[0,0,1] op_sel_hi:[1,1,0] neg_lo:[0,0,1] neg_hi:[0,0,1]
	v_pk_fma_f32 v[92:93], v[94:95], v[92:93], v[130:131] op_sel:[0,0,1] op_sel_hi:[1,1,0]
	v_and_b32_e32 v123, 0xffff0000, v123
	v_mov_b32_e32 v133, v93
	v_pk_add_f32 v[92:93], v[132:133], v[122:123]
	ds_read2_b32 v[126:127], v121 offset0:16 offset1:84
	ds_read2_b32 v[128:129], v121 offset0:152 offset1:220
	v_pk_mul_f32 v[130:131], v[96:97], v[92:93]
	v_cvt_pk_bf16_f32 v122, v92, v93
	v_pk_fma_f32 v[132:133], v[94:95], v[92:93], v[130:131] op_sel:[0,0,1] op_sel_hi:[1,1,0] neg_lo:[0,0,1] neg_hi:[0,0,1]
	v_pk_fma_f32 v[92:93], v[94:95], v[92:93], v[130:131] op_sel:[0,0,1] op_sel_hi:[1,1,0]
	ds_write2_b32 v83, v134, v122 offset1:68
	s_waitcnt lgkmcnt(3)
	v_lshlrev_b32_e32 v122, 16, v124
	v_and_b32_e32 v123, 0xffff0000, v124
	v_mov_b32_e32 v133, v93
	v_pk_add_f32 v[92:93], v[132:133], v[122:123]
	v_lshlrev_b32_e32 v122, 16, v125
	v_and_b32_e32 v123, 0xffff0000, v125
	v_pk_mul_f32 v[124:125], v[96:97], v[92:93]
	v_cvt_pk_bf16_f32 v132, v92, v93
	v_pk_fma_f32 v[130:131], v[94:95], v[92:93], v[124:125] op_sel:[0,0,1] op_sel_hi:[1,1,0] neg_lo:[0,0,1] neg_hi:[0,0,1]
	v_pk_fma_f32 v[92:93], v[94:95], v[92:93], v[124:125] op_sel:[0,0,1] op_sel_hi:[1,1,0]
	s_add_i32 s2, s2, 8
	v_mov_b32_e32 v131, v93
	v_pk_add_f32 v[92:93], v[130:131], v[122:123]
	s_waitcnt lgkmcnt(2)
	v_and_b32_e32 v123, 0xffff0000, v126
	v_pk_mul_f32 v[124:125], v[98:99], v[92:93] op_sel:[0,1]
	v_cvt_pk_bf16_f32 v122, v92, v93
	v_pk_fma_f32 v[130:131], v[90:91], v[92:93], v[124:125] neg_lo:[0,0,1] neg_hi:[0,0,1]
	v_pk_fma_f32 v[92:93], v[90:91], v[92:93], v[124:125] op_sel_hi:[1,0,1]
	ds_write2_b32 v83, v132, v122 offset0:136 offset1:204
	v_lshlrev_b32_e32 v122, 16, v126
	v_mov_b32_e32 v131, v93
	v_pk_add_f32 v[92:93], v[130:131], v[122:123]
	v_lshlrev_b32_e32 v124, 16, v127
	v_pk_mul_f32 v[122:123], v[90:91], v[92:93]
	v_pk_mul_f32 v[130:131], v[90:91], v[92:93] op_sel:[0,1] op_sel_hi:[1,0]
	v_mov_b32_e32 v122, v123
	v_mov_b32_e32 v123, v131
	v_cvt_pk_bf16_f32 v126, v92, v93
	v_pk_fma_f32 v[122:123], v[90:91], v[92:93], v[122:123] neg_lo:[0,0,1] neg_hi:[0,0,1]
	v_pk_fma_f32 v[92:93], v[90:91], v[92:93], v[130:131] op_sel:[0,1,0] op_sel_hi:[1,0,0]
	v_and_b32_e32 v125, 0xffff0000, v127
	v_mov_b32_e32 v123, v93
	v_pk_add_f32 v[92:93], v[122:123], v[124:125]
	s_waitcnt lgkmcnt(2)
	v_and_b32_e32 v123, 0xffff0000, v128
	v_cvt_pk_bf16_f32 v122, v92, v93
	v_pk_mul_f32 v[124:125], v[98:99], v[92:93] op_sel:[0,1]
	ds_write2_b32 v121, v126, v122 offset0:16 offset1:84
	v_pk_fma_f32 v[126:127], v[90:91], v[92:93], v[124:125] neg_lo:[0,0,1] neg_hi:[0,0,1]
	v_pk_fma_f32 v[92:93], v[90:91], v[92:93], v[124:125] op_sel_hi:[1,0,1]
	v_lshlrev_b32_e32 v122, 16, v128
	v_mov_b32_e32 v127, v93
	v_pk_add_f32 v[92:93], v[126:127], v[122:123]
	v_lshlrev_b32_e32 v124, 16, v129
	v_pk_mul_f32 v[122:123], v[90:91], v[92:93]
	v_pk_mul_f32 v[126:127], v[90:91], v[92:93] op_sel:[0,1] op_sel_hi:[1,0]
	v_mov_b32_e32 v122, v123
	v_mov_b32_e32 v123, v127
	v_cvt_pk_bf16_f32 v128, v92, v93
	v_pk_fma_f32 v[122:123], v[90:91], v[92:93], v[122:123] neg_lo:[0,0,1] neg_hi:[0,0,1]
	v_pk_fma_f32 v[92:93], v[90:91], v[92:93], v[126:127] op_sel:[0,1,0] op_sel_hi:[1,0,0]
	v_and_b32_e32 v125, 0xffff0000, v129
	v_mov_b32_e32 v123, v93
	v_pk_add_f32 v[92:93], v[122:123], v[124:125]
	v_add_u32_e32 v83, 0x880, v83
	v_cvt_pk_bf16_f32 v122, v92, v93
	s_cmp_lt_u32 s2, 24
	ds_write2_b32 v121, v128, v122 offset0:152 offset1:220
	s_cbranch_scc1 .LBB0_439
	s_waitcnt lgkmcnt(0)
	ds_read_b128 v[122:125], v117 offset:32768
	ds_read_b128 v[126:129], v117 offset:32832
	v_or_b32_e32 v83, s14, v78
	v_mad_u32_u24 v83, v83, s15, v120
	s_mov_b32 s14, 32
	s_waitcnt lgkmcnt(1)
	v_mfma_f32_16x16x32_bf16 v[122:125], v[52:55], v[122:125], v[0:3]
	s_mov_b64 s[4:5], 0
	s_waitcnt lgkmcnt(0)
	v_mfma_f32_16x16x32_bf16 v[122:125], v[48:51], v[126:129], v[122:125]
	ds_read_b128 v[126:129], v117 offset:32896
	s_waitcnt lgkmcnt(0)
	v_mfma_f32_16x16x32_bf16 v[122:125], v[44:47], v[126:129], v[122:125]
	ds_read_b128 v[126:129], v117 offset:32960
	s_waitcnt lgkmcnt(0)
	v_mfma_f32_16x16x32_bf16 v[122:125], v[40:43], v[126:129], v[122:125]
	v_lshlrev_b32_e32 v126, 16, v102
	v_and_b32_e32 v127, 0xffff0000, v102
	s_nop 5
	v_pk_fma_f32 v[122:123], v[4:5], v[126:127], v[122:123]
	s_nop 0
	v_mul_f32_e32 v102, 0x3d372713, v122
	v_mul_f32_e32 v102, v122, v102
	v_fma_f32 v102, v122, v102, v122
	v_mul_f32_e32 v102, 0x3f4c422a, v102
	v_add_f32_e32 v102, v102, v102
	v_mul_f32_e32 v102, 0xbfb8aa3b, v102
	v_exp_f32_e32 v126, v102
	v_mul_f32_e32 v102, 0x3d372713, v123
	v_mul_f32_e32 v102, v123, v102
	v_fma_f32 v102, v123, v102, v123
	v_mul_f32_e32 v102, 0x3f4c422a, v102
	v_add_f32_e32 v102, v102, v102
	v_mul_f32_e32 v102, 0xbfb8aa3b, v102
	v_exp_f32_e32 v127, v102
	s_nop 0
	v_pk_add_f32 v[126:127], v[126:127], 1.0 op_sel_hi:[1,0]
	s_nop 0
	v_rcp_f32_e32 v127, v127
	v_rcp_f32_e32 v126, v126
	v_lshlrev_b32_e32 v102, 16, v103
	v_and_b32_e32 v103, 0xffff0000, v103
	v_pk_fma_f32 v[102:103], v[6:7], v[102:103], v[124:125]
	v_pk_mul_f32 v[122:123], v[122:123], v[126:127]
	v_mul_f32_e32 v121, 0x3d372713, v102
	v_mul_f32_e32 v121, v102, v121
	v_fma_f32 v121, v102, v121, v102
	v_mul_f32_e32 v121, 0x3f4c422a, v121
	v_add_f32_e32 v121, v121, v121
	v_mul_f32_e32 v121, 0xbfb8aa3b, v121
	v_exp_f32_e32 v124, v121
	v_mul_f32_e32 v121, 0x3d372713, v103
	v_mul_f32_e32 v121, v103, v121
	v_fma_f32 v121, v103, v121, v103
	v_mul_f32_e32 v121, 0x3f4c422a, v121
	v_add_f32_e32 v121, v121, v121
	v_mul_f32_e32 v121, 0xbfb8aa3b, v121
	v_exp_f32_e32 v125, v121
	v_cvt_pk_bf16_f32 v122, v122, v123
	v_pk_add_f32 v[124:125], v[124:125], 1.0 op_sel_hi:[1,0]
	s_nop 0
	v_rcp_f32_e32 v125, v125
	v_rcp_f32_e32 v124, v124
	s_nop 0
	v_pk_mul_f32 v[102:103], v[102:103], v[124:125]
	s_nop 0
	v_cvt_pk_bf16_f32 v123, v102, v103
	ds_write_b64 v83, v[122:123]
	ds_read_b128 v[122:125], v117 offset:37120
	ds_read_b128 v[126:129], v117 offset:37184
	s_waitcnt lgkmcnt(1)
	v_mfma_f32_16x16x32_bf16 v[122:125], v[52:55], v[122:125], v[0:3]
	v_lshlrev_b32_e32 v102, 16, v100
	v_and_b32_e32 v103, 0xffff0000, v100
	s_waitcnt lgkmcnt(0)
	v_mfma_f32_16x16x32_bf16 v[122:125], v[48:51], v[126:129], v[122:125]
	ds_read_b128 v[126:129], v117 offset:37248
	s_waitcnt lgkmcnt(0)
	v_mfma_f32_16x16x32_bf16 v[122:125], v[44:47], v[126:129], v[122:125]
	ds_read_b128 v[126:129], v117 offset:37312
	s_waitcnt lgkmcnt(0)
	v_mfma_f32_16x16x32_bf16 v[122:125], v[40:43], v[126:129], v[122:125]
	s_nop 7
	v_pk_fma_f32 v[102:103], v[4:5], v[102:103], v[122:123]
	s_nop 0
	v_mul_f32_e32 v100, 0x3d372713, v102
	v_mul_f32_e32 v100, v102, v100
	v_fma_f32 v100, v102, v100, v102
	v_mul_f32_e32 v100, 0x3f4c422a, v100
	v_add_f32_e32 v100, v100, v100
	v_mul_f32_e32 v100, 0xbfb8aa3b, v100
	v_exp_f32_e32 v122, v100
	v_mul_f32_e32 v100, 0x3d372713, v103
	v_mul_f32_e32 v100, v103, v100
	v_fma_f32 v100, v103, v100, v103
	v_mul_f32_e32 v100, 0x3f4c422a, v100
	v_add_f32_e32 v100, v100, v100
	v_mul_f32_e32 v100, 0xbfb8aa3b, v100
	v_exp_f32_e32 v123, v100
	s_nop 0
	v_pk_add_f32 v[122:123], v[122:123], 1.0 op_sel_hi:[1,0]
	s_nop 0
	v_rcp_f32_e32 v123, v123
	v_rcp_f32_e32 v122, v122
	v_lshlrev_b32_e32 v100, 16, v101
	v_and_b32_e32 v101, 0xffff0000, v101
	v_pk_fma_f32 v[100:101], v[6:7], v[100:101], v[124:125]
	v_pk_mul_f32 v[102:103], v[102:103], v[122:123]
	v_mul_f32_e32 v121, 0x3d372713, v100
	v_mul_f32_e32 v121, v100, v121
	v_fma_f32 v121, v100, v121, v100
	v_mul_f32_e32 v121, 0x3f4c422a, v121
	v_add_f32_e32 v121, v121, v121
	v_mul_f32_e32 v121, 0xbfb8aa3b, v121
	v_exp_f32_e32 v122, v121
	v_mul_f32_e32 v121, 0x3d372713, v101
	v_mul_f32_e32 v121, v101, v121
	v_fma_f32 v121, v101, v121, v101
	v_mul_f32_e32 v121, 0x3f4c422a, v121
	v_add_f32_e32 v121, v121, v121
	v_mul_f32_e32 v121, 0xbfb8aa3b, v121
	v_exp_f32_e32 v123, v121
	v_cvt_pk_bf16_f32 v102, v102, v103
	v_pk_add_f32 v[122:123], v[122:123], 1.0 op_sel_hi:[1,0]
	s_nop 0
	v_rcp_f32_e32 v123, v123
	v_rcp_f32_e32 v122, v122
	s_nop 0
	v_pk_mul_f32 v[100:101], v[100:101], v[122:123]
	s_and_b64 vcc, exec, s[12:13]
	v_cvt_pk_bf16_f32 v103, v100, v101
	ds_write_b64 v83, v[102:103] offset:8448
	s_nop 7
	s_cbranch_vccz .LBB0_438
	s_and_b64 vcc, exec, s[24:25]
	s_cbranch_vccz .LBB0_432
	s_ashr_i32 s29, s28, 31
	s_lshl_b64 s[2:3], s[28:29], 8
	v_lshl_add_u64 v[4:5], v[88:89], 0, s[2:3]
	v_add_co_u32_e32 v6, vcc, 0x645c000, v4
	s_nop 1
	v_addc_co_u32_e32 v7, vcc, 0, v5, vcc
	v_add_co_u32_e32 v4, vcc, 0x667c000, v4
	global_store_dword v[6:7], v92, off
	s_nop 0
	v_addc_co_u32_e32 v5, vcc, 0, v5, vcc
	global_store_dword v[4:5], v93, off
	s_branch .LBB0_432

.LBB0_445:
	s_waitcnt vmcnt(0)
	v_add_f32_e32 v4, v28, v4
	v_add_f32_e32 v5, v29, v5
	v_add_u32_e32 v10, v121, v32
	v_mul_f32_e32 v4, 0xbfb8aa3b, v4
	v_mul_f32_e32 v5, 0xbfb8aa3b, v5
	ds_read_b64 v[10:11], v10
	v_exp_f32_e32 v4, v4
	v_exp_f32_e32 v5, v5
	v_add_f32_e32 v6, v30, v6
	v_add_f32_e32 v7, v31, v7
	s_waitcnt lgkmcnt(0)
	v_lshlrev_b32_e32 v12, 16, v10
	v_pk_add_f32 v[4:5], v[4:5], 1.0 op_sel_hi:[1,0]
	v_and_b32_e32 v13, 0xffff0000, v10
	v_mul_f32_e32 v6, 0xbfb8aa3b, v6
	v_mul_f32_e32 v7, 0xbfb8aa3b, v7
	v_exp_f32_e32 v6, v6
	v_rcp_f32_e32 v5, v5
	v_exp_f32_e32 v7, v7
	v_or_b32_e32 v8, s18, v33
	v_mul_i32_i24_e32 v8, 0x1400, v8
	v_rcp_f32_e32 v4, v4
	v_pk_add_f32 v[6:7], v[6:7], 1.0 op_sel_hi:[1,0]
	v_pk_mul_f32 v[4:5], v[4:5], v[12:13]
	v_lshlrev_b32_e32 v10, 16, v11
	v_and_b32_e32 v11, 0xffff0000, v11
	v_mov_b32_e32 v9, v195
	v_rcp_f32_e32 v7, v7
	v_cvt_pk_bf16_f32 v4, v4, v5
	v_add_f32_e32 v0, v20, v0
	v_add_f32_e32 v1, v21, v1
	v_rcp_f32_e32 v6, v6
	s_nop 0
	v_pk_mul_f32 v[6:7], v[6:7], v[10:11]
	v_mul_f32_e32 v0, 0xbfb8aa3b, v0
	v_cvt_pk_bf16_f32 v5, v6, v7
	v_lshl_add_u64 v[6:7], s[26:27], 0, v[8:9]
	v_lshl_add_u64 v[6:7], v[6:7], 0, s[74:75]
	v_lshl_add_u64 v[8:9], v[92:93], 1, v[6:7]
	flat_store_dwordx2 v[8:9], v[4:5]
	v_add_u32_e32 v4, v127, v32
	v_mul_f32_e32 v1, 0xbfb8aa3b, v1
	ds_read_b64 v[4:5], v4
	v_exp_f32_e32 v0, v0
	v_exp_f32_e32 v1, v1
	v_add_f32_e32 v2, v22, v2
	v_add_f32_e32 v3, v23, v3
	s_waitcnt lgkmcnt(0)
	v_lshlrev_b32_e32 v8, 16, v4
	v_pk_add_f32 v[0:1], v[0:1], 1.0 op_sel_hi:[1,0]
	v_and_b32_e32 v9, 0xffff0000, v4
	v_mul_f32_e32 v2, 0xbfb8aa3b, v2
	v_mul_f32_e32 v3, 0xbfb8aa3b, v3
	v_exp_f32_e32 v2, v2
	v_rcp_f32_e32 v1, v1
	v_exp_f32_e32 v3, v3
	s_add_i32 s17, s17, s81
	s_cmp_gt_u32 s17, 3
	v_rcp_f32_e32 v0, v0
	v_pk_add_f32 v[2:3], v[2:3], 1.0 op_sel_hi:[1,0]
	v_pk_mul_f32 v[0:1], v[0:1], v[8:9]
	v_lshlrev_b32_e32 v4, 16, v5
	v_and_b32_e32 v5, 0xffff0000, v5
	v_cvt_pk_bf16_f32 v0, v0, v1
	v_rcp_f32_e32 v3, v3
	s_movk_i32 s11, 0x210
	v_rcp_f32_e32 v2, v2
	s_nop 0
	v_pk_mul_f32 v[2:3], v[2:3], v[4:5]
	s_nop 0
	v_cvt_pk_bf16_f32 v1, v2, v3
	v_lshl_add_u64 v[2:3], v[94:95], 1, v[6:7]
	flat_store_dwordx2 v[2:3], v[0:1]
	s_waitcnt lgkmcnt(0)
	s_barrier
	s_cbranch_scc1 .LBB0_454

.LBB0_448:
	s_or_b32 s3, s2, s20
	s_lshl_b32 s42, s3, 10
	v_lshl_add_u64 v[42:43], v[106:107], 0, s[42:43]
	v_lshlrev_b64 v[42:43], 2, v[42:43]
	v_lshl_add_u64 v[46:47], s[50:51], 0, v[42:43]
	v_lshl_add_u64 v[44:45], s[48:49], 0, v[42:43]
	global_load_dword v138, v[46:47], off
	global_load_dword v136, v[44:45], off
	v_add_co_u32_e32 v48, vcc, 0x1000, v44
	s_mulk_i32 s2, 0x110
	s_nop 0
	v_addc_co_u32_e32 v49, vcc, 0, v45, vcc
	global_load_dword v130, v[48:49], off
	v_add_co_u32_e32 v48, vcc, 0x1000, v46
	v_lshl_add_u64 v[42:43], s[94:95], 0, v[42:43]
	s_nop 0
	v_addc_co_u32_e32 v49, vcc, 0, v47, vcc
	global_load_dword v134, v[48:49], off
	v_add_co_u32_e32 v48, vcc, s22, v44
	s_mov_b32 s3, 0x647d000
	s_nop 0
	v_addc_co_u32_e32 v49, vcc, 0, v45, vcc
	v_add_co_u32_e32 v50, vcc, s22, v46
	global_load_dword v128, v[48:49], off offset:-4096
	s_nop 0
	v_addc_co_u32_e32 v51, vcc, 0, v47, vcc
	global_load_dword v132, v[50:51], off offset:-4096
	global_load_dword v124, v[48:49], off
	global_load_dword v126, v[50:51], off
	v_add_co_u32_e32 v48, vcc, s84, v44
	s_waitcnt vmcnt(7)
	v_pk_mul_f32 v[138:139], v[40:41], v[138:139] op_sel_hi:[1,0]
	v_addc_co_u32_e32 v49, vcc, 0, v45, vcc
	v_add_co_u32_e32 v50, vcc, s84, v46
	global_load_dword v120, v[48:49], off offset:-4096
	s_nop 0
	v_addc_co_u32_e32 v51, vcc, 0, v47, vcc
	global_load_dword v122, v[50:51], off offset:-4096
	global_load_dword v116, v[48:49], off
	global_load_dword v118, v[50:51], off
	v_add_co_u32_e32 v48, vcc, s23, v44
	s_waitcnt vmcnt(10)
	v_pk_fma_f32 v[144:145], v[102:103], v[136:137], v[138:139] neg_lo:[0,0,1] neg_hi:[0,0,1]
	v_addc_co_u32_e32 v49, vcc, 0, v45, vcc
	v_add_co_u32_e32 v50, vcc, s23, v46
	global_load_dword v112, v[48:49], off offset:-4096
	s_nop 0
	v_addc_co_u32_e32 v51, vcc, 0, v47, vcc
	global_load_dword v114, v[50:51], off offset:-4096
	global_load_dword v108, v[48:49], off
	global_load_dword v110, v[50:51], off
	v_add_co_u32_e32 v48, vcc, s33, v44
	v_pk_fma_f32 v[138:139], v[102:103], v[136:137], v[138:139] op_sel_hi:[1,0,1]
	s_nop 0
	v_addc_co_u32_e32 v49, vcc, 0, v45, vcc
	v_add_co_u32_e32 v50, vcc, s33, v46
	global_load_dword v72, v[48:49], off offset:-4096
	s_nop 0
	v_addc_co_u32_e32 v51, vcc, 0, v47, vcc
	global_load_dword v74, v[50:51], off offset:-4096
	global_load_dword v68, v[48:49], off
	global_load_dword v70, v[50:51], off
	v_add_co_u32_e32 v48, vcc, s87, v44
	v_mov_b32_e32 v145, v139
	s_nop 0
	v_addc_co_u32_e32 v49, vcc, 0, v45, vcc
	v_add_co_u32_e32 v50, vcc, s87, v46
	global_load_dword v64, v[48:49], off offset:-4096
	s_nop 0
	v_addc_co_u32_e32 v51, vcc, 0, v47, vcc
	global_load_dword v66, v[50:51], off offset:-4096
	global_load_dword v60, v[48:49], off
	global_load_dword v62, v[50:51], off
	v_add_co_u32_e32 v48, vcc, s85, v44
	s_waitcnt vmcnt(6)
	v_pk_mul_f32 v[74:75], v[40:41], v[74:75] op_sel_hi:[1,0]
	v_addc_co_u32_e32 v49, vcc, 0, v45, vcc
	v_add_co_u32_e32 v50, vcc, s85, v46
	global_load_dword v56, v[48:49], off offset:-4096
	s_nop 0
	v_addc_co_u32_e32 v51, vcc, 0, v47, vcc
	v_add_co_u32_e32 v44, vcc, s88, v44
	global_load_dword v58, v[50:51], off offset:-4096
	global_load_dword v52, v[48:49], off
	global_load_dword v54, v[50:51], off
	v_addc_co_u32_e32 v45, vcc, 0, v45, vcc
	v_add_co_u32_e32 v46, vcc, s88, v46
	global_load_dword v48, v[44:45], off offset:-4096
	s_nop 0
	v_addc_co_u32_e32 v47, vcc, 0, v47, vcc
	global_load_dword v50, v[46:47], off offset:-4096
	s_nop 0
	global_load_dword v44, v[44:45], off
	s_nop 0
	global_load_dword v46, v[46:47], off
	v_add_u32_e32 v45, s2, v115
	v_add_u32_e32 v47, 0x8000, v45
	ds_read2_b32 v[140:141], v47 offset1:68
	s_waitcnt vmcnt(12)
	v_pk_mul_f32 v[70:71], v[40:41], v[70:71] op_sel_hi:[1,0]
	s_waitcnt vmcnt(10)
	v_pk_mul_f32 v[66:67], v[40:41], v[66:67] op_sel_hi:[1,0]
	s_waitcnt vmcnt(8)
	v_pk_mul_f32 v[62:63], v[40:41], v[62:63] op_sel_hi:[1,0]
	s_mov_b32 s2, 16
	s_waitcnt lgkmcnt(0)
	v_lshlrev_b32_e32 v142, 16, v140
	v_and_b32_e32 v143, 0xffff0000, v140
	v_pk_add_f32 v[138:139], v[144:145], v[142:143]
	v_add_co_u32_e32 v142, vcc, s3, v42
	s_mov_b32 s3, 0x669d000
	s_nop 0
	v_addc_co_u32_e32 v143, vcc, 0, v43, vcc
	v_add_co_u32_e32 v144, vcc, s3, v42
	v_cvt_pk_bf16_f32 v49, v138, v139
	s_nop 0
	v_addc_co_u32_e32 v145, vcc, 0, v43, vcc
	global_store_dword v[142:143], v138, off offset:-4096
	global_store_dword v[144:145], v139, off offset:-4096
	v_lshlrev_b32_e32 v138, 16, v141
	v_and_b32_e32 v139, 0xffff0000, v141
	v_pk_mul_f32 v[140:141], v[40:41], v[134:135] op_sel_hi:[1,0]
	s_mov_b32 s3, 0x647f000
	v_pk_fma_f32 v[146:147], v[102:103], v[130:131], v[140:141] neg_lo:[0,0,1] neg_hi:[0,0,1]
	v_pk_fma_f32 v[140:141], v[102:103], v[130:131], v[140:141] op_sel_hi:[1,0,1]
	s_waitcnt vmcnt(8)
	v_pk_mul_f32 v[58:59], v[40:41], v[58:59] op_sel_hi:[1,0]
	v_mov_b32_e32 v147, v141
	v_pk_add_f32 v[138:139], v[146:147], v[138:139]
	s_waitcnt vmcnt(6)
	v_pk_mul_f32 v[54:55], v[40:41], v[54:55] op_sel_hi:[1,0]
	v_cvt_pk_bf16_f32 v51, v138, v139
	ds_write2_b32 v47, v49, v51 offset1:68
	global_store_dword v[142:143], v138, off
	global_store_dword v[144:145], v139, off
	ds_read2_b32 v[138:139], v47 offset0:136 offset1:204
	v_pk_mul_f32 v[142:143], v[40:41], v[132:133] op_sel_hi:[1,0]
	s_waitcnt lgkmcnt(0)
	v_lshlrev_b32_e32 v140, 16, v138
	v_pk_fma_f32 v[144:145], v[102:103], v[128:129], v[142:143] neg_lo:[0,0,1] neg_hi:[0,0,1]
	v_pk_fma_f32 v[142:143], v[102:103], v[128:129], v[142:143] op_sel_hi:[1,0,1]
	v_and_b32_e32 v141, 0xffff0000, v138
	v_add_co_u32_e32 v142, vcc, s3, v42
	v_mov_b32_e32 v145, v143
	s_nop 0
	v_addc_co_u32_e32 v143, vcc, 0, v43, vcc
	s_mov_b32 s3, 0x669f000
	v_pk_add_f32 v[140:141], v[144:145], v[140:141]
	v_add_co_u32_e32 v144, vcc, s3, v42
	v_cvt_pk_bf16_f32 v49, v140, v141
	s_nop 0
	v_addc_co_u32_e32 v145, vcc, 0, v43, vcc
	global_store_dword v[142:143], v140, off offset:-4096
	global_store_dword v[144:145], v141, off offset:-4096
	v_pk_mul_f32 v[140:141], v[40:41], v[126:127] op_sel_hi:[1,0]
	v_lshlrev_b32_e32 v138, 16, v139
	v_pk_fma_f32 v[146:147], v[102:103], v[124:125], v[140:141] neg_lo:[0,0,1] neg_hi:[0,0,1]
	v_pk_fma_f32 v[140:141], v[102:103], v[124:125], v[140:141] op_sel_hi:[1,0,1]
	v_and_b32_e32 v139, 0xffff0000, v139
	v_mov_b32_e32 v147, v141
	v_pk_add_f32 v[138:139], v[146:147], v[138:139]
	s_mov_b32 s3, 0x6481000
	v_cvt_pk_bf16_f32 v51, v138, v139
	ds_write2_b32 v47, v49, v51 offset0:136 offset1:204
	global_store_dword v[142:143], v138, off
	global_store_dword v[144:145], v139, off
	v_add_u32_e32 v47, 0x8400, v45
	ds_read2_b32 v[138:139], v47 offset0:16 offset1:84
	v_pk_mul_f32 v[142:143], v[40:41], v[122:123] op_sel_hi:[1,0]
	s_waitcnt lgkmcnt(0)
	v_lshlrev_b32_e32 v140, 16, v138
	v_pk_fma_f32 v[144:145], v[102:103], v[120:121], v[142:143] neg_lo:[0,0,1] neg_hi:[0,0,1]
	v_pk_fma_f32 v[142:143], v[102:103], v[120:121], v[142:143] op_sel_hi:[1,0,1]
	v_and_b32_e32 v141, 0xffff0000, v138
	v_add_co_u32_e32 v142, vcc, s3, v42
	v_mov_b32_e32 v145, v143
	s_nop 0
	v_addc_co_u32_e32 v143, vcc, 0, v43, vcc
	s_mov_b32 s3, 0x66a1000
	v_pk_add_f32 v[140:141], v[144:145], v[140:141]
	v_add_co_u32_e32 v144, vcc, s3, v42
	v_cvt_pk_bf16_f32 v49, v140, v141
	s_nop 0
	v_addc_co_u32_e32 v145, vcc, 0, v43, vcc
	global_store_dword v[142:143], v140, off offset:-4096
	global_store_dword v[144:145], v141, off offset:-4096
	v_pk_mul_f32 v[140:141], v[40:41], v[118:119] op_sel_hi:[1,0]
	v_lshlrev_b32_e32 v138, 16, v139
	v_pk_fma_f32 v[146:147], v[102:103], v[116:117], v[140:141] neg_lo:[0,0,1] neg_hi:[0,0,1]
	v_pk_fma_f32 v[140:141], v[102:103], v[116:117], v[140:141] op_sel_hi:[1,0,1]
	v_and_b32_e32 v139, 0xffff0000, v139
	v_mov_b32_e32 v147, v141
	v_pk_add_f32 v[138:139], v[146:147], v[138:139]
	s_mov_b32 s3, 0x6483000
	v_cvt_pk_bf16_f32 v51, v138, v139
	ds_write2_b32 v47, v49, v51 offset0:16 offset1:84
	global_store_dword v[142:143], v138, off
	global_store_dword v[144:145], v139, off
	ds_read2_b32 v[138:139], v47 offset0:152 offset1:220
	v_pk_mul_f32 v[142:143], v[40:41], v[114:115] op_sel_hi:[1,0]
	s_waitcnt lgkmcnt(0)
	v_lshlrev_b32_e32 v140, 16, v138
	v_pk_fma_f32 v[144:145], v[102:103], v[112:113], v[142:143] neg_lo:[0,0,1] neg_hi:[0,0,1]
	v_pk_fma_f32 v[142:143], v[102:103], v[112:113], v[142:143] op_sel_hi:[1,0,1]
	v_and_b32_e32 v141, 0xffff0000, v138
	v_add_co_u32_e32 v142, vcc, s3, v42
	v_mov_b32_e32 v145, v143
	s_nop 0
	v_addc_co_u32_e32 v143, vcc, 0, v43, vcc
	s_mov_b32 s3, 0x66a3000
	v_pk_add_f32 v[140:141], v[144:145], v[140:141]
	v_add_co_u32_e32 v144, vcc, s3, v42
	v_cvt_pk_bf16_f32 v49, v140, v141
	s_nop 0
	v_addc_co_u32_e32 v145, vcc, 0, v43, vcc
	global_store_dword v[142:143], v140, off offset:-4096
	global_store_dword v[144:145], v141, off offset:-4096
	v_pk_mul_f32 v[140:141], v[40:41], v[110:111] op_sel_hi:[1,0]
	v_lshlrev_b32_e32 v138, 16, v139
	v_pk_fma_f32 v[146:147], v[102:103], v[108:109], v[140:141] neg_lo:[0,0,1] neg_hi:[0,0,1]
	v_pk_fma_f32 v[140:141], v[102:103], v[108:109], v[140:141] op_sel_hi:[1,0,1]
	v_and_b32_e32 v139, 0xffff0000, v139
	v_mov_b32_e32 v147, v141
	v_pk_add_f32 v[138:139], v[146:147], v[138:139]
	s_mov_b32 s3, 0x6485000
	v_cvt_pk_bf16_f32 v51, v138, v139
	ds_write2_b32 v47, v49, v51 offset0:152 offset1:220
	global_store_dword v[142:143], v138, off
	global_store_dword v[144:145], v139, off
	v_add_u32_e32 v47, 0x8800, v45
	ds_read2_b32 v[138:139], v47 offset0:32 offset1:100
	v_pk_fma_f32 v[142:143], v[102:103], v[72:73], v[74:75] neg_lo:[0,0,1] neg_hi:[0,0,1]
	v_pk_fma_f32 v[72:73], v[102:103], v[72:73], v[74:75] op_sel_hi:[1,0,1]
	v_add_co_u32_e32 v74, vcc, s3, v42
	s_waitcnt lgkmcnt(0)
	v_lshlrev_b32_e32 v140, 16, v138
	v_and_b32_e32 v141, 0xffff0000, v138
	v_mov_b32_e32 v143, v73
	v_addc_co_u32_e32 v75, vcc, 0, v43, vcc
	s_mov_b32 s3, 0x66a5000
	v_pk_add_f32 v[72:73], v[142:143], v[140:141]
	v_add_co_u32_e32 v140, vcc, s3, v42
	v_cvt_pk_bf16_f32 v49, v72, v73
	s_nop 0
	v_addc_co_u32_e32 v141, vcc, 0, v43, vcc
	global_store_dword v[74:75], v72, off offset:-4096
	global_store_dword v[140:141], v73, off offset:-4096
	v_lshlrev_b32_e32 v72, 16, v139
	v_and_b32_e32 v73, 0xffff0000, v139
	v_pk_fma_f32 v[138:139], v[102:103], v[68:69], v[70:71] neg_lo:[0,0,1] neg_hi:[0,0,1]
	v_pk_fma_f32 v[68:69], v[102:103], v[68:69], v[70:71] op_sel_hi:[1,0,1]
	s_mov_b32 s3, 0x6487000
	v_mov_b32_e32 v139, v69
	v_pk_add_f32 v[68:69], v[138:139], v[72:73]
	v_pk_fma_f32 v[72:73], v[102:103], v[64:65], v[66:67] neg_lo:[0,0,1] neg_hi:[0,0,1]
	v_cvt_pk_bf16_f32 v51, v68, v69
	ds_write2_b32 v47, v49, v51 offset0:32 offset1:100
	global_store_dword v[74:75], v68, off
	global_store_dword v[140:141], v69, off
	ds_read2_b32 v[68:69], v47 offset0:168 offset1:236
	v_pk_fma_f32 v[64:65], v[102:103], v[64:65], v[66:67] op_sel_hi:[1,0,1]
	v_add_co_u32_e32 v66, vcc, s3, v42
	v_mov_b32_e32 v73, v65
	s_waitcnt lgkmcnt(0)
	v_lshlrev_b32_e32 v70, 16, v68
	v_and_b32_e32 v71, 0xffff0000, v68
	v_addc_co_u32_e32 v67, vcc, 0, v43, vcc
	s_mov_b32 s3, 0x66a7000
	v_pk_add_f32 v[64:65], v[72:73], v[70:71]
	v_add_co_u32_e32 v70, vcc, s3, v42
	v_cvt_pk_bf16_f32 v49, v64, v65
	s_nop 0
	v_addc_co_u32_e32 v71, vcc, 0, v43, vcc
	global_store_dword v[66:67], v64, off offset:-4096
	global_store_dword v[70:71], v65, off offset:-4096
	v_lshlrev_b32_e32 v64, 16, v69
	v_and_b32_e32 v65, 0xffff0000, v69
	v_pk_fma_f32 v[68:69], v[102:103], v[60:61], v[62:63] neg_lo:[0,0,1] neg_hi:[0,0,1]
	v_pk_fma_f32 v[60:61], v[102:103], v[60:61], v[62:63] op_sel_hi:[1,0,1]
	s_mov_b32 s3, 0x6489000
	v_mov_b32_e32 v69, v61
	v_pk_add_f32 v[60:61], v[68:69], v[64:65]
	v_pk_fma_f32 v[64:65], v[102:103], v[56:57], v[58:59] neg_lo:[0,0,1] neg_hi:[0,0,1]
	v_cvt_pk_bf16_f32 v51, v60, v61
	ds_write2_b32 v47, v49, v51 offset0:168 offset1:236
	global_store_dword v[66:67], v60, off
	global_store_dword v[70:71], v61, off
	v_add_u32_e32 v66, 0x8c00, v45
	ds_read2_b32 v[60:61], v66 offset0:48 offset1:116
	v_pk_fma_f32 v[56:57], v[102:103], v[56:57], v[58:59] op_sel_hi:[1,0,1]
	v_add_co_u32_e32 v58, vcc, s3, v42
	v_mov_b32_e32 v65, v57
	s_waitcnt lgkmcnt(0)
	v_lshlrev_b32_e32 v62, 16, v60
	v_and_b32_e32 v63, 0xffff0000, v60
	v_addc_co_u32_e32 v59, vcc, 0, v43, vcc
	s_mov_b32 s3, 0x66a9000
	v_pk_add_f32 v[56:57], v[64:65], v[62:63]
	v_add_co_u32_e32 v62, vcc, s3, v42
	v_cvt_pk_bf16_f32 v45, v56, v57
	s_nop 0
	v_addc_co_u32_e32 v63, vcc, 0, v43, vcc
	global_store_dword v[58:59], v56, off offset:-4096
	global_store_dword v[62:63], v57, off offset:-4096
	v_lshlrev_b32_e32 v56, 16, v61
	v_and_b32_e32 v57, 0xffff0000, v61
	v_pk_fma_f32 v[60:61], v[102:103], v[52:53], v[54:55] neg_lo:[0,0,1] neg_hi:[0,0,1]
	v_pk_fma_f32 v[52:53], v[102:103], v[52:53], v[54:55] op_sel_hi:[1,0,1]
	s_waitcnt vmcnt(28)
	v_pk_mul_f32 v[50:51], v[40:41], v[50:51] op_sel_hi:[1,0]
	v_mov_b32_e32 v61, v53
	v_pk_add_f32 v[52:53], v[60:61], v[56:57]
	v_pk_fma_f32 v[56:57], v[102:103], v[48:49], v[50:51] neg_lo:[0,0,1] neg_hi:[0,0,1]
	v_cvt_pk_bf16_f32 v47, v52, v53
	ds_write2_b32 v66, v45, v47 offset0:48 offset1:116
	global_store_dword v[58:59], v52, off
	global_store_dword v[62:63], v53, off
	ds_read2_b32 v[52:53], v66 offset0:184 offset1:252
	v_pk_fma_f32 v[48:49], v[102:103], v[48:49], v[50:51] op_sel_hi:[1,0,1]
	s_mov_b32 s3, 0x648a000
	v_mov_b32_e32 v57, v49
	v_add_co_u32_e32 v50, vcc, s3, v42
	s_waitcnt lgkmcnt(0)
	v_lshlrev_b32_e32 v54, 16, v52
	v_and_b32_e32 v55, 0xffff0000, v52
	v_pk_add_f32 v[48:49], v[56:57], v[54:55]
	v_addc_co_u32_e32 v51, vcc, 0, v43, vcc
	s_mov_b32 s3, 0x66aa000
	global_store_dword v[50:51], v48, off
	v_add_co_u32_e32 v50, vcc, s3, v42
	s_waitcnt vmcnt(29)
	v_pk_mul_f32 v[46:47], v[40:41], v[46:47] op_sel_hi:[1,0]
	v_addc_co_u32_e32 v51, vcc, 0, v43, vcc
	global_store_dword v[50:51], v49, off
	v_pk_fma_f32 v[50:51], v[102:103], v[44:45], v[46:47] neg_lo:[0,0,1] neg_hi:[0,0,1]
	v_pk_fma_f32 v[44:45], v[102:103], v[44:45], v[46:47] op_sel_hi:[1,0,1]
	v_cvt_pk_bf16_f32 v52, v48, v49
	v_lshlrev_b32_e32 v48, 16, v53
	v_and_b32_e32 v49, 0xffff0000, v53
	v_mov_b32_e32 v51, v45
	v_pk_add_f32 v[44:45], v[50:51], v[48:49]
	s_nop 0
	v_cvt_pk_bf16_f32 v46, v44, v45
	ds_write2_b32 v66, v52, v46 offset0:184 offset1:252
	v_add_co_u32_e32 v46, vcc, 0x648b000, v42
	s_nop 1
	v_addc_co_u32_e32 v47, vcc, 0, v43, vcc
	v_add_co_u32_e32 v42, vcc, 0x66ab000, v42
	global_store_dword v[46:47], v44, off
	s_nop 0
	v_addc_co_u32_e32 v43, vcc, 0, v43, vcc
	global_store_dword v[42:43], v45, off
	s_and_b64 vcc, exec, s[14:15]
	s_mov_b64 s[14:15], 0
	s_cbranch_vccnz .LBB0_448
	v_xor_b32_e32 v12, 0x80000000, v12
	v_cvt_pk_bf16_f32 v8, v8, v12
	v_xor_b32_e32 v12, 0x80000000, v13
	v_cvt_pk_bf16_f32 v9, v9, v12
	v_xor_b32_e32 v12, 0x80000000, v14
	v_cvt_pk_bf16_f32 v10, v10, v12
	v_xor_b32_e32 v12, 0x80000000, v15
	s_waitcnt lgkmcnt(0)
	v_xor_b32_e32 v20, 0x80000000, v20
	v_cvt_pk_bf16_f32 v11, v11, v12
	ds_read_b128 v[12:15], v131 offset:32768
	v_cvt_pk_bf16_f32 v16, v16, v20
	v_xor_b32_e32 v20, 0x80000000, v21
	v_cvt_pk_bf16_f32 v17, v17, v20
	v_xor_b32_e32 v20, 0x80000000, v22
	v_cvt_pk_bf16_f32 v18, v18, v20
	v_xor_b32_e32 v20, 0x80000000, v23
	v_cvt_pk_bf16_f32 v19, v19, v20
	ds_read_b128 v[20:23], v131 offset:32832
	v_xor_b32_e32 v28, 0x80000000, v28
	s_waitcnt lgkmcnt(1)
	v_mfma_f32_16x16x32_bf16 v[12:15], v[8:11], v[12:15], v[0:3]
	v_cvt_pk_bf16_f32 v24, v24, v28
	v_xor_b32_e32 v28, 0x80000000, v29
	v_cvt_pk_bf16_f32 v25, v25, v28
	v_xor_b32_e32 v28, 0x80000000, v30
	v_cvt_pk_bf16_f32 v26, v26, v28
	v_xor_b32_e32 v28, 0x80000000, v31
	v_cvt_pk_bf16_f32 v27, v27, v28
	s_waitcnt lgkmcnt(0)
	v_mfma_f32_16x16x32_bf16 v[12:15], v[16:19], v[20:23], v[12:15]
	ds_read_b128 v[20:23], v131 offset:32896
	v_xor_b32_e32 v36, 0x80000000, v36
	v_cvt_pk_bf16_f32 v32, v32, v36
	v_xor_b32_e32 v36, 0x80000000, v37
	v_cvt_pk_bf16_f32 v33, v33, v36
	v_xor_b32_e32 v36, 0x80000000, v38
	v_cvt_pk_bf16_f32 v34, v34, v36
	v_xor_b32_e32 v36, 0x80000000, v39
	v_cvt_pk_bf16_f32 v35, v35, v36
	s_waitcnt lgkmcnt(0)
	v_mfma_f32_16x16x32_bf16 v[12:15], v[24:27], v[20:23], v[12:15]
	ds_read_b128 v[20:23], v131 offset:32960
	s_mov_b32 s4, 1
	s_waitcnt lgkmcnt(0)
	v_mfma_f32_16x16x32_bf16 v[12:15], v[32:35], v[20:23], v[12:15]
	v_lshlrev_b32_e32 v20, 16, v104
	v_and_b32_e32 v21, 0xffff0000, v104
	s_nop 5
	v_pk_fma_f32 v[12:13], v[4:5], v[20:21], v[12:13]
	s_nop 0
	v_mul_f32_e32 v20, 0x3d372713, v12
	v_mul_f32_e32 v21, 0x3d372713, v13
	v_mul_f32_e32 v20, v12, v20
	v_mul_f32_e32 v21, v13, v21
	v_fma_f32 v20, v12, v20, v12
	v_fma_f32 v21, v13, v21, v13
	v_mul_f32_e32 v20, 0x3f4c422a, v20
	v_mul_f32_e32 v21, 0x3f4c422a, v21
	v_add_f32_e32 v20, v20, v20
	v_add_f32_e32 v21, v21, v21
	v_mul_f32_e32 v20, 0xbfb8aa3b, v20
	v_mul_f32_e32 v21, 0xbfb8aa3b, v21
	v_exp_f32_e32 v20, v20
	v_exp_f32_e32 v21, v21
	s_nop 0
	v_pk_add_f32 v[20:21], v[20:21], 1.0 op_sel_hi:[1,0]
	s_nop 0
	v_rcp_f32_e32 v21, v21
	v_rcp_f32_e32 v20, v20
	s_nop 0
	v_pk_mul_f32 v[12:13], v[12:13], v[20:21]
	v_lshlrev_b32_e32 v20, 16, v105
	v_and_b32_e32 v21, 0xffff0000, v105
	v_pk_fma_f32 v[14:15], v[6:7], v[20:21], v[14:15]
	v_cvt_pk_bf16_f32 v12, v12, v13
	v_mul_f32_e32 v20, 0x3d372713, v14
	v_mul_f32_e32 v21, 0x3d372713, v15
	v_mul_f32_e32 v20, v14, v20
	v_mul_f32_e32 v21, v15, v21
	v_fma_f32 v20, v14, v20, v14
	v_fma_f32 v21, v15, v21, v15
	v_mul_f32_e32 v20, 0x3f4c422a, v20
	v_mul_f32_e32 v21, 0x3f4c422a, v21
	v_add_f32_e32 v20, v20, v20
	v_add_f32_e32 v21, v21, v21
	v_mul_f32_e32 v20, 0xbfb8aa3b, v20
	v_mul_f32_e32 v21, 0xbfb8aa3b, v21
	v_exp_f32_e32 v20, v20
	v_exp_f32_e32 v21, v21
	s_nop 0
	v_pk_add_f32 v[20:21], v[20:21], 1.0 op_sel_hi:[1,0]
	s_nop 0
	v_rcp_f32_e32 v21, v21
	v_rcp_f32_e32 v20, v20
	s_nop 0
	v_pk_mul_f32 v[14:15], v[14:15], v[20:21]
	v_lshl_add_u32 v20, s12, 5, v137
	v_cvt_pk_bf16_f32 v13, v14, v15
	ds_write_b64 v20, v[12:13]
	ds_read_b128 v[12:15], v131 offset:37120
	s_waitcnt lgkmcnt(0)
	v_mfma_f32_16x16x32_bf16 v[8:11], v[8:11], v[12:15], v[0:3]
	ds_read_b128 v[12:15], v131 offset:37184
	s_waitcnt lgkmcnt(0)
	v_mfma_f32_16x16x32_bf16 v[8:11], v[16:19], v[12:15], v[8:11]
	ds_read_b128 v[12:15], v131 offset:37248
	s_waitcnt lgkmcnt(0)
	v_mfma_f32_16x16x32_bf16 v[8:11], v[24:27], v[12:15], v[8:11]
	ds_read_b128 v[12:15], v131 offset:37312
	s_waitcnt lgkmcnt(0)
	v_mfma_f32_16x16x32_bf16 v[8:11], v[32:35], v[12:15], v[8:11]
	v_lshlrev_b32_e32 v12, 16, v100
	v_and_b32_e32 v13, 0xffff0000, v100
	s_nop 5
	v_pk_fma_f32 v[4:5], v[4:5], v[12:13], v[8:9]
	s_nop 0
	v_mul_f32_e32 v8, 0x3d372713, v4
	v_mul_f32_e32 v9, 0x3d372713, v5
	v_mul_f32_e32 v8, v4, v8
	v_mul_f32_e32 v9, v5, v9
	v_fma_f32 v8, v4, v8, v4
	v_fma_f32 v9, v5, v9, v5
	v_mul_f32_e32 v8, 0x3f4c422a, v8
	v_mul_f32_e32 v9, 0x3f4c422a, v9
	v_add_f32_e32 v8, v8, v8
	v_add_f32_e32 v9, v9, v9
	v_mul_f32_e32 v8, 0xbfb8aa3b, v8
	v_mul_f32_e32 v9, 0xbfb8aa3b, v9
	v_exp_f32_e32 v8, v8
	v_exp_f32_e32 v9, v9
	s_nop 0
	v_pk_add_f32 v[8:9], v[8:9], 1.0 op_sel_hi:[1,0]
	s_nop 0
	v_rcp_f32_e32 v9, v9
	v_rcp_f32_e32 v8, v8
	s_nop 0
	v_pk_mul_f32 v[4:5], v[4:5], v[8:9]
	v_lshlrev_b32_e32 v8, 16, v101
	v_and_b32_e32 v9, 0xffff0000, v101
	v_pk_fma_f32 v[6:7], v[6:7], v[8:9], v[10:11]
	v_cvt_pk_bf16_f32 v4, v4, v5
	v_mul_f32_e32 v8, 0x3d372713, v6
	v_mul_f32_e32 v9, 0x3d372713, v7
	v_mul_f32_e32 v8, v6, v8
	v_mul_f32_e32 v9, v7, v9
	v_fma_f32 v8, v6, v8, v6
	v_fma_f32 v9, v7, v9, v7
	v_mul_f32_e32 v8, 0x3f4c422a, v8
	v_mul_f32_e32 v9, 0x3f4c422a, v9
	v_add_f32_e32 v8, v8, v8
	v_add_f32_e32 v9, v9, v9
	v_mul_f32_e32 v8, 0xbfb8aa3b, v8
	v_mul_f32_e32 v9, 0xbfb8aa3b, v9
	v_exp_f32_e32 v8, v8
	v_exp_f32_e32 v9, v9
	s_nop 0
	v_pk_add_f32 v[8:9], v[8:9], 1.0 op_sel_hi:[1,0]
	s_nop 0
	v_rcp_f32_e32 v9, v9
	s_mov_b64 s[2:3], 0
	v_rcp_f32_e32 v8, v8
	s_nop 0
	v_pk_mul_f32 v[6:7], v[6:7], v[8:9]
	s_andn2_b64 vcc, exec, s[10:11]
	v_cvt_pk_bf16_f32 v5, v6, v7
	ds_write_b64 v20, v[4:5] offset:8448
	s_nop 7
	s_cbranch_vccnz .LBB0_447
	v_mov_b32_e32 v0, v192
	v_mov_b32_e32 v4, v192
	v_mov_b32_e32 v8, v192
	v_mov_b32_e32 v12, v192
	v_mov_b32_e32 v16, v192
	v_mov_b32_e32 v20, v192
	v_mov_b32_e32 v24, v192
	v_mov_b32_e32 v28, v192
	s_waitcnt lgkmcnt(0)
	s_barrier
	flat_load_dwordx4 v[32:35], v[86:87]
	flat_load_dwordx4 v[36:39], v[88:89]
	ds_read_b128 v[40:43], v133
	v_mov_b32_e32 v1, v0
	v_mov_b32_e32 v2, v0
	v_mov_b32_e32 v3, v0
	v_mov_b32_e32 v5, v4
	v_mov_b32_e32 v6, v4
	v_mov_b32_e32 v7, v4
	v_mov_b32_e32 v9, v8
	v_mov_b32_e32 v10, v8
	v_mov_b32_e32 v11, v8
	v_mov_b32_e32 v13, v12
	v_mov_b32_e32 v14, v12
	v_mov_b32_e32 v15, v12
	v_mov_b32_e32 v17, v16
	v_mov_b32_e32 v18, v16
	v_mov_b32_e32 v19, v16
	v_mov_b32_e32 v21, v20
	v_mov_b32_e32 v22, v20
	v_mov_b32_e32 v23, v20
	v_mov_b32_e32 v25, v24
	v_mov_b32_e32 v26, v24
	v_mov_b32_e32 v27, v24
	v_mov_b32_e32 v29, v28
	v_mov_b32_e32 v30, v28
	v_mov_b32_e32 v31, v28
	s_cmp_lg_u32 s19, 0
	s_mov_b64 s[2:3], -1
	s_waitcnt vmcnt(0) lgkmcnt(0)
	v_mfma_f32_16x16x32_bf16 v[0:3], v[32:35], v[40:43], v[0:3]
	v_mfma_f32_16x16x32_bf16 v[4:7], v[36:39], v[40:43], v[4:7]
	ds_read_b128 v[40:43], v133 offset:8448
	s_waitcnt lgkmcnt(0)
	v_mfma_f32_16x16x32_bf16 v[8:11], v[32:35], v[40:43], v[8:11]
	v_mfma_f32_16x16x32_bf16 v[12:15], v[36:39], v[40:43], v[12:15]
	ds_read_b128 v[40:43], v133 offset:16896
	s_waitcnt lgkmcnt(0)
	v_mfma_f32_16x16x32_bf16 v[16:19], v[32:35], v[40:43], v[16:19]
	v_mfma_f32_16x16x32_bf16 v[20:23], v[36:39], v[40:43], v[20:23]
	ds_read_b128 v[40:43], v133 offset:25344
	s_waitcnt lgkmcnt(0)
	v_mfma_f32_16x16x32_bf16 v[24:27], v[32:35], v[40:43], v[24:27]
	v_mfma_f32_16x16x32_bf16 v[28:31], v[36:39], v[40:43], v[28:31]
	flat_load_dwordx4 v[32:35], v[86:87] offset:64
	flat_load_dwordx4 v[36:39], v[88:89] offset:64
	ds_read_b128 v[40:43], v133 offset:64
	s_waitcnt vmcnt(0) lgkmcnt(0)
	v_mfma_f32_16x16x32_bf16 v[0:3], v[32:35], v[40:43], v[0:3]
	v_mfma_f32_16x16x32_bf16 v[4:7], v[36:39], v[40:43], v[4:7]
	ds_read_b128 v[40:43], v133 offset:8512
	s_waitcnt lgkmcnt(0)
	v_mfma_f32_16x16x32_bf16 v[8:11], v[32:35], v[40:43], v[8:11]
	v_mfma_f32_16x16x32_bf16 v[12:15], v[36:39], v[40:43], v[12:15]
	ds_read_b128 v[40:43], v133 offset:16960
	s_waitcnt lgkmcnt(0)
	v_mfma_f32_16x16x32_bf16 v[16:19], v[32:35], v[40:43], v[16:19]
	v_mfma_f32_16x16x32_bf16 v[20:23], v[36:39], v[40:43], v[20:23]
	ds_read_b128 v[40:43], v133 offset:25408
	s_waitcnt lgkmcnt(0)
	v_mfma_f32_16x16x32_bf16 v[24:27], v[32:35], v[40:43], v[24:27]
	v_mfma_f32_16x16x32_bf16 v[28:31], v[36:39], v[40:43], v[28:31]
	flat_load_dwordx4 v[32:35], v[86:87] offset:128
	flat_load_dwordx4 v[36:39], v[88:89] offset:128
	ds_read_b128 v[40:43], v133 offset:128
	s_waitcnt vmcnt(0) lgkmcnt(0)
	v_mfma_f32_16x16x32_bf16 v[0:3], v[32:35], v[40:43], v[0:3]
	v_mfma_f32_16x16x32_bf16 v[4:7], v[36:39], v[40:43], v[4:7]
	ds_read_b128 v[40:43], v133 offset:8576
	s_waitcnt lgkmcnt(0)
	v_mfma_f32_16x16x32_bf16 v[8:11], v[32:35], v[40:43], v[8:11]
	v_mfma_f32_16x16x32_bf16 v[12:15], v[36:39], v[40:43], v[12:15]
	ds_read_b128 v[40:43], v133 offset:17024
	s_waitcnt lgkmcnt(0)
	v_mfma_f32_16x16x32_bf16 v[16:19], v[32:35], v[40:43], v[16:19]
	v_mfma_f32_16x16x32_bf16 v[20:23], v[36:39], v[40:43], v[20:23]
	ds_read_b128 v[40:43], v133 offset:25472
	s_waitcnt lgkmcnt(0)
	v_mfma_f32_16x16x32_bf16 v[24:27], v[32:35], v[40:43], v[24:27]
	v_mfma_f32_16x16x32_bf16 v[28:31], v[36:39], v[40:43], v[28:31]
	flat_load_dwordx4 v[32:35], v[86:87] offset:192
	flat_load_dwordx4 v[36:39], v[88:89] offset:192
	ds_read_b128 v[40:43], v133 offset:192
	s_waitcnt vmcnt(0) lgkmcnt(0)
	v_mfma_f32_16x16x32_bf16 v[0:3], v[32:35], v[40:43], v[0:3]
	v_mfma_f32_16x16x32_bf16 v[4:7], v[36:39], v[40:43], v[4:7]
	ds_read_b128 v[40:43], v133 offset:8640
	s_waitcnt lgkmcnt(0)
	v_mfma_f32_16x16x32_bf16 v[8:11], v[32:35], v[40:43], v[8:11]
	v_mfma_f32_16x16x32_bf16 v[12:15], v[36:39], v[40:43], v[12:15]
	ds_read_b128 v[40:43], v133 offset:17088
	s_waitcnt lgkmcnt(0)
	v_mfma_f32_16x16x32_bf16 v[16:19], v[32:35], v[40:43], v[16:19]
	v_mfma_f32_16x16x32_bf16 v[20:23], v[36:39], v[40:43], v[20:23]
	ds_read_b128 v[40:43], v133 offset:25536
	s_waitcnt lgkmcnt(0)
	v_mfma_f32_16x16x32_bf16 v[24:27], v[32:35], v[40:43], v[24:27]
	v_mfma_f32_16x16x32_bf16 v[28:31], v[36:39], v[40:43], v[28:31]
	flat_load_dwordx4 v[32:35], v[86:87] offset:256
	flat_load_dwordx4 v[36:39], v[88:89] offset:256
	ds_read_b128 v[40:43], v133 offset:256
	s_waitcnt vmcnt(0) lgkmcnt(0)
	v_mfma_f32_16x16x32_bf16 v[0:3], v[32:35], v[40:43], v[0:3]
	v_mfma_f32_16x16x32_bf16 v[4:7], v[36:39], v[40:43], v[4:7]
	ds_read_b128 v[40:43], v133 offset:8704
	s_waitcnt lgkmcnt(0)
	v_mfma_f32_16x16x32_bf16 v[8:11], v[32:35], v[40:43], v[8:11]
	v_mfma_f32_16x16x32_bf16 v[12:15], v[36:39], v[40:43], v[12:15]
	ds_read_b128 v[40:43], v133 offset:17152
	s_waitcnt lgkmcnt(0)
	v_mfma_f32_16x16x32_bf16 v[16:19], v[32:35], v[40:43], v[16:19]
	v_mfma_f32_16x16x32_bf16 v[20:23], v[36:39], v[40:43], v[20:23]
	ds_read_b128 v[40:43], v133 offset:25600
	s_waitcnt lgkmcnt(0)
	v_mfma_f32_16x16x32_bf16 v[24:27], v[32:35], v[40:43], v[24:27]
	v_mfma_f32_16x16x32_bf16 v[28:31], v[36:39], v[40:43], v[28:31]
	flat_load_dwordx4 v[32:35], v[86:87] offset:320
	flat_load_dwordx4 v[36:39], v[88:89] offset:320
	ds_read_b128 v[40:43], v133 offset:320
	s_waitcnt vmcnt(0) lgkmcnt(0)
	v_mfma_f32_16x16x32_bf16 v[0:3], v[32:35], v[40:43], v[0:3]
	v_mfma_f32_16x16x32_bf16 v[4:7], v[36:39], v[40:43], v[4:7]
	ds_read_b128 v[40:43], v133 offset:8768
	s_waitcnt lgkmcnt(0)
	v_mfma_f32_16x16x32_bf16 v[8:11], v[32:35], v[40:43], v[8:11]
	v_mfma_f32_16x16x32_bf16 v[12:15], v[36:39], v[40:43], v[12:15]
	ds_read_b128 v[40:43], v133 offset:17216
	s_waitcnt lgkmcnt(0)
	v_mfma_f32_16x16x32_bf16 v[16:19], v[32:35], v[40:43], v[16:19]
	v_mfma_f32_16x16x32_bf16 v[20:23], v[36:39], v[40:43], v[20:23]
	ds_read_b128 v[40:43], v133 offset:25664
	s_waitcnt lgkmcnt(0)
	v_mfma_f32_16x16x32_bf16 v[24:27], v[32:35], v[40:43], v[24:27]
	v_mfma_f32_16x16x32_bf16 v[28:31], v[36:39], v[40:43], v[28:31]
	flat_load_dwordx4 v[32:35], v[86:87] offset:384
	flat_load_dwordx4 v[36:39], v[88:89] offset:384
	ds_read_b128 v[40:43], v133 offset:384
	s_waitcnt vmcnt(0) lgkmcnt(0)
	v_mfma_f32_16x16x32_bf16 v[0:3], v[32:35], v[40:43], v[0:3]
	v_mfma_f32_16x16x32_bf16 v[4:7], v[36:39], v[40:43], v[4:7]
	ds_read_b128 v[40:43], v133 offset:8832
	s_waitcnt lgkmcnt(0)
	v_mfma_f32_16x16x32_bf16 v[8:11], v[32:35], v[40:43], v[8:11]
	v_mfma_f32_16x16x32_bf16 v[40:43], v[36:39], v[40:43], v[12:15]
	s_nop 2
	ds_read_b128 v[12:15], v133 offset:17280
	s_waitcnt lgkmcnt(0)
	v_mfma_f32_16x16x32_bf16 v[44:47], v[32:35], v[12:15], v[16:19]
	v_mfma_f32_16x16x32_bf16 v[20:23], v[36:39], v[12:15], v[20:23]
	ds_read_b128 v[12:15], v133 offset:25728
	s_waitcnt lgkmcnt(0)
	v_mfma_f32_16x16x32_bf16 v[52:55], v[36:39], v[12:15], v[28:31]
	s_nop 2
	flat_load_dwordx4 v[28:31], v[86:87] offset:448
	flat_load_dwordx4 v[56:59], v[88:89] offset:448
	v_mfma_f32_16x16x32_bf16 v[48:51], v[32:35], v[12:15], v[24:27]
	ds_read_b128 v[12:15], v133 offset:448
	s_waitcnt vmcnt(0) lgkmcnt(0)
	v_mfma_f32_16x16x32_bf16 v[24:27], v[28:31], v[12:15], v[0:3]
	s_nop 2
	ds_read_b128 v[0:3], v133 offset:8896
	v_mfma_f32_16x16x32_bf16 v[16:19], v[56:59], v[12:15], v[4:7]
	s_waitcnt lgkmcnt(0)
	v_mfma_f32_16x16x32_bf16 v[12:15], v[28:31], v[0:3], v[8:11]
	v_mfma_f32_16x16x32_bf16 v[8:11], v[56:59], v[0:3], v[40:43]
	ds_read_b128 v[0:3], v133 offset:17344
	s_waitcnt lgkmcnt(0)
	v_mfma_f32_16x16x32_bf16 v[36:39], v[28:31], v[0:3], v[44:47]
	v_mfma_f32_16x16x32_bf16 v[32:35], v[56:59], v[0:3], v[20:23]
	ds_read_b128 v[0:3], v133 offset:25792
	s_waitcnt lgkmcnt(0)
	v_mfma_f32_16x16x32_bf16 v[28:31], v[28:31], v[0:3], v[48:51]
	v_mfma_f32_16x16x32_bf16 v[20:23], v[56:59], v[0:3], v[52:55]
	global_load_dwordx4 v[4:7], v[90:91], off
	global_load_dwordx4 v[0:3], v[90:91], off offset:64
	s_cbranch_scc0 .LBB0_452
	s_waitcnt vmcnt(1)
	v_add_f32_e32 v36, v36, v4
	v_add_f32_e32 v37, v37, v5
	v_mul_f32_e32 v36, 0xbfb8aa3b, v36
	v_mul_f32_e32 v37, 0xbfb8aa3b, v37
	ds_read_b64 v[42:43], v125
	v_exp_f32_e32 v36, v36
	v_exp_f32_e32 v37, v37
	v_add_f32_e32 v38, v38, v6
	v_add_f32_e32 v39, v39, v7
	s_waitcnt lgkmcnt(0)
	v_lshlrev_b32_e32 v44, 16, v42
	v_pk_add_f32 v[36:37], v[36:37], 1.0 op_sel_hi:[1,0]
	v_and_b32_e32 v45, 0xffff0000, v42
	v_mul_f32_e32 v38, 0xbfb8aa3b, v38
	v_mul_f32_e32 v39, 0xbfb8aa3b, v39
	v_exp_f32_e32 v38, v38
	v_rcp_f32_e32 v37, v37
	v_exp_f32_e32 v39, v39
	v_or_b32_e32 v40, s18, v81
	v_mul_u32_u24_e32 v40, 0x1400, v40
	v_rcp_f32_e32 v36, v36
	v_pk_add_f32 v[38:39], v[38:39], 1.0 op_sel_hi:[1,0]
	v_pk_mul_f32 v[36:37], v[36:37], v[44:45]
	v_lshlrev_b32_e32 v42, 16, v43
	v_and_b32_e32 v43, 0xffff0000, v43
	v_mov_b32_e32 v41, v195
	v_rcp_f32_e32 v39, v39
	v_cvt_pk_bf16_f32 v36, v36, v37
	s_waitcnt vmcnt(0)
	v_add_f32_e32 v32, v32, v0
	v_add_f32_e32 v33, v33, v1
	v_rcp_f32_e32 v38, v38
	s_nop 0
	v_pk_mul_f32 v[38:39], v[38:39], v[42:43]
	v_mul_f32_e32 v32, 0xbfb8aa3b, v32
	v_cvt_pk_bf16_f32 v37, v38, v39
	v_lshl_add_u64 v[38:39], s[26:27], 0, v[40:41]
	v_lshl_add_u64 v[38:39], v[38:39], 0, s[74:75]
	v_lshl_add_u64 v[40:41], v[92:93], 1, v[38:39]
	flat_store_dwordx2 v[40:41], v[36:37]
	v_mul_f32_e32 v33, 0xbfb8aa3b, v33
	ds_read_b64 v[36:37], v125 offset:32
	v_exp_f32_e32 v32, v32
	v_exp_f32_e32 v33, v33
	v_add_f32_e32 v34, v34, v2
	v_add_f32_e32 v35, v35, v3
	s_waitcnt lgkmcnt(0)
	v_lshlrev_b32_e32 v40, 16, v36
	v_pk_add_f32 v[32:33], v[32:33], 1.0 op_sel_hi:[1,0]
	v_and_b32_e32 v41, 0xffff0000, v36
	v_mul_f32_e32 v34, 0xbfb8aa3b, v34
	v_mul_f32_e32 v35, 0xbfb8aa3b, v35
	v_exp_f32_e32 v34, v34
	v_rcp_f32_e32 v33, v33
	v_exp_f32_e32 v35, v35
	v_rcp_f32_e32 v32, v32
	v_pk_add_f32 v[34:35], v[34:35], 1.0 op_sel_hi:[1,0]
	v_pk_mul_f32 v[32:33], v[32:33], v[40:41]
	v_lshlrev_b32_e32 v36, 16, v37
	v_and_b32_e32 v37, 0xffff0000, v37
	v_cvt_pk_bf16_f32 v32, v32, v33
	v_rcp_f32_e32 v35, v35
	s_mov_b64 s[2:3], 0
	v_rcp_f32_e32 v34, v34
	s_nop 0
	v_pk_mul_f32 v[34:35], v[34:35], v[36:37]
	s_nop 0
	v_cvt_pk_bf16_f32 v33, v34, v35
	v_lshl_add_u64 v[34:35], v[94:95], 1, v[38:39]
	flat_store_dwordx2 v[34:35], v[32:33]
	s_nop 7
.LBB0_452:
	s_andn2_b64 vcc, exec, s[2:3]
	v_mov_b32_e32 v33, v111
	v_mov_b32_e32 v32, v119
	v_readlane_b32 s65, v255, 11
	v_readlane_b32 s64, v255, 12
	s_movk_i32 s62, 0x7fff
	s_mov_b64 s[70:71], 0x80
	s_mov_b64 s[68:69], 0xc00
	s_mov_b32 s56, s96
	s_cbranch_vccnz .LBB0_445
	s_waitcnt vmcnt(0)
	v_add_f32_e32 v24, v24, v4
	v_add_f32_e32 v25, v25, v5
	v_mul_f32_e32 v24, 0xbfb8aa3b, v24
	v_mul_f32_e32 v25, 0xbfb8aa3b, v25
	ds_read_b64 v[22:23], v123
	v_exp_f32_e32 v24, v24
	v_exp_f32_e32 v25, v25
	v_mul_u32_u24_e32 v20, 0x1400, v135
	v_mov_b32_e32 v21, v195
	s_waitcnt lgkmcnt(0)
	v_lshlrev_b32_e32 v28, 16, v22
	v_pk_add_f32 v[24:25], v[24:25], 1.0 op_sel_hi:[1,0]
	v_and_b32_e32 v29, 0xffff0000, v22
	v_lshl_add_u64 v[20:21], s[26:27], 0, v[20:21]
	v_lshl_add_u64 v[20:21], v[20:21], 0, s[74:75]
	v_add_f32_e32 v16, v16, v0
	v_rcp_f32_e32 v25, v25
	v_add_f32_e32 v17, v17, v1
	v_mul_f32_e32 v16, 0xbfb8aa3b, v16
	v_mul_f32_e32 v17, 0xbfb8aa3b, v17
	v_rcp_f32_e32 v24, v24
	v_add_f32_e32 v22, v26, v6
	v_mul_f32_e32 v22, 0xbfb8aa3b, v22
	v_exp_f32_e32 v26, v22
	v_add_f32_e32 v22, v27, v7
	v_mul_f32_e32 v22, 0xbfb8aa3b, v22
	v_exp_f32_e32 v27, v22
	v_pk_mul_f32 v[24:25], v[24:25], v[28:29]
	v_lshlrev_b32_e32 v22, 16, v23
	v_and_b32_e32 v23, 0xffff0000, v23
	v_pk_add_f32 v[26:27], v[26:27], 1.0 op_sel_hi:[1,0]
	v_cvt_pk_bf16_f32 v24, v24, v25
	v_exp_f32_e32 v16, v16
	v_exp_f32_e32 v17, v17
	v_add_f32_e32 v18, v18, v2
	v_rcp_f32_e32 v27, v27
	v_pk_add_f32 v[16:17], v[16:17], 1.0 op_sel_hi:[1,0]
	v_add_f32_e32 v19, v19, v3
	v_mul_f32_e32 v18, 0xbfb8aa3b, v18
	v_rcp_f32_e32 v26, v26
	s_nop 0
	v_pk_mul_f32 v[22:23], v[26:27], v[22:23]
	v_mul_f32_e32 v19, 0xbfb8aa3b, v19
	v_cvt_pk_bf16_f32 v25, v22, v23
	v_lshl_add_u64 v[22:23], v[92:93], 1, v[20:21]
	flat_store_dwordx2 v[22:23], v[24:25]
	ds_read_b64 v[22:23], v123 offset:32
	v_exp_f32_e32 v18, v18
	v_exp_f32_e32 v19, v19
	v_mov_b32_e32 v33, v79
	v_mov_b32_e32 v32, v117
	s_waitcnt lgkmcnt(0)
	v_lshlrev_b32_e32 v24, 16, v22
	v_and_b32_e32 v25, 0xffff0000, v22
	v_pk_add_f32 v[18:19], v[18:19], 1.0 op_sel_hi:[1,0]
	v_rcp_f32_e32 v17, v17
	v_rcp_f32_e32 v16, v16
	s_nop 0
	v_pk_mul_f32 v[16:17], v[16:17], v[24:25]
	v_lshlrev_b32_e32 v22, 16, v23
	v_and_b32_e32 v23, 0xffff0000, v23
	v_cvt_pk_bf16_f32 v16, v16, v17
	v_rcp_f32_e32 v19, v19
	v_rcp_f32_e32 v18, v18
	s_nop 0
	v_pk_mul_f32 v[18:19], v[18:19], v[22:23]
	v_mov_b64_e32 v[30:31], v[14:15]
	v_cvt_pk_bf16_f32 v17, v18, v19
	v_lshl_add_u64 v[18:19], v[94:95], 1, v[20:21]
	v_mov_b64_e32 v[22:23], v[10:11]
	v_mov_b64_e32 v[28:29], v[12:13]
	v_mov_b64_e32 v[20:21], v[8:9]
	flat_store_dwordx2 v[18:19], v[16:17]
	s_branch .LBB0_445

.LBB0_457:
	v_or_b32_e32 v51, s6, v72
	v_or_b32_e32 v51, s10, v51
	v_mad_i64_i32 v[70:71], s[2:3], v51, s86, v[40:41]
	v_add_lshl_u32 v51, s5, v72, 2
	flat_load_dwordx2 v[64:65], v[70:71] offset:96
	flat_load_dwordx2 v[66:67], v[70:71] offset:64
	flat_load_dwordx2 v[68:69], v[70:71] offset:32
	global_load_dword v62, v51, s[8:9] offset:64
	s_nop 0
	flat_load_dwordx2 v[70:71], v[70:71]
	v_or_b32_e32 v51, s5, v72
	v_or_b32_e32 v53, s10, v51
	v_mad_i64_i32 v[74:75], s[2:3], v53, s86, v[40:41]
	v_lshlrev_b32_e32 v51, 2, v51
	flat_load_dwordx2 v[78:79], v[74:75] offset:96
	flat_load_dwordx2 v[80:81], v[74:75] offset:64
	flat_load_dwordx2 v[82:83], v[74:75] offset:32
	global_load_dword v72, v51, s[8:9]
	flat_load_dwordx2 v[84:85], v[74:75]
	v_or_b32_e32 v51, s5, v49
	v_mov_b64_e32 v[74:75], s[0:1]
	v_mad_i64_i32 v[76:77], s[2:3], v51, s86, v[74:75]
	s_mov_b64 s[10:11], 0x2040600
	v_lshl_add_u64 v[76:77], v[76:77], 0, s[10:11]
	s_add_i32 s19, s19, s81
	s_waitcnt vmcnt(0) lgkmcnt(0)
	v_lshlrev_b32_e32 v90, 16, v84
	v_mul_f32_e32 v51, 0x3d372713, v90
	v_mul_f32_e32 v51, v51, v90
	v_mov_b32_e32 v53, v90
	v_fmac_f32_e32 v53, v51, v53
	v_mul_f32_e32 v51, 0x3f4c422a, v53
	v_add_f32_e32 v51, v51, v51
	v_and_b32_e32 v91, 0xffff0000, v84
	v_mul_f32_e32 v51, 0xbfb8aa3b, v51
	v_exp_f32_e32 v92, v51
	v_mul_f32_e32 v51, 0x3d372713, v91
	v_mul_f32_e32 v51, v51, v91
	v_mov_b32_e32 v53, v91
	v_fmac_f32_e32 v53, v51, v53
	v_mul_f32_e32 v51, 0x3f4c422a, v53
	v_add_f32_e32 v51, v51, v51
	v_mul_f32_e32 v51, 0xbfb8aa3b, v51
	v_exp_f32_e32 v93, v51
	s_nop 0
	v_pk_add_f32 v[92:93], v[92:93], 1.0 op_sel_hi:[1,0]
	s_nop 0
	v_rcp_f32_e32 v93, v93
	v_lshlrev_b32_e32 v84, 16, v85
	v_rcp_f32_e32 v92, v92
	v_mul_f32_e32 v51, 0x3d372713, v84
	v_mul_f32_e32 v51, v51, v84
	v_mov_b32_e32 v53, v84
	v_fmac_f32_e32 v53, v51, v53
	v_mul_f32_e32 v51, 0x3f4c422a, v53
	v_add_f32_e32 v51, v51, v51
	v_pk_mul_f32 v[90:91], v[92:93], v[90:91]
	v_pk_add_f32 v[28:29], v[28:29], v[72:73] op_sel_hi:[1,0]
	v_and_b32_e32 v85, 0xffff0000, v85
	v_mul_f32_e32 v51, 0xbfb8aa3b, v51
	v_pk_mul_f32 v[28:29], v[28:29], v[90:91]
	v_exp_f32_e32 v90, v51
	v_mul_f32_e32 v51, 0x3d372713, v85
	v_mul_f32_e32 v51, v51, v85
	v_mov_b32_e32 v53, v85
	v_fmac_f32_e32 v53, v51, v53
	v_mul_f32_e32 v51, 0x3f4c422a, v53
	v_add_f32_e32 v51, v51, v51
	v_mul_f32_e32 v51, 0xbfb8aa3b, v51
	v_exp_f32_e32 v91, v51
	v_cvt_pk_bf16_f32 v28, v28, v29
	v_pk_add_f32 v[90:91], v[90:91], 1.0 op_sel_hi:[1,0]
	s_nop 0
	v_rcp_f32_e32 v91, v91
	v_rcp_f32_e32 v90, v90
	s_nop 0
	v_pk_mul_f32 v[84:85], v[90:91], v[84:85]
	v_pk_add_f32 v[30:31], v[30:31], v[72:73] op_sel_hi:[1,0]
	s_nop 0
	v_pk_mul_f32 v[30:31], v[30:31], v[84:85]
	s_nop 0
	v_cvt_pk_bf16_f32 v29, v30, v31
	v_lshl_add_u64 v[30:31], v[76:77], 0, v[54:55]
	flat_store_dwordx2 v[30:31], v[28:29]
	v_lshlrev_b32_e32 v28, 16, v82
	v_mul_f32_e32 v30, 0x3d372713, v28
	v_mul_f32_e32 v30, v30, v28
	v_mov_b32_e32 v31, v28
	v_and_b32_e32 v29, 0xffff0000, v82
	v_fmac_f32_e32 v31, v30, v31
	v_mul_f32_e32 v30, 0x3f4c422a, v31
	v_mul_f32_e32 v31, 0x3d372713, v29
	v_mul_f32_e32 v31, v31, v29
	v_mov_b32_e32 v51, v29
	v_fmac_f32_e32 v51, v31, v51
	v_mul_f32_e32 v31, 0x3f4c422a, v51
	v_add_f32_e32 v30, v30, v30
	v_add_f32_e32 v31, v31, v31
	v_mul_f32_e32 v30, 0xbfb8aa3b, v30
	v_mul_f32_e32 v31, 0xbfb8aa3b, v31
	v_exp_f32_e32 v30, v30
	v_exp_f32_e32 v31, v31
	s_nop 0
	v_pk_add_f32 v[30:31], v[30:31], 1.0 op_sel_hi:[1,0]
	s_nop 0
	v_rcp_f32_e32 v31, v31
	v_rcp_f32_e32 v30, v30
	s_nop 0
	v_pk_mul_f32 v[28:29], v[30:31], v[28:29]
	v_pk_add_f32 v[24:25], v[24:25], v[72:73] op_sel_hi:[1,0]
	s_nop 0
	v_pk_mul_f32 v[24:25], v[24:25], v[28:29]
	v_lshlrev_b32_e32 v28, 16, v83
	v_mul_f32_e32 v30, 0x3d372713, v28
	v_mul_f32_e32 v30, v30, v28
	v_mov_b32_e32 v31, v28
	v_and_b32_e32 v29, 0xffff0000, v83
	v_fmac_f32_e32 v31, v30, v31
	v_mul_f32_e32 v30, 0x3f4c422a, v31
	v_mul_f32_e32 v31, 0x3d372713, v29
	v_mul_f32_e32 v31, v31, v29
	v_mov_b32_e32 v51, v29
	v_fmac_f32_e32 v51, v31, v51
	v_mul_f32_e32 v31, 0x3f4c422a, v51
	v_add_f32_e32 v30, v30, v30
	v_add_f32_e32 v31, v31, v31
	v_mul_f32_e32 v30, 0xbfb8aa3b, v30
	v_mul_f32_e32 v31, 0xbfb8aa3b, v31
	v_exp_f32_e32 v30, v30
	v_exp_f32_e32 v31, v31
	v_cvt_pk_bf16_f32 v24, v24, v25
	v_pk_add_f32 v[30:31], v[30:31], 1.0 op_sel_hi:[1,0]
	s_nop 0
	v_rcp_f32_e32 v31, v31
	v_rcp_f32_e32 v30, v30
	s_nop 0
	v_pk_mul_f32 v[28:29], v[30:31], v[28:29]
	v_pk_add_f32 v[26:27], v[26:27], v[72:73] op_sel_hi:[1,0]
	v_pk_add_f32 v[20:21], v[20:21], v[72:73] op_sel_hi:[1,0]
	v_pk_mul_f32 v[26:27], v[26:27], v[28:29]
	v_pk_add_f32 v[22:23], v[22:23], v[72:73] op_sel_hi:[1,0]
	v_cvt_pk_bf16_f32 v25, v26, v27
	v_lshl_add_u64 v[26:27], v[76:77], 0, v[56:57]
	flat_store_dwordx2 v[26:27], v[24:25]
	v_lshlrev_b32_e32 v24, 16, v80
	v_mul_f32_e32 v26, 0x3d372713, v24
	v_mul_f32_e32 v26, v26, v24
	v_mov_b32_e32 v27, v24
	v_and_b32_e32 v25, 0xffff0000, v80
	v_fmac_f32_e32 v27, v26, v27
	v_mul_f32_e32 v26, 0x3f4c422a, v27
	v_mul_f32_e32 v27, 0x3d372713, v25
	v_mul_f32_e32 v27, v27, v25
	v_mov_b32_e32 v28, v25
	v_fmac_f32_e32 v28, v27, v28
	v_mul_f32_e32 v27, 0x3f4c422a, v28
	v_add_f32_e32 v26, v26, v26
	v_add_f32_e32 v27, v27, v27
	v_mul_f32_e32 v26, 0xbfb8aa3b, v26
	v_mul_f32_e32 v27, 0xbfb8aa3b, v27
	v_exp_f32_e32 v26, v26
	v_exp_f32_e32 v27, v27
	v_pk_add_f32 v[16:17], v[16:17], v[72:73] op_sel_hi:[1,0]
	v_pk_add_f32 v[18:19], v[18:19], v[72:73] op_sel_hi:[1,0]
	v_pk_add_f32 v[12:13], v[12:13], v[62:63] op_sel_hi:[1,0]
	v_pk_add_f32 v[26:27], v[26:27], 1.0 op_sel_hi:[1,0]
	v_pk_add_f32 v[14:15], v[14:15], v[62:63] op_sel_hi:[1,0]
	v_pk_add_f32 v[8:9], v[62:63], v[8:9] op_sel_hi:[0,1]
	v_pk_add_f32 v[10:11], v[62:63], v[10:11] op_sel_hi:[0,1]
	v_pk_add_f32 v[4:5], v[62:63], v[4:5] op_sel_hi:[0,1]
	v_rcp_f32_e32 v27, v27
	v_pk_add_f32 v[6:7], v[62:63], v[6:7] op_sel_hi:[0,1]
	v_pk_add_f32 v[0:1], v[62:63], v[0:1] op_sel_hi:[0,1]
	v_pk_add_f32 v[2:3], v[62:63], v[2:3] op_sel_hi:[0,1]
	v_rcp_f32_e32 v26, v26
	s_nop 0
	v_pk_mul_f32 v[24:25], v[26:27], v[24:25]
	s_nop 0
	v_pk_mul_f32 v[20:21], v[20:21], v[24:25]
	v_lshlrev_b32_e32 v24, 16, v81
	v_mul_f32_e32 v26, 0x3d372713, v24
	v_mul_f32_e32 v26, v26, v24
	v_mov_b32_e32 v27, v24
	v_and_b32_e32 v25, 0xffff0000, v81
	v_fmac_f32_e32 v27, v26, v27
	v_mul_f32_e32 v26, 0x3f4c422a, v27
	v_mul_f32_e32 v27, 0x3d372713, v25
	v_mul_f32_e32 v27, v27, v25
	v_mov_b32_e32 v28, v25
	v_fmac_f32_e32 v28, v27, v28
	v_mul_f32_e32 v27, 0x3f4c422a, v28
	v_add_f32_e32 v26, v26, v26
	v_add_f32_e32 v27, v27, v27
	v_mul_f32_e32 v26, 0xbfb8aa3b, v26
	v_mul_f32_e32 v27, 0xbfb8aa3b, v27
	v_exp_f32_e32 v26, v26
	v_exp_f32_e32 v27, v27
	v_cvt_pk_bf16_f32 v20, v20, v21
	v_pk_add_f32 v[26:27], v[26:27], 1.0 op_sel_hi:[1,0]
	s_nop 0
	v_rcp_f32_e32 v27, v27
	v_rcp_f32_e32 v26, v26
	s_nop 0
	v_pk_mul_f32 v[24:25], v[26:27], v[24:25]
	s_nop 0
	v_pk_mul_f32 v[22:23], v[22:23], v[24:25]
	s_nop 0
	v_cvt_pk_bf16_f32 v21, v22, v23
	v_lshl_add_u64 v[22:23], v[76:77], 0, v[58:59]
	flat_store_dwordx2 v[22:23], v[20:21]
	v_lshlrev_b32_e32 v20, 16, v78
	v_mul_f32_e32 v22, 0x3d372713, v20
	v_mul_f32_e32 v22, v22, v20
	v_mov_b32_e32 v23, v20
	v_and_b32_e32 v21, 0xffff0000, v78
	v_fmac_f32_e32 v23, v22, v23
	v_mul_f32_e32 v22, 0x3f4c422a, v23
	v_mul_f32_e32 v23, 0x3d372713, v21
	v_mul_f32_e32 v23, v23, v21
	v_mov_b32_e32 v24, v21
	v_fmac_f32_e32 v24, v23, v24
	v_mul_f32_e32 v23, 0x3f4c422a, v24
	v_add_f32_e32 v22, v22, v22
	v_add_f32_e32 v23, v23, v23
	v_mul_f32_e32 v22, 0xbfb8aa3b, v22
	v_mul_f32_e32 v23, 0xbfb8aa3b, v23
	v_exp_f32_e32 v22, v22
	v_exp_f32_e32 v23, v23
	s_nop 0
	v_pk_add_f32 v[22:23], v[22:23], 1.0 op_sel_hi:[1,0]
	s_nop 0
	v_rcp_f32_e32 v23, v23
	v_rcp_f32_e32 v22, v22
	s_nop 0
	v_pk_mul_f32 v[20:21], v[22:23], v[20:21]
	s_nop 0
	v_pk_mul_f32 v[16:17], v[16:17], v[20:21]
	v_lshlrev_b32_e32 v20, 16, v79
	v_mul_f32_e32 v22, 0x3d372713, v20
	v_mul_f32_e32 v22, v22, v20
	v_mov_b32_e32 v23, v20
	v_and_b32_e32 v21, 0xffff0000, v79
	v_fmac_f32_e32 v23, v22, v23
	v_mul_f32_e32 v22, 0x3f4c422a, v23
	v_mul_f32_e32 v23, 0x3d372713, v21
	v_mul_f32_e32 v23, v23, v21
	v_mov_b32_e32 v24, v21
	v_fmac_f32_e32 v24, v23, v24
	v_mul_f32_e32 v23, 0x3f4c422a, v24
	v_add_f32_e32 v22, v22, v22
	v_add_f32_e32 v23, v23, v23
	v_mul_f32_e32 v22, 0xbfb8aa3b, v22
	v_mul_f32_e32 v23, 0xbfb8aa3b, v23
	v_exp_f32_e32 v22, v22
	v_exp_f32_e32 v23, v23
	v_cvt_pk_bf16_f32 v16, v16, v17
	v_pk_add_f32 v[22:23], v[22:23], 1.0 op_sel_hi:[1,0]
	s_nop 0
	v_rcp_f32_e32 v23, v23
	v_rcp_f32_e32 v22, v22
	s_nop 0
	v_pk_mul_f32 v[20:21], v[22:23], v[20:21]
	s_nop 0
	v_pk_mul_f32 v[18:19], v[18:19], v[20:21]
	s_nop 0
	v_cvt_pk_bf16_f32 v17, v18, v19
	v_lshl_add_u64 v[18:19], v[76:77], 0, v[60:61]
	flat_store_dwordx2 v[18:19], v[16:17]
	v_lshlrev_b32_e32 v18, 16, v70
	v_mul_f32_e32 v20, 0x3d372713, v18
	v_mul_f32_e32 v20, v20, v18
	v_mov_b32_e32 v21, v18
	v_and_b32_e32 v19, 0xffff0000, v70
	v_fmac_f32_e32 v21, v20, v21
	v_mul_f32_e32 v20, 0x3f4c422a, v21
	v_mul_f32_e32 v21, 0x3d372713, v19
	v_mul_f32_e32 v21, v21, v19
	v_mov_b32_e32 v22, v19
	v_fmac_f32_e32 v22, v21, v22
	v_mul_f32_e32 v21, 0x3f4c422a, v22
	v_add_f32_e32 v20, v20, v20
	v_add_f32_e32 v21, v21, v21
	v_mul_f32_e32 v20, 0xbfb8aa3b, v20
	v_mul_f32_e32 v21, 0xbfb8aa3b, v21
	v_exp_f32_e32 v20, v20
	v_exp_f32_e32 v21, v21
	v_or_b32_e32 v16, s6, v49
	v_mad_i64_i32 v[16:17], s[2:3], v16, s86, v[74:75]
	v_pk_add_f32 v[20:21], v[20:21], 1.0 op_sel_hi:[1,0]
	v_lshl_add_u64 v[16:17], v[16:17], 0, s[10:11]
	v_rcp_f32_e32 v21, v21
	v_rcp_f32_e32 v20, v20
	s_nop 0
	v_pk_mul_f32 v[18:19], v[20:21], v[18:19]
	s_nop 0
	v_pk_mul_f32 v[12:13], v[12:13], v[18:19]
	v_lshlrev_b32_e32 v18, 16, v71
	v_mul_f32_e32 v20, 0x3d372713, v18
	v_mul_f32_e32 v20, v20, v18
	v_mov_b32_e32 v21, v18
	v_and_b32_e32 v19, 0xffff0000, v71
	v_fmac_f32_e32 v21, v20, v21
	v_mul_f32_e32 v20, 0x3f4c422a, v21
	v_mul_f32_e32 v21, 0x3d372713, v19
	v_mul_f32_e32 v21, v21, v19
	v_mov_b32_e32 v22, v19
	v_fmac_f32_e32 v22, v21, v22
	v_mul_f32_e32 v21, 0x3f4c422a, v22
	v_add_f32_e32 v20, v20, v20
	v_add_f32_e32 v21, v21, v21
	v_mul_f32_e32 v20, 0xbfb8aa3b, v20
	v_mul_f32_e32 v21, 0xbfb8aa3b, v21
	v_exp_f32_e32 v20, v20
	v_exp_f32_e32 v21, v21
	v_cvt_pk_bf16_f32 v12, v12, v13
	v_pk_add_f32 v[20:21], v[20:21], 1.0 op_sel_hi:[1,0]
	s_nop 0
	v_rcp_f32_e32 v21, v21
	v_rcp_f32_e32 v20, v20
	s_nop 0
	v_pk_mul_f32 v[18:19], v[20:21], v[18:19]
	s_nop 0
	v_pk_mul_f32 v[14:15], v[14:15], v[18:19]
	s_nop 0
	v_cvt_pk_bf16_f32 v13, v14, v15
	v_lshl_add_u64 v[14:15], v[16:17], 0, v[54:55]
	flat_store_dwordx2 v[14:15], v[12:13]
	v_lshlrev_b32_e32 v12, 16, v68
	v_mul_f32_e32 v14, 0x3d372713, v12
	v_mul_f32_e32 v14, v14, v12
	v_mov_b32_e32 v15, v12
	v_and_b32_e32 v13, 0xffff0000, v68
	v_fmac_f32_e32 v15, v14, v15
	v_mul_f32_e32 v14, 0x3f4c422a, v15
	v_mul_f32_e32 v15, 0x3d372713, v13
	v_mul_f32_e32 v15, v15, v13
	v_mov_b32_e32 v18, v13
	v_fmac_f32_e32 v18, v15, v18
	v_mul_f32_e32 v15, 0x3f4c422a, v18
	v_add_f32_e32 v14, v14, v14
	v_add_f32_e32 v15, v15, v15
	v_mul_f32_e32 v14, 0xbfb8aa3b, v14
	v_mul_f32_e32 v15, 0xbfb8aa3b, v15
	v_exp_f32_e32 v14, v14
	v_exp_f32_e32 v15, v15
	s_nop 0
	v_pk_add_f32 v[14:15], v[14:15], 1.0 op_sel_hi:[1,0]
	s_nop 0
	v_rcp_f32_e32 v15, v15
	v_rcp_f32_e32 v14, v14
	s_nop 0
	v_pk_mul_f32 v[12:13], v[14:15], v[12:13]
	s_nop 0
	v_pk_mul_f32 v[8:9], v[8:9], v[12:13]
	v_lshlrev_b32_e32 v12, 16, v69
	v_mul_f32_e32 v14, 0x3d372713, v12
	v_mul_f32_e32 v14, v14, v12
	v_mov_b32_e32 v15, v12
	v_and_b32_e32 v13, 0xffff0000, v69
	v_fmac_f32_e32 v15, v14, v15
	v_mul_f32_e32 v14, 0x3f4c422a, v15
	v_mul_f32_e32 v15, 0x3d372713, v13
	v_mul_f32_e32 v15, v15, v13
	v_mov_b32_e32 v18, v13
	v_fmac_f32_e32 v18, v15, v18
	v_mul_f32_e32 v15, 0x3f4c422a, v18
	v_add_f32_e32 v14, v14, v14
	v_add_f32_e32 v15, v15, v15
	v_mul_f32_e32 v14, 0xbfb8aa3b, v14
	v_mul_f32_e32 v15, 0xbfb8aa3b, v15
	v_exp_f32_e32 v14, v14
	v_exp_f32_e32 v15, v15
	v_cvt_pk_bf16_f32 v8, v8, v9
	v_pk_add_f32 v[14:15], v[14:15], 1.0 op_sel_hi:[1,0]
	s_nop 0
	v_rcp_f32_e32 v15, v15
	v_rcp_f32_e32 v14, v14
	s_nop 0
	v_pk_mul_f32 v[12:13], v[14:15], v[12:13]
	s_nop 0
	v_pk_mul_f32 v[10:11], v[10:11], v[12:13]
	s_nop 0
	v_cvt_pk_bf16_f32 v9, v10, v11
	v_lshl_add_u64 v[10:11], v[16:17], 0, v[56:57]
	flat_store_dwordx2 v[10:11], v[8:9]
	v_lshlrev_b32_e32 v8, 16, v66
	v_mul_f32_e32 v10, 0x3d372713, v8
	v_mul_f32_e32 v10, v10, v8
	v_mov_b32_e32 v11, v8
	v_and_b32_e32 v9, 0xffff0000, v66
	v_fmac_f32_e32 v11, v10, v11
	v_mul_f32_e32 v10, 0x3f4c422a, v11
	v_mul_f32_e32 v11, 0x3d372713, v9
	v_mul_f32_e32 v11, v11, v9
	v_mov_b32_e32 v12, v9
	v_fmac_f32_e32 v12, v11, v12
	v_mul_f32_e32 v11, 0x3f4c422a, v12
	v_add_f32_e32 v10, v10, v10
	v_add_f32_e32 v11, v11, v11
	v_mul_f32_e32 v10, 0xbfb8aa3b, v10
	v_mul_f32_e32 v11, 0xbfb8aa3b, v11
	v_exp_f32_e32 v10, v10
	v_exp_f32_e32 v11, v11
	s_nop 0
	v_pk_add_f32 v[10:11], v[10:11], 1.0 op_sel_hi:[1,0]
	s_nop 0
	v_rcp_f32_e32 v11, v11
	v_rcp_f32_e32 v10, v10
	s_nop 0
	v_pk_mul_f32 v[8:9], v[10:11], v[8:9]
	s_nop 0
	v_pk_mul_f32 v[4:5], v[4:5], v[8:9]
	v_lshlrev_b32_e32 v8, 16, v67
	v_mul_f32_e32 v10, 0x3d372713, v8
	v_mul_f32_e32 v10, v10, v8
	v_mov_b32_e32 v11, v8
	v_and_b32_e32 v9, 0xffff0000, v67
	v_fmac_f32_e32 v11, v10, v11
	v_mul_f32_e32 v10, 0x3f4c422a, v11
	v_mul_f32_e32 v11, 0x3d372713, v9
	v_mul_f32_e32 v11, v11, v9
	v_mov_b32_e32 v12, v9
	v_fmac_f32_e32 v12, v11, v12
	v_mul_f32_e32 v11, 0x3f4c422a, v12
	v_add_f32_e32 v10, v10, v10
	v_add_f32_e32 v11, v11, v11
	v_mul_f32_e32 v10, 0xbfb8aa3b, v10
	v_mul_f32_e32 v11, 0xbfb8aa3b, v11
	v_exp_f32_e32 v10, v10
	v_exp_f32_e32 v11, v11
	v_cvt_pk_bf16_f32 v4, v4, v5
	v_pk_add_f32 v[10:11], v[10:11], 1.0 op_sel_hi:[1,0]
	s_nop 0
	v_rcp_f32_e32 v11, v11
	v_rcp_f32_e32 v10, v10
	s_nop 0
	v_pk_mul_f32 v[8:9], v[10:11], v[8:9]
	s_nop 0
	v_pk_mul_f32 v[6:7], v[6:7], v[8:9]
	s_nop 0
	v_cvt_pk_bf16_f32 v5, v6, v7
	v_lshl_add_u64 v[6:7], v[16:17], 0, v[58:59]
	flat_store_dwordx2 v[6:7], v[4:5]
	v_lshlrev_b32_e32 v4, 16, v64
	v_mul_f32_e32 v6, 0x3d372713, v4
	v_mul_f32_e32 v6, v6, v4
	v_mov_b32_e32 v7, v4
	v_and_b32_e32 v5, 0xffff0000, v64
	v_fmac_f32_e32 v7, v6, v7
	v_mul_f32_e32 v6, 0x3f4c422a, v7
	v_mul_f32_e32 v7, 0x3d372713, v5
	v_mul_f32_e32 v7, v7, v5
	v_mov_b32_e32 v8, v5
	v_fmac_f32_e32 v8, v7, v8
	v_mul_f32_e32 v7, 0x3f4c422a, v8
	v_add_f32_e32 v6, v6, v6
	v_add_f32_e32 v7, v7, v7
	v_mul_f32_e32 v6, 0xbfb8aa3b, v6
	v_mul_f32_e32 v7, 0xbfb8aa3b, v7
	v_exp_f32_e32 v6, v6
	v_exp_f32_e32 v7, v7
	s_nop 0
	v_pk_add_f32 v[6:7], v[6:7], 1.0 op_sel_hi:[1,0]
	s_nop 0
	v_rcp_f32_e32 v7, v7
	v_rcp_f32_e32 v6, v6
	s_nop 0
	v_pk_mul_f32 v[4:5], v[6:7], v[4:5]
	s_nop 0
	v_pk_mul_f32 v[0:1], v[0:1], v[4:5]
	v_lshlrev_b32_e32 v4, 16, v65
	v_mul_f32_e32 v6, 0x3d372713, v4
	v_mul_f32_e32 v6, v6, v4
	v_mov_b32_e32 v7, v4
	v_and_b32_e32 v5, 0xffff0000, v65
	v_fmac_f32_e32 v7, v6, v7
	v_mul_f32_e32 v6, 0x3f4c422a, v7
	v_mul_f32_e32 v7, 0x3d372713, v5
	v_mul_f32_e32 v7, v7, v5
	v_mov_b32_e32 v8, v5
	v_fmac_f32_e32 v8, v7, v8
	v_mul_f32_e32 v7, 0x3f4c422a, v8
	v_add_f32_e32 v6, v6, v6
	v_add_f32_e32 v7, v7, v7
	v_mul_f32_e32 v6, 0xbfb8aa3b, v6
	v_mul_f32_e32 v7, 0xbfb8aa3b, v7
	v_exp_f32_e32 v6, v6
	v_exp_f32_e32 v7, v7
	v_cvt_pk_bf16_f32 v0, v0, v1
	v_pk_add_f32 v[6:7], v[6:7], 1.0 op_sel_hi:[1,0]
	s_nop 0
	v_rcp_f32_e32 v7, v7
	v_readlane_b32 s2, v254, 6
	s_add_i32 s18, s18, s2
	s_cmpk_gt_i32 s19, 0xff
	v_rcp_f32_e32 v6, v6
	s_nop 0
	v_pk_mul_f32 v[4:5], v[6:7], v[4:5]
	s_nop 0
	v_pk_mul_f32 v[2:3], v[2:3], v[4:5]
	s_nop 0
	v_cvt_pk_bf16_f32 v1, v2, v3
	v_lshl_add_u64 v[2:3], v[16:17], 0, v[60:61]
	flat_store_dwordx2 v[2:3], v[0:1]
	s_waitcnt lgkmcnt(0)
	s_barrier
	s_cbranch_scc1 .LBB0_465

.LBB0_460:
	s_add_i32 s24, s3, s21
	s_mul_i32 s25, s24, 0x1400
	s_add_i32 s22, s24, 0x58
	s_add_i32 s23, s25, 0x6e000
	s_mul_hi_i32 s22, s22, 0x1400
	s_add_u32 s23, s0, s23
	s_addc_u32 s26, s1, s22
	s_add_u32 s22, s23, 0x2040200
	s_addc_u32 s23, s26, 0
	v_mov_b32_e32 v49, v195
	v_mov_b32_e32 v51, v195
	v_mov_b32_e32 v53, v195
	v_lshl_add_u64 v[24:25], s[22:23], 0, v[194:195]
	v_lshl_add_u64 v[64:65], s[22:23], 0, v[48:49]
	v_lshl_add_u64 v[66:67], s[22:23], 0, v[50:51]
	v_lshl_add_u64 v[68:69], s[22:23], 0, v[52:53]
	s_add_i32 s22, s24, 0x60
	s_add_i32 s23, s25, 0x78000
	s_mul_hi_i32 s22, s22, 0x1400
	s_add_u32 s23, s0, s23
	s_addc_u32 s26, s1, s22
	s_add_u32 s22, s23, 0x2040200
	s_addc_u32 s23, s26, 0
	v_lshl_add_u64 v[26:27], s[22:23], 0, v[194:195]
	v_lshl_add_u64 v[28:29], s[22:23], 0, v[48:49]
	v_lshl_add_u64 v[30:31], s[22:23], 0, v[50:51]
	v_lshl_add_u64 v[62:63], s[22:23], 0, v[52:53]
	s_add_i32 s22, s24, 0x68
	s_add_i32 s23, s25, 0x82000
	s_mul_hi_i32 s22, s22, 0x1400
	s_add_u32 s23, s0, s23
	s_addc_u32 s26, s1, s22
	s_add_u32 s22, s23, 0x2040200
	s_addc_u32 s23, s26, 0
	v_lshl_add_u64 v[16:17], s[22:23], 0, v[194:195]
	v_lshl_add_u64 v[18:19], s[22:23], 0, v[48:49]
	v_lshl_add_u64 v[20:21], s[22:23], 0, v[50:51]
	v_lshl_add_u64 v[22:23], s[22:23], 0, v[52:53]
	s_add_i32 s22, s24, 0x70
	s_add_i32 s23, s25, 0x8c000
	s_mul_hi_i32 s22, s22, 0x1400
	s_add_u32 s23, s0, s23
	s_addc_u32 s26, s1, s22
	s_add_u32 s22, s23, 0x2040200
	s_addc_u32 s23, s26, 0
	s_addk_i32 s24, 0x78
	s_add_i32 s25, s25, 0x96000
	v_lshl_add_u64 v[0:1], s[22:23], 0, v[194:195]
	v_lshl_add_u64 v[2:3], s[22:23], 0, v[48:49]
	v_lshl_add_u64 v[4:5], s[22:23], 0, v[50:51]
	v_lshl_add_u64 v[6:7], s[22:23], 0, v[52:53]
	s_mul_hi_i32 s22, s24, 0x1400
	s_add_u32 s23, s0, s25
	v_lshl_add_u64 v[74:75], s[14:15], 0, v[46:47]
	s_addc_u32 s24, s1, s22
	s_add_u32 s22, s23, 0x2040200
	v_add_co_u32_e32 v76, vcc, s31, v74
	s_addc_u32 s23, s24, 0
	s_nop 0
	v_addc_co_u32_e32 v77, vcc, 0, v75, vcc
	v_lshl_add_u64 v[10:11], s[22:23], 0, v[48:49]
	v_lshl_add_u64 v[12:13], s[22:23], 0, v[50:51]
	flat_load_ushort v49, v[76:77] offset:512
	flat_load_ushort v51, v[76:77] offset:640
	v_lshl_add_u64 v[8:9], s[22:23], 0, v[194:195]
	v_lshl_add_u64 v[14:15], s[22:23], 0, v[52:53]
	v_lshl_add_u64 v[72:73], s[12:13], 0, v[46:47]
	v_lshl_add_u64 v[70:71], s[10:11], 0, v[46:47]
	s_add_i32 s21, s21, 64
	s_add_u32 s10, s10, 0x50000
	s_addc_u32 s11, s11, 0
	s_add_u32 s12, s12, 0x50000
	s_addc_u32 s13, s13, 0
	s_add_u32 s14, s14, 0x50000
	s_addc_u32 s15, s15, 0
	s_cmp_ge_i32 s21, s2
	s_waitcnt vmcnt(0) lgkmcnt(0)
	v_lshlrev_b32_e32 v74, 16, v49
	v_mul_f32_e32 v49, 0x3d372713, v74
	v_lshlrev_b32_e32 v75, 16, v51
	v_mul_f32_e32 v49, v49, v74
	v_mov_b32_e32 v51, v74
	v_fmac_f32_e32 v51, v49, v51
	v_mul_f32_e32 v49, 0x3f4c422a, v51
	v_add_f32_e32 v49, v49, v49
	v_mul_f32_e32 v49, 0xbfb8aa3b, v49
	v_exp_f32_e32 v78, v49
	v_mul_f32_e32 v49, 0x3d372713, v75
	v_mul_f32_e32 v49, v49, v75
	v_mov_b32_e32 v51, v75
	v_fmac_f32_e32 v51, v49, v51
	v_mul_f32_e32 v49, 0x3f4c422a, v51
	v_add_f32_e32 v49, v49, v49
	v_mul_f32_e32 v49, 0xbfb8aa3b, v49
	v_exp_f32_e32 v79, v49
	s_nop 0
	v_pk_add_f32 v[78:79], v[78:79], 1.0 op_sel_hi:[1,0]
	s_nop 0
	v_rcp_f32_e32 v79, v79
	flat_load_ushort v51, v[76:77] offset:768
	flat_load_ushort v53, v[76:77] offset:896
	v_rcp_f32_e32 v78, v78
	s_nop 0
	v_pk_mul_f32 v[74:75], v[78:79], v[74:75]
	s_waitcnt vmcnt(0) lgkmcnt(0)
	v_lshlrev_b32_e32 v76, 16, v51
	v_mul_f32_e32 v51, 0x3d372713, v76
	v_lshlrev_b32_e32 v77, 16, v53
	v_mul_f32_e32 v51, v51, v76
	v_mov_b32_e32 v53, v76
	v_fmac_f32_e32 v53, v51, v53
	v_mul_f32_e32 v51, 0x3f4c422a, v53
	v_add_f32_e32 v51, v51, v51
	v_mul_f32_e32 v51, 0xbfb8aa3b, v51
	v_exp_f32_e32 v94, v51
	v_mul_f32_e32 v51, 0x3d372713, v77
	v_mul_f32_e32 v51, v51, v77
	v_mov_b32_e32 v53, v77
	v_fmac_f32_e32 v53, v51, v53
	v_mul_f32_e32 v51, 0x3f4c422a, v53
	v_add_f32_e32 v51, v51, v51
	v_mul_f32_e32 v51, 0xbfb8aa3b, v51
	v_exp_f32_e32 v95, v51
	v_add_f32_e32 v49, 0, v74
	v_add_f32_e32 v49, v49, v75
	v_pk_mul_f32 v[78:79], v[74:75], v[74:75]
	v_pk_add_f32 v[94:95], v[94:95], 1.0 op_sel_hi:[1,0]
	s_nop 0
	v_rcp_f32_e32 v95, v95
	v_rcp_f32_e32 v94, v94
	s_nop 0
	v_pk_mul_f32 v[76:77], v[94:95], v[76:77]
	v_add_f32_e32 v51, v78, v79
	v_add_f32_e32 v49, v49, v76
	v_add_f32_e32 v49, v49, v77
	v_pk_mul_f32 v[94:95], v[76:77], v[76:77]
	s_nop 0
	v_add_f32_dpp v49, v49, v49 quad_perm:[1,0,3,2] row_mask:0xf bank_mask:0xf bound_ctrl:1
	v_add_f32_e32 v51, v51, v94
	v_add_f32_e32 v51, v51, v95
	v_add_f32_dpp v49, v49, v49 quad_perm:[2,3,0,1] row_mask:0xf bank_mask:0xf bound_ctrl:1
	s_nop 1
	v_add_f32_dpp v49, v49, v49 row_half_mirror row_mask:0xf bank_mask:0xf bound_ctrl:1
	s_nop 1
	v_add_f32_dpp v49, v49, v49 row_mirror row_mask:0xf bank_mask:0xf bound_ctrl:1
	s_nop 0
	v_readlane_b32 s23, v49, 0
	v_readlane_b32 s26, v49, 16
	v_readlane_b32 s25, v49, 32
	v_readlane_b32 s27, v49, 48
	v_add_f32_dpp v49, v51, v51 quad_perm:[1,0,3,2] row_mask:0xf bank_mask:0xf bound_ctrl:1
	v_mov_b32_e32 v79, s26
	v_mov_b32_e32 v95, s27
	v_add_f32_dpp v49, v49, v49 quad_perm:[2,3,0,1] row_mask:0xf bank_mask:0xf bound_ctrl:1
	s_nop 1
	v_add_f32_dpp v49, v49, v49 row_half_mirror row_mask:0xf bank_mask:0xf bound_ctrl:1
	s_nop 1
	v_add_f32_dpp v49, v49, v49 row_mirror row_mask:0xf bank_mask:0xf bound_ctrl:1
	s_nop 0
	v_readlane_b32 s28, v49, 16
	v_readlane_b32 s29, v49, 48
	v_readlane_b32 s22, v49, 0
	v_readlane_b32 s24, v49, 32
	v_mov_b32_e32 v78, s28
	v_mov_b32_e32 v94, s29
	v_pk_add_f32 v[78:79], s[22:23], v[78:79]
	v_pk_add_f32 v[94:95], s[24:25], v[94:95]
	s_nop 0
	v_pk_add_f32 v[78:79], v[78:79], v[94:95]
	s_nop 0
	v_pk_mul_f32 v[78:79], v[78:79], s[34:35] op_sel_hi:[1,0]
	s_nop 0
	v_fma_f32 v49, -v79, v79, v78
	v_max_f32_e32 v49, 0, v49
	v_add_f32_e32 v49, 0x3727c5ac, v49
	v_cmp_gt_f32_e32 vcc, s30, v49
	v_mul_f32_e32 v51, 0x4b800000, v49
	s_nop 0
	v_cndmask_b32_e32 v49, v49, v51, vcc
	v_rsq_f32_e32 v49, v49
	s_nop 0
	v_mul_f32_e32 v51, 0x45800000, v49
	v_cndmask_b32_e32 v49, v49, v51, vcc
	v_add_co_u32_e32 v72, vcc, s31, v72
	v_sub_f32_e32 v51, v74, v79
	s_nop 0
	v_addc_co_u32_e32 v73, vcc, 0, v73, vcc
	flat_load_ushort v74, v[72:73] offset:512
	flat_load_ushort v78, v[72:73] offset:640
	flat_load_ushort v93, v[72:73] offset:768
	s_nop 0
	flat_load_ushort v72, v[72:73] offset:896
	v_add_co_u32_e32 v70, vcc, s31, v70
	v_mul_f32_e32 v51, v51, v49
	s_nop 0
	v_addc_co_u32_e32 v71, vcc, 0, v71, vcc
	flat_load_ushort v73, v[70:71] offset:512
	flat_load_ushort v94, v[70:71] offset:640
	flat_load_ushort v95, v[70:71] offset:768
	s_nop 0
	flat_load_ushort v70, v[70:71] offset:896
	s_nop 0
	flat_load_ushort v71, v[24:25]
	flat_load_ushort v96, v[64:65]
	s_nop 0
	flat_load_ushort v64, v[66:67]
	flat_load_ushort v65, v[68:69]
	flat_load_ushort v53, v[26:27]
	s_nop 0
	flat_load_ushort v28, v[28:29]
	s_nop 0
	flat_load_ushort v26, v[30:31]
	flat_load_ushort v27, v[62:63]
	flat_load_ushort v24, v[16:17]
	flat_load_ushort v25, v[18:19]
	s_nop 0
	flat_load_ushort v18, v[20:21]
	flat_load_ushort v19, v[22:23]
	flat_load_ushort v16, v[0:1]
	flat_load_ushort v17, v[2:3]
	s_nop 0
	flat_load_ushort v4, v[4:5]
	s_nop 0
	flat_load_ushort v5, v[6:7]
	flat_load_ushort v2, v[8:9]
	flat_load_ushort v3, v[10:11]
	flat_load_ushort v0, v[12:13]
	flat_load_ushort v1, v[14:15]
	v_sub_f32_e32 v6, v75, v79
	v_mul_f32_e32 v6, v6, v49
	v_fma_f32 v6, v81, v6, v85
	v_cvt_pk_bf16_f32 v6, v6, s0
	ds_write_b16 v92, v6 offset:16896
	v_sub_f32_e32 v6, v76, v79
	v_mul_f32_e32 v6, v6, v49
	v_fma_f32 v6, v82, v6, v90
	v_cvt_pk_bf16_f32 v6, v6, s0
	ds_write_b16 v92, v6 offset:33792
	v_sub_f32_e32 v6, v77, v79
	v_mul_f32_e32 v6, v6, v49
	v_fma_f32 v6, v83, v6, v91
	v_cvt_pk_bf16_f32 v6, v6, s0
	ds_write_b16 v92, v6 offset:50688
	v_fma_f32 v51, v80, v51, v84
	v_cvt_pk_bf16_f32 v51, v51, s0
	ds_write_b16 v92, v51
	s_waitcnt vmcnt(0) lgkmcnt(0)
	v_lshlrev_b32_e32 v6, 16, v74
	v_mul_f32_e32 v8, 0x3d372713, v6
	v_mul_f32_e32 v8, v8, v6
	v_mov_b32_e32 v9, v6
	v_lshlrev_b32_e32 v7, 16, v78
	v_fmac_f32_e32 v9, v8, v9
	v_mul_f32_e32 v8, 0x3f4c422a, v9
	v_mul_f32_e32 v9, 0x3d372713, v7
	v_mul_f32_e32 v9, v9, v7
	v_mov_b32_e32 v10, v7
	v_fmac_f32_e32 v10, v9, v10
	v_mul_f32_e32 v9, 0x3f4c422a, v10
	v_add_f32_e32 v8, v8, v8
	v_add_f32_e32 v9, v9, v9
	v_mul_f32_e32 v8, 0xbfb8aa3b, v8
	v_mul_f32_e32 v9, 0xbfb8aa3b, v9
	v_exp_f32_e32 v8, v8
	v_exp_f32_e32 v9, v9
	v_lshlrev_b32_e32 v4, 16, v4
	v_lshlrev_b32_e32 v5, 16, v5
	v_lshlrev_b32_e32 v2, 16, v2
	v_pk_add_f32 v[8:9], v[8:9], 1.0 op_sel_hi:[1,0]
	v_lshlrev_b32_e32 v3, 16, v3
	v_lshlrev_b32_e32 v0, 16, v0
	v_lshlrev_b32_e32 v1, 16, v1
	v_rcp_f32_e32 v9, v9
	v_rcp_f32_e32 v8, v8
	v_lshlrev_b32_e32 v10, 16, v93
	v_mul_f32_e32 v12, 0x3d372713, v10
	v_mul_f32_e32 v12, v12, v10
	v_mov_b32_e32 v13, v10
	v_lshlrev_b32_e32 v11, 16, v72
	v_fmac_f32_e32 v13, v12, v13
	v_mul_f32_e32 v12, 0x3f4c422a, v13
	v_mul_f32_e32 v13, 0x3d372713, v11
	v_mul_f32_e32 v13, v13, v11
	v_mov_b32_e32 v15, v11
	v_fmac_f32_e32 v15, v13, v15
	v_mul_f32_e32 v13, 0x3f4c422a, v15
	v_add_f32_e32 v12, v12, v12
	v_add_f32_e32 v13, v13, v13
	v_mul_f32_e32 v12, 0xbfb8aa3b, v12
	v_mul_f32_e32 v13, 0xbfb8aa3b, v13
	v_exp_f32_e32 v12, v12
	v_exp_f32_e32 v13, v13
	v_pk_mul_f32 v[6:7], v[8:9], v[6:7]
	v_pk_add_f32 v[12:13], v[12:13], 1.0 op_sel_hi:[1,0]
	s_nop 0
	v_add_f32_e32 v8, 0, v6
	v_add_f32_e32 v14, v8, v7
	v_pk_mul_f32 v[8:9], v[6:7], v[6:7]
	v_rcp_f32_e32 v13, v13
	v_add_f32_e32 v8, v8, v9
	v_rcp_f32_e32 v12, v12
	s_nop 0
	v_pk_mul_f32 v[10:11], v[12:13], v[10:11]
	s_nop 0
	v_add_f32_e32 v12, v14, v10
	v_add_f32_e32 v14, v12, v11
	v_pk_mul_f32 v[12:13], v[10:11], v[10:11]
	s_nop 0
	v_add_f32_e32 v8, v8, v12
	v_add_f32_e32 v8, v8, v13
	v_add_f32_dpp v9, v14, v14 quad_perm:[1,0,3,2] row_mask:0xf bank_mask:0xf bound_ctrl:1
	s_nop 0
	v_add_f32_dpp v8, v8, v8 quad_perm:[1,0,3,2] row_mask:0xf bank_mask:0xf bound_ctrl:1
	v_add_f32_dpp v9, v9, v9 quad_perm:[2,3,0,1] row_mask:0xf bank_mask:0xf bound_ctrl:1
	s_nop 0
	v_add_f32_dpp v8, v8, v8 quad_perm:[2,3,0,1] row_mask:0xf bank_mask:0xf bound_ctrl:1
	v_add_f32_dpp v9, v9, v9 row_half_mirror row_mask:0xf bank_mask:0xf bound_ctrl:1
	s_nop 0
	v_add_f32_dpp v8, v8, v8 row_half_mirror row_mask:0xf bank_mask:0xf bound_ctrl:1
	v_add_f32_dpp v9, v9, v9 row_mirror row_mask:0xf bank_mask:0xf bound_ctrl:1
	s_nop 0
	v_add_f32_dpp v8, v8, v8 row_mirror row_mask:0xf bank_mask:0xf bound_ctrl:1
	v_readlane_b32 s26, v9, 16
	v_readlane_b32 s27, v9, 48
	v_readlane_b32 s28, v8, 16
	v_readlane_b32 s29, v8, 48
	v_readlane_b32 s23, v9, 0
	v_readlane_b32 s25, v9, 32
	v_readlane_b32 s22, v8, 0
	v_readlane_b32 s24, v8, 32
	v_mov_b32_e32 v8, s28
	v_mov_b32_e32 v9, s26
	v_mov_b32_e32 v12, s29
	v_mov_b32_e32 v13, s27
	v_pk_add_f32 v[8:9], s[22:23], v[8:9]
	v_pk_add_f32 v[12:13], s[24:25], v[12:13]
	s_nop 0
	v_pk_add_f32 v[8:9], v[8:9], v[12:13]
	s_nop 0
	v_pk_mul_f32 v[8:9], v[8:9], s[34:35] op_sel_hi:[1,0]
	s_nop 0
	v_fma_f32 v8, -v9, v9, v8
	v_max_f32_e32 v8, 0, v8
	v_add_f32_e32 v8, 0x3727c5ac, v8
	v_cmp_gt_f32_e32 vcc, s30, v8
	v_mul_f32_e32 v12, 0x4b800000, v8
	v_sub_f32_e32 v6, v6, v9
	v_cndmask_b32_e32 v8, v8, v12, vcc
	v_rsq_f32_e32 v8, v8
	s_nop 0
	v_mul_f32_e32 v12, 0x45800000, v8
	v_cndmask_b32_e32 v8, v8, v12, vcc
	v_mul_f32_e32 v6, v6, v8
	v_fma_f32 v6, v80, v6, v84
	v_cvt_pk_bf16_f32 v6, v6, s0
	ds_write_b16 v92, v6 offset:16
	v_sub_f32_e32 v6, v7, v9
	v_mul_f32_e32 v6, v6, v8
	v_fma_f32 v6, v81, v6, v85
	v_cvt_pk_bf16_f32 v6, v6, s0
	ds_write_b16 v92, v6 offset:16912
	v_sub_f32_e32 v6, v10, v9
	v_mul_f32_e32 v6, v6, v8
	v_fma_f32 v6, v82, v6, v90
	v_cvt_pk_bf16_f32 v6, v6, s0
	ds_write_b16 v92, v6 offset:33808
	v_sub_f32_e32 v6, v11, v9
	v_mul_f32_e32 v6, v6, v8
	v_fma_f32 v6, v83, v6, v91
	v_cvt_pk_bf16_f32 v6, v6, s0
	ds_write_b16 v92, v6 offset:50704
	v_lshlrev_b32_e32 v6, 16, v73
	v_mul_f32_e32 v8, 0x3d372713, v6
	v_mul_f32_e32 v8, v8, v6
	v_mov_b32_e32 v9, v6
	v_lshlrev_b32_e32 v7, 16, v94
	v_fmac_f32_e32 v9, v8, v9
	v_mul_f32_e32 v8, 0x3f4c422a, v9
	v_mul_f32_e32 v9, 0x3d372713, v7
	v_mul_f32_e32 v9, v9, v7
	v_mov_b32_e32 v10, v7
	v_fmac_f32_e32 v10, v9, v10
	v_mul_f32_e32 v9, 0x3f4c422a, v10
	v_add_f32_e32 v8, v8, v8
	v_add_f32_e32 v9, v9, v9
	v_mul_f32_e32 v8, 0xbfb8aa3b, v8
	v_mul_f32_e32 v9, 0xbfb8aa3b, v9
	v_exp_f32_e32 v8, v8
	v_exp_f32_e32 v9, v9
	s_nop 0
	v_pk_add_f32 v[8:9], v[8:9], 1.0 op_sel_hi:[1,0]
	s_nop 0
	v_rcp_f32_e32 v9, v9
	v_rcp_f32_e32 v8, v8
	v_lshlrev_b32_e32 v10, 16, v95
	v_mul_f32_e32 v12, 0x3d372713, v10
	v_mul_f32_e32 v12, v12, v10
	v_mov_b32_e32 v13, v10
	v_lshlrev_b32_e32 v11, 16, v70
	v_fmac_f32_e32 v13, v12, v13
	v_mul_f32_e32 v12, 0x3f4c422a, v13
	v_mul_f32_e32 v13, 0x3d372713, v11
	v_mul_f32_e32 v13, v13, v11
	v_mov_b32_e32 v15, v11
	v_fmac_f32_e32 v15, v13, v15
	v_mul_f32_e32 v13, 0x3f4c422a, v15
	v_add_f32_e32 v12, v12, v12
	v_add_f32_e32 v13, v13, v13
	v_mul_f32_e32 v12, 0xbfb8aa3b, v12
	v_mul_f32_e32 v13, 0xbfb8aa3b, v13
	v_exp_f32_e32 v12, v12
	v_exp_f32_e32 v13, v13
	v_pk_mul_f32 v[6:7], v[8:9], v[6:7]
	v_pk_add_f32 v[12:13], v[12:13], 1.0 op_sel_hi:[1,0]
	s_nop 0
	v_add_f32_e32 v8, 0, v6
	v_add_f32_e32 v14, v8, v7
	v_pk_mul_f32 v[8:9], v[6:7], v[6:7]
	v_rcp_f32_e32 v13, v13
	v_add_f32_e32 v8, v8, v9
	v_rcp_f32_e32 v12, v12
	s_nop 0
	v_pk_mul_f32 v[10:11], v[12:13], v[10:11]
	s_nop 0
	v_add_f32_e32 v12, v14, v10
	v_add_f32_e32 v14, v12, v11
	v_pk_mul_f32 v[12:13], v[10:11], v[10:11]
	s_nop 0
	v_add_f32_e32 v8, v8, v12
	v_add_f32_e32 v8, v8, v13
	v_add_f32_dpp v9, v14, v14 quad_perm:[1,0,3,2] row_mask:0xf bank_mask:0xf bound_ctrl:1
	s_nop 0
	v_add_f32_dpp v8, v8, v8 quad_perm:[1,0,3,2] row_mask:0xf bank_mask:0xf bound_ctrl:1
	v_add_f32_dpp v9, v9, v9 quad_perm:[2,3,0,1] row_mask:0xf bank_mask:0xf bound_ctrl:1
	s_nop 0
	v_add_f32_dpp v8, v8, v8 quad_perm:[2,3,0,1] row_mask:0xf bank_mask:0xf bound_ctrl:1
	v_add_f32_dpp v9, v9, v9 row_half_mirror row_mask:0xf bank_mask:0xf bound_ctrl:1
	s_nop 0
	v_add_f32_dpp v8, v8, v8 row_half_mirror row_mask:0xf bank_mask:0xf bound_ctrl:1
	v_add_f32_dpp v9, v9, v9 row_mirror row_mask:0xf bank_mask:0xf bound_ctrl:1
	s_nop 0
	v_add_f32_dpp v8, v8, v8 row_mirror row_mask:0xf bank_mask:0xf bound_ctrl:1
	v_readlane_b32 s26, v9, 16
	v_readlane_b32 s27, v9, 48
	v_readlane_b32 s28, v8, 16
	v_readlane_b32 s29, v8, 48
	v_readlane_b32 s23, v9, 0
	v_readlane_b32 s25, v9, 32
	v_readlane_b32 s22, v8, 0
	v_readlane_b32 s24, v8, 32
	v_mov_b32_e32 v8, s28
	v_mov_b32_e32 v9, s26
	v_mov_b32_e32 v12, s29
	v_mov_b32_e32 v13, s27
	v_pk_add_f32 v[8:9], s[22:23], v[8:9]
	v_pk_add_f32 v[12:13], s[24:25], v[12:13]
	s_nop 0
	v_pk_add_f32 v[8:9], v[8:9], v[12:13]
	s_nop 0
	v_pk_mul_f32 v[8:9], v[8:9], s[34:35] op_sel_hi:[1,0]
	s_nop 0
	v_fma_f32 v8, -v9, v9, v8
	v_max_f32_e32 v8, 0, v8
	v_add_f32_e32 v8, 0x3727c5ac, v8
	v_cmp_gt_f32_e32 vcc, s30, v8
	v_mul_f32_e32 v12, 0x4b800000, v8
	v_sub_f32_e32 v6, v6, v9
	v_cndmask_b32_e32 v8, v8, v12, vcc
	v_rsq_f32_e32 v8, v8
	s_nop 0
	v_mul_f32_e32 v12, 0x45800000, v8
	v_cndmask_b32_e32 v8, v8, v12, vcc
	v_mul_f32_e32 v6, v6, v8
	v_fma_f32 v6, v80, v6, v84
	v_cvt_pk_bf16_f32 v6, v6, s0
	ds_write_b16 v92, v6 offset:32
	v_sub_f32_e32 v6, v7, v9
	v_mul_f32_e32 v6, v6, v8
	v_fma_f32 v6, v81, v6, v85
	v_cvt_pk_bf16_f32 v6, v6, s0
	ds_write_b16 v92, v6 offset:16928
	v_sub_f32_e32 v6, v10, v9
	v_mul_f32_e32 v6, v6, v8
	v_fma_f32 v6, v82, v6, v90
	v_cvt_pk_bf16_f32 v6, v6, s0
	ds_write_b16 v92, v6 offset:33824
	v_sub_f32_e32 v6, v11, v9
	v_mul_f32_e32 v6, v6, v8
	v_fma_f32 v6, v83, v6, v91
	v_cvt_pk_bf16_f32 v6, v6, s0
	ds_write_b16 v92, v6 offset:50720
	v_lshlrev_b32_e32 v6, 16, v71
	v_mul_f32_e32 v8, 0x3d372713, v6
	v_mul_f32_e32 v8, v8, v6
	v_mov_b32_e32 v9, v6
	v_lshlrev_b32_e32 v7, 16, v96
	v_fmac_f32_e32 v9, v8, v9
	v_mul_f32_e32 v8, 0x3f4c422a, v9
	v_mul_f32_e32 v9, 0x3d372713, v7
	v_mul_f32_e32 v9, v9, v7
	v_mov_b32_e32 v10, v7
	v_fmac_f32_e32 v10, v9, v10
	v_mul_f32_e32 v9, 0x3f4c422a, v10
	v_add_f32_e32 v8, v8, v8
	v_add_f32_e32 v9, v9, v9
	v_mul_f32_e32 v8, 0xbfb8aa3b, v8
	v_mul_f32_e32 v9, 0xbfb8aa3b, v9
	v_exp_f32_e32 v8, v8
	v_exp_f32_e32 v9, v9
	s_nop 0
	v_pk_add_f32 v[8:9], v[8:9], 1.0 op_sel_hi:[1,0]
	s_nop 0
	v_rcp_f32_e32 v9, v9
	v_rcp_f32_e32 v8, v8
	v_lshlrev_b32_e32 v10, 16, v64
	v_mul_f32_e32 v12, 0x3d372713, v10
	v_mul_f32_e32 v12, v12, v10
	v_mov_b32_e32 v13, v10
	v_lshlrev_b32_e32 v11, 16, v65
	v_fmac_f32_e32 v13, v12, v13
	v_mul_f32_e32 v12, 0x3f4c422a, v13
	v_mul_f32_e32 v13, 0x3d372713, v11
	v_mul_f32_e32 v13, v13, v11
	v_mov_b32_e32 v15, v11
	v_fmac_f32_e32 v15, v13, v15
	v_mul_f32_e32 v13, 0x3f4c422a, v15
	v_add_f32_e32 v12, v12, v12
	v_add_f32_e32 v13, v13, v13
	v_mul_f32_e32 v12, 0xbfb8aa3b, v12
	v_mul_f32_e32 v13, 0xbfb8aa3b, v13
	v_exp_f32_e32 v12, v12
	v_exp_f32_e32 v13, v13
	v_pk_mul_f32 v[6:7], v[8:9], v[6:7]
	v_pk_add_f32 v[12:13], v[12:13], 1.0 op_sel_hi:[1,0]
	s_nop 0
	v_add_f32_e32 v8, 0, v6
	v_add_f32_e32 v14, v8, v7
	v_pk_mul_f32 v[8:9], v[6:7], v[6:7]
	v_rcp_f32_e32 v13, v13
	v_add_f32_e32 v8, v8, v9
	v_rcp_f32_e32 v12, v12
	s_nop 0
	v_pk_mul_f32 v[10:11], v[12:13], v[10:11]
	s_nop 0
	v_add_f32_e32 v12, v14, v10
	v_add_f32_e32 v14, v12, v11
	v_pk_mul_f32 v[12:13], v[10:11], v[10:11]
	s_nop 0
	v_add_f32_e32 v8, v8, v12
	v_add_f32_e32 v8, v8, v13
	v_add_f32_dpp v9, v14, v14 quad_perm:[1,0,3,2] row_mask:0xf bank_mask:0xf bound_ctrl:1
	s_nop 0
	v_add_f32_dpp v8, v8, v8 quad_perm:[1,0,3,2] row_mask:0xf bank_mask:0xf bound_ctrl:1
	v_add_f32_dpp v9, v9, v9 quad_perm:[2,3,0,1] row_mask:0xf bank_mask:0xf bound_ctrl:1
	s_nop 0
	v_add_f32_dpp v8, v8, v8 quad_perm:[2,3,0,1] row_mask:0xf bank_mask:0xf bound_ctrl:1
	v_add_f32_dpp v9, v9, v9 row_half_mirror row_mask:0xf bank_mask:0xf bound_ctrl:1
	s_nop 0
	v_add_f32_dpp v8, v8, v8 row_half_mirror row_mask:0xf bank_mask:0xf bound_ctrl:1
	v_add_f32_dpp v9, v9, v9 row_mirror row_mask:0xf bank_mask:0xf bound_ctrl:1
	s_nop 0
	v_add_f32_dpp v8, v8, v8 row_mirror row_mask:0xf bank_mask:0xf bound_ctrl:1
	v_readlane_b32 s26, v9, 16
	v_readlane_b32 s27, v9, 48
	v_readlane_b32 s28, v8, 16
	v_readlane_b32 s29, v8, 48
	v_readlane_b32 s23, v9, 0
	v_readlane_b32 s25, v9, 32
	v_readlane_b32 s22, v8, 0
	v_readlane_b32 s24, v8, 32
	v_mov_b32_e32 v8, s28
	v_mov_b32_e32 v9, s26
	v_mov_b32_e32 v12, s29
	v_mov_b32_e32 v13, s27
	v_pk_add_f32 v[8:9], s[22:23], v[8:9]
	v_pk_add_f32 v[12:13], s[24:25], v[12:13]
	s_nop 0
	v_pk_add_f32 v[8:9], v[8:9], v[12:13]
	s_nop 0
	v_pk_mul_f32 v[8:9], v[8:9], s[34:35] op_sel_hi:[1,0]
	s_nop 0
	v_fma_f32 v8, -v9, v9, v8
	v_max_f32_e32 v8, 0, v8
	v_add_f32_e32 v8, 0x3727c5ac, v8
	v_cmp_gt_f32_e32 vcc, s30, v8
	v_mul_f32_e32 v12, 0x4b800000, v8
	v_sub_f32_e32 v6, v6, v9
	v_cndmask_b32_e32 v8, v8, v12, vcc
	v_rsq_f32_e32 v8, v8
	s_nop 0
	v_mul_f32_e32 v12, 0x45800000, v8
	v_cndmask_b32_e32 v8, v8, v12, vcc
	v_mul_f32_e32 v6, v6, v8
	v_fma_f32 v6, v80, v6, v84
	v_cvt_pk_bf16_f32 v6, v6, s0
	ds_write_b16 v92, v6 offset:48
	v_sub_f32_e32 v6, v7, v9
	v_mul_f32_e32 v6, v6, v8
	v_fma_f32 v6, v81, v6, v85
	v_cvt_pk_bf16_f32 v6, v6, s0
	ds_write_b16 v92, v6 offset:16944
	v_sub_f32_e32 v6, v10, v9
	v_mul_f32_e32 v6, v6, v8
	v_fma_f32 v6, v82, v6, v90
	v_cvt_pk_bf16_f32 v6, v6, s0
	ds_write_b16 v92, v6 offset:33840
	v_sub_f32_e32 v6, v11, v9
	v_mul_f32_e32 v6, v6, v8
	v_fma_f32 v6, v83, v6, v91
	v_cvt_pk_bf16_f32 v6, v6, s0
	ds_write_b16 v92, v6 offset:50736
	v_lshlrev_b32_e32 v6, 16, v53
	v_mul_f32_e32 v8, 0x3d372713, v6
	v_mul_f32_e32 v8, v8, v6
	v_mov_b32_e32 v9, v6
	v_lshlrev_b32_e32 v7, 16, v28
	v_fmac_f32_e32 v9, v8, v9
	v_mul_f32_e32 v8, 0x3f4c422a, v9
	v_mul_f32_e32 v9, 0x3d372713, v7
	v_mul_f32_e32 v9, v9, v7
	v_mov_b32_e32 v10, v7
	v_fmac_f32_e32 v10, v9, v10
	v_mul_f32_e32 v9, 0x3f4c422a, v10
	v_add_f32_e32 v8, v8, v8
	v_add_f32_e32 v9, v9, v9
	v_mul_f32_e32 v8, 0xbfb8aa3b, v8
	v_mul_f32_e32 v9, 0xbfb8aa3b, v9
	v_exp_f32_e32 v8, v8
	v_exp_f32_e32 v9, v9
	s_nop 0
	v_pk_add_f32 v[8:9], v[8:9], 1.0 op_sel_hi:[1,0]
	s_nop 0
	v_rcp_f32_e32 v9, v9
	v_rcp_f32_e32 v8, v8
	v_lshlrev_b32_e32 v10, 16, v26
	v_mul_f32_e32 v12, 0x3d372713, v10
	v_mul_f32_e32 v12, v12, v10
	v_mov_b32_e32 v13, v10
	v_lshlrev_b32_e32 v11, 16, v27
	v_fmac_f32_e32 v13, v12, v13
	v_mul_f32_e32 v12, 0x3f4c422a, v13
	v_mul_f32_e32 v13, 0x3d372713, v11
	v_mul_f32_e32 v13, v13, v11
	v_mov_b32_e32 v15, v11
	v_fmac_f32_e32 v15, v13, v15
	v_mul_f32_e32 v13, 0x3f4c422a, v15
	v_add_f32_e32 v12, v12, v12
	v_add_f32_e32 v13, v13, v13
	v_mul_f32_e32 v12, 0xbfb8aa3b, v12
	v_mul_f32_e32 v13, 0xbfb8aa3b, v13
	v_exp_f32_e32 v12, v12
	v_exp_f32_e32 v13, v13
	v_pk_mul_f32 v[6:7], v[8:9], v[6:7]
	v_pk_add_f32 v[12:13], v[12:13], 1.0 op_sel_hi:[1,0]
	s_nop 0
	v_add_f32_e32 v8, 0, v6
	v_add_f32_e32 v14, v8, v7
	v_pk_mul_f32 v[8:9], v[6:7], v[6:7]
	v_rcp_f32_e32 v13, v13
	v_add_f32_e32 v8, v8, v9
	v_rcp_f32_e32 v12, v12
	s_nop 0
	v_pk_mul_f32 v[10:11], v[12:13], v[10:11]
	s_nop 0
	v_add_f32_e32 v12, v14, v10
	v_add_f32_e32 v14, v12, v11
	v_pk_mul_f32 v[12:13], v[10:11], v[10:11]
	s_nop 0
	v_add_f32_e32 v8, v8, v12
	v_add_f32_e32 v8, v8, v13
	v_add_f32_dpp v9, v14, v14 quad_perm:[1,0,3,2] row_mask:0xf bank_mask:0xf bound_ctrl:1
	s_nop 0
	v_add_f32_dpp v8, v8, v8 quad_perm:[1,0,3,2] row_mask:0xf bank_mask:0xf bound_ctrl:1
	v_add_f32_dpp v9, v9, v9 quad_perm:[2,3,0,1] row_mask:0xf bank_mask:0xf bound_ctrl:1
	s_nop 0
	v_add_f32_dpp v8, v8, v8 quad_perm:[2,3,0,1] row_mask:0xf bank_mask:0xf bound_ctrl:1
	v_add_f32_dpp v9, v9, v9 row_half_mirror row_mask:0xf bank_mask:0xf bound_ctrl:1
	s_nop 0
	v_add_f32_dpp v8, v8, v8 row_half_mirror row_mask:0xf bank_mask:0xf bound_ctrl:1
	v_add_f32_dpp v9, v9, v9 row_mirror row_mask:0xf bank_mask:0xf bound_ctrl:1
	s_nop 0
	v_add_f32_dpp v8, v8, v8 row_mirror row_mask:0xf bank_mask:0xf bound_ctrl:1
	v_readlane_b32 s26, v9, 16
	v_readlane_b32 s27, v9, 48
	v_readlane_b32 s28, v8, 16
	v_readlane_b32 s29, v8, 48
	v_readlane_b32 s23, v9, 0
	v_readlane_b32 s25, v9, 32
	v_readlane_b32 s22, v8, 0
	v_readlane_b32 s24, v8, 32
	v_mov_b32_e32 v8, s28
	v_mov_b32_e32 v9, s26
	v_mov_b32_e32 v12, s29
	v_mov_b32_e32 v13, s27
	v_pk_add_f32 v[8:9], s[22:23], v[8:9]
	v_pk_add_f32 v[12:13], s[24:25], v[12:13]
	s_nop 0
	v_pk_add_f32 v[8:9], v[8:9], v[12:13]
	s_nop 0
	v_pk_mul_f32 v[8:9], v[8:9], s[34:35] op_sel_hi:[1,0]
	s_nop 0
	v_fma_f32 v8, -v9, v9, v8
	v_max_f32_e32 v8, 0, v8
	v_add_f32_e32 v8, 0x3727c5ac, v8
	v_cmp_gt_f32_e32 vcc, s30, v8
	v_mul_f32_e32 v12, 0x4b800000, v8
	v_sub_f32_e32 v6, v6, v9
	v_cndmask_b32_e32 v8, v8, v12, vcc
	v_rsq_f32_e32 v8, v8
	s_nop 0
	v_mul_f32_e32 v12, 0x45800000, v8
	v_cndmask_b32_e32 v8, v8, v12, vcc
	v_mul_f32_e32 v6, v6, v8
	v_fma_f32 v6, v80, v6, v84
	v_cvt_pk_bf16_f32 v6, v6, s0
	ds_write_b16 v92, v6 offset:64
	v_sub_f32_e32 v6, v7, v9
	v_mul_f32_e32 v6, v6, v8
	v_fma_f32 v6, v81, v6, v85
	v_cvt_pk_bf16_f32 v6, v6, s0
	ds_write_b16 v92, v6 offset:16960
	v_sub_f32_e32 v6, v10, v9
	v_mul_f32_e32 v6, v6, v8
	v_fma_f32 v6, v82, v6, v90
	v_cvt_pk_bf16_f32 v6, v6, s0
	ds_write_b16 v92, v6 offset:33856
	v_sub_f32_e32 v6, v11, v9
	v_mul_f32_e32 v6, v6, v8
	v_fma_f32 v6, v83, v6, v91
	v_cvt_pk_bf16_f32 v6, v6, s0
	ds_write_b16 v92, v6 offset:50752
	v_lshlrev_b32_e32 v6, 16, v24
	v_mul_f32_e32 v8, 0x3d372713, v6
	v_mul_f32_e32 v8, v8, v6
	v_mov_b32_e32 v9, v6
	v_lshlrev_b32_e32 v7, 16, v25
	v_fmac_f32_e32 v9, v8, v9
	v_mul_f32_e32 v8, 0x3f4c422a, v9
	v_mul_f32_e32 v9, 0x3d372713, v7
	v_mul_f32_e32 v9, v9, v7
	v_mov_b32_e32 v10, v7
	v_fmac_f32_e32 v10, v9, v10
	v_mul_f32_e32 v9, 0x3f4c422a, v10
	v_add_f32_e32 v8, v8, v8
	v_add_f32_e32 v9, v9, v9
	v_mul_f32_e32 v8, 0xbfb8aa3b, v8
	v_mul_f32_e32 v9, 0xbfb8aa3b, v9
	v_exp_f32_e32 v8, v8
	v_exp_f32_e32 v9, v9
	s_nop 0
	v_pk_add_f32 v[8:9], v[8:9], 1.0 op_sel_hi:[1,0]
	s_nop 0
	v_rcp_f32_e32 v9, v9
	v_rcp_f32_e32 v8, v8
	v_lshlrev_b32_e32 v10, 16, v18
	v_mul_f32_e32 v12, 0x3d372713, v10
	v_mul_f32_e32 v12, v12, v10
	v_mov_b32_e32 v13, v10
	v_lshlrev_b32_e32 v11, 16, v19
	v_fmac_f32_e32 v13, v12, v13
	v_mul_f32_e32 v12, 0x3f4c422a, v13
	v_mul_f32_e32 v13, 0x3d372713, v11
	v_mul_f32_e32 v13, v13, v11
	v_mov_b32_e32 v15, v11
	v_fmac_f32_e32 v15, v13, v15
	v_mul_f32_e32 v13, 0x3f4c422a, v15
	v_add_f32_e32 v12, v12, v12
	v_add_f32_e32 v13, v13, v13
	v_mul_f32_e32 v12, 0xbfb8aa3b, v12
	v_mul_f32_e32 v13, 0xbfb8aa3b, v13
	v_exp_f32_e32 v12, v12
	v_exp_f32_e32 v13, v13
	v_pk_mul_f32 v[6:7], v[8:9], v[6:7]
	v_pk_add_f32 v[12:13], v[12:13], 1.0 op_sel_hi:[1,0]
	s_nop 0
	v_add_f32_e32 v8, 0, v6
	v_add_f32_e32 v14, v8, v7
	v_pk_mul_f32 v[8:9], v[6:7], v[6:7]
	v_rcp_f32_e32 v13, v13
	v_add_f32_e32 v8, v8, v9
	v_rcp_f32_e32 v12, v12
	s_nop 0
	v_pk_mul_f32 v[10:11], v[12:13], v[10:11]
	s_nop 0
	v_add_f32_e32 v12, v14, v10
	v_add_f32_e32 v14, v12, v11
	v_pk_mul_f32 v[12:13], v[10:11], v[10:11]
	s_nop 0
	v_add_f32_e32 v8, v8, v12
	v_add_f32_e32 v8, v8, v13
	v_add_f32_dpp v9, v14, v14 quad_perm:[1,0,3,2] row_mask:0xf bank_mask:0xf bound_ctrl:1
	s_nop 0
	v_add_f32_dpp v8, v8, v8 quad_perm:[1,0,3,2] row_mask:0xf bank_mask:0xf bound_ctrl:1
	v_add_f32_dpp v9, v9, v9 quad_perm:[2,3,0,1] row_mask:0xf bank_mask:0xf bound_ctrl:1
	s_nop 0
	v_add_f32_dpp v8, v8, v8 quad_perm:[2,3,0,1] row_mask:0xf bank_mask:0xf bound_ctrl:1
	v_add_f32_dpp v9, v9, v9 row_half_mirror row_mask:0xf bank_mask:0xf bound_ctrl:1
	s_nop 0
	v_add_f32_dpp v8, v8, v8 row_half_mirror row_mask:0xf bank_mask:0xf bound_ctrl:1
	v_add_f32_dpp v9, v9, v9 row_mirror row_mask:0xf bank_mask:0xf bound_ctrl:1
	s_nop 0
	v_add_f32_dpp v8, v8, v8 row_mirror row_mask:0xf bank_mask:0xf bound_ctrl:1
	v_readlane_b32 s26, v9, 16
	v_readlane_b32 s27, v9, 48
	v_readlane_b32 s28, v8, 16
	v_readlane_b32 s29, v8, 48
	v_readlane_b32 s23, v9, 0
	v_readlane_b32 s25, v9, 32
	v_readlane_b32 s22, v8, 0
	v_readlane_b32 s24, v8, 32
	v_mov_b32_e32 v8, s28
	v_mov_b32_e32 v9, s26
	v_mov_b32_e32 v12, s29
	v_mov_b32_e32 v13, s27
	v_pk_add_f32 v[8:9], s[22:23], v[8:9]
	v_pk_add_f32 v[12:13], s[24:25], v[12:13]
	s_nop 0
	v_pk_add_f32 v[8:9], v[8:9], v[12:13]
	s_nop 0
	v_pk_mul_f32 v[8:9], v[8:9], s[34:35] op_sel_hi:[1,0]
	s_nop 0
	v_fma_f32 v8, -v9, v9, v8
	v_max_f32_e32 v8, 0, v8
	v_add_f32_e32 v8, 0x3727c5ac, v8
	v_cmp_gt_f32_e32 vcc, s30, v8
	v_mul_f32_e32 v12, 0x4b800000, v8
	v_sub_f32_e32 v6, v6, v9
	v_cndmask_b32_e32 v8, v8, v12, vcc
	v_rsq_f32_e32 v8, v8
	s_nop 0
	v_mul_f32_e32 v12, 0x45800000, v8
	v_cndmask_b32_e32 v8, v8, v12, vcc
	v_mul_f32_e32 v6, v6, v8
	v_fma_f32 v6, v80, v6, v84
	v_cvt_pk_bf16_f32 v6, v6, s0
	ds_write_b16 v92, v6 offset:80
	v_sub_f32_e32 v6, v7, v9
	v_mul_f32_e32 v6, v6, v8
	v_fma_f32 v6, v81, v6, v85
	v_cvt_pk_bf16_f32 v6, v6, s0
	ds_write_b16 v92, v6 offset:16976
	v_sub_f32_e32 v6, v10, v9
	v_mul_f32_e32 v6, v6, v8
	v_fma_f32 v6, v82, v6, v90
	v_cvt_pk_bf16_f32 v6, v6, s0
	ds_write_b16 v92, v6 offset:33872
	v_sub_f32_e32 v6, v11, v9
	v_mul_f32_e32 v6, v6, v8
	v_fma_f32 v6, v83, v6, v91
	v_cvt_pk_bf16_f32 v6, v6, s0
	ds_write_b16 v92, v6 offset:50768
	v_lshlrev_b32_e32 v6, 16, v16
	v_mul_f32_e32 v8, 0x3d372713, v6
	v_mul_f32_e32 v8, v8, v6
	v_mov_b32_e32 v9, v6
	v_lshlrev_b32_e32 v7, 16, v17
	v_fmac_f32_e32 v9, v8, v9
	v_mul_f32_e32 v8, 0x3f4c422a, v9
	v_mul_f32_e32 v9, 0x3d372713, v7
	v_mul_f32_e32 v9, v9, v7
	v_mov_b32_e32 v10, v7
	v_fmac_f32_e32 v10, v9, v10
	v_mul_f32_e32 v9, 0x3f4c422a, v10
	v_add_f32_e32 v8, v8, v8
	v_add_f32_e32 v9, v9, v9
	v_mul_f32_e32 v8, 0xbfb8aa3b, v8
	v_mul_f32_e32 v9, 0xbfb8aa3b, v9
	v_exp_f32_e32 v8, v8
	v_exp_f32_e32 v9, v9
	s_nop 0
	v_pk_add_f32 v[8:9], v[8:9], 1.0 op_sel_hi:[1,0]
	s_nop 0
	v_rcp_f32_e32 v9, v9
	v_rcp_f32_e32 v8, v8
	v_mul_f32_e32 v10, 0x3d372713, v4
	v_mul_f32_e32 v10, v10, v4
	v_mov_b32_e32 v11, v4
	v_fmac_f32_e32 v11, v10, v11
	v_mul_f32_e32 v10, 0x3f4c422a, v11
	v_mul_f32_e32 v11, 0x3d372713, v5
	v_mul_f32_e32 v11, v11, v5
	v_mov_b32_e32 v13, v5
	v_fmac_f32_e32 v13, v11, v13
	v_mul_f32_e32 v11, 0x3f4c422a, v13
	v_add_f32_e32 v10, v10, v10
	v_add_f32_e32 v11, v11, v11
	v_mul_f32_e32 v10, 0xbfb8aa3b, v10
	v_mul_f32_e32 v11, 0xbfb8aa3b, v11
	v_exp_f32_e32 v10, v10
	v_exp_f32_e32 v11, v11
	v_pk_mul_f32 v[6:7], v[8:9], v[6:7]
	v_pk_add_f32 v[10:11], v[10:11], 1.0 op_sel_hi:[1,0]
	s_nop 0
	v_add_f32_e32 v8, 0, v6
	v_add_f32_e32 v12, v8, v7
	v_pk_mul_f32 v[8:9], v[6:7], v[6:7]
	v_rcp_f32_e32 v11, v11
	v_add_f32_e32 v8, v8, v9
	v_rcp_f32_e32 v10, v10
	s_nop 0
	v_pk_mul_f32 v[4:5], v[10:11], v[4:5]
	s_nop 0
	v_add_f32_e32 v10, v12, v4
	v_add_f32_e32 v12, v10, v5
	v_pk_mul_f32 v[10:11], v[4:5], v[4:5]
	s_nop 0
	v_add_f32_e32 v8, v8, v10
	v_add_f32_e32 v8, v8, v11
	v_add_f32_dpp v9, v12, v12 quad_perm:[1,0,3,2] row_mask:0xf bank_mask:0xf bound_ctrl:1
	s_nop 0
	v_add_f32_dpp v8, v8, v8 quad_perm:[1,0,3,2] row_mask:0xf bank_mask:0xf bound_ctrl:1
	v_add_f32_dpp v9, v9, v9 quad_perm:[2,3,0,1] row_mask:0xf bank_mask:0xf bound_ctrl:1
	s_nop 0
	v_add_f32_dpp v8, v8, v8 quad_perm:[2,3,0,1] row_mask:0xf bank_mask:0xf bound_ctrl:1
	v_add_f32_dpp v9, v9, v9 row_half_mirror row_mask:0xf bank_mask:0xf bound_ctrl:1
	s_nop 0
	v_add_f32_dpp v8, v8, v8 row_half_mirror row_mask:0xf bank_mask:0xf bound_ctrl:1
	v_add_f32_dpp v9, v9, v9 row_mirror row_mask:0xf bank_mask:0xf bound_ctrl:1
	s_nop 0
	v_add_f32_dpp v8, v8, v8 row_mirror row_mask:0xf bank_mask:0xf bound_ctrl:1
	v_readlane_b32 s26, v9, 16
	v_readlane_b32 s27, v9, 48
	v_readlane_b32 s28, v8, 16
	v_readlane_b32 s29, v8, 48
	v_readlane_b32 s23, v9, 0
	v_readlane_b32 s25, v9, 32
	v_readlane_b32 s22, v8, 0
	v_readlane_b32 s24, v8, 32
	v_mov_b32_e32 v8, s28
	v_mov_b32_e32 v9, s26
	v_mov_b32_e32 v10, s29
	v_mov_b32_e32 v11, s27
	v_pk_add_f32 v[8:9], s[22:23], v[8:9]
	v_pk_add_f32 v[10:11], s[24:25], v[10:11]
	s_nop 0
	v_pk_add_f32 v[8:9], v[8:9], v[10:11]
	s_nop 0
	v_pk_mul_f32 v[8:9], v[8:9], s[34:35] op_sel_hi:[1,0]
	s_nop 0
	v_fma_f32 v8, -v9, v9, v8
	v_max_f32_e32 v8, 0, v8
	v_add_f32_e32 v8, 0x3727c5ac, v8
	v_cmp_gt_f32_e32 vcc, s30, v8
	v_mul_f32_e32 v10, 0x4b800000, v8
	v_sub_f32_e32 v4, v4, v9
	v_cndmask_b32_e32 v8, v8, v10, vcc
	v_rsq_f32_e32 v8, v8
	v_sub_f32_e32 v6, v6, v9
	v_mul_f32_e32 v10, 0x45800000, v8
	v_cndmask_b32_e32 v8, v8, v10, vcc
	v_mul_f32_e32 v4, v4, v8
	v_fma_f32 v4, v82, v4, v90
	v_cvt_pk_bf16_f32 v4, v4, s0
	ds_write_b16 v92, v4 offset:33888
	v_sub_f32_e32 v4, v5, v9
	v_mul_f32_e32 v6, v6, v8
	v_mul_f32_e32 v4, v4, v8
	v_fma_f32 v6, v80, v6, v84
	v_fma_f32 v4, v83, v4, v91
	v_cvt_pk_bf16_f32 v6, v6, s0
	v_cvt_pk_bf16_f32 v4, v4, s0
	ds_write_b16 v92, v6 offset:96
	v_sub_f32_e32 v6, v7, v9
	ds_write_b16 v92, v4 offset:50784
	v_mul_f32_e32 v4, 0x3d372713, v2
	v_mul_f32_e32 v6, v6, v8
	v_mul_f32_e32 v4, v4, v2
	v_mov_b32_e32 v5, v2
	v_fma_f32 v6, v81, v6, v85
	v_fmac_f32_e32 v5, v4, v5
	v_cvt_pk_bf16_f32 v6, v6, s0
	v_mul_f32_e32 v4, 0x3f4c422a, v5
	v_mul_f32_e32 v5, 0x3d372713, v3
	ds_write_b16 v92, v6 offset:16992
	v_mul_f32_e32 v5, v5, v3
	v_mov_b32_e32 v6, v3
	v_fmac_f32_e32 v6, v5, v6
	v_mul_f32_e32 v5, 0x3f4c422a, v6
	v_add_f32_e32 v4, v4, v4
	v_add_f32_e32 v5, v5, v5
	v_mul_f32_e32 v4, 0xbfb8aa3b, v4
	v_mul_f32_e32 v5, 0xbfb8aa3b, v5
	v_exp_f32_e32 v4, v4
	v_exp_f32_e32 v5, v5
	s_nop 0
	v_pk_add_f32 v[4:5], v[4:5], 1.0 op_sel_hi:[1,0]
	s_nop 0
	v_rcp_f32_e32 v5, v5
	v_rcp_f32_e32 v4, v4
	v_mul_f32_e32 v6, 0x3d372713, v0
	v_mul_f32_e32 v6, v6, v0
	v_mov_b32_e32 v7, v0
	v_fmac_f32_e32 v7, v6, v7
	v_mul_f32_e32 v6, 0x3f4c422a, v7
	v_mul_f32_e32 v7, 0x3d372713, v1
	v_mul_f32_e32 v7, v7, v1
	v_mov_b32_e32 v9, v1
	v_fmac_f32_e32 v9, v7, v9
	v_mul_f32_e32 v7, 0x3f4c422a, v9
	v_add_f32_e32 v6, v6, v6
	v_add_f32_e32 v7, v7, v7
	v_mul_f32_e32 v6, 0xbfb8aa3b, v6
	v_mul_f32_e32 v7, 0xbfb8aa3b, v7
	v_exp_f32_e32 v6, v6
	v_exp_f32_e32 v7, v7
	v_pk_mul_f32 v[2:3], v[4:5], v[2:3]
	v_pk_add_f32 v[6:7], v[6:7], 1.0 op_sel_hi:[1,0]
	s_nop 0
	v_add_f32_e32 v4, 0, v2
	v_add_f32_e32 v8, v4, v3
	v_pk_mul_f32 v[4:5], v[2:3], v[2:3]
	v_rcp_f32_e32 v7, v7
	v_add_f32_e32 v4, v4, v5
	v_rcp_f32_e32 v6, v6
	s_nop 0
	v_pk_mul_f32 v[0:1], v[6:7], v[0:1]
	s_nop 0
	v_add_f32_e32 v6, v8, v0
	v_add_f32_e32 v8, v6, v1
	v_pk_mul_f32 v[6:7], v[0:1], v[0:1]
	s_nop 0
	v_add_f32_e32 v4, v4, v6
	v_add_f32_e32 v4, v4, v7
	v_add_f32_dpp v5, v8, v8 quad_perm:[1,0,3,2] row_mask:0xf bank_mask:0xf bound_ctrl:1
	s_nop 0
	v_add_f32_dpp v4, v4, v4 quad_perm:[1,0,3,2] row_mask:0xf bank_mask:0xf bound_ctrl:1
	v_add_f32_dpp v5, v5, v5 quad_perm:[2,3,0,1] row_mask:0xf bank_mask:0xf bound_ctrl:1
	s_nop 0
	v_add_f32_dpp v4, v4, v4 quad_perm:[2,3,0,1] row_mask:0xf bank_mask:0xf bound_ctrl:1
	v_add_f32_dpp v5, v5, v5 row_half_mirror row_mask:0xf bank_mask:0xf bound_ctrl:1
	s_nop 0
	v_add_f32_dpp v4, v4, v4 row_half_mirror row_mask:0xf bank_mask:0xf bound_ctrl:1
	v_add_f32_dpp v5, v5, v5 row_mirror row_mask:0xf bank_mask:0xf bound_ctrl:1
	s_nop 0
	v_add_f32_dpp v4, v4, v4 row_mirror row_mask:0xf bank_mask:0xf bound_ctrl:1
	v_readlane_b32 s26, v5, 16
	v_readlane_b32 s27, v5, 48
	v_readlane_b32 s28, v4, 16
	v_readlane_b32 s29, v4, 48
	v_readlane_b32 s23, v5, 0
	v_readlane_b32 s25, v5, 32
	v_readlane_b32 s22, v4, 0
	v_readlane_b32 s24, v4, 32
	v_mov_b32_e32 v4, s28
	v_mov_b32_e32 v5, s26
	v_mov_b32_e32 v6, s29
	v_mov_b32_e32 v7, s27
	v_pk_add_f32 v[4:5], s[22:23], v[4:5]
	v_pk_add_f32 v[6:7], s[24:25], v[6:7]
	s_nop 0
	v_pk_add_f32 v[4:5], v[4:5], v[6:7]
	s_nop 0
	v_pk_mul_f32 v[4:5], v[4:5], s[34:35] op_sel_hi:[1,0]
	s_nop 0
	v_fma_f32 v4, -v5, v5, v4
	v_max_f32_e32 v4, 0, v4
	v_add_f32_e32 v4, 0x3727c5ac, v4
	v_cmp_gt_f32_e32 vcc, s30, v4
	v_mul_f32_e32 v6, 0x4b800000, v4
	v_sub_f32_e32 v2, v2, v5
	v_cndmask_b32_e32 v4, v4, v6, vcc
	v_rsq_f32_e32 v4, v4
	v_sub_f32_e32 v0, v0, v5
	v_mul_f32_e32 v6, 0x45800000, v4
	v_cndmask_b32_e32 v4, v4, v6, vcc
	v_mul_f32_e32 v2, v2, v4
	v_mul_f32_e32 v0, v0, v4
	v_fma_f32 v2, v80, v2, v84
	v_fma_f32 v0, v82, v0, v90
	v_cvt_pk_bf16_f32 v2, v2, s0
	v_cvt_pk_bf16_f32 v0, v0, s0
	ds_write_b16 v92, v2 offset:112
	v_sub_f32_e32 v2, v3, v5
	ds_write_b16 v92, v0 offset:33904
	v_sub_f32_e32 v0, v1, v5
	v_mul_f32_e32 v2, v2, v4
	v_mul_f32_e32 v0, v0, v4
	v_fma_f32 v2, v81, v2, v85
	v_fma_f32 v0, v83, v0, v91
	v_cvt_pk_bf16_f32 v2, v2, s0
	v_cvt_pk_bf16_f32 v0, v0, s0
	ds_write_b16 v92, v2 offset:17008
	ds_write_b16 v92, v0 offset:50800
	v_add_u32_e32 v92, 0x80, v92
	s_cbranch_scc0 .LBB0_460

.LBB0_467:
	flat_load_dwordx2 v[30:31], v[18:19] offset:512
	flat_load_dwordx2 v[24:25], v[18:19]
	global_load_dwordx4 v[0:3], v[8:9], off
	global_load_dwordx4 v[4:7], v[10:11], off
	global_load_dword v20, v[12:13], off
	global_load_dword v22, v[14:15], off
	s_add_i32 s0, s0, s80
	s_cmpk_lt_i32 s0, 0x80
	s_waitcnt vmcnt(0) lgkmcnt(0)
	v_lshlrev_b32_e32 v26, 16, v30
	v_mul_f32_e32 v21, 0x3d372713, v26
	v_mul_f32_e32 v21, v21, v26
	v_mov_b32_e32 v23, v26
	v_fmac_f32_e32 v23, v21, v23
	v_mul_f32_e32 v21, 0x3f4c422a, v23
	v_add_f32_e32 v21, v21, v21
	v_and_b32_e32 v27, 0xffff0000, v30
	v_mul_f32_e32 v21, 0xbfb8aa3b, v21
	v_exp_f32_e32 v28, v21
	v_mul_f32_e32 v21, 0x3d372713, v27
	v_mul_f32_e32 v21, v21, v27
	v_mov_b32_e32 v23, v27
	v_fmac_f32_e32 v23, v21, v23
	v_mul_f32_e32 v21, 0x3f4c422a, v23
	v_add_f32_e32 v21, v21, v21
	v_mul_f32_e32 v21, 0xbfb8aa3b, v21
	v_exp_f32_e32 v29, v21
	s_nop 0
	v_pk_add_f32 v[28:29], v[28:29], 1.0 op_sel_hi:[1,0]
	s_nop 0
	v_rcp_f32_e32 v29, v29
	v_rcp_f32_e32 v28, v28
	v_lshlrev_b32_e32 v30, 16, v31
	v_pk_mul_f32 v[32:33], v[28:29], v[26:27]
	v_mul_f32_e32 v23, 0x3d372713, v30
	v_add_f32_e32 v21, 0, v32
	v_mul_f32_e32 v23, v23, v30
	v_mov_b32_e32 v32, v30
	v_fmac_f32_e32 v32, v23, v32
	v_mul_f32_e32 v23, 0x3f4c422a, v32
	v_add_f32_e32 v23, v23, v23
	v_and_b32_e32 v31, 0xffff0000, v31
	v_mul_f32_e32 v23, 0xbfb8aa3b, v23
	v_exp_f32_e32 v32, v23
	v_mul_f32_e32 v23, 0x3d372713, v31
	v_add_f32_e32 v21, v33, v21
	v_mul_f32_e32 v23, v23, v31
	v_mov_b32_e32 v33, v31
	v_fmac_f32_e32 v33, v23, v33
	v_mul_f32_e32 v23, 0x3f4c422a, v33
	v_add_f32_e32 v23, v23, v23
	v_mul_f32_e32 v23, 0xbfb8aa3b, v23
	v_exp_f32_e32 v33, v23
	s_nop 0
	v_pk_add_f32 v[32:33], v[32:33], 1.0 op_sel_hi:[1,0]
	s_nop 0
	v_rcp_f32_e32 v33, v33
	v_rcp_f32_e32 v32, v32
	s_nop 0
	v_pk_mul_f32 v[34:35], v[32:33], v[30:31]
	s_nop 0
	v_add_f32_e32 v21, v34, v21
	v_add_f32_e32 v21, v35, v21
	s_nop 1
	v_add_f32_dpp v21, v21, v21 quad_perm:[1,0,3,2] row_mask:0xf bank_mask:0xf bound_ctrl:1
	s_nop 1
	v_add_f32_dpp v21, v21, v21 quad_perm:[2,3,0,1] row_mask:0xf bank_mask:0xf bound_ctrl:1
	s_nop 1
	v_add_f32_dpp v21, v21, v21 row_half_mirror row_mask:0xf bank_mask:0xf bound_ctrl:1
	s_nop 1
	v_add_f32_dpp v21, v21, v21 row_mirror row_mask:0xf bank_mask:0xf bound_ctrl:1
	s_nop 0
	v_readlane_b32 s1, v21, 16
	v_readlane_b32 s4, v21, 48
	v_readlane_b32 s2, v21, 0
	v_readlane_b32 s3, v21, 32
	v_mov_b32_e32 v34, s1
	v_mov_b32_e32 v35, s4
	v_pk_add_f32 v[34:35], s[2:3], v[34:35]
	s_nop 0
	v_add_f32_e32 v21, v34, v35
	v_mul_f32_e32 v34, 0x3b800000, v21
	v_pk_fma_f32 v[26:27], v[28:29], v[26:27], v[34:35] op_sel_hi:[1,1,0] neg_lo:[0,0,1] neg_hi:[0,0,1]
	v_pk_fma_f32 v[30:31], v[32:33], v[30:31], v[34:35] op_sel_hi:[1,1,0] neg_lo:[0,0,1] neg_hi:[0,0,1]
	v_pk_mul_f32 v[28:29], v[26:27], v[26:27]
	v_pk_mul_f32 v[32:33], v[30:31], v[30:31]
	v_add_f32_e32 v21, v28, v29
	v_add_f32_e32 v21, v32, v21
	v_add_f32_e32 v21, v33, v21
	s_nop 1
	v_add_f32_dpp v21, v21, v21 quad_perm:[1,0,3,2] row_mask:0xf bank_mask:0xf bound_ctrl:1
	s_nop 1
	v_add_f32_dpp v21, v21, v21 quad_perm:[2,3,0,1] row_mask:0xf bank_mask:0xf bound_ctrl:1
	s_nop 1
	v_add_f32_dpp v21, v21, v21 row_half_mirror row_mask:0xf bank_mask:0xf bound_ctrl:1
	s_nop 1
	v_add_f32_dpp v21, v21, v21 row_mirror row_mask:0xf bank_mask:0xf bound_ctrl:1
	s_nop 0
	v_readlane_b32 s1, v21, 16
	v_readlane_b32 s4, v21, 48
	v_readlane_b32 s2, v21, 0
	v_readlane_b32 s3, v21, 32
	v_mov_b32_e32 v28, s1
	v_mov_b32_e32 v29, s4
	v_pk_add_f32 v[28:29], s[2:3], v[28:29]
	s_nop 0
	v_add_f32_e32 v21, v28, v29
	v_fmamk_f32 v21, v21, 0x3b800000, v238
	v_cmp_gt_f32_e32 vcc, s5, v21
	v_mul_f32_e32 v23, 0x4b800000, v21
	s_nop 0
	v_cndmask_b32_e32 v21, v21, v23, vcc
	v_rsq_f32_e32 v21, v21
	s_nop 0
	v_mul_f32_e32 v23, 0x45800000, v21
	v_cndmask_b32_e32 v28, v21, v23, vcc
	v_pk_mul_f32 v[26:27], v[26:27], v[28:29] op_sel_hi:[1,0]
	s_nop 0
	v_pk_fma_f32 v[0:1], v[0:1], v[26:27], v[4:5]
	v_lshlrev_b32_e32 v4, 16, v24
	v_mul_f32_e32 v21, 0x3d372713, v4
	v_mul_f32_e32 v21, v21, v4
	v_mov_b32_e32 v23, v4
	v_fmac_f32_e32 v23, v21, v23
	v_mul_f32_e32 v21, 0x3f4c422a, v23
	v_add_f32_e32 v21, v21, v21
	v_and_b32_e32 v5, 0xffff0000, v24
	v_mul_f32_e32 v21, 0xbfb8aa3b, v21
	v_exp_f32_e32 v26, v21
	v_mul_f32_e32 v21, 0x3d372713, v5
	v_mul_f32_e32 v21, v21, v5
	v_mov_b32_e32 v23, v5
	v_fmac_f32_e32 v23, v21, v23
	v_mul_f32_e32 v21, 0x3f4c422a, v23
	v_add_f32_e32 v21, v21, v21
	v_mul_f32_e32 v21, 0xbfb8aa3b, v21
	v_exp_f32_e32 v27, v21
	s_nop 0
	v_pk_add_f32 v[26:27], v[26:27], 1.0 op_sel_hi:[1,0]
	s_nop 0
	v_rcp_f32_e32 v27, v27
	v_rcp_f32_e32 v26, v26
	s_nop 0
	v_pk_mul_f32 v[4:5], v[26:27], v[4:5]
	v_pk_fma_f32 v[26:27], v[20:21], v[0:1], v[22:23] op_sel_hi:[0,1,0]
	v_pk_mul_f32 v[4:5], v[4:5], v[26:27]
	v_pk_mul_f32 v[26:27], v[30:31], v[28:29] op_sel_hi:[1,0]
	s_nop 0
	v_pk_fma_f32 v[2:3], v[2:3], v[26:27], v[6:7]
	v_lshlrev_b32_e32 v6, 16, v25
	v_mul_f32_e32 v21, 0x3d372713, v6
	v_mul_f32_e32 v21, v21, v6
	v_mov_b32_e32 v23, v6
	v_fmac_f32_e32 v23, v21, v23
	v_mul_f32_e32 v21, 0x3f4c422a, v23
	v_add_f32_e32 v21, v21, v21
	v_and_b32_e32 v7, 0xffff0000, v25
	v_mul_f32_e32 v21, 0xbfb8aa3b, v21
	v_exp_f32_e32 v24, v21
	v_mul_f32_e32 v21, 0x3d372713, v7
	v_mul_f32_e32 v21, v21, v7
	v_mov_b32_e32 v23, v7
	v_fmac_f32_e32 v23, v21, v23
	v_mul_f32_e32 v21, 0x3f4c422a, v23
	v_add_f32_e32 v21, v21, v21
	v_mul_f32_e32 v21, 0xbfb8aa3b, v21
	v_exp_f32_e32 v25, v21
	global_store_dwordx4 v[16:17], v[0:3], off
	v_lshl_add_u64 v[16:17], v[16:17], 0, s[6:7]
	v_pk_add_f32 v[24:25], v[24:25], 1.0 op_sel_hi:[1,0]
	s_nop 0
	v_cvt_pk_bf16_f32 v0, v4, v5
	v_rcp_f32_e32 v25, v25
	v_rcp_f32_e32 v24, v24
	s_nop 0
	v_pk_mul_f32 v[6:7], v[24:25], v[6:7]
	v_pk_fma_f32 v[20:21], v[20:21], v[2:3], v[22:23] op_sel_hi:[0,1,0]
	v_pk_mul_f32 v[6:7], v[6:7], v[20:21]
	s_nop 0
	v_cvt_pk_bf16_f32 v1, v6, v7
	flat_store_dwordx2 v[18:19], v[0:1] offset:1536
	v_lshl_add_u64 v[18:19], v[18:19], 0, s[8:9]
	s_cbranch_scc1 .LBB0_467
	s_mov_b32 s83, 0x800000

.LBB0_527:
	s_and_b64 vcc, exec, s[0:1]
	s_cbranch_vccz .LBB0_605
	v_readlane_b32 s2, v253, 9
	v_readlane_b32 s3, v253, 10
	s_mov_b64 s[0:1], -1
	s_and_b64 vcc, exec, s[2:3]
	s_cbranch_vccz .LBB0_600
	s_mov_b32 s38, s89
	v_mbcnt_lo_u32_b32 v11, -1, 0
	v_mbcnt_hi_u32_b32 v11, -1, v11
	s_mov_b64 s[0:1], s[78:79]
	v_and_b32_e32 v10, 63, v11
	s_mov_b64 s[4:5], -1
	s_mov_b64 s[8:9], 0
	s_cmp_lt_i32 s38, 1
	s_mov_b64 s[2:3], 0
	s_cbranch_scc1 .LBB0_534
	s_cmp_eq_u32 s38, 1
	s_cbranch_scc0 .LBB0_532
	s_mov_b32 s57, s43
	s_lshl_b64 s[2:3], s[56:57], 18
	s_lshl_b64 s[4:5], s[56:57], 11
	s_lshl_b64 s[10:11], s[56:57], 17
	v_readlane_b32 s6, v254, 18
	s_add_u32 s6, s0, s6
	v_readlane_b32 s7, v254, 17
	s_addc_u32 s7, s1, s7
	v_lshlrev_b32_e32 v194, 3, v10
	v_lshl_add_u64 v[0:1], s[6:7], 0, v[194:195]
	s_mov_b64 s[6:7], 0x2040000
	v_lshl_add_u64 v[8:9], v[0:1], 0, s[6:7]
	flat_load_dwordx2 v[22:23], v[8:9] offset:512
	v_add_co_u32_e32 v0, vcc, s97, v0
	v_readlane_b32 s12, v252, 2
	s_nop 0
	v_addc_co_u32_e32 v1, vcc, 0, v1, vcc
	flat_load_dwordx2 v[14:15], v[0:1]
	v_readlane_b32 s13, v252, 3
	v_readlane_b32 s14, v252, 4
	v_readlane_b32 s12, v255, 41
	v_readlane_b32 s15, v252, 5
	v_readlane_b32 s13, v255, 42
	s_add_u32 s6, s14, s12
	v_readlane_b32 s16, v252, 6
	s_addc_u32 s7, s15, s13
	v_lshlrev_b32_e32 v13, 4, v10
	v_readlane_b32 s17, v252, 7
	global_load_dwordx4 v[0:3], v13, s[6:7]
	s_add_u32 s6, s16, s12
	v_readlane_b32 s18, v252, 8
	s_addc_u32 s7, s17, s13
	v_lshrrev_b32_e32 v16, 4, v10
	v_readlane_b32 s19, v252, 9
	s_add_u32 s2, s18, s2
	v_readlane_b32 s20, v252, 10
	s_addc_u32 s3, s19, s3
	v_lshlrev_b32_e32 v12, 16, v16
	v_readlane_b32 s21, v252, 11
	global_load_dword v12, v12, s[2:3]
	s_add_u32 s2, s20, s4
	s_addc_u32 s3, s21, s5
	v_lshlrev_b32_e32 v16, 9, v16
	global_load_dword v16, v16, s[2:3]
	v_readlane_b32 s22, v252, 12
	global_load_dwordx4 v[4:7], v13, s[6:7]
	v_readlane_b32 s23, v252, 13
	v_readlane_b32 s24, v252, 14
	v_readlane_b32 s25, v252, 15
	v_readlane_b32 s26, v252, 16
	v_readlane_b32 s27, v252, 17
	s_waitcnt vmcnt(0) lgkmcnt(0)
	v_lshlrev_b32_e32 v18, 16, v22
	v_mul_f32_e32 v17, 0x3d372713, v18
	v_mul_f32_e32 v17, v17, v18
	v_mov_b32_e32 v20, v18
	v_fmac_f32_e32 v20, v17, v20
	v_mul_f32_e32 v17, 0x3f4c422a, v20
	v_add_f32_e32 v17, v17, v17
	v_and_b32_e32 v19, 0xffff0000, v22
	v_mul_f32_e32 v17, 0xbfb8aa3b, v17
	v_exp_f32_e32 v20, v17
	v_mul_f32_e32 v17, 0x3d372713, v19
	v_mul_f32_e32 v17, v17, v19
	v_mov_b32_e32 v21, v19
	v_fmac_f32_e32 v21, v17, v21
	v_mul_f32_e32 v17, 0x3f4c422a, v21
	v_add_f32_e32 v17, v17, v17
	v_mul_f32_e32 v17, 0xbfb8aa3b, v17
	v_exp_f32_e32 v21, v17
	s_nop 0
	v_pk_add_f32 v[20:21], v[20:21], 1.0 op_sel_hi:[1,0]
	s_nop 0
	v_rcp_f32_e32 v21, v21
	v_rcp_f32_e32 v20, v20
	s_nop 0
	v_pk_mul_f32 v[24:25], v[20:21], v[18:19]
	v_lshlrev_b32_e32 v22, 16, v23
	v_add_f32_e32 v17, 0, v24
	v_mul_f32_e32 v24, 0x3d372713, v22
	v_add_f32_e32 v17, v25, v17
	v_mul_f32_e32 v24, v24, v22
	v_mov_b32_e32 v25, v22
	v_and_b32_e32 v23, 0xffff0000, v23
	v_fmac_f32_e32 v25, v24, v25
	v_mul_f32_e32 v24, 0x3f4c422a, v25
	v_mul_f32_e32 v25, 0x3d372713, v23
	v_mul_f32_e32 v25, v25, v23
	v_mov_b32_e32 v26, v23
	v_fmac_f32_e32 v26, v25, v26
	v_mul_f32_e32 v25, 0x3f4c422a, v26
	v_add_f32_e32 v24, v24, v24
	v_add_f32_e32 v25, v25, v25
	v_mul_f32_e32 v24, 0xbfb8aa3b, v24
	v_mul_f32_e32 v25, 0xbfb8aa3b, v25
	v_exp_f32_e32 v24, v24
	v_exp_f32_e32 v25, v25
	s_nop 0
	v_pk_add_f32 v[24:25], v[24:25], 1.0 op_sel_hi:[1,0]
	s_nop 0
	v_rcp_f32_e32 v25, v25
	v_rcp_f32_e32 v24, v24
	s_nop 0
	v_pk_mul_f32 v[26:27], v[24:25], v[22:23]
	s_nop 0
	v_add_f32_e32 v17, v26, v17
	v_add_f32_e32 v17, v27, v17
	s_nop 1
	v_add_f32_dpp v17, v17, v17 quad_perm:[1,0,3,2] row_mask:0xf bank_mask:0xf bound_ctrl:1
	s_nop 1
	v_add_f32_dpp v17, v17, v17 quad_perm:[2,3,0,1] row_mask:0xf bank_mask:0xf bound_ctrl:1
	s_nop 1
	v_add_f32_dpp v17, v17, v17 row_half_mirror row_mask:0xf bank_mask:0xf bound_ctrl:1
	s_nop 1
	v_add_f32_dpp v17, v17, v17 row_mirror row_mask:0xf bank_mask:0xf bound_ctrl:1
	s_nop 0
	v_readlane_b32 s4, v17, 16
	v_readlane_b32 s5, v17, 48
	v_readlane_b32 s2, v17, 0
	v_readlane_b32 s3, v17, 32
	v_mov_b32_e32 v26, s4
	v_mov_b32_e32 v27, s5
	v_pk_add_f32 v[26:27], s[2:3], v[26:27]
	s_nop 0
	v_add_f32_e32 v17, v26, v27
	v_mul_f32_e32 v26, 0x3b800000, v17
	v_pk_fma_f32 v[18:19], v[20:21], v[18:19], v[26:27] op_sel_hi:[1,1,0] neg_lo:[0,0,1] neg_hi:[0,0,1]
	v_pk_fma_f32 v[22:23], v[24:25], v[22:23], v[26:27] op_sel_hi:[1,1,0] neg_lo:[0,0,1] neg_hi:[0,0,1]
	v_pk_mul_f32 v[20:21], v[18:19], v[18:19]
	v_pk_mul_f32 v[24:25], v[22:23], v[22:23]
	v_add_f32_e32 v17, v20, v21
	v_add_f32_e32 v17, v24, v17
	v_add_f32_e32 v17, v25, v17
	s_nop 1
	v_add_f32_dpp v17, v17, v17 quad_perm:[1,0,3,2] row_mask:0xf bank_mask:0xf bound_ctrl:1
	s_nop 1
	v_add_f32_dpp v17, v17, v17 quad_perm:[2,3,0,1] row_mask:0xf bank_mask:0xf bound_ctrl:1
	s_nop 1
	v_add_f32_dpp v17, v17, v17 row_half_mirror row_mask:0xf bank_mask:0xf bound_ctrl:1
	s_nop 1
	v_add_f32_dpp v17, v17, v17 row_mirror row_mask:0xf bank_mask:0xf bound_ctrl:1
	s_nop 0
	v_readlane_b32 s4, v17, 16
	v_readlane_b32 s5, v17, 48
	v_readlane_b32 s2, v17, 0
	v_readlane_b32 s3, v17, 32
	v_mov_b32_e32 v20, s4
	v_mov_b32_e32 v21, s5
	v_pk_add_f32 v[20:21], s[2:3], v[20:21]
	s_nop 0
	v_add_f32_e32 v17, v20, v21
	v_fmamk_f32 v17, v17, 0x3b800000, v238
	v_cmp_gt_f32_e32 vcc, s83, v17
	v_mul_f32_e32 v20, 0x4b800000, v17
	s_nop 0
	v_cndmask_b32_e32 v17, v17, v20, vcc
	v_rsq_f32_e32 v17, v17
	s_nop 0
	v_mul_f32_e32 v20, 0x45800000, v17
	v_cndmask_b32_e32 v20, v17, v20, vcc
	v_pk_mul_f32 v[18:19], v[18:19], v[20:21] op_sel_hi:[1,0]
	s_nop 0
	v_pk_fma_f32 v[0:1], v[0:1], v[18:19], v[4:5]
	v_lshlrev_b32_e32 v4, 16, v14
	v_and_b32_e32 v5, 0xffff0000, v14
	v_mul_f32_e32 v14, 0x3d372713, v4
	v_mul_f32_e32 v14, v14, v4
	v_mov_b32_e32 v17, v4
	v_fmac_f32_e32 v17, v14, v17
	v_mul_f32_e32 v14, 0x3f4c422a, v17
	v_add_f32_e32 v14, v14, v14
	v_mul_f32_e32 v14, 0xbfb8aa3b, v14
	v_exp_f32_e32 v18, v14
	v_mul_f32_e32 v14, 0x3d372713, v5
	v_mul_f32_e32 v14, v14, v5
	v_mov_b32_e32 v17, v5
	v_fmac_f32_e32 v17, v14, v17
	v_mul_f32_e32 v14, 0x3f4c422a, v17
	v_add_f32_e32 v14, v14, v14
	v_mul_f32_e32 v14, 0xbfb8aa3b, v14
	v_exp_f32_e32 v19, v14
	s_nop 0
	v_pk_add_f32 v[18:19], v[18:19], 1.0 op_sel_hi:[1,0]
	s_nop 0
	v_rcp_f32_e32 v19, v19
	v_rcp_f32_e32 v18, v18
	s_nop 0
	v_pk_mul_f32 v[4:5], v[18:19], v[4:5]
	v_pk_fma_f32 v[18:19], v[12:13], v[0:1], v[16:17] op_sel_hi:[0,1,0]
	v_pk_mul_f32 v[4:5], v[4:5], v[18:19]
	v_pk_mul_f32 v[18:19], v[22:23], v[20:21] op_sel_hi:[1,0]
	s_nop 0
	v_pk_fma_f32 v[2:3], v[2:3], v[18:19], v[6:7]
	v_lshlrev_b32_e32 v6, 16, v15
	v_mul_f32_e32 v14, 0x3d372713, v6
	v_and_b32_e32 v7, 0xffff0000, v15
	v_mul_f32_e32 v14, v14, v6
	v_mov_b32_e32 v15, v6
	v_fmac_f32_e32 v15, v14, v15
	v_mul_f32_e32 v14, 0x3f4c422a, v15
	v_mul_f32_e32 v15, 0x3d372713, v7
	v_mul_f32_e32 v15, v15, v7
	v_mov_b32_e32 v17, v7
	v_fmac_f32_e32 v17, v15, v17
	v_mul_f32_e32 v15, 0x3f4c422a, v17
	v_add_f32_e32 v14, v14, v14
	v_add_f32_e32 v15, v15, v15
	v_mul_f32_e32 v14, 0xbfb8aa3b, v14
	v_mul_f32_e32 v15, 0xbfb8aa3b, v15
	v_exp_f32_e32 v14, v14
	v_exp_f32_e32 v15, v15
	s_nop 0
	v_pk_add_f32 v[14:15], v[14:15], 1.0 op_sel_hi:[1,0]
	s_nop 0
	v_rcp_f32_e32 v15, v15
	v_readlane_b32 s2, v253, 33
	s_add_u32 s2, s2, s10
	v_readlane_b32 s3, v253, 35
	v_rcp_f32_e32 v14, v14
	s_nop 0
	v_pk_mul_f32 v[6:7], v[14:15], v[6:7]
	v_pk_fma_f32 v[14:15], v[12:13], v[2:3], v[16:17] op_sel_hi:[0,1,0]
	v_pk_mul_f32 v[6:7], v[6:7], v[14:15]
	s_addc_u32 s3, s3, s11
	global_store_dwordx4 v13, v[0:3], s[2:3]
	s_nop 1
	v_cvt_pk_bf16_f32 v0, v4, v5
	v_cvt_pk_bf16_f32 v1, v6, v7
	flat_store_dwordx2 v[8:9], v[0:1] offset:1536

.LBB0_603:
	s_add_i32 s6, s65, s4
	s_mul_i32 s5, s6, 0x1400
	s_add_i32 s7, s6, 0xffffc080
	s_add_i32 s9, s5, 0xfb0a0000
	s_mul_hi_i32 s7, s7, 0x1400
	s_add_u32 s9, s0, s9
	s_addc_u32 s7, s1, s7
	s_add_u32 s12, s9, 0x2040200
	s_addc_u32 s13, s7, 0
	s_add_i32 s7, s6, 0xffffc088
	s_add_i32 s9, s5, 0xfb0aa000
	s_mul_hi_i32 s7, s7, 0x1400
	s_add_u32 s9, s0, s9
	v_mov_b32_e32 v5, v195
	v_mov_b32_e32 v7, v195
	v_mov_b32_e32 v9, v195
	s_addc_u32 s7, s1, s7
	v_lshl_add_u64 v[116:117], s[12:13], 0, v[194:195]
	v_lshl_add_u64 v[118:119], s[12:13], 0, v[4:5]
	v_lshl_add_u64 v[120:121], s[12:13], 0, v[6:7]
	v_lshl_add_u64 v[122:123], s[12:13], 0, v[8:9]
	s_add_u32 s12, s9, 0x2040200
	s_addc_u32 s13, s7, 0
	s_add_i32 s7, s6, 0xffffc090
	s_add_i32 s9, s5, 0xfb0b4000
	s_mul_hi_i32 s7, s7, 0x1400
	s_add_u32 s9, s0, s9
	s_addc_u32 s7, s1, s7
	v_lshl_add_u64 v[10:11], s[12:13], 0, v[194:195]
	v_lshl_add_u64 v[12:13], s[12:13], 0, v[4:5]
	v_lshl_add_u64 v[14:15], s[12:13], 0, v[6:7]
	v_lshl_add_u64 v[16:17], s[12:13], 0, v[8:9]
	s_add_u32 s12, s9, 0x2040200
	s_addc_u32 s13, s7, 0
	s_add_i32 s7, s6, 0xffffc098
	s_add_i32 s9, s5, 0xfb0be000
	s_mul_hi_i32 s7, s7, 0x1400
	s_add_u32 s9, s0, s9
	s_addc_u32 s7, s1, s7
	v_lshl_add_u64 v[18:19], s[12:13], 0, v[194:195]
	v_lshl_add_u64 v[20:21], s[12:13], 0, v[4:5]
	v_lshl_add_u64 v[22:23], s[12:13], 0, v[6:7]
	v_lshl_add_u64 v[24:25], s[12:13], 0, v[8:9]
	s_add_u32 s12, s9, 0x2040200
	s_addc_u32 s13, s7, 0
	s_add_i32 s7, s6, 0xffffc0a0
	s_add_i32 s9, s5, 0xfb0c8000
	s_mul_hi_i32 s7, s7, 0x1400
	s_add_u32 s9, s0, s9
	s_addc_u32 s7, s1, s7
	v_lshl_add_u64 v[26:27], s[12:13], 0, v[194:195]
	v_lshl_add_u64 v[28:29], s[12:13], 0, v[4:5]
	v_lshl_add_u64 v[30:31], s[12:13], 0, v[6:7]
	v_lshl_add_u64 v[32:33], s[12:13], 0, v[8:9]
	s_add_u32 s12, s9, 0x2040200
	s_addc_u32 s13, s7, 0
	s_add_i32 s7, s6, 0xffffc0a8
	s_add_i32 s9, s5, 0xfb0d2000
	s_mul_hi_i32 s7, s7, 0x1400
	s_add_u32 s9, s0, s9
	s_addc_u32 s7, s1, s7
	v_lshl_add_u64 v[34:35], s[12:13], 0, v[194:195]
	v_lshl_add_u64 v[76:77], s[12:13], 0, v[4:5]
	v_lshl_add_u64 v[78:79], s[12:13], 0, v[6:7]
	v_lshl_add_u64 v[80:81], s[12:13], 0, v[8:9]
	s_add_u32 s12, s9, 0x2040200
	s_addc_u32 s13, s7, 0
	s_add_i32 s7, s6, 0xffffc0b0
	s_add_i32 s9, s5, 0xfb0dc000
	s_mul_hi_i32 s7, s7, 0x1400
	s_add_u32 s9, s0, s9
	s_addc_u32 s7, s1, s7
	v_lshl_add_u64 v[82:83], s[12:13], 0, v[194:195]
	v_lshl_add_u64 v[84:85], s[12:13], 0, v[4:5]
	v_lshl_add_u64 v[86:87], s[12:13], 0, v[6:7]
	v_lshl_add_u64 v[88:89], s[12:13], 0, v[8:9]
	s_add_u32 s12, s9, 0x2040200
	s_addc_u32 s13, s7, 0
	s_add_i32 s7, s6, 0xffffc0b8
	s_add_i32 s9, s5, 0xfb0e6000
	s_mul_hi_i32 s7, s7, 0x1400
	s_add_u32 s9, s0, s9
	s_addc_u32 s7, s1, s7
	v_lshl_add_u64 v[90:91], s[12:13], 0, v[194:195]
	v_lshl_add_u64 v[92:93], s[12:13], 0, v[4:5]
	v_lshl_add_u64 v[94:95], s[12:13], 0, v[6:7]
	v_lshl_add_u64 v[96:97], s[12:13], 0, v[8:9]
	s_add_u32 s12, s9, 0x2040200
	s_addc_u32 s13, s7, 0
	s_add_i32 s7, s6, 0xffffc0c0
	s_add_i32 s9, s5, 0xfb0f0000
	s_mul_hi_i32 s7, s7, 0x1400
	s_add_u32 s9, s0, s9
	s_addc_u32 s7, s1, s7
	v_lshl_add_u64 v[98:99], s[12:13], 0, v[194:195]
	v_lshl_add_u64 v[100:101], s[12:13], 0, v[4:5]
	v_lshl_add_u64 v[102:103], s[12:13], 0, v[6:7]
	v_lshl_add_u64 v[104:105], s[12:13], 0, v[8:9]
	s_add_u32 s12, s9, 0x2040200
	s_addc_u32 s13, s7, 0
	s_add_i32 s7, s6, 0xffffc0c8
	s_add_i32 s9, s5, 0xfb0fa000
	s_mul_hi_i32 s7, s7, 0x1400
	s_add_u32 s9, s0, s9
	s_addc_u32 s7, s1, s7
	v_lshl_add_u64 v[124:125], s[12:13], 0, v[194:195]
	v_lshl_add_u64 v[126:127], s[12:13], 0, v[4:5]
	v_lshl_add_u64 v[128:129], s[12:13], 0, v[6:7]
	v_lshl_add_u64 v[130:131], s[12:13], 0, v[8:9]
	s_add_u32 s12, s9, 0x2040200
	s_addc_u32 s13, s7, 0
	s_add_i32 s7, s6, 0xffffc0d0
	s_add_i32 s9, s5, 0xfb104000
	s_mul_hi_i32 s7, s7, 0x1400
	s_add_u32 s9, s0, s9
	s_addc_u32 s7, s1, s7
	v_lshl_add_u64 v[132:133], s[12:13], 0, v[194:195]
	v_lshl_add_u64 v[134:135], s[12:13], 0, v[4:5]
	v_lshl_add_u64 v[136:137], s[12:13], 0, v[6:7]
	v_lshl_add_u64 v[138:139], s[12:13], 0, v[8:9]
	s_add_u32 s12, s9, 0x2040200
	s_addc_u32 s13, s7, 0
	s_add_i32 s7, s6, 0xffffc0d8
	s_add_i32 s9, s5, 0xfb10e000
	s_mul_hi_i32 s7, s7, 0x1400
	s_add_u32 s9, s0, s9
	s_addc_u32 s7, s1, s7
	v_lshl_add_u64 v[140:141], s[12:13], 0, v[194:195]
	v_lshl_add_u64 v[142:143], s[12:13], 0, v[4:5]
	v_lshl_add_u64 v[144:145], s[12:13], 0, v[6:7]
	v_lshl_add_u64 v[146:147], s[12:13], 0, v[8:9]
	s_add_u32 s12, s9, 0x2040200
	s_addc_u32 s13, s7, 0
	s_add_i32 s7, s6, 0xffffc0e0
	s_add_i32 s9, s5, 0xfb118000
	s_mul_hi_i32 s7, s7, 0x1400
	s_add_u32 s9, s0, s9
	s_addc_u32 s7, s1, s7
	v_lshl_add_u64 v[148:149], s[12:13], 0, v[194:195]
	v_lshl_add_u64 v[150:151], s[12:13], 0, v[4:5]
	v_lshl_add_u64 v[152:153], s[12:13], 0, v[6:7]
	v_lshl_add_u64 v[154:155], s[12:13], 0, v[8:9]
	s_add_u32 s12, s9, 0x2040200
	s_addc_u32 s13, s7, 0
	s_add_i32 s7, s6, 0xffffc0e8
	s_add_i32 s9, s5, 0xfb122000
	s_mul_hi_i32 s7, s7, 0x1400
	s_add_u32 s9, s0, s9
	s_addc_u32 s7, s1, s7
	v_lshl_add_u64 v[156:157], s[12:13], 0, v[194:195]
	v_lshl_add_u64 v[158:159], s[12:13], 0, v[4:5]
	v_lshl_add_u64 v[160:161], s[12:13], 0, v[6:7]
	v_lshl_add_u64 v[162:163], s[12:13], 0, v[8:9]
	s_add_u32 s12, s9, 0x2040200
	s_addc_u32 s13, s7, 0
	s_add_i32 s7, s6, 0xffffc0f0
	s_add_i32 s9, s5, 0xfb12c000
	s_mul_hi_i32 s7, s7, 0x1400
	s_add_u32 s9, s0, s9
	s_addc_u32 s7, s1, s7
	v_lshl_add_u64 v[164:165], s[12:13], 0, v[194:195]
	v_lshl_add_u64 v[166:167], s[12:13], 0, v[4:5]
	v_lshl_add_u64 v[168:169], s[12:13], 0, v[6:7]
	v_lshl_add_u64 v[170:171], s[12:13], 0, v[8:9]
	s_add_u32 s12, s9, 0x2040200
	s_addc_u32 s13, s7, 0
	s_addk_i32 s6, 0xc0f8
	s_add_i32 s5, s5, 0xfb136000
	s_mul_hi_i32 s6, s6, 0x1400
	s_add_u32 s5, s0, s5
	s_addc_u32 s7, s1, s6
	s_add_u32 s6, s5, 0x2040200
	s_addc_u32 s7, s7, 0
	v_lshl_add_u64 v[174:175], s[12:13], 0, v[4:5]
	v_lshl_add_u64 v[176:177], s[12:13], 0, v[6:7]
	v_lshl_add_u64 v[182:183], s[6:7], 0, v[4:5]
	v_lshl_add_u64 v[184:185], s[6:7], 0, v[6:7]
	flat_load_ushort v5, v[116:117]
	flat_load_ushort v7, v[118:119]
	v_lshl_add_u64 v[180:181], s[6:7], 0, v[194:195]
	v_lshl_add_u64 v[186:187], s[6:7], 0, v[8:9]
	v_lshl_add_u64 v[178:179], s[12:13], 0, v[8:9]
	v_lshl_add_u64 v[172:173], s[12:13], 0, v[194:195]
	s_addk_i32 s4, 0x80
	s_cmp_lt_i32 s4, 0
	s_waitcnt vmcnt(0) lgkmcnt(0)
	v_lshlrev_b32_e32 v116, 16, v5
	v_mul_f32_e32 v5, 0x3d372713, v116
	v_lshlrev_b32_e32 v117, 16, v7
	v_mul_f32_e32 v5, v5, v116
	v_mov_b32_e32 v7, v116
	v_fmac_f32_e32 v7, v5, v7
	v_mul_f32_e32 v5, 0x3f4c422a, v7
	v_add_f32_e32 v5, v5, v5
	v_mul_f32_e32 v5, 0xbfb8aa3b, v5
	v_exp_f32_e32 v118, v5
	v_mul_f32_e32 v5, 0x3d372713, v117
	v_mul_f32_e32 v5, v5, v117
	v_mov_b32_e32 v7, v117
	v_fmac_f32_e32 v7, v5, v7
	v_mul_f32_e32 v5, 0x3f4c422a, v7
	v_add_f32_e32 v5, v5, v5
	v_mul_f32_e32 v5, 0xbfb8aa3b, v5
	v_exp_f32_e32 v119, v5
	s_nop 0
	v_pk_add_f32 v[118:119], v[118:119], 1.0 op_sel_hi:[1,0]
	s_nop 0
	v_rcp_f32_e32 v119, v119
	flat_load_ushort v7, v[120:121]
	flat_load_ushort v9, v[122:123]
	v_rcp_f32_e32 v118, v118
	s_nop 0
	v_pk_mul_f32 v[188:189], v[118:119], v[116:117]
	s_waitcnt vmcnt(0) lgkmcnt(0)
	v_lshlrev_b32_e32 v118, 16, v7
	v_mul_f32_e32 v7, 0x3d372713, v118
	v_lshlrev_b32_e32 v119, 16, v9
	v_mul_f32_e32 v7, v7, v118
	v_mov_b32_e32 v9, v118
	v_fmac_f32_e32 v9, v7, v9
	v_mul_f32_e32 v7, 0x3f4c422a, v9
	v_add_f32_e32 v7, v7, v7
	v_mul_f32_e32 v7, 0xbfb8aa3b, v7
	v_exp_f32_e32 v120, v7
	v_mul_f32_e32 v7, 0x3d372713, v119
	v_mul_f32_e32 v7, v7, v119
	v_mov_b32_e32 v9, v119
	v_fmac_f32_e32 v9, v7, v9
	v_mul_f32_e32 v7, 0x3f4c422a, v9
	v_add_f32_e32 v7, v7, v7
	v_mul_f32_e32 v7, 0xbfb8aa3b, v7
	v_exp_f32_e32 v121, v7
	v_add_f32_e32 v5, 0, v188
	v_add_f32_e32 v5, v5, v189
	v_pk_mul_f32 v[116:117], v[188:189], v[188:189]
	v_pk_add_f32 v[120:121], v[120:121], 1.0 op_sel_hi:[1,0]
	s_nop 0
	v_rcp_f32_e32 v121, v121
	v_rcp_f32_e32 v120, v120
	s_nop 0
	v_pk_mul_f32 v[122:123], v[120:121], v[118:119]
	v_add_f32_e32 v7, v116, v117
	v_add_f32_e32 v5, v5, v122
	v_add_f32_e32 v5, v5, v123
	v_pk_mul_f32 v[118:119], v[122:123], v[122:123]
	s_nop 0
	v_add_f32_dpp v5, v5, v5 quad_perm:[1,0,3,2] row_mask:0xf bank_mask:0xf bound_ctrl:1
	v_add_f32_e32 v7, v7, v118
	v_add_f32_e32 v7, v7, v119
	v_add_f32_dpp v5, v5, v5 quad_perm:[2,3,0,1] row_mask:0xf bank_mask:0xf bound_ctrl:1
	s_nop 1
	v_add_f32_dpp v5, v5, v5 row_half_mirror row_mask:0xf bank_mask:0xf bound_ctrl:1
	s_nop 1
	v_add_f32_dpp v5, v5, v5 row_mirror row_mask:0xf bank_mask:0xf bound_ctrl:1
	s_nop 0
	v_readlane_b32 s7, v5, 0
	v_readlane_b32 s5, v5, 16
	v_readlane_b32 s13, v5, 32
	v_readlane_b32 s9, v5, 48
	v_add_f32_dpp v5, v7, v7 quad_perm:[1,0,3,2] row_mask:0xf bank_mask:0xf bound_ctrl:1
	v_mov_b32_e32 v117, s5
	v_mov_b32_e32 v119, s9
	v_add_f32_dpp v5, v5, v5 quad_perm:[2,3,0,1] row_mask:0xf bank_mask:0xf bound_ctrl:1
	s_nop 1
	v_add_f32_dpp v5, v5, v5 row_half_mirror row_mask:0xf bank_mask:0xf bound_ctrl:1
	s_nop 1
	v_add_f32_dpp v5, v5, v5 row_mirror row_mask:0xf bank_mask:0xf bound_ctrl:1
	s_nop 0
	v_readlane_b32 s11, v5, 16
	v_readlane_b32 s14, v5, 48
	v_readlane_b32 s6, v5, 0
	v_readlane_b32 s12, v5, 32
	v_mov_b32_e32 v116, s11
	v_mov_b32_e32 v118, s14
	v_pk_add_f32 v[116:117], s[6:7], v[116:117]
	v_pk_add_f32 v[118:119], s[12:13], v[118:119]
	s_nop 0
	v_pk_add_f32 v[116:117], v[116:117], v[118:119]
	s_nop 0
	v_pk_mul_f32 v[120:121], v[116:117], s[20:21] op_sel_hi:[1,0]
	s_nop 0
	v_fma_f32 v5, -v121, v121, v120
	v_max_f32_e32 v5, 0, v5
	v_add_f32_e32 v5, 0x3727c5ac, v5
	v_cmp_gt_f32_e32 vcc, s18, v5
	v_mul_f32_e32 v7, 0x4b800000, v5
	s_nop 0
	v_cndmask_b32_e32 v5, v5, v7, vcc
	v_rsq_f32_e32 v5, v5
	s_nop 0
	v_mul_f32_e32 v7, 0x45800000, v5
	v_cndmask_b32_e32 v190, v5, v7, vcc
	v_sub_f32_e32 v5, v188, v121
	v_mul_f32_e32 v5, v5, v190
	v_fma_f32 v5, v67, v5, v106
	v_cvt_pk_bf16_f32 v188, v5, s0
	flat_load_ushort v191, v[10:11]
	flat_load_ushort v193, v[12:13]
	flat_load_ushort v196, v[14:15]
	flat_load_ushort v202, v[16:17]
	flat_load_ushort v203, v[18:19]
	flat_load_ushort v206, v[20:21]
	flat_load_ushort v207, v[22:23]
	flat_load_ushort v208, v[24:25]
	flat_load_ushort v209, v[26:27]
	flat_load_ushort v210, v[28:29]
	flat_load_ushort v211, v[30:31]
	flat_load_ushort v212, v[32:33]
	flat_load_ushort v119, v[34:35]
	flat_load_ushort v120, v[76:77]
	flat_load_ushort v117, v[78:79]
	flat_load_ushort v118, v[80:81]
	flat_load_ushort v115, v[82:83]
	flat_load_ushort v116, v[84:85]
	s_nop 0
	flat_load_ushort v87, v[86:87]
	s_nop 0
	flat_load_ushort v88, v[88:89]
	s_nop 0
	flat_load_ushort v85, v[90:91]
	flat_load_ushort v86, v[92:93]
	flat_load_ushort v83, v[94:95]
	flat_load_ushort v84, v[96:97]
	flat_load_ushort v81, v[98:99]
	flat_load_ushort v82, v[100:101]
	flat_load_ushort v79, v[102:103]
	flat_load_ushort v80, v[104:105]
	flat_load_ushort v77, v[124:125]
	flat_load_ushort v78, v[126:127]
	flat_load_ushort v14, v[128:129]
	flat_load_ushort v15, v[130:131]
	flat_load_ushort v12, v[132:133]
	flat_load_ushort v13, v[134:135]
	flat_load_ushort v10, v[136:137]
	flat_load_ushort v11, v[138:139]
	flat_load_ushort v35, v[140:141]
	flat_load_ushort v76, v[142:143]
	flat_load_ushort v33, v[144:145]
	flat_load_ushort v34, v[146:147]
	flat_load_ushort v31, v[148:149]
	flat_load_ushort v32, v[150:151]
	flat_load_ushort v29, v[152:153]
	flat_load_ushort v30, v[154:155]
	flat_load_ushort v27, v[156:157]
	flat_load_ushort v28, v[158:159]
	flat_load_ushort v25, v[160:161]
	flat_load_ushort v26, v[162:163]
	flat_load_ushort v23, v[164:165]
	flat_load_ushort v24, v[166:167]
	flat_load_ushort v21, v[168:169]
	flat_load_ushort v22, v[170:171]
	flat_load_ushort v19, v[172:173]
	flat_load_ushort v20, v[174:175]
	flat_load_ushort v17, v[176:177]
	flat_load_ushort v18, v[178:179]
	flat_load_ushort v9, v[180:181]
	flat_load_ushort v16, v[182:183]
	flat_load_ushort v5, v[184:185]
	flat_load_ushort v7, v[186:187]
	v_sub_f32_e32 v89, v189, v121
	v_mul_f32_e32 v89, v89, v190
	v_fma_f32 v89, v107, v89, v108
	v_cvt_pk_bf16_f32 v89, v89, s0
	ds_write_b16 v114, v89 offset:16896
	v_sub_f32_e32 v89, v122, v121
	v_mul_f32_e32 v89, v89, v190
	v_fma_f32 v89, v110, v89, v111
	v_cvt_pk_bf16_f32 v89, v89, s0
	ds_write_b16 v114, v89 offset:33792
	v_sub_f32_e32 v89, v123, v121
	v_mul_f32_e32 v89, v89, v190
	v_fma_f32 v89, v112, v89, v113
	v_cvt_pk_bf16_f32 v89, v89, s0
	ds_write_b16 v114, v89 offset:50688
	ds_write_b16 v114, v188
	s_waitcnt vmcnt(0) lgkmcnt(0)
	v_lshlrev_b32_e32 v90, 16, v191
	v_mul_f32_e32 v89, 0x3d372713, v90
	v_mul_f32_e32 v89, v89, v90
	v_mov_b32_e32 v92, v90
	v_fmac_f32_e32 v92, v89, v92
	v_mul_f32_e32 v89, 0x3f4c422a, v92
	v_add_f32_e32 v89, v89, v89
	v_lshlrev_b32_e32 v91, 16, v193
	v_mul_f32_e32 v89, 0xbfb8aa3b, v89
	v_exp_f32_e32 v92, v89
	v_mul_f32_e32 v89, 0x3d372713, v91
	v_mul_f32_e32 v89, v89, v91
	v_mov_b32_e32 v93, v91
	v_fmac_f32_e32 v93, v89, v93
	v_mul_f32_e32 v89, 0x3f4c422a, v93
	v_add_f32_e32 v89, v89, v89
	v_mul_f32_e32 v89, 0xbfb8aa3b, v89
	v_exp_f32_e32 v93, v89
	v_lshlrev_b32_e32 v14, 16, v14
	v_pk_add_f32 v[92:93], v[92:93], 1.0 op_sel_hi:[1,0]
	v_lshlrev_b32_e32 v15, 16, v15
	v_lshlrev_b32_e32 v12, 16, v12
	v_lshlrev_b32_e32 v13, 16, v13
	v_lshlrev_b32_e32 v10, 16, v10
	v_rcp_f32_e32 v93, v93
	v_lshlrev_b32_e32 v11, 16, v11
	v_lshlrev_b32_e32 v94, 16, v196
	v_mul_f32_e32 v96, 0x3d372713, v94
	v_mul_f32_e32 v96, v96, v94
	v_mov_b32_e32 v97, v94
	v_lshlrev_b32_e32 v95, 16, v202
	v_fmac_f32_e32 v97, v96, v97
	v_mul_f32_e32 v96, 0x3f4c422a, v97
	v_mul_f32_e32 v97, 0x3d372713, v95
	v_mul_f32_e32 v97, v97, v95
	v_mov_b32_e32 v98, v95
	v_fmac_f32_e32 v98, v97, v98
	v_mul_f32_e32 v97, 0x3f4c422a, v98
	v_add_f32_e32 v96, v96, v96
	v_add_f32_e32 v97, v97, v97
	v_mul_f32_e32 v96, 0xbfb8aa3b, v96
	v_mul_f32_e32 v97, 0xbfb8aa3b, v97
	v_exp_f32_e32 v96, v96
	v_exp_f32_e32 v97, v97
	v_rcp_f32_e32 v92, v92
	s_nop 0
	v_pk_mul_f32 v[90:91], v[92:93], v[90:91]
	v_pk_add_f32 v[96:97], v[96:97], 1.0 op_sel_hi:[1,0]
	s_nop 0
	v_add_f32_e32 v89, 0, v90
	v_add_f32_e32 v89, v89, v91
	v_pk_mul_f32 v[92:93], v[90:91], v[90:91]
	v_rcp_f32_e32 v97, v97
	v_add_f32_e32 v92, v92, v93
	v_rcp_f32_e32 v96, v96
	s_nop 0
	v_pk_mul_f32 v[94:95], v[96:97], v[94:95]
	s_nop 0
	v_add_f32_e32 v89, v89, v94
	v_add_f32_e32 v89, v89, v95
	v_pk_mul_f32 v[96:97], v[94:95], v[94:95]
	s_nop 0
	v_add_f32_dpp v89, v89, v89 quad_perm:[1,0,3,2] row_mask:0xf bank_mask:0xf bound_ctrl:1
	v_add_f32_e32 v92, v92, v96
	v_add_f32_e32 v92, v92, v97
	v_add_f32_dpp v89, v89, v89 quad_perm:[2,3,0,1] row_mask:0xf bank_mask:0xf bound_ctrl:1
	s_nop 1
	v_add_f32_dpp v89, v89, v89 row_half_mirror row_mask:0xf bank_mask:0xf bound_ctrl:1
	s_nop 1
	v_add_f32_dpp v89, v89, v89 row_mirror row_mask:0xf bank_mask:0xf bound_ctrl:1
	s_nop 0
	v_readlane_b32 s7, v89, 0
	v_readlane_b32 s5, v89, 16
	v_readlane_b32 s13, v89, 32
	v_readlane_b32 s9, v89, 48
	v_add_f32_dpp v89, v92, v92 quad_perm:[1,0,3,2] row_mask:0xf bank_mask:0xf bound_ctrl:1
	v_mov_b32_e32 v93, s5
	v_mov_b32_e32 v97, s9
	v_add_f32_dpp v89, v89, v89 quad_perm:[2,3,0,1] row_mask:0xf bank_mask:0xf bound_ctrl:1
	s_nop 1
	v_add_f32_dpp v89, v89, v89 row_half_mirror row_mask:0xf bank_mask:0xf bound_ctrl:1
	s_nop 1
	v_add_f32_dpp v89, v89, v89 row_mirror row_mask:0xf bank_mask:0xf bound_ctrl:1
	s_nop 0
	v_readlane_b32 s11, v89, 16
	v_readlane_b32 s14, v89, 48
	v_readlane_b32 s6, v89, 0
	v_readlane_b32 s12, v89, 32
	v_mov_b32_e32 v92, s11
	v_mov_b32_e32 v96, s14
	v_pk_add_f32 v[92:93], s[6:7], v[92:93]
	v_pk_add_f32 v[96:97], s[12:13], v[96:97]
	s_nop 0
	v_pk_add_f32 v[92:93], v[92:93], v[96:97]
	s_nop 0
	v_pk_mul_f32 v[92:93], v[92:93], s[20:21] op_sel_hi:[1,0]
	s_nop 0
	v_fma_f32 v89, -v93, v93, v92
	v_max_f32_e32 v89, 0, v89
	v_add_f32_e32 v89, 0x3727c5ac, v89
	v_cmp_gt_f32_e32 vcc, s18, v89
	v_mul_f32_e32 v92, 0x4b800000, v89
	v_sub_f32_e32 v90, v90, v93
	v_cndmask_b32_e32 v89, v89, v92, vcc
	v_rsq_f32_e32 v89, v89
	s_nop 0
	v_mul_f32_e32 v92, 0x45800000, v89
	v_cndmask_b32_e32 v89, v89, v92, vcc
	v_mul_f32_e32 v90, v90, v89
	v_fma_f32 v90, v67, v90, v106
	v_cvt_pk_bf16_f32 v90, v90, s0
	ds_write_b16 v114, v90 offset:16
	v_sub_f32_e32 v90, v91, v93
	v_mul_f32_e32 v90, v90, v89
	v_fma_f32 v90, v107, v90, v108
	v_cvt_pk_bf16_f32 v90, v90, s0
	ds_write_b16 v114, v90 offset:16912
	v_sub_f32_e32 v90, v94, v93
	v_mul_f32_e32 v90, v90, v89
	v_fma_f32 v90, v110, v90, v111
	v_cvt_pk_bf16_f32 v90, v90, s0
	ds_write_b16 v114, v90 offset:33808
	v_sub_f32_e32 v90, v95, v93
	v_mul_f32_e32 v89, v90, v89
	v_fma_f32 v89, v112, v89, v113
	v_cvt_pk_bf16_f32 v89, v89, s0
	v_lshlrev_b32_e32 v90, 16, v203
	ds_write_b16 v114, v89 offset:50704
	v_mul_f32_e32 v89, 0x3d372713, v90
	v_mul_f32_e32 v89, v89, v90
	v_mov_b32_e32 v92, v90
	v_fmac_f32_e32 v92, v89, v92
	v_mul_f32_e32 v89, 0x3f4c422a, v92
	v_add_f32_e32 v89, v89, v89
	v_lshlrev_b32_e32 v91, 16, v206
	v_mul_f32_e32 v89, 0xbfb8aa3b, v89
	v_exp_f32_e32 v92, v89
	v_mul_f32_e32 v89, 0x3d372713, v91
	v_mul_f32_e32 v89, v89, v91
	v_mov_b32_e32 v93, v91
	v_fmac_f32_e32 v93, v89, v93
	v_mul_f32_e32 v89, 0x3f4c422a, v93
	v_add_f32_e32 v89, v89, v89
	v_mul_f32_e32 v89, 0xbfb8aa3b, v89
	v_exp_f32_e32 v93, v89
	s_nop 0
	v_pk_add_f32 v[92:93], v[92:93], 1.0 op_sel_hi:[1,0]
	s_nop 0
	v_rcp_f32_e32 v93, v93
	v_lshlrev_b32_e32 v94, 16, v207
	v_mul_f32_e32 v96, 0x3d372713, v94
	v_mul_f32_e32 v96, v96, v94
	v_mov_b32_e32 v97, v94
	v_lshlrev_b32_e32 v95, 16, v208
	v_fmac_f32_e32 v97, v96, v97
	v_mul_f32_e32 v96, 0x3f4c422a, v97
	v_mul_f32_e32 v97, 0x3d372713, v95
	v_mul_f32_e32 v97, v97, v95
	v_mov_b32_e32 v98, v95
	v_fmac_f32_e32 v98, v97, v98
	v_mul_f32_e32 v97, 0x3f4c422a, v98
	v_add_f32_e32 v96, v96, v96
	v_add_f32_e32 v97, v97, v97
	v_mul_f32_e32 v96, 0xbfb8aa3b, v96
	v_mul_f32_e32 v97, 0xbfb8aa3b, v97
	v_exp_f32_e32 v96, v96
	v_exp_f32_e32 v97, v97
	v_rcp_f32_e32 v92, v92
	s_nop 0
	v_pk_mul_f32 v[90:91], v[92:93], v[90:91]
	v_pk_add_f32 v[96:97], v[96:97], 1.0 op_sel_hi:[1,0]
	s_nop 0
	v_add_f32_e32 v89, 0, v90
	v_add_f32_e32 v89, v89, v91
	v_pk_mul_f32 v[92:93], v[90:91], v[90:91]
	v_rcp_f32_e32 v97, v97
	v_add_f32_e32 v92, v92, v93
	v_rcp_f32_e32 v96, v96
	s_nop 0
	v_pk_mul_f32 v[94:95], v[96:97], v[94:95]
	s_nop 0
	v_add_f32_e32 v89, v89, v94
	v_add_f32_e32 v89, v89, v95
	v_pk_mul_f32 v[96:97], v[94:95], v[94:95]
	s_nop 0
	v_add_f32_dpp v89, v89, v89 quad_perm:[1,0,3,2] row_mask:0xf bank_mask:0xf bound_ctrl:1
	v_add_f32_e32 v92, v92, v96
	v_add_f32_e32 v92, v92, v97
	v_add_f32_dpp v89, v89, v89 quad_perm:[2,3,0,1] row_mask:0xf bank_mask:0xf bound_ctrl:1
	s_nop 1
	v_add_f32_dpp v89, v89, v89 row_half_mirror row_mask:0xf bank_mask:0xf bound_ctrl:1
	s_nop 1
	v_add_f32_dpp v89, v89, v89 row_mirror row_mask:0xf bank_mask:0xf bound_ctrl:1
	s_nop 0
	v_readlane_b32 s7, v89, 0
	v_readlane_b32 s5, v89, 16
	v_readlane_b32 s13, v89, 32
	v_readlane_b32 s9, v89, 48
	v_add_f32_dpp v89, v92, v92 quad_perm:[1,0,3,2] row_mask:0xf bank_mask:0xf bound_ctrl:1
	v_mov_b32_e32 v93, s5
	v_mov_b32_e32 v97, s9
	v_add_f32_dpp v89, v89, v89 quad_perm:[2,3,0,1] row_mask:0xf bank_mask:0xf bound_ctrl:1
	s_nop 1
	v_add_f32_dpp v89, v89, v89 row_half_mirror row_mask:0xf bank_mask:0xf bound_ctrl:1
	s_nop 1
	v_add_f32_dpp v89, v89, v89 row_mirror row_mask:0xf bank_mask:0xf bound_ctrl:1
	s_nop 0
	v_readlane_b32 s11, v89, 16
	v_readlane_b32 s14, v89, 48
	v_readlane_b32 s6, v89, 0
	v_readlane_b32 s12, v89, 32
	v_mov_b32_e32 v92, s11
	v_mov_b32_e32 v96, s14
	v_pk_add_f32 v[92:93], s[6:7], v[92:93]
	v_pk_add_f32 v[96:97], s[12:13], v[96:97]
	s_nop 0
	v_pk_add_f32 v[92:93], v[92:93], v[96:97]
	s_nop 0
	v_pk_mul_f32 v[92:93], v[92:93], s[20:21] op_sel_hi:[1,0]
	s_nop 0
	v_fma_f32 v89, -v93, v93, v92
	v_max_f32_e32 v89, 0, v89
	v_add_f32_e32 v89, 0x3727c5ac, v89
	v_cmp_gt_f32_e32 vcc, s18, v89
	v_mul_f32_e32 v92, 0x4b800000, v89
	v_sub_f32_e32 v90, v90, v93
	v_cndmask_b32_e32 v89, v89, v92, vcc
	v_rsq_f32_e32 v89, v89
	s_nop 0
	v_mul_f32_e32 v92, 0x45800000, v89
	v_cndmask_b32_e32 v89, v89, v92, vcc
	v_mul_f32_e32 v90, v90, v89
	v_fma_f32 v90, v67, v90, v106
	v_cvt_pk_bf16_f32 v90, v90, s0
	ds_write_b16 v114, v90 offset:32
	v_sub_f32_e32 v90, v91, v93
	v_mul_f32_e32 v90, v90, v89
	v_fma_f32 v90, v107, v90, v108
	v_cvt_pk_bf16_f32 v90, v90, s0
	ds_write_b16 v114, v90 offset:16928
	v_sub_f32_e32 v90, v94, v93
	v_mul_f32_e32 v90, v90, v89
	v_fma_f32 v90, v110, v90, v111
	v_cvt_pk_bf16_f32 v90, v90, s0
	ds_write_b16 v114, v90 offset:33824
	v_sub_f32_e32 v90, v95, v93
	v_mul_f32_e32 v89, v90, v89
	v_fma_f32 v89, v112, v89, v113
	v_cvt_pk_bf16_f32 v89, v89, s0
	v_lshlrev_b32_e32 v90, 16, v209
	ds_write_b16 v114, v89 offset:50720
	v_mul_f32_e32 v89, 0x3d372713, v90
	v_mul_f32_e32 v89, v89, v90
	v_mov_b32_e32 v92, v90
	v_fmac_f32_e32 v92, v89, v92
	v_mul_f32_e32 v89, 0x3f4c422a, v92
	v_add_f32_e32 v89, v89, v89
	v_lshlrev_b32_e32 v91, 16, v210
	v_mul_f32_e32 v89, 0xbfb8aa3b, v89
	v_exp_f32_e32 v92, v89
	v_mul_f32_e32 v89, 0x3d372713, v91
	v_mul_f32_e32 v89, v89, v91
	v_mov_b32_e32 v93, v91
	v_fmac_f32_e32 v93, v89, v93
	v_mul_f32_e32 v89, 0x3f4c422a, v93
	v_add_f32_e32 v89, v89, v89
	v_mul_f32_e32 v89, 0xbfb8aa3b, v89
	v_exp_f32_e32 v93, v89
	s_nop 0
	v_pk_add_f32 v[92:93], v[92:93], 1.0 op_sel_hi:[1,0]
	s_nop 0
	v_rcp_f32_e32 v93, v93
	v_lshlrev_b32_e32 v94, 16, v211
	v_mul_f32_e32 v96, 0x3d372713, v94
	v_mul_f32_e32 v96, v96, v94
	v_mov_b32_e32 v97, v94
	v_lshlrev_b32_e32 v95, 16, v212
	v_fmac_f32_e32 v97, v96, v97
	v_mul_f32_e32 v96, 0x3f4c422a, v97
	v_mul_f32_e32 v97, 0x3d372713, v95
	v_mul_f32_e32 v97, v97, v95
	v_mov_b32_e32 v98, v95
	v_fmac_f32_e32 v98, v97, v98
	v_mul_f32_e32 v97, 0x3f4c422a, v98
	v_add_f32_e32 v96, v96, v96
	v_add_f32_e32 v97, v97, v97
	v_mul_f32_e32 v96, 0xbfb8aa3b, v96
	v_mul_f32_e32 v97, 0xbfb8aa3b, v97
	v_exp_f32_e32 v96, v96
	v_exp_f32_e32 v97, v97
	v_rcp_f32_e32 v92, v92
	s_nop 0
	v_pk_mul_f32 v[90:91], v[92:93], v[90:91]
	v_pk_add_f32 v[96:97], v[96:97], 1.0 op_sel_hi:[1,0]
	s_nop 0
	v_add_f32_e32 v89, 0, v90
	v_add_f32_e32 v89, v89, v91
	v_pk_mul_f32 v[92:93], v[90:91], v[90:91]
	v_rcp_f32_e32 v97, v97
	v_add_f32_e32 v92, v92, v93
	v_rcp_f32_e32 v96, v96
	s_nop 0
	v_pk_mul_f32 v[94:95], v[96:97], v[94:95]
	s_nop 0
	v_add_f32_e32 v89, v89, v94
	v_add_f32_e32 v89, v89, v95
	v_pk_mul_f32 v[96:97], v[94:95], v[94:95]
	s_nop 0
	v_add_f32_dpp v89, v89, v89 quad_perm:[1,0,3,2] row_mask:0xf bank_mask:0xf bound_ctrl:1
	v_add_f32_e32 v92, v92, v96
	v_add_f32_e32 v92, v92, v97
	v_add_f32_dpp v89, v89, v89 quad_perm:[2,3,0,1] row_mask:0xf bank_mask:0xf bound_ctrl:1
	s_nop 1
	v_add_f32_dpp v89, v89, v89 row_half_mirror row_mask:0xf bank_mask:0xf bound_ctrl:1
	s_nop 1
	v_add_f32_dpp v89, v89, v89 row_mirror row_mask:0xf bank_mask:0xf bound_ctrl:1
	s_nop 0
	v_readlane_b32 s7, v89, 0
	v_readlane_b32 s5, v89, 16
	v_readlane_b32 s13, v89, 32
	v_readlane_b32 s9, v89, 48
	v_add_f32_dpp v89, v92, v92 quad_perm:[1,0,3,2] row_mask:0xf bank_mask:0xf bound_ctrl:1
	v_mov_b32_e32 v93, s5
	v_mov_b32_e32 v97, s9
	v_add_f32_dpp v89, v89, v89 quad_perm:[2,3,0,1] row_mask:0xf bank_mask:0xf bound_ctrl:1
	s_nop 1
	v_add_f32_dpp v89, v89, v89 row_half_mirror row_mask:0xf bank_mask:0xf bound_ctrl:1
	s_nop 1
	v_add_f32_dpp v89, v89, v89 row_mirror row_mask:0xf bank_mask:0xf bound_ctrl:1
	s_nop 0
	v_readlane_b32 s11, v89, 16
	v_readlane_b32 s14, v89, 48
	v_readlane_b32 s6, v89, 0
	v_readlane_b32 s12, v89, 32
	v_mov_b32_e32 v92, s11
	v_mov_b32_e32 v96, s14
	v_pk_add_f32 v[92:93], s[6:7], v[92:93]
	v_pk_add_f32 v[96:97], s[12:13], v[96:97]
	s_nop 0
	v_pk_add_f32 v[92:93], v[92:93], v[96:97]
	s_nop 0
	v_pk_mul_f32 v[92:93], v[92:93], s[20:21] op_sel_hi:[1,0]
	s_nop 0
	v_fma_f32 v89, -v93, v93, v92
	v_max_f32_e32 v89, 0, v89
	v_add_f32_e32 v89, 0x3727c5ac, v89
	v_cmp_gt_f32_e32 vcc, s18, v89
	v_mul_f32_e32 v92, 0x4b800000, v89
	v_sub_f32_e32 v90, v90, v93
	v_cndmask_b32_e32 v89, v89, v92, vcc
	v_rsq_f32_e32 v89, v89
	s_nop 0
	v_mul_f32_e32 v92, 0x45800000, v89
	v_cndmask_b32_e32 v89, v89, v92, vcc
	v_mul_f32_e32 v90, v90, v89
	v_fma_f32 v90, v67, v90, v106
	v_cvt_pk_bf16_f32 v90, v90, s0
	ds_write_b16 v114, v90 offset:48
	v_sub_f32_e32 v90, v91, v93
	v_mul_f32_e32 v90, v90, v89
	v_fma_f32 v90, v107, v90, v108
	v_cvt_pk_bf16_f32 v90, v90, s0
	ds_write_b16 v114, v90 offset:16944
	v_sub_f32_e32 v90, v94, v93
	v_mul_f32_e32 v90, v90, v89
	v_fma_f32 v90, v110, v90, v111
	v_cvt_pk_bf16_f32 v90, v90, s0
	ds_write_b16 v114, v90 offset:33840
	v_sub_f32_e32 v90, v95, v93
	v_mul_f32_e32 v89, v90, v89
	v_fma_f32 v89, v112, v89, v113
	v_cvt_pk_bf16_f32 v89, v89, s0
	v_lshlrev_b32_e32 v90, 16, v119
	ds_write_b16 v114, v89 offset:50736
	v_mul_f32_e32 v89, 0x3d372713, v90
	v_mul_f32_e32 v89, v89, v90
	v_mov_b32_e32 v92, v90
	v_fmac_f32_e32 v92, v89, v92
	v_mul_f32_e32 v89, 0x3f4c422a, v92
	v_add_f32_e32 v89, v89, v89
	v_lshlrev_b32_e32 v91, 16, v120
	v_mul_f32_e32 v89, 0xbfb8aa3b, v89
	v_exp_f32_e32 v92, v89
	v_mul_f32_e32 v89, 0x3d372713, v91
	v_mul_f32_e32 v89, v89, v91
	v_mov_b32_e32 v93, v91
	v_fmac_f32_e32 v93, v89, v93
	v_mul_f32_e32 v89, 0x3f4c422a, v93
	v_add_f32_e32 v89, v89, v89
	v_mul_f32_e32 v89, 0xbfb8aa3b, v89
	v_exp_f32_e32 v93, v89
	s_nop 0
	v_pk_add_f32 v[92:93], v[92:93], 1.0 op_sel_hi:[1,0]
	s_nop 0
	v_rcp_f32_e32 v93, v93
	v_lshlrev_b32_e32 v94, 16, v117
	v_mul_f32_e32 v96, 0x3d372713, v94
	v_mul_f32_e32 v96, v96, v94
	v_mov_b32_e32 v97, v94
	v_lshlrev_b32_e32 v95, 16, v118
	v_fmac_f32_e32 v97, v96, v97
	v_mul_f32_e32 v96, 0x3f4c422a, v97
	v_mul_f32_e32 v97, 0x3d372713, v95
	v_mul_f32_e32 v97, v97, v95
	v_mov_b32_e32 v98, v95
	v_fmac_f32_e32 v98, v97, v98
	v_mul_f32_e32 v97, 0x3f4c422a, v98
	v_add_f32_e32 v96, v96, v96
	v_add_f32_e32 v97, v97, v97
	v_mul_f32_e32 v96, 0xbfb8aa3b, v96
	v_mul_f32_e32 v97, 0xbfb8aa3b, v97
	v_exp_f32_e32 v96, v96
	v_exp_f32_e32 v97, v97
	v_rcp_f32_e32 v92, v92
	s_nop 0
	v_pk_mul_f32 v[90:91], v[92:93], v[90:91]
	v_pk_add_f32 v[96:97], v[96:97], 1.0 op_sel_hi:[1,0]
	s_nop 0
	v_add_f32_e32 v89, 0, v90
	v_add_f32_e32 v89, v89, v91
	v_pk_mul_f32 v[92:93], v[90:91], v[90:91]
	v_rcp_f32_e32 v97, v97
	v_add_f32_e32 v92, v92, v93
	v_rcp_f32_e32 v96, v96
	s_nop 0
	v_pk_mul_f32 v[94:95], v[96:97], v[94:95]
	s_nop 0
	v_add_f32_e32 v89, v89, v94
	v_add_f32_e32 v89, v89, v95
	v_pk_mul_f32 v[96:97], v[94:95], v[94:95]
	s_nop 0
	v_add_f32_dpp v89, v89, v89 quad_perm:[1,0,3,2] row_mask:0xf bank_mask:0xf bound_ctrl:1
	v_add_f32_e32 v92, v92, v96
	v_add_f32_e32 v92, v92, v97
	v_add_f32_dpp v89, v89, v89 quad_perm:[2,3,0,1] row_mask:0xf bank_mask:0xf bound_ctrl:1
	s_nop 1
	v_add_f32_dpp v89, v89, v89 row_half_mirror row_mask:0xf bank_mask:0xf bound_ctrl:1
	s_nop 1
	v_add_f32_dpp v89, v89, v89 row_mirror row_mask:0xf bank_mask:0xf bound_ctrl:1
	s_nop 0
	v_readlane_b32 s7, v89, 0
	v_readlane_b32 s5, v89, 16
	v_readlane_b32 s13, v89, 32
	v_readlane_b32 s9, v89, 48
	v_add_f32_dpp v89, v92, v92 quad_perm:[1,0,3,2] row_mask:0xf bank_mask:0xf bound_ctrl:1
	v_mov_b32_e32 v93, s5
	v_mov_b32_e32 v97, s9
	v_add_f32_dpp v89, v89, v89 quad_perm:[2,3,0,1] row_mask:0xf bank_mask:0xf bound_ctrl:1
	s_nop 1
	v_add_f32_dpp v89, v89, v89 row_half_mirror row_mask:0xf bank_mask:0xf bound_ctrl:1
	s_nop 1
	v_add_f32_dpp v89, v89, v89 row_mirror row_mask:0xf bank_mask:0xf bound_ctrl:1
	s_nop 0
	v_readlane_b32 s11, v89, 16
	v_readlane_b32 s14, v89, 48
	v_readlane_b32 s6, v89, 0
	v_readlane_b32 s12, v89, 32
	v_mov_b32_e32 v92, s11
	v_mov_b32_e32 v96, s14
	v_pk_add_f32 v[92:93], s[6:7], v[92:93]
	v_pk_add_f32 v[96:97], s[12:13], v[96:97]
	s_nop 0
	v_pk_add_f32 v[92:93], v[92:93], v[96:97]
	s_nop 0
	v_pk_mul_f32 v[92:93], v[92:93], s[20:21] op_sel_hi:[1,0]
	s_nop 0
	v_fma_f32 v89, -v93, v93, v92
	v_max_f32_e32 v89, 0, v89
	v_add_f32_e32 v89, 0x3727c5ac, v89
	v_cmp_gt_f32_e32 vcc, s18, v89
	v_mul_f32_e32 v92, 0x4b800000, v89
	v_sub_f32_e32 v90, v90, v93
	v_cndmask_b32_e32 v89, v89, v92, vcc
	v_rsq_f32_e32 v89, v89
	s_nop 0
	v_mul_f32_e32 v92, 0x45800000, v89
	v_cndmask_b32_e32 v89, v89, v92, vcc
	v_mul_f32_e32 v90, v90, v89
	v_fma_f32 v90, v67, v90, v106
	v_cvt_pk_bf16_f32 v90, v90, s0
	ds_write_b16 v114, v90 offset:64
	v_sub_f32_e32 v90, v91, v93
	v_mul_f32_e32 v90, v90, v89
	v_fma_f32 v90, v107, v90, v108
	v_cvt_pk_bf16_f32 v90, v90, s0
	ds_write_b16 v114, v90 offset:16960
	v_sub_f32_e32 v90, v94, v93
	v_mul_f32_e32 v90, v90, v89
	v_fma_f32 v90, v110, v90, v111
	v_cvt_pk_bf16_f32 v90, v90, s0
	ds_write_b16 v114, v90 offset:33856
	v_sub_f32_e32 v90, v95, v93
	v_mul_f32_e32 v89, v90, v89
	v_fma_f32 v89, v112, v89, v113
	v_cvt_pk_bf16_f32 v89, v89, s0
	v_lshlrev_b32_e32 v90, 16, v115
	ds_write_b16 v114, v89 offset:50752
	v_mul_f32_e32 v89, 0x3d372713, v90
	v_mul_f32_e32 v89, v89, v90
	v_mov_b32_e32 v92, v90
	v_fmac_f32_e32 v92, v89, v92
	v_mul_f32_e32 v89, 0x3f4c422a, v92
	v_add_f32_e32 v89, v89, v89
	v_lshlrev_b32_e32 v91, 16, v116
	v_mul_f32_e32 v89, 0xbfb8aa3b, v89
	v_exp_f32_e32 v92, v89
	v_mul_f32_e32 v89, 0x3d372713, v91
	v_mul_f32_e32 v89, v89, v91
	v_mov_b32_e32 v93, v91
	v_fmac_f32_e32 v93, v89, v93
	v_mul_f32_e32 v89, 0x3f4c422a, v93
	v_add_f32_e32 v89, v89, v89
	v_mul_f32_e32 v89, 0xbfb8aa3b, v89
	v_exp_f32_e32 v93, v89
	s_nop 0
	v_pk_add_f32 v[92:93], v[92:93], 1.0 op_sel_hi:[1,0]
	s_nop 0
	v_rcp_f32_e32 v93, v93
	v_rcp_f32_e32 v92, v92
	s_nop 0
	v_pk_mul_f32 v[90:91], v[92:93], v[90:91]
	s_nop 0
	v_add_f32_e32 v89, 0, v90
	v_add_f32_e32 v96, v89, v91
	v_lshlrev_b32_e32 v89, 16, v88
	v_lshlrev_b32_e32 v88, 16, v87
	v_mul_f32_e32 v87, 0x3d372713, v88
	v_mul_f32_e32 v87, v87, v88
	v_mov_b32_e32 v94, v88
	v_fmac_f32_e32 v94, v87, v94
	v_mul_f32_e32 v87, 0x3f4c422a, v94
	v_add_f32_e32 v87, v87, v87
	v_mul_f32_e32 v87, 0xbfb8aa3b, v87
	v_exp_f32_e32 v94, v87
	v_mul_f32_e32 v87, 0x3d372713, v89
	v_mul_f32_e32 v87, v87, v89
	v_mov_b32_e32 v95, v89
	v_fmac_f32_e32 v95, v87, v95
	v_mul_f32_e32 v87, 0x3f4c422a, v95
	v_add_f32_e32 v87, v87, v87
	v_mul_f32_e32 v87, 0xbfb8aa3b, v87
	v_exp_f32_e32 v95, v87
	v_pk_mul_f32 v[92:93], v[90:91], v[90:91]
	v_pk_add_f32 v[94:95], v[94:95], 1.0 op_sel_hi:[1,0]
	s_nop 0
	v_add_f32_e32 v92, v92, v93
	v_rcp_f32_e32 v95, v95
	v_rcp_f32_e32 v94, v94
	s_nop 0
	v_pk_mul_f32 v[88:89], v[94:95], v[88:89]
	s_nop 0
	v_add_f32_e32 v87, v96, v88
	v_add_f32_e32 v87, v87, v89
	v_pk_mul_f32 v[94:95], v[88:89], v[88:89]
	s_nop 0
	v_add_f32_dpp v87, v87, v87 quad_perm:[1,0,3,2] row_mask:0xf bank_mask:0xf bound_ctrl:1
	v_add_f32_e32 v92, v92, v94
	v_add_f32_e32 v92, v92, v95
	v_add_f32_dpp v87, v87, v87 quad_perm:[2,3,0,1] row_mask:0xf bank_mask:0xf bound_ctrl:1
	s_nop 1
	v_add_f32_dpp v87, v87, v87 row_half_mirror row_mask:0xf bank_mask:0xf bound_ctrl:1
	s_nop 1
	v_add_f32_dpp v87, v87, v87 row_mirror row_mask:0xf bank_mask:0xf bound_ctrl:1
	s_nop 0
	v_readlane_b32 s7, v87, 0
	v_readlane_b32 s5, v87, 16
	v_readlane_b32 s13, v87, 32
	v_readlane_b32 s9, v87, 48
	v_add_f32_dpp v87, v92, v92 quad_perm:[1,0,3,2] row_mask:0xf bank_mask:0xf bound_ctrl:1
	v_mov_b32_e32 v93, s5
	v_mov_b32_e32 v95, s9
	v_add_f32_dpp v87, v87, v87 quad_perm:[2,3,0,1] row_mask:0xf bank_mask:0xf bound_ctrl:1
	s_nop 1
	v_add_f32_dpp v87, v87, v87 row_half_mirror row_mask:0xf bank_mask:0xf bound_ctrl:1
	s_nop 1
	v_add_f32_dpp v87, v87, v87 row_mirror row_mask:0xf bank_mask:0xf bound_ctrl:1
	s_nop 0
	v_readlane_b32 s11, v87, 16
	v_readlane_b32 s14, v87, 48
	v_readlane_b32 s6, v87, 0
	v_readlane_b32 s12, v87, 32
	v_mov_b32_e32 v92, s11
	v_mov_b32_e32 v94, s14
	v_pk_add_f32 v[92:93], s[6:7], v[92:93]
	v_pk_add_f32 v[94:95], s[12:13], v[94:95]
	s_nop 0
	v_pk_add_f32 v[92:93], v[92:93], v[94:95]
	s_nop 0
	v_pk_mul_f32 v[92:93], v[92:93], s[20:21] op_sel_hi:[1,0]
	s_nop 0
	v_fma_f32 v87, -v93, v93, v92
	v_max_f32_e32 v87, 0, v87
	v_add_f32_e32 v87, 0x3727c5ac, v87
	v_cmp_gt_f32_e32 vcc, s18, v87
	v_mul_f32_e32 v92, 0x4b800000, v87
	v_sub_f32_e32 v90, v90, v93
	v_cndmask_b32_e32 v87, v87, v92, vcc
	v_rsq_f32_e32 v87, v87
	v_sub_f32_e32 v88, v88, v93
	v_mul_f32_e32 v92, 0x45800000, v87
	v_cndmask_b32_e32 v87, v87, v92, vcc
	v_mul_f32_e32 v90, v90, v87
	v_mul_f32_e32 v88, v88, v87
	v_fma_f32 v90, v67, v90, v106
	v_fma_f32 v88, v110, v88, v111
	v_cvt_pk_bf16_f32 v90, v90, s0
	v_cvt_pk_bf16_f32 v88, v88, s0
	ds_write_b16 v114, v90 offset:80
	v_sub_f32_e32 v90, v91, v93
	ds_write_b16 v114, v88 offset:33872
	v_sub_f32_e32 v88, v89, v93
	v_mul_f32_e32 v90, v90, v87
	v_mul_f32_e32 v87, v88, v87
	v_fma_f32 v87, v112, v87, v113
	v_cvt_pk_bf16_f32 v87, v87, s0
	ds_write_b16 v114, v87 offset:50768
	v_lshlrev_b32_e32 v87, 16, v86
	v_lshlrev_b32_e32 v86, 16, v85
	v_mul_f32_e32 v85, 0x3d372713, v86
	v_mul_f32_e32 v85, v85, v86
	v_mov_b32_e32 v88, v86
	v_fmac_f32_e32 v88, v85, v88
	v_mul_f32_e32 v85, 0x3f4c422a, v88
	v_add_f32_e32 v85, v85, v85
	v_mul_f32_e32 v85, 0xbfb8aa3b, v85
	v_exp_f32_e32 v88, v85
	v_mul_f32_e32 v85, 0x3d372713, v87
	v_mul_f32_e32 v85, v85, v87
	v_mov_b32_e32 v89, v87
	v_fmac_f32_e32 v89, v85, v89
	v_mul_f32_e32 v85, 0x3f4c422a, v89
	v_add_f32_e32 v85, v85, v85
	v_mul_f32_e32 v85, 0xbfb8aa3b, v85
	v_exp_f32_e32 v89, v85
	v_fma_f32 v90, v107, v90, v108
	v_cvt_pk_bf16_f32 v90, v90, s0
	ds_write_b16 v114, v90 offset:16976
	v_pk_add_f32 v[88:89], v[88:89], 1.0 op_sel_hi:[1,0]
	s_nop 0
	v_rcp_f32_e32 v89, v89
	v_rcp_f32_e32 v88, v88
	s_nop 0
	v_pk_mul_f32 v[86:87], v[88:89], v[86:87]
	s_nop 0
	v_add_f32_e32 v85, 0, v86
	v_add_f32_e32 v92, v85, v87
	v_lshlrev_b32_e32 v85, 16, v84
	v_lshlrev_b32_e32 v84, 16, v83
	v_mul_f32_e32 v83, 0x3d372713, v84
	v_mul_f32_e32 v83, v83, v84
	v_mov_b32_e32 v90, v84
	v_fmac_f32_e32 v90, v83, v90
	v_mul_f32_e32 v83, 0x3f4c422a, v90
	v_add_f32_e32 v83, v83, v83
	v_mul_f32_e32 v83, 0xbfb8aa3b, v83
	v_exp_f32_e32 v90, v83
	v_mul_f32_e32 v83, 0x3d372713, v85
	v_mul_f32_e32 v83, v83, v85
	v_mov_b32_e32 v91, v85
	v_fmac_f32_e32 v91, v83, v91
	v_mul_f32_e32 v83, 0x3f4c422a, v91
	v_add_f32_e32 v83, v83, v83
	v_mul_f32_e32 v83, 0xbfb8aa3b, v83
	v_exp_f32_e32 v91, v83
	v_pk_mul_f32 v[88:89], v[86:87], v[86:87]
	v_pk_add_f32 v[90:91], v[90:91], 1.0 op_sel_hi:[1,0]
	s_nop 0
	v_add_f32_e32 v88, v88, v89
	v_rcp_f32_e32 v91, v91
	v_rcp_f32_e32 v90, v90
	s_nop 0
	v_pk_mul_f32 v[84:85], v[90:91], v[84:85]
	s_nop 0
	v_add_f32_e32 v83, v92, v84
	v_add_f32_e32 v83, v83, v85
	v_pk_mul_f32 v[90:91], v[84:85], v[84:85]
	s_nop 0
	v_add_f32_dpp v83, v83, v83 quad_perm:[1,0,3,2] row_mask:0xf bank_mask:0xf bound_ctrl:1
	v_add_f32_e32 v88, v88, v90
	v_add_f32_e32 v88, v88, v91
	v_add_f32_dpp v83, v83, v83 quad_perm:[2,3,0,1] row_mask:0xf bank_mask:0xf bound_ctrl:1
	s_nop 1
	v_add_f32_dpp v83, v83, v83 row_half_mirror row_mask:0xf bank_mask:0xf bound_ctrl:1
	s_nop 1
	v_add_f32_dpp v83, v83, v83 row_mirror row_mask:0xf bank_mask:0xf bound_ctrl:1
	s_nop 0
	v_readlane_b32 s7, v83, 0
	v_readlane_b32 s5, v83, 16
	v_readlane_b32 s13, v83, 32
	v_readlane_b32 s9, v83, 48
	v_add_f32_dpp v83, v88, v88 quad_perm:[1,0,3,2] row_mask:0xf bank_mask:0xf bound_ctrl:1
	v_mov_b32_e32 v89, s5
	v_mov_b32_e32 v91, s9
	v_add_f32_dpp v83, v83, v83 quad_perm:[2,3,0,1] row_mask:0xf bank_mask:0xf bound_ctrl:1
	s_nop 1
	v_add_f32_dpp v83, v83, v83 row_half_mirror row_mask:0xf bank_mask:0xf bound_ctrl:1
	s_nop 1
	v_add_f32_dpp v83, v83, v83 row_mirror row_mask:0xf bank_mask:0xf bound_ctrl:1
	s_nop 0
	v_readlane_b32 s11, v83, 16
	v_readlane_b32 s14, v83, 48
	v_readlane_b32 s6, v83, 0
	v_readlane_b32 s12, v83, 32
	v_mov_b32_e32 v88, s11
	v_mov_b32_e32 v90, s14
	v_pk_add_f32 v[88:89], s[6:7], v[88:89]
	v_pk_add_f32 v[90:91], s[12:13], v[90:91]
	s_nop 0
	v_pk_add_f32 v[88:89], v[88:89], v[90:91]
	s_nop 0
	v_pk_mul_f32 v[88:89], v[88:89], s[20:21] op_sel_hi:[1,0]
	s_nop 0
	v_fma_f32 v83, -v89, v89, v88
	v_max_f32_e32 v83, 0, v83
	v_add_f32_e32 v83, 0x3727c5ac, v83
	v_cmp_gt_f32_e32 vcc, s18, v83
	v_mul_f32_e32 v88, 0x4b800000, v83
	v_sub_f32_e32 v86, v86, v89
	v_cndmask_b32_e32 v83, v83, v88, vcc
	v_rsq_f32_e32 v83, v83
	v_sub_f32_e32 v84, v84, v89
	v_mul_f32_e32 v88, 0x45800000, v83
	v_cndmask_b32_e32 v83, v83, v88, vcc
	v_mul_f32_e32 v86, v86, v83
	v_mul_f32_e32 v84, v84, v83
	v_fma_f32 v86, v67, v86, v106
	v_fma_f32 v84, v110, v84, v111
	v_cvt_pk_bf16_f32 v86, v86, s0
	v_cvt_pk_bf16_f32 v84, v84, s0
	ds_write_b16 v114, v86 offset:96
	v_sub_f32_e32 v86, v87, v89
	ds_write_b16 v114, v84 offset:33888
	v_sub_f32_e32 v84, v85, v89
	v_mul_f32_e32 v86, v86, v83
	v_mul_f32_e32 v83, v84, v83
	v_fma_f32 v83, v112, v83, v113
	v_cvt_pk_bf16_f32 v83, v83, s0
	ds_write_b16 v114, v83 offset:50784
	v_lshlrev_b32_e32 v83, 16, v82
	v_lshlrev_b32_e32 v82, 16, v81
	v_mul_f32_e32 v81, 0x3d372713, v82
	v_mul_f32_e32 v81, v81, v82
	v_mov_b32_e32 v84, v82
	v_fmac_f32_e32 v84, v81, v84
	v_mul_f32_e32 v81, 0x3f4c422a, v84
	v_add_f32_e32 v81, v81, v81
	v_mul_f32_e32 v81, 0xbfb8aa3b, v81
	v_exp_f32_e32 v84, v81
	v_mul_f32_e32 v81, 0x3d372713, v83
	v_mul_f32_e32 v81, v81, v83
	v_mov_b32_e32 v85, v83
	v_fmac_f32_e32 v85, v81, v85
	v_mul_f32_e32 v81, 0x3f4c422a, v85
	v_add_f32_e32 v81, v81, v81
	v_mul_f32_e32 v81, 0xbfb8aa3b, v81
	v_exp_f32_e32 v85, v81
	v_fma_f32 v86, v107, v86, v108
	v_cvt_pk_bf16_f32 v86, v86, s0
	ds_write_b16 v114, v86 offset:16992
	v_pk_add_f32 v[84:85], v[84:85], 1.0 op_sel_hi:[1,0]
	s_nop 0
	v_rcp_f32_e32 v85, v85
	v_rcp_f32_e32 v84, v84
	s_nop 0
	v_pk_mul_f32 v[82:83], v[84:85], v[82:83]
	s_nop 0
	v_add_f32_e32 v81, 0, v82
	v_add_f32_e32 v88, v81, v83
	v_lshlrev_b32_e32 v81, 16, v80
	v_lshlrev_b32_e32 v80, 16, v79
	v_mul_f32_e32 v79, 0x3d372713, v80
	v_mul_f32_e32 v79, v79, v80
	v_mov_b32_e32 v86, v80
	v_fmac_f32_e32 v86, v79, v86
	v_mul_f32_e32 v79, 0x3f4c422a, v86
	v_add_f32_e32 v79, v79, v79
	v_mul_f32_e32 v79, 0xbfb8aa3b, v79
	v_exp_f32_e32 v86, v79
	v_mul_f32_e32 v79, 0x3d372713, v81
	v_mul_f32_e32 v79, v79, v81
	v_mov_b32_e32 v87, v81
	v_fmac_f32_e32 v87, v79, v87
	v_mul_f32_e32 v79, 0x3f4c422a, v87
	v_add_f32_e32 v79, v79, v79
	v_mul_f32_e32 v79, 0xbfb8aa3b, v79
	v_exp_f32_e32 v87, v79
	v_pk_mul_f32 v[84:85], v[82:83], v[82:83]
	v_pk_add_f32 v[86:87], v[86:87], 1.0 op_sel_hi:[1,0]
	s_nop 0
	v_add_f32_e32 v84, v84, v85
	v_rcp_f32_e32 v87, v87
	v_rcp_f32_e32 v86, v86
	s_nop 0
	v_pk_mul_f32 v[80:81], v[86:87], v[80:81]
	s_nop 0
	v_add_f32_e32 v79, v88, v80
	v_add_f32_e32 v79, v79, v81
	v_pk_mul_f32 v[86:87], v[80:81], v[80:81]
	s_nop 0
	v_add_f32_dpp v79, v79, v79 quad_perm:[1,0,3,2] row_mask:0xf bank_mask:0xf bound_ctrl:1
	v_add_f32_e32 v84, v84, v86
	v_add_f32_e32 v84, v84, v87
	v_add_f32_dpp v79, v79, v79 quad_perm:[2,3,0,1] row_mask:0xf bank_mask:0xf bound_ctrl:1
	s_nop 1
	v_add_f32_dpp v79, v79, v79 row_half_mirror row_mask:0xf bank_mask:0xf bound_ctrl:1
	s_nop 1
	v_add_f32_dpp v79, v79, v79 row_mirror row_mask:0xf bank_mask:0xf bound_ctrl:1
	s_nop 0
	v_readlane_b32 s7, v79, 0
	v_readlane_b32 s5, v79, 16
	v_readlane_b32 s13, v79, 32
	v_readlane_b32 s9, v79, 48
	v_add_f32_dpp v79, v84, v84 quad_perm:[1,0,3,2] row_mask:0xf bank_mask:0xf bound_ctrl:1
	v_mov_b32_e32 v85, s5
	v_mov_b32_e32 v87, s9
	v_add_f32_dpp v79, v79, v79 quad_perm:[2,3,0,1] row_mask:0xf bank_mask:0xf bound_ctrl:1
	s_nop 1
	v_add_f32_dpp v79, v79, v79 row_half_mirror row_mask:0xf bank_mask:0xf bound_ctrl:1
	s_nop 1
	v_add_f32_dpp v79, v79, v79 row_mirror row_mask:0xf bank_mask:0xf bound_ctrl:1
	s_nop 0
	v_readlane_b32 s11, v79, 16
	v_readlane_b32 s14, v79, 48
	v_readlane_b32 s6, v79, 0
	v_readlane_b32 s12, v79, 32
	v_mov_b32_e32 v84, s11
	v_mov_b32_e32 v86, s14
	v_pk_add_f32 v[84:85], s[6:7], v[84:85]
	v_pk_add_f32 v[86:87], s[12:13], v[86:87]
	s_nop 0
	v_pk_add_f32 v[84:85], v[84:85], v[86:87]
	s_nop 0
	v_pk_mul_f32 v[84:85], v[84:85], s[20:21] op_sel_hi:[1,0]
	s_nop 0
	v_fma_f32 v79, -v85, v85, v84
	v_max_f32_e32 v79, 0, v79
	v_add_f32_e32 v79, 0x3727c5ac, v79
	v_cmp_gt_f32_e32 vcc, s18, v79
	v_mul_f32_e32 v84, 0x4b800000, v79
	v_sub_f32_e32 v82, v82, v85
	v_cndmask_b32_e32 v79, v79, v84, vcc
	v_rsq_f32_e32 v79, v79
	v_sub_f32_e32 v80, v80, v85
	v_mul_f32_e32 v84, 0x45800000, v79
	v_cndmask_b32_e32 v79, v79, v84, vcc
	v_mul_f32_e32 v82, v82, v79
	v_mul_f32_e32 v80, v80, v79
	v_fma_f32 v82, v67, v82, v106
	v_fma_f32 v80, v110, v80, v111
	v_cvt_pk_bf16_f32 v82, v82, s0
	v_cvt_pk_bf16_f32 v80, v80, s0
	ds_write_b16 v114, v82 offset:112
	v_sub_f32_e32 v82, v83, v85
	ds_write_b16 v114, v80 offset:33904
	v_sub_f32_e32 v80, v81, v85
	v_mul_f32_e32 v82, v82, v79
	v_mul_f32_e32 v79, v80, v79
	v_fma_f32 v79, v112, v79, v113
	v_cvt_pk_bf16_f32 v79, v79, s0
	ds_write_b16 v114, v79 offset:50800
	v_lshlrev_b32_e32 v79, 16, v78
	v_lshlrev_b32_e32 v78, 16, v77
	v_mul_f32_e32 v77, 0x3d372713, v78
	v_mul_f32_e32 v77, v77, v78
	v_mov_b32_e32 v80, v78
	v_fmac_f32_e32 v80, v77, v80
	v_mul_f32_e32 v77, 0x3f4c422a, v80
	v_add_f32_e32 v77, v77, v77
	v_mul_f32_e32 v77, 0xbfb8aa3b, v77
	v_exp_f32_e32 v80, v77
	v_mul_f32_e32 v77, 0x3d372713, v79
	v_mul_f32_e32 v77, v77, v79
	v_mov_b32_e32 v81, v79
	v_fmac_f32_e32 v81, v77, v81
	v_mul_f32_e32 v77, 0x3f4c422a, v81
	v_add_f32_e32 v77, v77, v77
	v_mul_f32_e32 v77, 0xbfb8aa3b, v77
	v_exp_f32_e32 v81, v77
	v_fma_f32 v82, v107, v82, v108
	v_cvt_pk_bf16_f32 v82, v82, s0
	ds_write_b16 v114, v82 offset:17008
	v_pk_add_f32 v[80:81], v[80:81], 1.0 op_sel_hi:[1,0]
	s_nop 0
	v_rcp_f32_e32 v81, v81
	v_mul_f32_e32 v82, 0x3d372713, v14
	v_mul_f32_e32 v82, v82, v14
	v_mov_b32_e32 v83, v14
	v_fmac_f32_e32 v83, v82, v83
	v_mul_f32_e32 v82, 0x3f4c422a, v83
	v_mul_f32_e32 v83, 0x3d372713, v15
	v_mul_f32_e32 v83, v83, v15
	v_mov_b32_e32 v84, v15
	v_fmac_f32_e32 v84, v83, v84
	v_mul_f32_e32 v83, 0x3f4c422a, v84
	v_add_f32_e32 v82, v82, v82
	v_add_f32_e32 v83, v83, v83
	v_mul_f32_e32 v82, 0xbfb8aa3b, v82
	v_mul_f32_e32 v83, 0xbfb8aa3b, v83
	v_exp_f32_e32 v82, v82
	v_exp_f32_e32 v83, v83
	v_rcp_f32_e32 v80, v80
	s_nop 0
	v_pk_mul_f32 v[78:79], v[80:81], v[78:79]
	v_pk_add_f32 v[82:83], v[82:83], 1.0 op_sel_hi:[1,0]
	s_nop 0
	v_add_f32_e32 v77, 0, v78
	v_add_f32_e32 v77, v77, v79
	v_pk_mul_f32 v[80:81], v[78:79], v[78:79]
	v_rcp_f32_e32 v83, v83
	v_add_f32_e32 v80, v80, v81
	v_rcp_f32_e32 v82, v82
	s_nop 0
	v_pk_mul_f32 v[14:15], v[82:83], v[14:15]
	s_nop 0
	v_add_f32_e32 v77, v77, v14
	v_add_f32_e32 v77, v77, v15
	v_pk_mul_f32 v[82:83], v[14:15], v[14:15]
	s_nop 0
	v_add_f32_dpp v77, v77, v77 quad_perm:[1,0,3,2] row_mask:0xf bank_mask:0xf bound_ctrl:1
	v_add_f32_e32 v80, v80, v82
	v_add_f32_e32 v80, v80, v83
	v_add_f32_dpp v77, v77, v77 quad_perm:[2,3,0,1] row_mask:0xf bank_mask:0xf bound_ctrl:1
	s_nop 1
	v_add_f32_dpp v77, v77, v77 row_half_mirror row_mask:0xf bank_mask:0xf bound_ctrl:1
	s_nop 1
	v_add_f32_dpp v77, v77, v77 row_mirror row_mask:0xf bank_mask:0xf bound_ctrl:1
	s_nop 0
	v_readlane_b32 s7, v77, 0
	v_readlane_b32 s5, v77, 16
	v_readlane_b32 s13, v77, 32
	v_readlane_b32 s9, v77, 48
	v_add_f32_dpp v77, v80, v80 quad_perm:[1,0,3,2] row_mask:0xf bank_mask:0xf bound_ctrl:1
	v_mov_b32_e32 v81, s5
	v_mov_b32_e32 v83, s9
	v_add_f32_dpp v77, v77, v77 quad_perm:[2,3,0,1] row_mask:0xf bank_mask:0xf bound_ctrl:1
	s_nop 1
	v_add_f32_dpp v77, v77, v77 row_half_mirror row_mask:0xf bank_mask:0xf bound_ctrl:1
	s_nop 1
	v_add_f32_dpp v77, v77, v77 row_mirror row_mask:0xf bank_mask:0xf bound_ctrl:1
	s_nop 0
	v_readlane_b32 s11, v77, 16
	v_readlane_b32 s14, v77, 48
	v_readlane_b32 s6, v77, 0
	v_readlane_b32 s12, v77, 32
	v_mov_b32_e32 v80, s11
	v_mov_b32_e32 v82, s14
	v_pk_add_f32 v[80:81], s[6:7], v[80:81]
	v_pk_add_f32 v[82:83], s[12:13], v[82:83]
	s_nop 0
	v_pk_add_f32 v[80:81], v[80:81], v[82:83]
	s_nop 0
	v_pk_mul_f32 v[80:81], v[80:81], s[20:21] op_sel_hi:[1,0]
	s_nop 0
	v_fma_f32 v77, -v81, v81, v80
	v_max_f32_e32 v77, 0, v77
	v_add_f32_e32 v77, 0x3727c5ac, v77
	v_cmp_gt_f32_e32 vcc, s18, v77
	v_mul_f32_e32 v80, 0x4b800000, v77
	v_sub_f32_e32 v14, v14, v81
	v_cndmask_b32_e32 v77, v77, v80, vcc
	v_rsq_f32_e32 v77, v77
	v_sub_f32_e32 v78, v78, v81
	v_mul_f32_e32 v80, 0x45800000, v77
	v_cndmask_b32_e32 v77, v77, v80, vcc
	v_mul_f32_e32 v14, v14, v77
	v_fma_f32 v14, v110, v14, v111
	v_cvt_pk_bf16_f32 v14, v14, s0
	ds_write_b16 v114, v14 offset:33920
	v_sub_f32_e32 v14, v15, v81
	v_mul_f32_e32 v14, v14, v77
	v_fma_f32 v14, v112, v14, v113
	v_cvt_pk_bf16_f32 v14, v14, s0
	v_mul_f32_e32 v78, v78, v77
	ds_write_b16 v114, v14 offset:50816
	v_mul_f32_e32 v14, 0x3d372713, v12
	v_fma_f32 v78, v67, v78, v106
	v_mul_f32_e32 v14, v14, v12
	v_mov_b32_e32 v15, v12
	v_cvt_pk_bf16_f32 v78, v78, s0
	v_fmac_f32_e32 v15, v14, v15
	ds_write_b16 v114, v78 offset:128
	v_sub_f32_e32 v78, v79, v81
	v_mul_f32_e32 v14, 0x3f4c422a, v15
	v_mul_f32_e32 v15, 0x3d372713, v13
	v_mul_f32_e32 v78, v78, v77
	v_mul_f32_e32 v15, v15, v13
	v_mov_b32_e32 v77, v13
	v_fmac_f32_e32 v77, v15, v77
	v_mul_f32_e32 v15, 0x3f4c422a, v77
	v_add_f32_e32 v14, v14, v14
	v_add_f32_e32 v15, v15, v15
	v_mul_f32_e32 v14, 0xbfb8aa3b, v14
	v_mul_f32_e32 v15, 0xbfb8aa3b, v15
	v_exp_f32_e32 v14, v14
	v_exp_f32_e32 v15, v15
	v_fma_f32 v78, v107, v78, v108
	v_cvt_pk_bf16_f32 v78, v78, s0
	ds_write_b16 v114, v78 offset:17024
	v_pk_add_f32 v[14:15], v[14:15], 1.0 op_sel_hi:[1,0]
	s_nop 0
	v_rcp_f32_e32 v15, v15
	v_mul_f32_e32 v78, 0x3d372713, v10
	v_mul_f32_e32 v78, v78, v10
	v_mov_b32_e32 v79, v10
	v_fmac_f32_e32 v79, v78, v79
	v_mul_f32_e32 v78, 0x3f4c422a, v79
	v_mul_f32_e32 v79, 0x3d372713, v11
	v_mul_f32_e32 v79, v79, v11
	v_mov_b32_e32 v80, v11
	v_fmac_f32_e32 v80, v79, v80
	v_mul_f32_e32 v79, 0x3f4c422a, v80
	v_add_f32_e32 v78, v78, v78
	v_add_f32_e32 v79, v79, v79
	v_mul_f32_e32 v78, 0xbfb8aa3b, v78
	v_mul_f32_e32 v79, 0xbfb8aa3b, v79
	v_exp_f32_e32 v78, v78
	v_exp_f32_e32 v79, v79
	v_rcp_f32_e32 v14, v14
	s_nop 0
	v_pk_mul_f32 v[12:13], v[14:15], v[12:13]
	v_pk_add_f32 v[78:79], v[78:79], 1.0 op_sel_hi:[1,0]
	s_nop 0
	v_add_f32_e32 v14, 0, v12
	v_add_f32_e32 v77, v14, v13
	v_pk_mul_f32 v[14:15], v[12:13], v[12:13]
	v_rcp_f32_e32 v79, v79
	v_add_f32_e32 v14, v14, v15
	v_rcp_f32_e32 v78, v78
	s_nop 0
	v_pk_mul_f32 v[10:11], v[78:79], v[10:11]
	v_lshlrev_b32_e32 v81, 16, v76
	v_pk_mul_f32 v[78:79], v[10:11], v[10:11]
	v_add_f32_e32 v77, v77, v10
	v_add_f32_e32 v14, v14, v78
	v_add_f32_e32 v77, v77, v11
	v_add_f32_e32 v14, v14, v79
	s_nop 0
	v_add_f32_dpp v15, v77, v77 quad_perm:[1,0,3,2] row_mask:0xf bank_mask:0xf bound_ctrl:1
	v_add_f32_dpp v14, v14, v14 quad_perm:[1,0,3,2] row_mask:0xf bank_mask:0xf bound_ctrl:1
	s_nop 0
	v_add_f32_dpp v15, v15, v15 quad_perm:[2,3,0,1] row_mask:0xf bank_mask:0xf bound_ctrl:1
	v_add_f32_dpp v14, v14, v14 quad_perm:[2,3,0,1] row_mask:0xf bank_mask:0xf bound_ctrl:1
	s_nop 0
	v_add_f32_dpp v15, v15, v15 row_half_mirror row_mask:0xf bank_mask:0xf bound_ctrl:1
	v_add_f32_dpp v14, v14, v14 row_half_mirror row_mask:0xf bank_mask:0xf bound_ctrl:1
	s_nop 0
	v_add_f32_dpp v15, v15, v15 row_mirror row_mask:0xf bank_mask:0xf bound_ctrl:1
	v_add_f32_dpp v14, v14, v14 row_mirror row_mask:0xf bank_mask:0xf bound_ctrl:1
	v_readlane_b32 s5, v15, 16
	v_readlane_b32 s9, v15, 48
	v_readlane_b32 s11, v14, 16
	v_readlane_b32 s14, v14, 48
	v_readlane_b32 s7, v15, 0
	v_readlane_b32 s13, v15, 32
	v_readlane_b32 s6, v14, 0
	v_readlane_b32 s12, v14, 32
	v_mov_b32_e32 v14, s11
	v_mov_b32_e32 v15, s5
	v_mov_b32_e32 v78, s14
	v_mov_b32_e32 v79, s9
	v_pk_add_f32 v[14:15], s[6:7], v[14:15]
	v_pk_add_f32 v[78:79], s[12:13], v[78:79]
	s_nop 0
	v_pk_add_f32 v[14:15], v[14:15], v[78:79]
	s_nop 0
	v_pk_mul_f32 v[14:15], v[14:15], s[20:21] op_sel_hi:[1,0]
	s_nop 0
	v_fma_f32 v14, -v15, v15, v14
	v_max_f32_e32 v14, 0, v14
	v_add_f32_e32 v14, 0x3727c5ac, v14
	v_cmp_gt_f32_e32 vcc, s18, v14
	v_mul_f32_e32 v77, 0x4b800000, v14
	v_sub_f32_e32 v12, v12, v15
	v_cndmask_b32_e32 v14, v14, v77, vcc
	v_rsq_f32_e32 v14, v14
	v_sub_f32_e32 v10, v10, v15
	v_sub_f32_e32 v11, v11, v15
	v_mul_f32_e32 v77, 0x45800000, v14
	v_cndmask_b32_e32 v14, v14, v77, vcc
	global_load_dword v77, v[0:1], off
	global_load_dword v78, v[2:3], off
	v_mul_f32_e32 v12, v12, v14
	v_mul_f32_e32 v80, v10, v14
	s_waitcnt vmcnt(0)
	v_fma_f32 v12, v77, v12, v78
	v_cvt_pk_bf16_f32 v12, v12, s0
	ds_write_b16 v114, v12 offset:144
	v_sub_f32_e32 v12, v13, v15
	v_mul_f32_e32 v79, v12, v14
	global_load_dword v12, v[0:1], off offset:256
	global_load_dword v13, v[2:3], off offset:256
	v_mul_f32_e32 v15, v11, v14
	s_waitcnt vmcnt(0)
	v_fma_f32 v79, v12, v79, v13
	v_cvt_pk_bf16_f32 v79, v79, s0
	ds_write_b16 v114, v79 offset:17040
	global_load_dword v10, v[0:1], off offset:512
	global_load_dword v79, v[2:3], off offset:512
	s_waitcnt vmcnt(0)
	v_fma_f32 v80, v10, v80, v79
	v_cvt_pk_bf16_f32 v80, v80, s0
	ds_write_b16 v114, v80 offset:33936
	global_load_dword v11, v[0:1], off offset:768
	global_load_dword v14, v[2:3], off offset:768
	v_lshlrev_b32_e32 v80, 16, v35
	v_mov_b32_e32 v35, v80
	s_waitcnt vmcnt(0)
	v_fma_f32 v15, v11, v15, v14
	v_cvt_pk_bf16_f32 v15, v15, s0
	ds_write_b16 v114, v15 offset:50832
	v_mul_f32_e32 v15, 0x3d372713, v80
	v_mul_f32_e32 v15, v15, v80
	v_fmac_f32_e32 v35, v15, v35
	v_mul_f32_e32 v15, 0x3f4c422a, v35
	v_add_f32_e32 v15, v15, v15
	v_mul_f32_e32 v15, 0xbfb8aa3b, v15
	v_exp_f32_e32 v82, v15
	v_mul_f32_e32 v15, 0x3d372713, v81
	v_mul_f32_e32 v15, v15, v81
	v_mov_b32_e32 v35, v81
	v_fmac_f32_e32 v35, v15, v35
	v_mul_f32_e32 v15, 0x3f4c422a, v35
	v_add_f32_e32 v15, v15, v15
	v_mul_f32_e32 v15, 0xbfb8aa3b, v15
	v_exp_f32_e32 v83, v15
	s_nop 0
	v_pk_add_f32 v[82:83], v[82:83], 1.0 op_sel_hi:[1,0]
	s_nop 0
	v_rcp_f32_e32 v83, v83
	v_lshlrev_b32_e32 v35, 16, v34
	v_lshlrev_b32_e32 v34, 16, v33
	v_mul_f32_e32 v33, 0x3d372713, v34
	v_mul_f32_e32 v33, v33, v34
	v_mov_b32_e32 v76, v34
	v_fmac_f32_e32 v76, v33, v76
	v_mul_f32_e32 v33, 0x3f4c422a, v76
	v_add_f32_e32 v33, v33, v33
	v_mul_f32_e32 v33, 0xbfb8aa3b, v33
	v_exp_f32_e32 v84, v33
	v_mul_f32_e32 v33, 0x3d372713, v35
	v_mul_f32_e32 v33, v33, v35
	v_mov_b32_e32 v76, v35
	v_fmac_f32_e32 v76, v33, v76
	v_mul_f32_e32 v33, 0x3f4c422a, v76
	v_add_f32_e32 v33, v33, v33
	v_mul_f32_e32 v33, 0xbfb8aa3b, v33
	v_exp_f32_e32 v85, v33
	v_rcp_f32_e32 v82, v82
	s_nop 0
	v_pk_mul_f32 v[80:81], v[82:83], v[80:81]
	v_pk_add_f32 v[84:85], v[84:85], 1.0 op_sel_hi:[1,0]
	s_nop 0
	v_add_f32_e32 v15, 0, v80
	v_add_f32_e32 v15, v15, v81
	v_pk_mul_f32 v[82:83], v[80:81], v[80:81]
	v_rcp_f32_e32 v85, v85
	v_rcp_f32_e32 v84, v84
	s_nop 0
	v_pk_mul_f32 v[34:35], v[84:85], v[34:35]
	v_add_f32_e32 v33, v82, v83
	v_add_f32_e32 v15, v15, v34
	v_add_f32_e32 v15, v15, v35
	v_pk_mul_f32 v[84:85], v[34:35], v[34:35]
	s_nop 0
	v_add_f32_dpp v15, v15, v15 quad_perm:[1,0,3,2] row_mask:0xf bank_mask:0xf bound_ctrl:1
	v_add_f32_e32 v33, v33, v84
	v_add_f32_e32 v33, v33, v85
	v_add_f32_dpp v15, v15, v15 quad_perm:[2,3,0,1] row_mask:0xf bank_mask:0xf bound_ctrl:1
	s_nop 1
	v_add_f32_dpp v15, v15, v15 row_half_mirror row_mask:0xf bank_mask:0xf bound_ctrl:1
	s_nop 1
	v_add_f32_dpp v15, v15, v15 row_mirror row_mask:0xf bank_mask:0xf bound_ctrl:1
	s_nop 0
	v_readlane_b32 s7, v15, 0
	v_readlane_b32 s5, v15, 16
	v_readlane_b32 s13, v15, 32
	v_readlane_b32 s9, v15, 48
	v_add_f32_dpp v15, v33, v33 quad_perm:[1,0,3,2] row_mask:0xf bank_mask:0xf bound_ctrl:1
	v_mov_b32_e32 v83, s5
	v_mov_b32_e32 v85, s9
	v_add_f32_dpp v15, v15, v15 quad_perm:[2,3,0,1] row_mask:0xf bank_mask:0xf bound_ctrl:1
	s_nop 1
	v_add_f32_dpp v15, v15, v15 row_half_mirror row_mask:0xf bank_mask:0xf bound_ctrl:1
	s_nop 1
	v_add_f32_dpp v15, v15, v15 row_mirror row_mask:0xf bank_mask:0xf bound_ctrl:1
	s_nop 0
	v_readlane_b32 s11, v15, 16
	v_readlane_b32 s14, v15, 48
	v_readlane_b32 s6, v15, 0
	v_readlane_b32 s12, v15, 32
	v_mov_b32_e32 v82, s11
	v_mov_b32_e32 v84, s14
	v_pk_add_f32 v[82:83], s[6:7], v[82:83]
	v_pk_add_f32 v[84:85], s[12:13], v[84:85]
	s_nop 0
	v_pk_add_f32 v[82:83], v[82:83], v[84:85]
	s_nop 0
	v_pk_mul_f32 v[82:83], v[82:83], s[20:21] op_sel_hi:[1,0]
	s_nop 0
	v_fma_f32 v15, -v83, v83, v82
	v_max_f32_e32 v15, 0, v15
	v_add_f32_e32 v15, 0x3727c5ac, v15
	v_cmp_gt_f32_e32 vcc, s18, v15
	v_mul_f32_e32 v33, 0x4b800000, v15
	s_nop 0
	v_cndmask_b32_e32 v15, v15, v33, vcc
	v_rsq_f32_e32 v15, v15
	s_nop 0
	v_mul_f32_e32 v33, 0x45800000, v15
	v_cndmask_b32_e32 v15, v15, v33, vcc
	v_sub_f32_e32 v33, v80, v83
	v_mul_f32_e32 v33, v33, v15
	v_fma_f32 v33, v77, v33, v78
	v_cvt_pk_bf16_f32 v33, v33, s0
	ds_write_b16 v114, v33 offset:160
	v_sub_f32_e32 v33, v81, v83
	v_mul_f32_e32 v33, v33, v15
	v_fma_f32 v33, v12, v33, v13
	v_cvt_pk_bf16_f32 v33, v33, s0
	ds_write_b16 v114, v33 offset:17056
	v_sub_f32_e32 v33, v34, v83
	v_mul_f32_e32 v33, v33, v15
	v_fma_f32 v33, v10, v33, v79
	v_cvt_pk_bf16_f32 v33, v33, s0
	ds_write_b16 v114, v33 offset:33952
	v_sub_f32_e32 v33, v35, v83
	v_mul_f32_e32 v15, v33, v15
	v_fma_f32 v15, v11, v15, v14
	v_cvt_pk_bf16_f32 v15, v15, s0
	v_lshlrev_b32_e32 v33, 16, v32
	v_lshlrev_b32_e32 v32, 16, v31
	ds_write_b16 v114, v15 offset:50848
	v_mul_f32_e32 v15, 0x3d372713, v32
	v_mul_f32_e32 v15, v15, v32
	v_mov_b32_e32 v31, v32
	v_fmac_f32_e32 v31, v15, v31
	v_mul_f32_e32 v15, 0x3f4c422a, v31
	v_add_f32_e32 v15, v15, v15
	v_mul_f32_e32 v15, 0xbfb8aa3b, v15
	v_exp_f32_e32 v34, v15
	v_mul_f32_e32 v15, 0x3d372713, v33
	v_mul_f32_e32 v15, v15, v33
	v_mov_b32_e32 v31, v33
	v_fmac_f32_e32 v31, v15, v31
	v_mul_f32_e32 v15, 0x3f4c422a, v31
	v_add_f32_e32 v15, v15, v15
	v_mul_f32_e32 v15, 0xbfb8aa3b, v15
	v_exp_f32_e32 v35, v15
	s_nop 0
	v_pk_add_f32 v[34:35], v[34:35], 1.0 op_sel_hi:[1,0]
	s_nop 0
	v_rcp_f32_e32 v35, v35
	v_lshlrev_b32_e32 v31, 16, v30
	v_lshlrev_b32_e32 v30, 16, v29
	v_mul_f32_e32 v29, 0x3d372713, v30
	v_mul_f32_e32 v29, v29, v30
	v_mov_b32_e32 v76, v30
	v_fmac_f32_e32 v76, v29, v76
	v_mul_f32_e32 v29, 0x3f4c422a, v76
	v_add_f32_e32 v29, v29, v29
	v_mul_f32_e32 v29, 0xbfb8aa3b, v29
	v_exp_f32_e32 v80, v29
	v_mul_f32_e32 v29, 0x3d372713, v31
	v_mul_f32_e32 v29, v29, v31
	v_mov_b32_e32 v76, v31
	v_fmac_f32_e32 v76, v29, v76
	v_mul_f32_e32 v29, 0x3f4c422a, v76
	v_add_f32_e32 v29, v29, v29
	v_mul_f32_e32 v29, 0xbfb8aa3b, v29
	v_exp_f32_e32 v81, v29
	v_rcp_f32_e32 v34, v34
	s_nop 0
	v_pk_mul_f32 v[32:33], v[34:35], v[32:33]
	v_pk_add_f32 v[80:81], v[80:81], 1.0 op_sel_hi:[1,0]
	s_nop 0
	v_add_f32_e32 v15, 0, v32
	v_add_f32_e32 v15, v15, v33
	v_pk_mul_f32 v[34:35], v[32:33], v[32:33]
	v_rcp_f32_e32 v81, v81
	v_rcp_f32_e32 v80, v80
	s_nop 0
	v_pk_mul_f32 v[30:31], v[80:81], v[30:31]
	v_add_f32_e32 v29, v34, v35
	v_add_f32_e32 v15, v15, v30
	v_add_f32_e32 v15, v15, v31
	v_pk_mul_f32 v[80:81], v[30:31], v[30:31]
	s_nop 0
	v_add_f32_dpp v15, v15, v15 quad_perm:[1,0,3,2] row_mask:0xf bank_mask:0xf bound_ctrl:1
	v_add_f32_e32 v29, v29, v80
	v_add_f32_e32 v29, v29, v81
	v_add_f32_dpp v15, v15, v15 quad_perm:[2,3,0,1] row_mask:0xf bank_mask:0xf bound_ctrl:1
	s_nop 1
	v_add_f32_dpp v15, v15, v15 row_half_mirror row_mask:0xf bank_mask:0xf bound_ctrl:1
	s_nop 1
	v_add_f32_dpp v15, v15, v15 row_mirror row_mask:0xf bank_mask:0xf bound_ctrl:1
	s_nop 0
	v_readlane_b32 s7, v15, 0
	v_readlane_b32 s5, v15, 16
	v_readlane_b32 s13, v15, 32
	v_readlane_b32 s9, v15, 48
	v_add_f32_dpp v15, v29, v29 quad_perm:[1,0,3,2] row_mask:0xf bank_mask:0xf bound_ctrl:1
	v_mov_b32_e32 v35, s5
	v_mov_b32_e32 v81, s9
	v_add_f32_dpp v15, v15, v15 quad_perm:[2,3,0,1] row_mask:0xf bank_mask:0xf bound_ctrl:1
	s_nop 1
	v_add_f32_dpp v15, v15, v15 row_half_mirror row_mask:0xf bank_mask:0xf bound_ctrl:1
	s_nop 1
	v_add_f32_dpp v15, v15, v15 row_mirror row_mask:0xf bank_mask:0xf bound_ctrl:1
	s_nop 0
	v_readlane_b32 s11, v15, 16
	v_readlane_b32 s14, v15, 48
	v_readlane_b32 s6, v15, 0
	v_readlane_b32 s12, v15, 32
	v_mov_b32_e32 v34, s11
	v_mov_b32_e32 v80, s14
	v_pk_add_f32 v[34:35], s[6:7], v[34:35]
	v_pk_add_f32 v[80:81], s[12:13], v[80:81]
	s_nop 0
	v_pk_add_f32 v[34:35], v[34:35], v[80:81]
	s_nop 0
	v_pk_mul_f32 v[34:35], v[34:35], s[20:21] op_sel_hi:[1,0]
	s_nop 0
	v_fma_f32 v15, -v35, v35, v34
	v_max_f32_e32 v15, 0, v15
	v_add_f32_e32 v15, 0x3727c5ac, v15
	v_cmp_gt_f32_e32 vcc, s18, v15
	v_mul_f32_e32 v29, 0x4b800000, v15
	s_nop 0
	v_cndmask_b32_e32 v15, v15, v29, vcc
	v_rsq_f32_e32 v15, v15
	s_nop 0
	v_mul_f32_e32 v29, 0x45800000, v15
	v_cndmask_b32_e32 v15, v15, v29, vcc
	v_sub_f32_e32 v29, v32, v35
	v_mul_f32_e32 v29, v29, v15
	v_fma_f32 v29, v77, v29, v78
	v_cvt_pk_bf16_f32 v29, v29, s0
	ds_write_b16 v114, v29 offset:176
	v_sub_f32_e32 v29, v33, v35
	v_mul_f32_e32 v29, v29, v15
	v_fma_f32 v29, v12, v29, v13
	v_cvt_pk_bf16_f32 v29, v29, s0
	ds_write_b16 v114, v29 offset:17072
	v_sub_f32_e32 v29, v30, v35
	v_mul_f32_e32 v29, v29, v15
	v_fma_f32 v29, v10, v29, v79
	v_cvt_pk_bf16_f32 v29, v29, s0
	ds_write_b16 v114, v29 offset:33968
	v_sub_f32_e32 v29, v31, v35
	v_mul_f32_e32 v15, v29, v15
	v_fma_f32 v15, v11, v15, v14
	v_cvt_pk_bf16_f32 v15, v15, s0
	v_lshlrev_b32_e32 v29, 16, v28
	v_lshlrev_b32_e32 v28, 16, v27
	ds_write_b16 v114, v15 offset:50864
	v_mul_f32_e32 v15, 0x3d372713, v28
	v_mul_f32_e32 v15, v15, v28
	v_mov_b32_e32 v27, v28
	v_fmac_f32_e32 v27, v15, v27
	v_mul_f32_e32 v15, 0x3f4c422a, v27
	v_add_f32_e32 v15, v15, v15
	v_mul_f32_e32 v15, 0xbfb8aa3b, v15
	v_exp_f32_e32 v30, v15
	v_mul_f32_e32 v15, 0x3d372713, v29
	v_mul_f32_e32 v15, v15, v29
	v_mov_b32_e32 v27, v29
	v_fmac_f32_e32 v27, v15, v27
	v_mul_f32_e32 v15, 0x3f4c422a, v27
	v_add_f32_e32 v15, v15, v15
	v_mul_f32_e32 v15, 0xbfb8aa3b, v15
	v_exp_f32_e32 v31, v15
	s_nop 0
	v_pk_add_f32 v[30:31], v[30:31], 1.0 op_sel_hi:[1,0]
	s_nop 0
	v_rcp_f32_e32 v31, v31
	v_lshlrev_b32_e32 v27, 16, v26
	v_lshlrev_b32_e32 v26, 16, v25
	v_mul_f32_e32 v25, 0x3d372713, v26
	v_mul_f32_e32 v25, v25, v26
	v_mov_b32_e32 v32, v26
	v_fmac_f32_e32 v32, v25, v32
	v_mul_f32_e32 v25, 0x3f4c422a, v32
	v_add_f32_e32 v25, v25, v25
	v_mul_f32_e32 v25, 0xbfb8aa3b, v25
	v_exp_f32_e32 v32, v25
	v_mul_f32_e32 v25, 0x3d372713, v27
	v_mul_f32_e32 v25, v25, v27
	v_mov_b32_e32 v33, v27
	v_fmac_f32_e32 v33, v25, v33
	v_mul_f32_e32 v25, 0x3f4c422a, v33
	v_add_f32_e32 v25, v25, v25
	v_mul_f32_e32 v25, 0xbfb8aa3b, v25
	v_exp_f32_e32 v33, v25
	v_rcp_f32_e32 v30, v30
	s_nop 0
	v_pk_mul_f32 v[28:29], v[30:31], v[28:29]
	v_pk_add_f32 v[32:33], v[32:33], 1.0 op_sel_hi:[1,0]
	s_nop 0
	v_add_f32_e32 v15, 0, v28
	v_add_f32_e32 v15, v15, v29
	v_pk_mul_f32 v[30:31], v[28:29], v[28:29]
	v_rcp_f32_e32 v33, v33
	v_rcp_f32_e32 v32, v32
	s_nop 0
	v_pk_mul_f32 v[26:27], v[32:33], v[26:27]
	v_add_f32_e32 v25, v30, v31
	v_add_f32_e32 v15, v15, v26
	v_add_f32_e32 v15, v15, v27
	v_pk_mul_f32 v[32:33], v[26:27], v[26:27]
	s_nop 0
	v_add_f32_dpp v15, v15, v15 quad_perm:[1,0,3,2] row_mask:0xf bank_mask:0xf bound_ctrl:1
	v_add_f32_e32 v25, v25, v32
	v_add_f32_e32 v25, v25, v33
	v_add_f32_dpp v15, v15, v15 quad_perm:[2,3,0,1] row_mask:0xf bank_mask:0xf bound_ctrl:1
	s_nop 1
	v_add_f32_dpp v15, v15, v15 row_half_mirror row_mask:0xf bank_mask:0xf bound_ctrl:1
	s_nop 1
	v_add_f32_dpp v15, v15, v15 row_mirror row_mask:0xf bank_mask:0xf bound_ctrl:1
	s_nop 0
	v_readlane_b32 s7, v15, 0
	v_readlane_b32 s5, v15, 16
	v_readlane_b32 s13, v15, 32
	v_readlane_b32 s9, v15, 48
	v_add_f32_dpp v15, v25, v25 quad_perm:[1,0,3,2] row_mask:0xf bank_mask:0xf bound_ctrl:1
	v_mov_b32_e32 v31, s5
	v_mov_b32_e32 v33, s9
	v_add_f32_dpp v15, v15, v15 quad_perm:[2,3,0,1] row_mask:0xf bank_mask:0xf bound_ctrl:1
	s_nop 1
	v_add_f32_dpp v15, v15, v15 row_half_mirror row_mask:0xf bank_mask:0xf bound_ctrl:1
	s_nop 1
	v_add_f32_dpp v15, v15, v15 row_mirror row_mask:0xf bank_mask:0xf bound_ctrl:1
	s_nop 0
	v_readlane_b32 s11, v15, 16
	v_readlane_b32 s14, v15, 48
	v_readlane_b32 s6, v15, 0
	v_readlane_b32 s12, v15, 32
	v_mov_b32_e32 v30, s11
	v_mov_b32_e32 v32, s14
	v_pk_add_f32 v[30:31], s[6:7], v[30:31]
	v_pk_add_f32 v[32:33], s[12:13], v[32:33]
	s_nop 0
	v_pk_add_f32 v[30:31], v[30:31], v[32:33]
	s_nop 0
	v_pk_mul_f32 v[30:31], v[30:31], s[20:21] op_sel_hi:[1,0]
	s_nop 0
	v_fma_f32 v15, -v31, v31, v30
	v_max_f32_e32 v15, 0, v15
	v_add_f32_e32 v15, 0x3727c5ac, v15
	v_cmp_gt_f32_e32 vcc, s18, v15
	v_mul_f32_e32 v25, 0x4b800000, v15
	s_nop 0
	v_cndmask_b32_e32 v15, v15, v25, vcc
	v_rsq_f32_e32 v15, v15
	s_nop 0
	v_mul_f32_e32 v25, 0x45800000, v15
	v_cndmask_b32_e32 v15, v15, v25, vcc
	v_sub_f32_e32 v25, v28, v31
	v_mul_f32_e32 v25, v25, v15
	v_fma_f32 v25, v77, v25, v78
	v_cvt_pk_bf16_f32 v25, v25, s0
	ds_write_b16 v114, v25 offset:192
	v_sub_f32_e32 v25, v29, v31
	v_mul_f32_e32 v25, v25, v15
	v_fma_f32 v25, v12, v25, v13
	v_cvt_pk_bf16_f32 v25, v25, s0
	ds_write_b16 v114, v25 offset:17088
	v_sub_f32_e32 v25, v26, v31
	v_mul_f32_e32 v25, v25, v15
	v_fma_f32 v25, v10, v25, v79
	v_cvt_pk_bf16_f32 v25, v25, s0
	ds_write_b16 v114, v25 offset:33984
	v_sub_f32_e32 v25, v27, v31
	v_mul_f32_e32 v15, v25, v15
	v_fma_f32 v15, v11, v15, v14
	v_cvt_pk_bf16_f32 v15, v15, s0
	v_lshlrev_b32_e32 v25, 16, v24
	v_lshlrev_b32_e32 v24, 16, v23
	ds_write_b16 v114, v15 offset:50880
	v_mul_f32_e32 v15, 0x3d372713, v24
	v_mul_f32_e32 v15, v15, v24
	v_mov_b32_e32 v23, v24
	v_fmac_f32_e32 v23, v15, v23
	v_mul_f32_e32 v15, 0x3f4c422a, v23
	v_add_f32_e32 v15, v15, v15
	v_mul_f32_e32 v15, 0xbfb8aa3b, v15
	v_exp_f32_e32 v26, v15
	v_mul_f32_e32 v15, 0x3d372713, v25
	v_mul_f32_e32 v15, v15, v25
	v_mov_b32_e32 v23, v25
	v_fmac_f32_e32 v23, v15, v23
	v_mul_f32_e32 v15, 0x3f4c422a, v23
	v_add_f32_e32 v15, v15, v15
	v_mul_f32_e32 v15, 0xbfb8aa3b, v15
	v_exp_f32_e32 v27, v15
	s_nop 0
	v_pk_add_f32 v[26:27], v[26:27], 1.0 op_sel_hi:[1,0]
	s_nop 0
	v_rcp_f32_e32 v27, v27
	v_lshlrev_b32_e32 v23, 16, v22
	v_lshlrev_b32_e32 v22, 16, v21
	v_mul_f32_e32 v21, 0x3d372713, v22
	v_mul_f32_e32 v21, v21, v22
	v_mov_b32_e32 v28, v22
	v_fmac_f32_e32 v28, v21, v28
	v_mul_f32_e32 v21, 0x3f4c422a, v28
	v_add_f32_e32 v21, v21, v21
	v_mul_f32_e32 v21, 0xbfb8aa3b, v21
	v_exp_f32_e32 v28, v21
	v_mul_f32_e32 v21, 0x3d372713, v23
	v_mul_f32_e32 v21, v21, v23
	v_mov_b32_e32 v29, v23
	v_fmac_f32_e32 v29, v21, v29
	v_mul_f32_e32 v21, 0x3f4c422a, v29
	v_add_f32_e32 v21, v21, v21
	v_mul_f32_e32 v21, 0xbfb8aa3b, v21
	v_exp_f32_e32 v29, v21
	v_rcp_f32_e32 v26, v26
	s_nop 0
	v_pk_mul_f32 v[24:25], v[26:27], v[24:25]
	v_pk_add_f32 v[28:29], v[28:29], 1.0 op_sel_hi:[1,0]
	s_nop 0
	v_add_f32_e32 v15, 0, v24
	v_add_f32_e32 v15, v15, v25
	v_pk_mul_f32 v[26:27], v[24:25], v[24:25]
	v_rcp_f32_e32 v29, v29
	v_rcp_f32_e32 v28, v28
	s_nop 0
	v_pk_mul_f32 v[22:23], v[28:29], v[22:23]
	v_add_f32_e32 v21, v26, v27
	v_add_f32_e32 v15, v15, v22
	v_add_f32_e32 v15, v15, v23
	v_pk_mul_f32 v[28:29], v[22:23], v[22:23]
	s_nop 0
	v_add_f32_dpp v15, v15, v15 quad_perm:[1,0,3,2] row_mask:0xf bank_mask:0xf bound_ctrl:1
	v_add_f32_e32 v21, v21, v28
	v_add_f32_e32 v21, v21, v29
	v_add_f32_dpp v15, v15, v15 quad_perm:[2,3,0,1] row_mask:0xf bank_mask:0xf bound_ctrl:1
	s_nop 1
	v_add_f32_dpp v15, v15, v15 row_half_mirror row_mask:0xf bank_mask:0xf bound_ctrl:1
	s_nop 1
	v_add_f32_dpp v15, v15, v15 row_mirror row_mask:0xf bank_mask:0xf bound_ctrl:1
	s_nop 0
	v_readlane_b32 s7, v15, 0
	v_readlane_b32 s5, v15, 16
	v_readlane_b32 s13, v15, 32
	v_readlane_b32 s9, v15, 48
	v_add_f32_dpp v15, v21, v21 quad_perm:[1,0,3,2] row_mask:0xf bank_mask:0xf bound_ctrl:1
	v_mov_b32_e32 v27, s5
	v_mov_b32_e32 v29, s9
	v_add_f32_dpp v15, v15, v15 quad_perm:[2,3,0,1] row_mask:0xf bank_mask:0xf bound_ctrl:1
	s_nop 1
	v_add_f32_dpp v15, v15, v15 row_half_mirror row_mask:0xf bank_mask:0xf bound_ctrl:1
	s_nop 1
	v_add_f32_dpp v15, v15, v15 row_mirror row_mask:0xf bank_mask:0xf bound_ctrl:1
	s_nop 0
	v_readlane_b32 s11, v15, 16
	v_readlane_b32 s14, v15, 48
	v_readlane_b32 s6, v15, 0
	v_readlane_b32 s12, v15, 32
	v_mov_b32_e32 v26, s11
	v_mov_b32_e32 v28, s14
	v_pk_add_f32 v[26:27], s[6:7], v[26:27]
	v_pk_add_f32 v[28:29], s[12:13], v[28:29]
	s_nop 0
	v_pk_add_f32 v[26:27], v[26:27], v[28:29]
	s_nop 0
	v_pk_mul_f32 v[26:27], v[26:27], s[20:21] op_sel_hi:[1,0]
	s_nop 0
	v_fma_f32 v15, -v27, v27, v26
	v_max_f32_e32 v15, 0, v15
	v_add_f32_e32 v15, 0x3727c5ac, v15
	v_cmp_gt_f32_e32 vcc, s18, v15
	v_mul_f32_e32 v21, 0x4b800000, v15
	s_nop 0
	v_cndmask_b32_e32 v15, v15, v21, vcc
	v_rsq_f32_e32 v15, v15
	s_nop 0
	v_mul_f32_e32 v21, 0x45800000, v15
	v_cndmask_b32_e32 v15, v15, v21, vcc
	v_sub_f32_e32 v21, v24, v27
	v_mul_f32_e32 v21, v21, v15
	v_fma_f32 v21, v77, v21, v78
	v_cvt_pk_bf16_f32 v21, v21, s0
	ds_write_b16 v114, v21 offset:208
	v_sub_f32_e32 v21, v25, v27
	v_mul_f32_e32 v21, v21, v15
	v_fma_f32 v21, v12, v21, v13
	v_cvt_pk_bf16_f32 v21, v21, s0
	ds_write_b16 v114, v21 offset:17104
	v_sub_f32_e32 v21, v22, v27
	v_mul_f32_e32 v21, v21, v15
	v_fma_f32 v21, v10, v21, v79
	v_cvt_pk_bf16_f32 v21, v21, s0
	ds_write_b16 v114, v21 offset:34000
	v_sub_f32_e32 v21, v23, v27
	v_mul_f32_e32 v15, v21, v15
	v_fma_f32 v15, v11, v15, v14
	v_cvt_pk_bf16_f32 v15, v15, s0
	v_lshlrev_b32_e32 v21, 16, v20
	v_lshlrev_b32_e32 v20, 16, v19
	ds_write_b16 v114, v15 offset:50896
	v_mul_f32_e32 v15, 0x3d372713, v20
	v_mul_f32_e32 v15, v15, v20
	v_mov_b32_e32 v19, v20
	v_fmac_f32_e32 v19, v15, v19
	v_mul_f32_e32 v15, 0x3f4c422a, v19
	v_add_f32_e32 v15, v15, v15
	v_mul_f32_e32 v15, 0xbfb8aa3b, v15
	v_exp_f32_e32 v22, v15
	v_mul_f32_e32 v15, 0x3d372713, v21
	v_mul_f32_e32 v15, v15, v21
	v_mov_b32_e32 v19, v21
	v_fmac_f32_e32 v19, v15, v19
	v_mul_f32_e32 v15, 0x3f4c422a, v19
	v_add_f32_e32 v15, v15, v15
	v_mul_f32_e32 v15, 0xbfb8aa3b, v15
	v_exp_f32_e32 v23, v15
	s_nop 0
	v_pk_add_f32 v[22:23], v[22:23], 1.0 op_sel_hi:[1,0]
	s_nop 0
	v_rcp_f32_e32 v23, v23
	v_lshlrev_b32_e32 v19, 16, v18
	v_lshlrev_b32_e32 v18, 16, v17
	v_mul_f32_e32 v17, 0x3d372713, v18
	v_mul_f32_e32 v17, v17, v18
	v_mov_b32_e32 v24, v18
	v_fmac_f32_e32 v24, v17, v24
	v_mul_f32_e32 v17, 0x3f4c422a, v24
	v_add_f32_e32 v17, v17, v17
	v_mul_f32_e32 v17, 0xbfb8aa3b, v17
	v_exp_f32_e32 v24, v17
	v_mul_f32_e32 v17, 0x3d372713, v19
	v_mul_f32_e32 v17, v17, v19
	v_mov_b32_e32 v25, v19
	v_fmac_f32_e32 v25, v17, v25
	v_mul_f32_e32 v17, 0x3f4c422a, v25
	v_add_f32_e32 v17, v17, v17
	v_mul_f32_e32 v17, 0xbfb8aa3b, v17
	v_exp_f32_e32 v25, v17
	v_rcp_f32_e32 v22, v22
	s_nop 0
	v_pk_mul_f32 v[20:21], v[22:23], v[20:21]
	v_pk_add_f32 v[24:25], v[24:25], 1.0 op_sel_hi:[1,0]
	s_nop 0
	v_add_f32_e32 v15, 0, v20
	v_add_f32_e32 v15, v15, v21
	v_pk_mul_f32 v[22:23], v[20:21], v[20:21]
	v_rcp_f32_e32 v25, v25
	v_rcp_f32_e32 v24, v24
	s_nop 0
	v_pk_mul_f32 v[18:19], v[24:25], v[18:19]
	v_add_f32_e32 v17, v22, v23
	v_add_f32_e32 v15, v15, v18
	v_add_f32_e32 v15, v15, v19
	v_pk_mul_f32 v[24:25], v[18:19], v[18:19]
	s_nop 0
	v_add_f32_dpp v15, v15, v15 quad_perm:[1,0,3,2] row_mask:0xf bank_mask:0xf bound_ctrl:1
	v_add_f32_e32 v17, v17, v24
	v_add_f32_e32 v17, v17, v25
	v_add_f32_dpp v15, v15, v15 quad_perm:[2,3,0,1] row_mask:0xf bank_mask:0xf bound_ctrl:1
	s_nop 1
	v_add_f32_dpp v15, v15, v15 row_half_mirror row_mask:0xf bank_mask:0xf bound_ctrl:1
	s_nop 1
	v_add_f32_dpp v15, v15, v15 row_mirror row_mask:0xf bank_mask:0xf bound_ctrl:1
	s_nop 0
	v_readlane_b32 s7, v15, 0
	v_readlane_b32 s5, v15, 16
	v_readlane_b32 s13, v15, 32
	v_readlane_b32 s9, v15, 48
	v_add_f32_dpp v15, v17, v17 quad_perm:[1,0,3,2] row_mask:0xf bank_mask:0xf bound_ctrl:1
	v_mov_b32_e32 v23, s5
	v_mov_b32_e32 v25, s9
	v_add_f32_dpp v15, v15, v15 quad_perm:[2,3,0,1] row_mask:0xf bank_mask:0xf bound_ctrl:1
	s_nop 1
	v_add_f32_dpp v15, v15, v15 row_half_mirror row_mask:0xf bank_mask:0xf bound_ctrl:1
	s_nop 1
	v_add_f32_dpp v15, v15, v15 row_mirror row_mask:0xf bank_mask:0xf bound_ctrl:1
	s_nop 0
	v_readlane_b32 s11, v15, 16
	v_readlane_b32 s14, v15, 48
	v_readlane_b32 s6, v15, 0
	v_readlane_b32 s12, v15, 32
	v_mov_b32_e32 v22, s11
	v_mov_b32_e32 v24, s14
	v_pk_add_f32 v[22:23], s[6:7], v[22:23]
	v_pk_add_f32 v[24:25], s[12:13], v[24:25]
	s_nop 0
	v_pk_add_f32 v[22:23], v[22:23], v[24:25]
	s_nop 0
	v_pk_mul_f32 v[22:23], v[22:23], s[20:21] op_sel_hi:[1,0]
	s_nop 0
	v_fma_f32 v15, -v23, v23, v22
	v_max_f32_e32 v15, 0, v15
	v_add_f32_e32 v15, 0x3727c5ac, v15
	v_cmp_gt_f32_e32 vcc, s18, v15
	v_mul_f32_e32 v17, 0x4b800000, v15
	s_nop 0
	v_cndmask_b32_e32 v15, v15, v17, vcc
	v_rsq_f32_e32 v15, v15
	s_nop 0
	v_mul_f32_e32 v17, 0x45800000, v15
	v_cndmask_b32_e32 v15, v15, v17, vcc
	v_sub_f32_e32 v17, v20, v23
	v_mul_f32_e32 v17, v17, v15
	v_fma_f32 v17, v77, v17, v78
	v_cvt_pk_bf16_f32 v17, v17, s0
	ds_write_b16 v114, v17 offset:224
	v_sub_f32_e32 v17, v21, v23
	v_mul_f32_e32 v17, v17, v15
	v_fma_f32 v17, v12, v17, v13
	v_cvt_pk_bf16_f32 v17, v17, s0
	ds_write_b16 v114, v17 offset:17120
	v_sub_f32_e32 v17, v18, v23
	v_mul_f32_e32 v17, v17, v15
	v_fma_f32 v17, v10, v17, v79
	v_cvt_pk_bf16_f32 v17, v17, s0
	ds_write_b16 v114, v17 offset:34016
	v_sub_f32_e32 v17, v19, v23
	v_mul_f32_e32 v15, v17, v15
	v_fma_f32 v15, v11, v15, v14
	v_lshlrev_b32_e32 v17, 16, v16
	v_lshlrev_b32_e32 v16, 16, v9
	v_cvt_pk_bf16_f32 v15, v15, s0
	v_mul_f32_e32 v9, 0x3d372713, v16
	ds_write_b16 v114, v15 offset:50912
	v_mul_f32_e32 v9, v9, v16
	v_mov_b32_e32 v15, v16
	v_fmac_f32_e32 v15, v9, v15
	v_mul_f32_e32 v9, 0x3f4c422a, v15
	v_add_f32_e32 v9, v9, v9
	v_mul_f32_e32 v9, 0xbfb8aa3b, v9
	v_exp_f32_e32 v18, v9
	v_mul_f32_e32 v9, 0x3d372713, v17
	v_mul_f32_e32 v9, v9, v17
	v_mov_b32_e32 v15, v17
	v_fmac_f32_e32 v15, v9, v15
	v_mul_f32_e32 v9, 0x3f4c422a, v15
	v_add_f32_e32 v9, v9, v9
	v_mul_f32_e32 v9, 0xbfb8aa3b, v9
	v_exp_f32_e32 v19, v9
	s_nop 0
	v_pk_add_f32 v[18:19], v[18:19], 1.0 op_sel_hi:[1,0]
	s_nop 0
	v_rcp_f32_e32 v19, v19
	v_lshlrev_b32_e32 v20, 16, v5
	v_mul_f32_e32 v5, 0x3d372713, v20
	v_lshlrev_b32_e32 v21, 16, v7
	v_mul_f32_e32 v5, v5, v20
	v_mov_b32_e32 v7, v20
	v_fmac_f32_e32 v7, v5, v7
	v_mul_f32_e32 v5, 0x3f4c422a, v7
	v_add_f32_e32 v5, v5, v5
	v_mul_f32_e32 v5, 0xbfb8aa3b, v5
	v_exp_f32_e32 v22, v5
	v_mul_f32_e32 v5, 0x3d372713, v21
	v_mul_f32_e32 v5, v5, v21
	v_mov_b32_e32 v7, v21
	v_fmac_f32_e32 v7, v5, v7
	v_mul_f32_e32 v5, 0x3f4c422a, v7
	v_add_f32_e32 v5, v5, v5
	v_mul_f32_e32 v5, 0xbfb8aa3b, v5
	v_exp_f32_e32 v23, v5
	v_rcp_f32_e32 v18, v18
	s_nop 0
	v_pk_mul_f32 v[16:17], v[18:19], v[16:17]
	v_pk_add_f32 v[22:23], v[22:23], 1.0 op_sel_hi:[1,0]
	s_nop 0
	v_add_f32_e32 v9, 0, v16
	v_add_f32_e32 v9, v9, v17
	v_pk_mul_f32 v[18:19], v[16:17], v[16:17]
	v_rcp_f32_e32 v23, v23
	v_rcp_f32_e32 v22, v22
	s_nop 0
	v_pk_mul_f32 v[20:21], v[22:23], v[20:21]
	v_add_f32_e32 v7, v18, v19
	v_add_f32_e32 v5, v9, v20
	v_add_f32_e32 v5, v5, v21
	v_pk_mul_f32 v[22:23], v[20:21], v[20:21]
	s_nop 0
	v_add_f32_dpp v5, v5, v5 quad_perm:[1,0,3,2] row_mask:0xf bank_mask:0xf bound_ctrl:1
	v_add_f32_e32 v7, v7, v22
	v_add_f32_e32 v7, v7, v23
	v_add_f32_dpp v5, v5, v5 quad_perm:[2,3,0,1] row_mask:0xf bank_mask:0xf bound_ctrl:1
	s_nop 1
	v_add_f32_dpp v5, v5, v5 row_half_mirror row_mask:0xf bank_mask:0xf bound_ctrl:1
	s_nop 1
	v_add_f32_dpp v5, v5, v5 row_mirror row_mask:0xf bank_mask:0xf bound_ctrl:1
	s_nop 0
	v_readlane_b32 s7, v5, 0
	v_readlane_b32 s5, v5, 16
	v_readlane_b32 s13, v5, 32
	v_readlane_b32 s9, v5, 48
	v_add_f32_dpp v5, v7, v7 quad_perm:[1,0,3,2] row_mask:0xf bank_mask:0xf bound_ctrl:1
	v_mov_b32_e32 v19, s5
	v_mov_b32_e32 v23, s9
	v_add_f32_dpp v5, v5, v5 quad_perm:[2,3,0,1] row_mask:0xf bank_mask:0xf bound_ctrl:1
	s_nop 1
	v_add_f32_dpp v5, v5, v5 row_half_mirror row_mask:0xf bank_mask:0xf bound_ctrl:1
	s_nop 1
	v_add_f32_dpp v5, v5, v5 row_mirror row_mask:0xf bank_mask:0xf bound_ctrl:1
	s_nop 0
	v_readlane_b32 s11, v5, 16
	v_readlane_b32 s14, v5, 48
	v_readlane_b32 s6, v5, 0
	v_readlane_b32 s12, v5, 32
	v_mov_b32_e32 v18, s11
	v_mov_b32_e32 v22, s14
	v_pk_add_f32 v[18:19], s[6:7], v[18:19]
	v_pk_add_f32 v[22:23], s[12:13], v[22:23]
	s_nop 0
	v_pk_add_f32 v[18:19], v[18:19], v[22:23]
	s_nop 0
	v_pk_mul_f32 v[18:19], v[18:19], s[20:21] op_sel_hi:[1,0]
	s_nop 0
	v_fma_f32 v5, -v19, v19, v18
	v_max_f32_e32 v5, 0, v5
	v_add_f32_e32 v5, 0x3727c5ac, v5
	v_cmp_gt_f32_e32 vcc, s18, v5
	v_mul_f32_e32 v7, 0x4b800000, v5
	s_nop 0
	v_cndmask_b32_e32 v5, v5, v7, vcc
	v_rsq_f32_e32 v5, v5
	s_nop 0
	v_mul_f32_e32 v7, 0x45800000, v5
	v_cndmask_b32_e32 v5, v5, v7, vcc
	v_sub_f32_e32 v7, v16, v19
	v_mul_f32_e32 v7, v7, v5
	v_fmac_f32_e32 v78, v77, v7
	v_cvt_pk_bf16_f32 v7, v78, s0
	ds_write_b16 v114, v7 offset:240
	v_sub_f32_e32 v7, v17, v19
	v_mul_f32_e32 v7, v7, v5
	v_fmac_f32_e32 v13, v12, v7
	v_cvt_pk_bf16_f32 v7, v13, s0
	ds_write_b16 v114, v7 offset:17136
	v_sub_f32_e32 v7, v20, v19
	v_mul_f32_e32 v7, v7, v5
	v_fmac_f32_e32 v79, v10, v7
	v_cvt_pk_bf16_f32 v7, v79, s0
	ds_write_b16 v114, v7 offset:34032
	v_sub_f32_e32 v7, v21, v19
	v_mul_f32_e32 v5, v7, v5
	v_fmac_f32_e32 v14, v11, v5
	v_cvt_pk_bf16_f32 v5, v14, s0
	ds_write_b16 v114, v5 offset:50928
	v_add_u32_e32 v114, 0x100, v114
	s_cbranch_scc1 .LBB0_603
.LBB0_604:
	v_readlane_b32 s4, v255, 29
	s_add_u32 s4, s0, s4
	v_or_b32_e32 v82, s10, v37
	s_addc_u32 s5, s1, 0
	v_lshlrev_b32_e32 v194, 4, v47
	v_or_b32_e32 v2, s3, v82
	v_lshl_add_u64 v[0:1], s[4:5], 0, v[194:195]
	s_mov_b64 s[4:5], 0x90a0000
	v_ashrrev_i32_e32 v3, 31, v2
	v_lshl_add_u64 v[76:77], v[0:1], 0, s[4:5]
	v_lshlrev_b64 v[2:3], 8, v[2:3]
	v_mov_b32_e32 v0, v192
	v_mov_b32_e32 v6, v192
	v_mov_b32_e32 v10, v192
	v_mov_b32_e32 v14, v192
	v_mov_b32_e32 v18, v192
	v_mov_b32_e32 v22, v192
	v_mov_b32_e32 v26, v192
	v_mov_b32_e32 v30, v192
	v_lshl_add_u64 v[2:3], v[76:77], 0, v[2:3]
	s_waitcnt vmcnt(0) lgkmcnt(0)
	s_barrier
	flat_load_dwordx4 v[32:35], v[2:3]
	v_or_b32_e32 v4, s2, v82
	v_ashrrev_i32_e32 v5, 31, v4
	v_lshlrev_b64 v[4:5], 8, v[4:5]
	v_lshl_add_u64 v[4:5], v[76:77], 0, v[4:5]
	flat_load_dwordx4 v[78:81], v[4:5]
	flat_load_dwordx4 v[90:93], v[2:3] offset:64
	v_or_b32_e32 v1, s8, v37
	s_movk_i32 s4, 0x108
	v_and_b32_e32 v2, 48, v57
	v_mul_lo_u32 v1, v1, s4
	v_add3_u32 v57, 0, v2, v1
	ds_read2_b64 v[86:89], v57 offset1:1
	v_mov_b32_e32 v1, v0
	v_add_u32_e32 v83, 0x1080, v57
	v_mov_b32_e32 v2, v0
	v_mov_b32_e32 v3, v0
	v_add_u32_e32 v84, 0x2100, v57
	v_add_u32_e32 v85, 0x3180, v57
	ds_read2_b64 v[94:97], v83 offset1:1
	ds_read2_b64 v[98:101], v84 offset1:1
	v_mov_b32_e32 v7, v6
	v_mov_b32_e32 v8, v6
	v_mov_b32_e32 v9, v6
	v_mov_b32_e32 v11, v10
	v_mov_b32_e32 v12, v10
	v_mov_b32_e32 v13, v10
	v_mov_b32_e32 v15, v14
	v_mov_b32_e32 v16, v14
	v_mov_b32_e32 v17, v14
	v_mov_b32_e32 v19, v18
	v_mov_b32_e32 v20, v18
	v_mov_b32_e32 v21, v18
	v_mov_b32_e32 v23, v22
	v_mov_b32_e32 v24, v22
	v_mov_b32_e32 v25, v22
	v_mov_b32_e32 v27, v26
	v_mov_b32_e32 v28, v26
	v_mov_b32_e32 v29, v26
	v_mov_b32_e32 v31, v30
	v_readlane_b32 s4, v253, 36
	s_waitcnt vmcnt(0) lgkmcnt(0)
	v_mfma_f32_16x16x32_bf16 v[110:113], v[86:89], v[78:81], v[18:21]
	v_or_b32_e32 v37, s4, v37
	s_mov_b64 s[4:5], 0x2040600
	v_mfma_f32_16x16x32_bf16 v[102:105], v[86:89], v[32:35], v[0:3]
	v_add_u32_e32 v86, 0x10c0, v57
	v_add_u32_e32 v87, 0x2140, v57
	v_add_u32_e32 v88, 0x31c0, v57
	ds_read2_b64 v[0:3], v85 offset1:1
	v_mfma_f32_16x16x32_bf16 v[6:9], v[94:97], v[32:35], v[6:9]
	ds_read2_b64 v[114:117], v87 offset1:1
	v_mfma_f32_16x16x32_bf16 v[10:13], v[98:101], v[32:35], v[10:13]
	s_waitcnt lgkmcnt(1)
	v_mfma_f32_16x16x32_bf16 v[14:17], v[0:3], v[32:35], v[14:17]
	v_mov_b32_e32 v32, v30
	v_mov_b32_e32 v33, v30
	v_mfma_f32_16x16x32_bf16 v[94:97], v[94:97], v[78:81], v[22:25]
	v_mfma_f32_16x16x32_bf16 v[98:101], v[98:101], v[78:81], v[26:29]
	v_mfma_f32_16x16x32_bf16 v[0:3], v[0:3], v[78:81], v[30:33]
	ds_read2_b64 v[78:81], v57 offset0:8 offset1:9
	s_waitcnt lgkmcnt(0)
	v_mfma_f32_16x16x32_bf16 v[28:31], v[78:81], v[90:93], v[102:105]
	s_nop 2
	ds_read2_b64 v[102:105], v86 offset1:1
	ds_read2_b64 v[32:35], v88 offset1:1
	s_waitcnt lgkmcnt(1)
	v_mfma_f32_16x16x32_bf16 v[24:27], v[102:105], v[90:93], v[6:9]
	v_mfma_f32_16x16x32_bf16 v[20:23], v[114:117], v[90:93], v[10:13]
	s_waitcnt lgkmcnt(0)
	v_mfma_f32_16x16x32_bf16 v[12:15], v[32:35], v[90:93], v[14:17]
	flat_load_dwordx4 v[90:93], v[4:5] offset:64
	v_lshlrev_b32_e32 v4, 2, v47
	s_waitcnt vmcnt(0) lgkmcnt(0)
	v_mfma_f32_16x16x32_bf16 v[8:11], v[102:105], v[90:93], v[94:97]
	s_nop 2
	v_lshlrev_b32_e32 v94, 16, v74
	v_mul_f32_e32 v47, 0x3d372713, v94
	v_mul_f32_e32 v47, v47, v94
	v_mov_b32_e32 v67, v94
	v_fmac_f32_e32 v67, v47, v67
	v_mul_f32_e32 v47, 0x3f4c422a, v67
	v_add_f32_e32 v47, v47, v47
	v_and_b32_e32 v95, 0xffff0000, v74
	v_mul_f32_e32 v47, 0xbfb8aa3b, v47
	v_mfma_f32_16x16x32_bf16 v[16:19], v[78:81], v[90:93], v[110:113]
	v_exp_f32_e32 v80, v47
	v_mul_f32_e32 v47, 0x3d372713, v95
	v_mul_f32_e32 v47, v47, v95
	v_mov_b32_e32 v67, v95
	v_fmac_f32_e32 v67, v47, v67
	v_mul_f32_e32 v47, 0x3f4c422a, v67
	v_add_f32_e32 v47, v47, v47
	v_mul_f32_e32 v47, 0xbfb8aa3b, v47
	v_exp_f32_e32 v81, v47
	v_mfma_f32_16x16x32_bf16 v[0:3], v[32:35], v[90:93], v[0:3]
	v_mov_b64_e32 v[32:33], s[0:1]
	v_or_b32_e32 v47, s3, v37
	v_pk_add_f32 v[34:35], v[80:81], 1.0 op_sel_hi:[1,0]
	v_mad_i64_i32 v[80:81], s[0:1], v47, s86, v[32:33]
	v_or_b32_e32 v78, s8, v4
	v_mfma_f32_16x16x32_bf16 v[4:7], v[114:117], v[90:93], v[98:101]
	v_lshl_add_u64 v[80:81], v[80:81], 0, s[4:5]
	v_rcp_f32_e32 v35, v35
	v_pk_add_f32 v[16:17], v[56:57], v[16:17] op_sel_hi:[0,1]
	v_lshlrev_b32_e32 v74, 16, v75
	v_mul_f32_e32 v67, 0x3d372713, v74
	v_mul_f32_e32 v67, v67, v74
	v_mov_b32_e32 v90, v74
	v_fmac_f32_e32 v90, v67, v90
	v_mul_f32_e32 v67, 0x3f4c422a, v90
	v_add_f32_e32 v67, v67, v67
	v_and_b32_e32 v75, 0xffff0000, v75
	v_mul_f32_e32 v67, 0xbfb8aa3b, v67
	v_exp_f32_e32 v90, v67
	v_mul_f32_e32 v67, 0x3d372713, v75
	v_mul_f32_e32 v67, v67, v75
	v_mov_b32_e32 v91, v75
	v_fmac_f32_e32 v91, v67, v91
	v_mul_f32_e32 v67, 0x3f4c422a, v91
	v_add_f32_e32 v67, v67, v67
	v_mul_f32_e32 v67, 0xbfb8aa3b, v67
	v_exp_f32_e32 v91, v67
	v_rcp_f32_e32 v34, v34
	s_nop 0
	v_pk_mul_f32 v[34:35], v[34:35], v[94:95]
	v_pk_add_f32 v[90:91], v[90:91], 1.0 op_sel_hi:[1,0]
	v_pk_add_f32 v[18:19], v[56:57], v[18:19] op_sel_hi:[0,1]
	v_pk_add_f32 v[8:9], v[56:57], v[8:9] op_sel_hi:[0,1]
	v_pk_add_f32 v[10:11], v[56:57], v[10:11] op_sel_hi:[0,1]
	v_pk_add_f32 v[4:5], v[56:57], v[4:5] op_sel_hi:[0,1]
	v_pk_add_f32 v[28:29], v[66:67], v[28:29] op_sel_hi:[0,1]
	v_pk_mul_f32 v[28:29], v[34:35], v[28:29]
	v_rcp_f32_e32 v35, v91
	v_pk_add_f32 v[6:7], v[56:57], v[6:7] op_sel_hi:[0,1]
	v_rcp_f32_e32 v34, v90
	s_nop 0
	v_pk_mul_f32 v[34:35], v[34:35], v[74:75]
	v_pk_add_f32 v[30:31], v[66:67], v[30:31] op_sel_hi:[0,1]
	v_pk_mul_f32 v[30:31], v[34:35], v[30:31]
	v_lshlrev_b32_e32 v34, 16, v72
	v_mul_f32_e32 v47, 0x3d372713, v34
	v_mul_f32_e32 v47, v47, v34
	v_mov_b32_e32 v67, v34
	v_fmac_f32_e32 v67, v47, v67
	v_mul_f32_e32 v47, 0x3f4c422a, v67
	v_add_f32_e32 v47, v47, v47
	v_and_b32_e32 v35, 0xffff0000, v72
	v_mul_f32_e32 v47, 0xbfb8aa3b, v47
	v_exp_f32_e32 v74, v47
	v_mul_f32_e32 v47, 0x3d372713, v35
	v_mul_f32_e32 v47, v47, v35
	v_mov_b32_e32 v67, v35
	v_fmac_f32_e32 v67, v47, v67
	v_mul_f32_e32 v47, 0x3f4c422a, v67
	v_add_f32_e32 v47, v47, v47
	v_mul_f32_e32 v47, 0xbfb8aa3b, v47
	v_exp_f32_e32 v75, v47
	v_cvt_pk_bf16_f32 v91, v30, v31
	v_ashrrev_i32_e32 v79, 31, v78
	v_cvt_pk_bf16_f32 v90, v28, v29
	v_pk_add_f32 v[30:31], v[74:75], 1.0 op_sel_hi:[1,0]
	v_lshlrev_b64 v[28:29], 1, v[78:79]
	v_lshl_add_u64 v[74:75], v[80:81], 0, v[28:29]
	flat_store_dwordx2 v[74:75], v[90:91]
	v_pk_add_f32 v[0:1], v[56:57], v[0:1] op_sel_hi:[0,1]
	v_rcp_f32_e32 v31, v31
	v_pk_add_f32 v[2:3], v[56:57], v[2:3] op_sel_hi:[0,1]
	v_lshlrev_b32_e32 v72, 16, v73
	v_mul_f32_e32 v74, 0x3d372713, v72
	v_mul_f32_e32 v74, v74, v72
	v_mov_b32_e32 v75, v72
	v_and_b32_e32 v73, 0xffff0000, v73
	v_fmac_f32_e32 v75, v74, v75
	v_mul_f32_e32 v74, 0x3f4c422a, v75
	v_mul_f32_e32 v75, 0x3d372713, v73
	v_mul_f32_e32 v75, v75, v73
	v_mov_b32_e32 v89, v73
	v_fmac_f32_e32 v89, v75, v89
	v_mul_f32_e32 v75, 0x3f4c422a, v89
	v_add_f32_e32 v74, v74, v74
	v_add_f32_e32 v75, v75, v75
	v_mul_f32_e32 v74, 0xbfb8aa3b, v74
	v_mul_f32_e32 v75, 0xbfb8aa3b, v75
	v_exp_f32_e32 v74, v74
	v_exp_f32_e32 v75, v75
	v_rcp_f32_e32 v30, v30
	s_nop 0
	v_pk_mul_f32 v[30:31], v[30:31], v[34:35]
	v_pk_add_f32 v[74:75], v[74:75], 1.0 op_sel_hi:[1,0]
	s_nop 0
	v_pk_add_f32 v[24:25], v[66:67], v[24:25] op_sel_hi:[0,1]
	v_pk_mul_f32 v[24:25], v[30:31], v[24:25]
	v_rcp_f32_e32 v31, v75
	v_rcp_f32_e32 v30, v74
	s_nop 0
	v_pk_mul_f32 v[30:31], v[30:31], v[72:73]
	v_pk_add_f32 v[26:27], v[66:67], v[26:27] op_sel_hi:[0,1]
	v_lshlrev_b32_e32 v34, 16, v70
	v_pk_mul_f32 v[26:27], v[30:31], v[26:27]
	v_mul_f32_e32 v31, 0x3d372713, v34
	v_mul_f32_e32 v31, v31, v34
	v_mov_b32_e32 v47, v34
	v_fmac_f32_e32 v47, v31, v47
	v_mul_f32_e32 v31, 0x3f4c422a, v47
	v_add_f32_e32 v31, v31, v31
	v_and_b32_e32 v35, 0xffff0000, v70
	v_mul_f32_e32 v31, 0xbfb8aa3b, v31
	v_exp_f32_e32 v72, v31
	v_mul_f32_e32 v31, 0x3d372713, v35
	v_mul_f32_e32 v31, v31, v35
	v_mov_b32_e32 v47, v35
	v_fmac_f32_e32 v47, v31, v47
	v_mul_f32_e32 v31, 0x3f4c422a, v47
	v_add_f32_e32 v31, v31, v31
	v_mul_f32_e32 v31, 0xbfb8aa3b, v31
	v_exp_f32_e32 v73, v31
	v_cvt_pk_bf16_f32 v24, v24, v25
	v_cvt_pk_bf16_f32 v25, v26, v27
	v_or_b32_e32 v30, 16, v78
	v_pk_add_f32 v[26:27], v[72:73], 1.0 op_sel_hi:[1,0]
	v_ashrrev_i32_e32 v31, 31, v30
	v_lshlrev_b64 v[30:31], 1, v[30:31]
	v_lshl_add_u64 v[72:73], v[80:81], 0, v[30:31]
	flat_store_dwordx2 v[72:73], v[24:25]
	v_rcp_f32_e32 v25, v27
	v_lshlrev_b32_e32 v70, 16, v71
	v_mul_f32_e32 v47, 0x3d372713, v70
	v_mul_f32_e32 v47, v47, v70
	v_mov_b32_e32 v67, v70
	v_fmac_f32_e32 v67, v47, v67
	v_mul_f32_e32 v47, 0x3f4c422a, v67
	v_add_f32_e32 v47, v47, v47
	v_and_b32_e32 v71, 0xffff0000, v71
	v_mul_f32_e32 v47, 0xbfb8aa3b, v47
	v_exp_f32_e32 v72, v47
	v_mul_f32_e32 v47, 0x3d372713, v71
	v_mul_f32_e32 v47, v47, v71
	v_mov_b32_e32 v67, v71
	v_fmac_f32_e32 v67, v47, v67
	v_mul_f32_e32 v47, 0x3f4c422a, v67
	v_add_f32_e32 v47, v47, v47
	v_mul_f32_e32 v47, 0xbfb8aa3b, v47
	v_exp_f32_e32 v73, v47
	v_rcp_f32_e32 v24, v26
	s_nop 0
	v_pk_mul_f32 v[24:25], v[24:25], v[34:35]
	v_pk_add_f32 v[26:27], v[72:73], 1.0 op_sel_hi:[1,0]
	s_nop 0
	v_pk_add_f32 v[20:21], v[66:67], v[20:21] op_sel_hi:[0,1]
	v_pk_mul_f32 v[20:21], v[24:25], v[20:21]
	v_rcp_f32_e32 v25, v27
	v_rcp_f32_e32 v24, v26
	s_nop 0
	v_pk_mul_f32 v[24:25], v[24:25], v[70:71]
	v_pk_add_f32 v[22:23], v[66:67], v[22:23] op_sel_hi:[0,1]
	v_lshlrev_b32_e32 v26, 16, v68
	v_pk_mul_f32 v[22:23], v[24:25], v[22:23]
	v_mul_f32_e32 v25, 0x3d372713, v26
	v_mul_f32_e32 v25, v25, v26
	v_mov_b32_e32 v34, v26
	v_fmac_f32_e32 v34, v25, v34
	v_mul_f32_e32 v25, 0x3f4c422a, v34
	v_add_f32_e32 v25, v25, v25
	v_and_b32_e32 v27, 0xffff0000, v68
	v_mul_f32_e32 v25, 0xbfb8aa3b, v25
	v_exp_f32_e32 v34, v25
	v_mul_f32_e32 v25, 0x3d372713, v27
	v_mul_f32_e32 v25, v25, v27
	v_mov_b32_e32 v35, v27
	v_fmac_f32_e32 v35, v25, v35
	v_mul_f32_e32 v25, 0x3f4c422a, v35
	v_add_f32_e32 v25, v25, v25
	v_mul_f32_e32 v25, 0xbfb8aa3b, v25
	v_exp_f32_e32 v35, v25
	v_cvt_pk_bf16_f32 v20, v20, v21
	v_cvt_pk_bf16_f32 v21, v22, v23
	v_or_b32_e32 v24, 32, v78
	v_pk_add_f32 v[22:23], v[34:35], 1.0 op_sel_hi:[1,0]
	v_ashrrev_i32_e32 v25, 31, v24
	v_lshlrev_b64 v[34:35], 1, v[24:25]
	v_lshl_add_u64 v[24:25], v[80:81], 0, v[34:35]
	flat_store_dwordx2 v[24:25], v[20:21]
	v_rcp_f32_e32 v21, v23
	v_lshlrev_b32_e32 v24, 16, v69
	v_mul_f32_e32 v67, 0x3d372713, v24
	v_mul_f32_e32 v67, v67, v24
	v_mov_b32_e32 v68, v24
	v_fmac_f32_e32 v68, v67, v68
	v_mul_f32_e32 v67, 0x3f4c422a, v68
	v_add_f32_e32 v67, v67, v67
	v_and_b32_e32 v25, 0xffff0000, v69
	v_mul_f32_e32 v67, 0xbfb8aa3b, v67
	v_exp_f32_e32 v68, v67
	v_mul_f32_e32 v67, 0x3d372713, v25
	v_mul_f32_e32 v67, v67, v25
	v_mov_b32_e32 v69, v25
	v_fmac_f32_e32 v69, v67, v69
	v_mul_f32_e32 v67, 0x3f4c422a, v69
	v_add_f32_e32 v67, v67, v67
	v_mul_f32_e32 v67, 0xbfb8aa3b, v67
	v_exp_f32_e32 v69, v67
	v_rcp_f32_e32 v20, v22
	s_nop 0
	v_pk_mul_f32 v[20:21], v[20:21], v[26:27]
	v_pk_add_f32 v[22:23], v[68:69], 1.0 op_sel_hi:[1,0]
	s_nop 0
	v_pk_add_f32 v[12:13], v[66:67], v[12:13] op_sel_hi:[0,1]
	v_pk_mul_f32 v[12:13], v[20:21], v[12:13]
	v_rcp_f32_e32 v21, v23
	v_rcp_f32_e32 v20, v22
	s_nop 0
	v_pk_mul_f32 v[20:21], v[20:21], v[24:25]
	v_pk_add_f32 v[14:15], v[66:67], v[14:15] op_sel_hi:[0,1]
	v_pk_mul_f32 v[14:15], v[20:21], v[14:15]
	v_or_b32_e32 v20, 48, v78
	v_cvt_pk_bf16_f32 v12, v12, v13
	v_cvt_pk_bf16_f32 v13, v14, v15
	v_ashrrev_i32_e32 v21, 31, v20
	v_lshlrev_b32_e32 v14, 16, v64
	v_lshlrev_b64 v[66:67], 1, v[20:21]
	v_mul_f32_e32 v20, 0x3d372713, v14
	v_mul_f32_e32 v20, v20, v14
	v_mov_b32_e32 v21, v14
	v_and_b32_e32 v15, 0xffff0000, v64
	v_fmac_f32_e32 v21, v20, v21
	v_mul_f32_e32 v20, 0x3f4c422a, v21
	v_mul_f32_e32 v21, 0x3d372713, v15
	v_mul_f32_e32 v21, v21, v15
	v_mov_b32_e32 v22, v15
	v_fmac_f32_e32 v22, v21, v22
	v_mul_f32_e32 v21, 0x3f4c422a, v22
	v_add_f32_e32 v20, v20, v20
	v_add_f32_e32 v21, v21, v21
	v_mul_f32_e32 v20, 0xbfb8aa3b, v20
	v_mul_f32_e32 v21, 0xbfb8aa3b, v21
	v_exp_f32_e32 v20, v20
	v_exp_f32_e32 v21, v21
	v_lshl_add_u64 v[22:23], v[80:81], 0, v[66:67]
	flat_store_dwordx2 v[22:23], v[12:13]
	v_or_b32_e32 v12, s2, v37
	v_pk_add_f32 v[20:21], v[20:21], 1.0 op_sel_hi:[1,0]
	v_mad_i64_i32 v[12:13], s[0:1], v12, s86, v[32:33]
	v_lshl_add_u64 v[12:13], v[12:13], 0, s[4:5]
	v_or_b32_e32 v37, 64, v37
	v_rcp_f32_e32 v21, v21
	v_lshlrev_b32_e32 v22, 16, v65
	v_mul_f32_e32 v24, 0x3d372713, v22
	v_mul_f32_e32 v24, v24, v22
	v_mov_b32_e32 v25, v22
	v_and_b32_e32 v23, 0xffff0000, v65
	v_fmac_f32_e32 v25, v24, v25
	v_mul_f32_e32 v24, 0x3f4c422a, v25
	v_mul_f32_e32 v25, 0x3d372713, v23
	v_mul_f32_e32 v25, v25, v23
	v_mov_b32_e32 v64, v23
	v_fmac_f32_e32 v64, v25, v64
	v_mul_f32_e32 v25, 0x3f4c422a, v64
	v_add_f32_e32 v24, v24, v24
	v_add_f32_e32 v25, v25, v25
	v_mul_f32_e32 v24, 0xbfb8aa3b, v24
	v_mul_f32_e32 v25, 0xbfb8aa3b, v25
	v_exp_f32_e32 v24, v24
	v_exp_f32_e32 v25, v25
	v_rcp_f32_e32 v20, v20
	s_nop 0
	v_pk_mul_f32 v[14:15], v[20:21], v[14:15]
	v_pk_add_f32 v[24:25], v[24:25], 1.0 op_sel_hi:[1,0]
	v_pk_mul_f32 v[14:15], v[14:15], v[16:17]
	s_nop 0
	v_cvt_pk_bf16_f32 v14, v14, v15
	v_add_u32_e32 v47, 0x1100, v57
	v_rcp_f32_e32 v17, v25
	v_rcp_f32_e32 v16, v24
	v_lshlrev_b32_e32 v20, 16, v62
	v_pk_mul_f32 v[16:17], v[16:17], v[22:23]
	v_mul_f32_e32 v22, 0x3d372713, v20
	v_mul_f32_e32 v22, v22, v20
	v_mov_b32_e32 v23, v20
	v_and_b32_e32 v21, 0xffff0000, v62
	v_fmac_f32_e32 v23, v22, v23
	v_mul_f32_e32 v22, 0x3f4c422a, v23
	v_mul_f32_e32 v23, 0x3d372713, v21
	v_mul_f32_e32 v23, v23, v21
	v_mov_b32_e32 v24, v21
	v_fmac_f32_e32 v24, v23, v24
	v_mul_f32_e32 v23, 0x3f4c422a, v24
	v_add_f32_e32 v22, v22, v22
	v_add_f32_e32 v23, v23, v23
	v_mul_f32_e32 v22, 0xbfb8aa3b, v22
	v_mul_f32_e32 v23, 0xbfb8aa3b, v23
	v_exp_f32_e32 v22, v22
	v_exp_f32_e32 v23, v23
	v_pk_mul_f32 v[16:17], v[16:17], v[18:19]
	v_mov_b32_e32 v62, v195
	v_cvt_pk_bf16_f32 v15, v16, v17
	v_pk_add_f32 v[18:19], v[22:23], 1.0 op_sel_hi:[1,0]
	v_lshl_add_u64 v[16:17], v[12:13], 0, v[28:29]
	flat_store_dwordx2 v[16:17], v[14:15]
	v_rcp_f32_e32 v15, v19
	v_lshlrev_b32_e32 v16, 16, v63
	v_mul_f32_e32 v22, 0x3d372713, v16
	v_mul_f32_e32 v22, v22, v16
	v_mov_b32_e32 v23, v16
	v_and_b32_e32 v17, 0xffff0000, v63
	v_fmac_f32_e32 v23, v22, v23
	v_mul_f32_e32 v22, 0x3f4c422a, v23
	v_mul_f32_e32 v23, 0x3d372713, v17
	v_mul_f32_e32 v23, v23, v17
	v_mov_b32_e32 v25, v17
	v_fmac_f32_e32 v25, v23, v25
	v_mul_f32_e32 v23, 0x3f4c422a, v25
	v_add_f32_e32 v22, v22, v22
	v_add_f32_e32 v23, v23, v23
	v_mul_f32_e32 v22, 0xbfb8aa3b, v22
	v_mul_f32_e32 v23, 0xbfb8aa3b, v23
	v_exp_f32_e32 v22, v22
	v_exp_f32_e32 v23, v23
	v_rcp_f32_e32 v14, v18
	s_nop 0
	v_pk_mul_f32 v[14:15], v[14:15], v[20:21]
	v_pk_add_f32 v[18:19], v[22:23], 1.0 op_sel_hi:[1,0]
	v_pk_mul_f32 v[8:9], v[14:15], v[8:9]
	s_nop 0
	v_cvt_pk_bf16_f32 v8, v8, v9
	v_mov_b32_e32 v24, v192
	v_rcp_f32_e32 v15, v19
	v_rcp_f32_e32 v14, v18
	s_nop 0
	v_pk_mul_f32 v[14:15], v[14:15], v[16:17]
	v_lshlrev_b32_e32 v16, 16, v60
	v_mul_f32_e32 v18, 0x3d372713, v16
	v_mul_f32_e32 v18, v18, v16
	v_mov_b32_e32 v19, v16
	v_and_b32_e32 v17, 0xffff0000, v60
	v_fmac_f32_e32 v19, v18, v19
	v_mul_f32_e32 v18, 0x3f4c422a, v19
	v_mul_f32_e32 v19, 0x3d372713, v17
	v_mul_f32_e32 v19, v19, v17
	v_mov_b32_e32 v20, v17
	v_fmac_f32_e32 v20, v19, v20
	v_mul_f32_e32 v19, 0x3f4c422a, v20
	v_add_f32_e32 v18, v18, v18
	v_add_f32_e32 v19, v19, v19
	v_mul_f32_e32 v18, 0xbfb8aa3b, v18
	v_mul_f32_e32 v19, 0xbfb8aa3b, v19
	v_exp_f32_e32 v18, v18
	v_exp_f32_e32 v19, v19
	v_pk_mul_f32 v[10:11], v[14:15], v[10:11]
	v_pk_add_f32 v[14:15], v[18:19], 1.0 op_sel_hi:[1,0]
	s_nop 0
	v_cvt_pk_bf16_f32 v9, v10, v11
	v_lshl_add_u64 v[10:11], v[12:13], 0, v[30:31]
	flat_store_dwordx2 v[10:11], v[8:9]
	v_rcp_f32_e32 v9, v15
	v_lshlrev_b32_e32 v10, 16, v61
	v_mul_f32_e32 v18, 0x3d372713, v10
	v_mul_f32_e32 v18, v18, v10
	v_mov_b32_e32 v19, v10
	v_and_b32_e32 v11, 0xffff0000, v61
	v_fmac_f32_e32 v19, v18, v19
	v_mul_f32_e32 v18, 0x3f4c422a, v19
	v_mul_f32_e32 v19, 0x3d372713, v11
	v_mul_f32_e32 v19, v19, v11
	v_mov_b32_e32 v21, v11
	v_fmac_f32_e32 v21, v19, v21
	v_mul_f32_e32 v19, 0x3f4c422a, v21
	v_add_f32_e32 v18, v18, v18
	v_add_f32_e32 v19, v19, v19
	v_mul_f32_e32 v18, 0xbfb8aa3b, v18
	v_mul_f32_e32 v19, 0xbfb8aa3b, v19
	v_exp_f32_e32 v18, v18
	v_exp_f32_e32 v19, v19
	v_rcp_f32_e32 v8, v14
	s_nop 0
	v_pk_mul_f32 v[8:9], v[8:9], v[16:17]
	v_pk_add_f32 v[14:15], v[18:19], 1.0 op_sel_hi:[1,0]
	v_pk_mul_f32 v[4:5], v[8:9], v[4:5]
	s_nop 0
	v_cvt_pk_bf16_f32 v4, v4, v5
	v_mov_b32_e32 v20, v192
	v_rcp_f32_e32 v9, v15
	v_rcp_f32_e32 v8, v14
	s_nop 0
	v_pk_mul_f32 v[8:9], v[8:9], v[10:11]
	v_lshlrev_b32_e32 v10, 16, v58
	v_mul_f32_e32 v14, 0x3d372713, v10
	v_mul_f32_e32 v14, v14, v10
	v_mov_b32_e32 v15, v10
	v_and_b32_e32 v11, 0xffff0000, v58
	v_fmac_f32_e32 v15, v14, v15
	v_mul_f32_e32 v14, 0x3f4c422a, v15
	v_mul_f32_e32 v15, 0x3d372713, v11
	v_mul_f32_e32 v15, v15, v11
	v_mov_b32_e32 v16, v11
	v_fmac_f32_e32 v16, v15, v16
	v_mul_f32_e32 v15, 0x3f4c422a, v16
	v_add_f32_e32 v14, v14, v14
	v_add_f32_e32 v15, v15, v15
	v_mul_f32_e32 v14, 0xbfb8aa3b, v14
	v_mul_f32_e32 v15, 0xbfb8aa3b, v15
	v_exp_f32_e32 v14, v14
	v_exp_f32_e32 v15, v15
	v_pk_mul_f32 v[6:7], v[8:9], v[6:7]
	v_mov_b32_e32 v58, v192
	v_cvt_pk_bf16_f32 v5, v6, v7
	v_pk_add_f32 v[8:9], v[14:15], 1.0 op_sel_hi:[1,0]
	v_lshl_add_u64 v[6:7], v[12:13], 0, v[34:35]
	flat_store_dwordx2 v[6:7], v[4:5]
	v_rcp_f32_e32 v5, v9
	v_lshlrev_b32_e32 v6, 16, v59
	v_mul_f32_e32 v14, 0x3d372713, v6
	v_mul_f32_e32 v14, v14, v6
	v_mov_b32_e32 v15, v6
	v_and_b32_e32 v7, 0xffff0000, v59
	v_fmac_f32_e32 v15, v14, v15
	v_mul_f32_e32 v14, 0x3f4c422a, v15
	v_mul_f32_e32 v15, 0x3d372713, v7
	v_mul_f32_e32 v15, v15, v7
	v_mov_b32_e32 v17, v7
	v_fmac_f32_e32 v17, v15, v17
	v_mul_f32_e32 v15, 0x3f4c422a, v17
	v_add_f32_e32 v14, v14, v14
	v_add_f32_e32 v15, v15, v15
	v_mul_f32_e32 v14, 0xbfb8aa3b, v14
	v_mul_f32_e32 v15, 0xbfb8aa3b, v15
	v_exp_f32_e32 v14, v14
	v_exp_f32_e32 v15, v15
	v_rcp_f32_e32 v4, v8
	s_nop 0
	v_pk_mul_f32 v[4:5], v[4:5], v[10:11]
	v_pk_add_f32 v[8:9], v[14:15], 1.0 op_sel_hi:[1,0]
	v_pk_mul_f32 v[0:1], v[4:5], v[0:1]
	s_nop 0
	v_cvt_pk_bf16_f32 v0, v0, v1
	v_mov_b32_e32 v16, v192
	v_rcp_f32_e32 v5, v9
	v_rcp_f32_e32 v4, v8
	s_nop 0
	v_pk_mul_f32 v[4:5], v[4:5], v[6:7]
	v_mov_b32_e32 v8, v192
	v_pk_mul_f32 v[2:3], v[4:5], v[2:3]
	v_or_b32_e32 v5, 64, v82
	v_cvt_pk_bf16_f32 v1, v2, v3
	v_lshl_add_u64 v[2:3], v[12:13], 0, v[66:67]
	flat_store_dwordx2 v[2:3], v[0:1]
	v_or_b32_e32 v0, s3, v5
	v_ashrrev_i32_e32 v1, 31, v0
	v_lshlrev_b64 v[0:1], 8, v[0:1]
	v_lshl_add_u64 v[2:3], v[76:77], 0, v[0:1]
	v_or_b32_e32 v0, s2, v5
	v_ashrrev_i32_e32 v1, 31, v0
	v_mov_b32_e32 v4, v192
	v_mov_b32_e32 v12, v192
	v_lshlrev_b64 v[0:1], 8, v[0:1]
	flat_load_dwordx4 v[68:71], v[2:3]
	v_lshl_add_u64 v[0:1], v[76:77], 0, v[0:1]
	flat_load_dwordx4 v[72:75], v[0:1]
	flat_load_dwordx4 v[76:79], v[2:3] offset:64
	ds_read2_b64 v[90:93], v57 offset1:1
	ds_read2_b64 v[80:83], v83 offset1:1
	ds_read2_b64 v[94:97], v84 offset1:1
	ds_read2_b64 v[98:101], v85 offset1:1
	v_mov_b32_e32 v9, v8
	v_mov_b32_e32 v5, v4
	v_mov_b32_e32 v6, v4
	v_mov_b32_e32 v7, v4
	v_mov_b32_e32 v10, v8
	v_mov_b32_e32 v11, v8
	v_mov_b32_e32 v13, v12
	v_mov_b32_e32 v14, v12
	v_mov_b32_e32 v15, v12
	v_mov_b32_e32 v17, v16
	v_mov_b32_e32 v18, v16
	v_mov_b32_e32 v19, v16
	v_mov_b32_e32 v21, v20
	v_mov_b32_e32 v22, v20
	v_mov_b32_e32 v23, v20
	v_mov_b32_e32 v25, v24
	v_mov_b32_e32 v26, v24
	v_mov_b32_e32 v27, v24
	v_mov_b32_e32 v59, v58
	v_mov_b32_e32 v60, v58
	v_mov_b32_e32 v61, v58
	v_mov_b32_e32 v63, v62
	v_mov_b32_e32 v64, v62
	v_mov_b32_e32 v65, v62
	s_waitcnt vmcnt(0) lgkmcnt(0)
	v_mfma_f32_16x16x32_bf16 v[4:7], v[90:93], v[68:71], v[4:7]
	v_mfma_f32_16x16x32_bf16 v[8:11], v[80:83], v[68:71], v[8:11]
	v_mfma_f32_16x16x32_bf16 v[12:15], v[94:97], v[68:71], v[12:15]
	v_mfma_f32_16x16x32_bf16 v[16:19], v[98:101], v[68:71], v[16:19]
	ds_read2_b64 v[68:71], v57 offset0:8 offset1:9
	v_mfma_f32_16x16x32_bf16 v[20:23], v[90:93], v[72:75], v[20:23]
	v_mfma_f32_16x16x32_bf16 v[24:27], v[80:83], v[72:75], v[24:27]
	ds_read2_b64 v[80:83], v87 offset1:1
	v_mfma_f32_16x16x32_bf16 v[58:61], v[94:97], v[72:75], v[58:61]
	v_mfma_f32_16x16x32_bf16 v[62:65], v[98:101], v[72:75], v[62:65]
	ds_read2_b64 v[72:75], v86 offset1:1
	ds_read2_b64 v[84:87], v88 offset1:1
	s_waitcnt lgkmcnt(3)
	v_mfma_f32_16x16x32_bf16 v[4:7], v[68:71], v[76:79], v[4:7]
	s_waitcnt lgkmcnt(1)
	v_mfma_f32_16x16x32_bf16 v[8:11], v[72:75], v[76:79], v[8:11]
	v_mfma_f32_16x16x32_bf16 v[12:15], v[80:83], v[76:79], v[12:15]
	s_waitcnt lgkmcnt(0)
	v_mfma_f32_16x16x32_bf16 v[16:19], v[84:87], v[76:79], v[16:19]
	flat_load_dwordx4 v[76:79], v[0:1] offset:64
	s_waitcnt vmcnt(0) lgkmcnt(0)
	v_mfma_f32_16x16x32_bf16 v[20:23], v[68:71], v[76:79], v[20:23]
	flat_load_dwordx4 v[68:71], v[2:3] offset:128
	v_mfma_f32_16x16x32_bf16 v[24:27], v[72:75], v[76:79], v[24:27]
	ds_read2_b64 v[72:75], v57 offset0:16 offset1:17
	v_mfma_f32_16x16x32_bf16 v[58:61], v[80:83], v[76:79], v[58:61]
	v_mfma_f32_16x16x32_bf16 v[62:65], v[84:87], v[76:79], v[62:65]
	ds_read2_b64 v[76:79], v47 offset1:1
	v_add_u32_e32 v47, 0x2180, v57
	ds_read2_b64 v[80:83], v47 offset1:1
	v_add_u32_e32 v47, 0x3200, v57
	ds_read2_b64 v[84:87], v47 offset1:1
	s_waitcnt vmcnt(0) lgkmcnt(0)
	v_mfma_f32_16x16x32_bf16 v[4:7], v[72:75], v[68:71], v[4:7]
	v_or_b32_e32 v47, s3, v37
	v_mfma_f32_16x16x32_bf16 v[8:11], v[76:79], v[68:71], v[8:11]
	v_mfma_f32_16x16x32_bf16 v[12:15], v[80:83], v[68:71], v[12:15]
	v_mfma_f32_16x16x32_bf16 v[16:19], v[84:87], v[68:71], v[16:19]
	flat_load_dwordx4 v[68:71], v[0:1] offset:128
	s_waitcnt vmcnt(0) lgkmcnt(0)
	v_mfma_f32_16x16x32_bf16 v[58:61], v[80:83], v[68:71], v[58:61]
	flat_load_dwordx4 v[80:83], v[2:3] offset:192
	v_add_u32_e32 v2, 0x1140, v57
	v_mfma_f32_16x16x32_bf16 v[72:75], v[72:75], v[68:71], v[20:23]
	v_mfma_f32_16x16x32_bf16 v[76:79], v[76:79], v[68:71], v[24:27]
	v_mfma_f32_16x16x32_bf16 v[62:65], v[84:87], v[68:71], v[62:65]
	ds_read2_b64 v[68:71], v57 offset0:24 offset1:25
	s_waitcnt vmcnt(0) lgkmcnt(0)
	v_mfma_f32_16x16x32_bf16 v[84:87], v[68:71], v[80:83], v[4:7]
	s_nop 2
	v_add_u32_e32 v6, 0x21c0, v57
	ds_read2_b64 v[2:5], v2 offset1:1
	ds_read2_b64 v[88:91], v6 offset1:1
	v_add_u32_e32 v6, 0x3240, v57
	ds_read2_b64 v[92:95], v6 offset1:1
	s_waitcnt lgkmcnt(2)
	v_mfma_f32_16x16x32_bf16 v[24:27], v[2:5], v[80:83], v[8:11]
	s_waitcnt lgkmcnt(1)
	v_mfma_f32_16x16x32_bf16 v[20:23], v[88:91], v[80:83], v[12:15]
	s_waitcnt lgkmcnt(0)
	v_mfma_f32_16x16x32_bf16 v[16:19], v[92:95], v[80:83], v[16:19]
	flat_load_dwordx4 v[80:83], v[0:1] offset:192
	s_waitcnt vmcnt(0) lgkmcnt(0)
	v_mfma_f32_16x16x32_bf16 v[8:11], v[2:5], v[80:83], v[76:79]
	s_nop 7
	v_pk_add_f32 v[8:9], v[36:37], v[8:9] op_sel_hi:[0,1]
	v_mfma_f32_16x16x32_bf16 v[4:7], v[88:91], v[80:83], v[58:61]
	v_add_f32_e64 v10, v36, v10
	v_add_f32_e64 v11, v36, v11
	s_nop 0
	v_lshlrev_b32_e32 v58, 16, v54
	v_mul_f32_e32 v0, 0x3d372713, v58
	v_mul_f32_e32 v0, v0, v58
	v_mov_b32_e32 v1, v58
	v_fmac_f32_e32 v1, v0, v1
	v_mul_f32_e32 v0, 0x3f4c422a, v1
	v_add_f32_e32 v0, v0, v0
	v_and_b32_e32 v59, 0xffff0000, v54
	v_mul_f32_e32 v0, 0xbfb8aa3b, v0
	v_exp_f32_e32 v56, v0
	v_mul_f32_e32 v0, 0x3d372713, v59
	v_mul_f32_e32 v0, v0, v59
	v_mov_b32_e32 v1, v59
	v_fmac_f32_e32 v1, v0, v1
	v_mul_f32_e32 v0, 0x3f4c422a, v1
	v_add_f32_e32 v0, v0, v0
	v_mul_f32_e32 v0, 0xbfb8aa3b, v0
	v_exp_f32_e32 v57, v0
	v_mfma_f32_16x16x32_bf16 v[0:3], v[92:95], v[80:83], v[62:65]
	v_add_f32_e64 v4, v36, v4
	v_add_f32_e64 v5, v36, v5
	v_pk_add_f32 v[6:7], v[36:37], v[6:7] op_sel_hi:[0,1]
	v_pk_add_f32 v[60:61], v[56:57], 1.0 op_sel_hi:[1,0]
	v_mad_i64_i32 v[56:57], s[0:1], v47, s86, v[32:33]
	v_mfma_f32_16x16x32_bf16 v[12:15], v[68:71], v[80:83], v[72:75]
	v_lshl_add_u64 v[56:57], v[56:57], 0, s[4:5]
	s_nop 0
	v_pk_add_f32 v[0:1], v[36:37], v[0:1] op_sel_hi:[0,1]
	v_rcp_f32_e32 v61, v61
	s_nop 3
	v_pk_add_f32 v[12:13], v[36:37], v[12:13] op_sel_hi:[0,1]
	v_lshlrev_b32_e32 v54, 16, v55
	v_mul_f32_e32 v62, 0x3d372713, v54
	v_mul_f32_e32 v62, v62, v54
	v_mov_b32_e32 v63, v54
	v_and_b32_e32 v55, 0xffff0000, v55
	v_fmac_f32_e32 v63, v62, v63
	v_mul_f32_e32 v62, 0x3f4c422a, v63
	v_mul_f32_e32 v63, 0x3d372713, v55
	v_mul_f32_e32 v63, v63, v55
	v_mov_b32_e32 v68, v55
	v_fmac_f32_e32 v68, v63, v68
	v_mul_f32_e32 v63, 0x3f4c422a, v68
	v_add_f32_e32 v62, v62, v62
	v_add_f32_e32 v63, v63, v63
	v_mul_f32_e32 v62, 0xbfb8aa3b, v62
	v_mul_f32_e32 v63, 0xbfb8aa3b, v63
	v_exp_f32_e32 v62, v62
	v_exp_f32_e32 v63, v63
	v_rcp_f32_e32 v60, v60
	s_nop 0
	v_pk_mul_f32 v[58:59], v[60:61], v[58:59]
	v_pk_add_f32 v[62:63], v[62:63], 1.0 op_sel_hi:[1,0]
	v_pk_add_f32 v[14:15], v[36:37], v[14:15] op_sel_hi:[0,1]
	v_pk_add_f32 v[60:61], v[46:47], v[84:85] op_sel_hi:[0,1]
	v_pk_mul_f32 v[58:59], v[58:59], v[60:61]
	v_pk_add_f32 v[2:3], v[36:37], v[2:3] op_sel_hi:[0,1]
	v_rcp_f32_e32 v61, v63
	v_cvt_pk_bf16_f32 v58, v58, v59
	v_rcp_f32_e32 v60, v62
	s_nop 0
	v_pk_mul_f32 v[54:55], v[60:61], v[54:55]
	v_lshlrev_b32_e32 v60, 16, v52
	v_mul_f32_e32 v47, 0x3d372713, v60
	v_and_b32_e32 v61, 0xffff0000, v52
	v_mul_f32_e32 v47, v47, v60
	v_mov_b32_e32 v52, v60
	v_fmac_f32_e32 v52, v47, v52
	v_mul_f32_e32 v47, 0x3f4c422a, v52
	v_add_f32_e32 v47, v47, v47
	v_mul_f32_e32 v47, 0xbfb8aa3b, v47
	v_exp_f32_e32 v62, v47
	v_mul_f32_e32 v47, 0x3d372713, v61
	v_mul_f32_e32 v47, v47, v61
	v_mov_b32_e32 v52, v61
	v_fmac_f32_e32 v52, v47, v52
	v_mul_f32_e32 v47, 0x3f4c422a, v52
	v_add_f32_e32 v47, v47, v47
	v_mul_f32_e32 v47, 0xbfb8aa3b, v47
	v_exp_f32_e32 v63, v47
	v_pk_add_f32 v[64:65], v[46:47], v[86:87] op_sel_hi:[0,1]
	v_pk_mul_f32 v[54:55], v[54:55], v[64:65]
	v_pk_add_f32 v[62:63], v[62:63], 1.0 op_sel_hi:[1,0]
	s_nop 0
	v_cvt_pk_bf16_f32 v59, v54, v55
	v_lshl_add_u64 v[54:55], v[56:57], 0, v[28:29]
	flat_store_dwordx2 v[54:55], v[58:59]
	v_rcp_f32_e32 v55, v63
	v_lshlrev_b32_e32 v52, 16, v53
	v_mul_f32_e32 v54, 0x3d372713, v52
	v_mul_f32_e32 v54, v54, v52
	v_mov_b32_e32 v58, v52
	v_fmac_f32_e32 v58, v54, v58
	v_mul_f32_e32 v54, 0x3f4c422a, v58
	v_add_f32_e32 v54, v54, v54
	v_and_b32_e32 v53, 0xffff0000, v53
	v_mul_f32_e32 v54, 0xbfb8aa3b, v54
	v_exp_f32_e32 v58, v54
	v_mul_f32_e32 v54, 0x3d372713, v53
	v_mul_f32_e32 v54, v54, v53
	v_mov_b32_e32 v59, v53
	v_fmac_f32_e32 v59, v54, v59
	v_mul_f32_e32 v54, 0x3f4c422a, v59
	v_add_f32_e32 v54, v54, v54
	v_mul_f32_e32 v54, 0xbfb8aa3b, v54
	v_exp_f32_e32 v59, v54
	v_rcp_f32_e32 v54, v62
	s_nop 0
	v_pk_mul_f32 v[54:55], v[54:55], v[60:61]
	v_pk_add_f32 v[58:59], v[58:59], 1.0 op_sel_hi:[1,0]
	s_nop 0
	v_pk_add_f32 v[24:25], v[46:47], v[24:25] op_sel_hi:[0,1]
	v_pk_mul_f32 v[24:25], v[54:55], v[24:25]
	v_rcp_f32_e32 v55, v59
	v_cvt_pk_bf16_f32 v24, v24, v25
	v_rcp_f32_e32 v54, v58
	s_nop 0
	v_pk_mul_f32 v[52:53], v[54:55], v[52:53]
	v_lshlrev_b32_e32 v54, 16, v50
	v_mul_f32_e32 v47, 0x3d372713, v54
	v_and_b32_e32 v55, 0xffff0000, v50
	v_mul_f32_e32 v47, v47, v54
	v_mov_b32_e32 v50, v54
	v_fmac_f32_e32 v50, v47, v50
	v_mul_f32_e32 v47, 0x3f4c422a, v50
	v_add_f32_e32 v47, v47, v47
	v_mul_f32_e32 v47, 0xbfb8aa3b, v47
	v_exp_f32_e32 v58, v47
	v_mul_f32_e32 v47, 0x3d372713, v55
	v_mul_f32_e32 v47, v47, v55
	v_mov_b32_e32 v50, v55
	v_fmac_f32_e32 v50, v47, v50
	v_mul_f32_e32 v47, 0x3f4c422a, v50
	v_add_f32_e32 v47, v47, v47
	v_mul_f32_e32 v47, 0xbfb8aa3b, v47
	v_exp_f32_e32 v59, v47
	v_pk_add_f32 v[26:27], v[46:47], v[26:27] op_sel_hi:[0,1]
	v_pk_mul_f32 v[26:27], v[52:53], v[26:27]
	v_pk_add_f32 v[52:53], v[58:59], 1.0 op_sel_hi:[1,0]
	s_nop 0
	v_cvt_pk_bf16_f32 v25, v26, v27
	v_lshl_add_u64 v[26:27], v[56:57], 0, v[30:31]
	flat_store_dwordx2 v[26:27], v[24:25]
	v_rcp_f32_e32 v25, v53
	v_lshlrev_b32_e32 v26, 16, v51
	v_mul_f32_e32 v50, 0x3d372713, v26
	v_and_b32_e32 v27, 0xffff0000, v51
	v_mul_f32_e32 v50, v50, v26
	v_mov_b32_e32 v51, v26
	v_fmac_f32_e32 v51, v50, v51
	v_mul_f32_e32 v50, 0x3f4c422a, v51
	v_mul_f32_e32 v51, 0x3d372713, v27
	v_mul_f32_e32 v51, v51, v27
	v_mov_b32_e32 v58, v27
	v_fmac_f32_e32 v58, v51, v58
	v_mul_f32_e32 v51, 0x3f4c422a, v58
	v_add_f32_e32 v50, v50, v50
	v_add_f32_e32 v51, v51, v51
	v_mul_f32_e32 v50, 0xbfb8aa3b, v50
	v_mul_f32_e32 v51, 0xbfb8aa3b, v51
	v_exp_f32_e32 v50, v50
	v_exp_f32_e32 v51, v51
	v_rcp_f32_e32 v24, v52
	s_nop 0
	v_pk_mul_f32 v[24:25], v[24:25], v[54:55]
	v_pk_add_f32 v[50:51], v[50:51], 1.0 op_sel_hi:[1,0]
	s_nop 0
	v_pk_add_f32 v[20:21], v[46:47], v[20:21] op_sel_hi:[0,1]
	v_pk_mul_f32 v[20:21], v[24:25], v[20:21]
	v_rcp_f32_e32 v25, v51
	v_cvt_pk_bf16_f32 v20, v20, v21
	v_rcp_f32_e32 v24, v50
	s_nop 0
	v_pk_mul_f32 v[24:25], v[24:25], v[26:27]
	v_lshlrev_b32_e32 v26, 16, v48
	v_mul_f32_e32 v47, 0x3d372713, v26
	v_and_b32_e32 v27, 0xffff0000, v48
	v_mul_f32_e32 v47, v47, v26
	v_mov_b32_e32 v48, v26
	v_fmac_f32_e32 v48, v47, v48
	v_mul_f32_e32 v47, 0x3f4c422a, v48
	v_add_f32_e32 v47, v47, v47
	v_mul_f32_e32 v47, 0xbfb8aa3b, v47
	v_exp_f32_e32 v50, v47
	v_mul_f32_e32 v47, 0x3d372713, v27
	v_mul_f32_e32 v47, v47, v27
	v_mov_b32_e32 v48, v27
	v_fmac_f32_e32 v48, v47, v48
	v_mul_f32_e32 v47, 0x3f4c422a, v48
	v_add_f32_e32 v47, v47, v47
	v_mul_f32_e32 v47, 0xbfb8aa3b, v47
	v_exp_f32_e32 v51, v47
	v_pk_add_f32 v[22:23], v[46:47], v[22:23] op_sel_hi:[0,1]
	v_pk_mul_f32 v[22:23], v[24:25], v[22:23]
	v_pk_add_f32 v[24:25], v[50:51], 1.0 op_sel_hi:[1,0]
	s_nop 0
	v_cvt_pk_bf16_f32 v21, v22, v23
	v_lshl_add_u64 v[22:23], v[56:57], 0, v[34:35]
	flat_store_dwordx2 v[22:23], v[20:21]
	v_rcp_f32_e32 v21, v25
	v_lshlrev_b32_e32 v22, 16, v49
	v_mul_f32_e32 v48, 0x3d372713, v22
	v_and_b32_e32 v23, 0xffff0000, v49
	v_mul_f32_e32 v48, v48, v22
	v_mov_b32_e32 v49, v22
	v_fmac_f32_e32 v49, v48, v49
	v_mul_f32_e32 v48, 0x3f4c422a, v49
	v_mul_f32_e32 v49, 0x3d372713, v23
	v_mul_f32_e32 v49, v49, v23
	v_mov_b32_e32 v50, v23
	v_fmac_f32_e32 v50, v49, v50
	v_mul_f32_e32 v49, 0x3f4c422a, v50
	v_add_f32_e32 v48, v48, v48
	v_add_f32_e32 v49, v49, v49
	v_mul_f32_e32 v48, 0xbfb8aa3b, v48
	v_mul_f32_e32 v49, 0xbfb8aa3b, v49
	v_exp_f32_e32 v48, v48
	v_exp_f32_e32 v49, v49
	v_rcp_f32_e32 v20, v24
	s_nop 0
	v_pk_mul_f32 v[20:21], v[20:21], v[26:27]
	v_pk_add_f32 v[24:25], v[48:49], 1.0 op_sel_hi:[1,0]
	s_nop 0
	v_pk_add_f32 v[16:17], v[46:47], v[16:17] op_sel_hi:[0,1]
	v_pk_mul_f32 v[16:17], v[20:21], v[16:17]
	v_rcp_f32_e32 v21, v25
	v_rcp_f32_e32 v20, v24
	s_nop 0
	v_pk_mul_f32 v[20:21], v[20:21], v[22:23]
	v_pk_add_f32 v[18:19], v[46:47], v[18:19] op_sel_hi:[0,1]
	v_pk_mul_f32 v[18:19], v[20:21], v[18:19]
	v_cvt_pk_bf16_f32 v16, v16, v17
	v_cvt_pk_bf16_f32 v17, v18, v19
	v_lshlrev_b32_e32 v18, 16, v44
	v_mul_f32_e32 v20, 0x3d372713, v18
	v_mul_f32_e32 v20, v20, v18
	v_mov_b32_e32 v21, v18
	v_and_b32_e32 v19, 0xffff0000, v44
	v_fmac_f32_e32 v21, v20, v21
	v_mul_f32_e32 v20, 0x3f4c422a, v21
	v_mul_f32_e32 v21, 0x3d372713, v19
	v_mul_f32_e32 v21, v21, v19
	v_mov_b32_e32 v22, v19
	v_fmac_f32_e32 v22, v21, v22
	v_mul_f32_e32 v21, 0x3f4c422a, v22
	v_add_f32_e32 v20, v20, v20
	v_add_f32_e32 v21, v21, v21
	v_mul_f32_e32 v20, 0xbfb8aa3b, v20
	v_mul_f32_e32 v21, 0xbfb8aa3b, v21
	v_exp_f32_e32 v20, v20
	v_exp_f32_e32 v21, v21
	v_lshl_add_u64 v[22:23], v[56:57], 0, v[66:67]
	flat_store_dwordx2 v[22:23], v[16:17]
	v_or_b32_e32 v16, s2, v37
	v_pk_add_f32 v[20:21], v[20:21], 1.0 op_sel_hi:[1,0]
	v_mad_i64_i32 v[16:17], s[0:1], v16, s86, v[32:33]
	v_lshl_add_u64 v[16:17], v[16:17], 0, s[4:5]
	v_rcp_f32_e32 v21, v21
	v_lshlrev_b32_e32 v22, 16, v45
	v_mul_f32_e32 v24, 0x3d372713, v22
	v_mul_f32_e32 v24, v24, v22
	v_mov_b32_e32 v25, v22
	v_and_b32_e32 v23, 0xffff0000, v45
	v_fmac_f32_e32 v25, v24, v25
	v_mul_f32_e32 v24, 0x3f4c422a, v25
	v_mul_f32_e32 v25, 0x3d372713, v23
	v_mul_f32_e32 v25, v25, v23
	v_mov_b32_e32 v33, v23
	v_fmac_f32_e32 v33, v25, v33
	v_mul_f32_e32 v25, 0x3f4c422a, v33
	v_add_f32_e32 v24, v24, v24
	v_add_f32_e32 v25, v25, v25
	v_mul_f32_e32 v24, 0xbfb8aa3b, v24
	v_mul_f32_e32 v25, 0xbfb8aa3b, v25
	v_exp_f32_e32 v24, v24
	v_exp_f32_e32 v25, v25
	v_rcp_f32_e32 v20, v20
	s_nop 0
	v_pk_mul_f32 v[18:19], v[20:21], v[18:19]
	v_pk_add_f32 v[24:25], v[24:25], 1.0 op_sel_hi:[1,0]
	v_pk_mul_f32 v[12:13], v[18:19], v[12:13]
	s_nop 0
	v_cvt_pk_bf16_f32 v12, v12, v13
	v_rcp_f32_e32 v19, v25
	v_rcp_f32_e32 v18, v24
	v_lshlrev_b32_e32 v20, 16, v42
	v_pk_mul_f32 v[18:19], v[18:19], v[22:23]
	v_mul_f32_e32 v22, 0x3d372713, v20
	v_mul_f32_e32 v22, v22, v20
	v_mov_b32_e32 v23, v20
	v_and_b32_e32 v21, 0xffff0000, v42
	v_fmac_f32_e32 v23, v22, v23
	v_mul_f32_e32 v22, 0x3f4c422a, v23
	v_mul_f32_e32 v23, 0x3d372713, v21
	v_mul_f32_e32 v23, v23, v21
	v_mov_b32_e32 v24, v21
	v_fmac_f32_e32 v24, v23, v24
	v_mul_f32_e32 v23, 0x3f4c422a, v24
	v_add_f32_e32 v22, v22, v22
	v_add_f32_e32 v23, v23, v23
	v_mul_f32_e32 v22, 0xbfb8aa3b, v22
	v_mul_f32_e32 v23, 0xbfb8aa3b, v23
	v_exp_f32_e32 v22, v22
	v_exp_f32_e32 v23, v23
	v_pk_mul_f32 v[14:15], v[18:19], v[14:15]
	v_pk_add_f32 v[18:19], v[22:23], 1.0 op_sel_hi:[1,0]
	s_nop 0
	v_cvt_pk_bf16_f32 v13, v14, v15
	v_lshl_add_u64 v[14:15], v[16:17], 0, v[28:29]
	flat_store_dwordx2 v[14:15], v[12:13]
	v_rcp_f32_e32 v13, v19
	v_lshlrev_b32_e32 v14, 16, v43
	v_mul_f32_e32 v22, 0x3d372713, v14
	v_mul_f32_e32 v22, v22, v14
	v_mov_b32_e32 v23, v14
	v_and_b32_e32 v15, 0xffff0000, v43
	v_fmac_f32_e32 v23, v22, v23
	v_mul_f32_e32 v22, 0x3f4c422a, v23
	v_mul_f32_e32 v23, 0x3d372713, v15
	v_mul_f32_e32 v23, v23, v15
	v_mov_b32_e32 v25, v15
	v_fmac_f32_e32 v25, v23, v25
	v_mul_f32_e32 v23, 0x3f4c422a, v25
	v_add_f32_e32 v22, v22, v22
	v_add_f32_e32 v23, v23, v23
	v_mul_f32_e32 v22, 0xbfb8aa3b, v22
	v_mul_f32_e32 v23, 0xbfb8aa3b, v23
	v_exp_f32_e32 v22, v22
	v_exp_f32_e32 v23, v23
	v_rcp_f32_e32 v12, v18
	s_nop 0
	v_pk_mul_f32 v[12:13], v[12:13], v[20:21]
	v_pk_add_f32 v[18:19], v[22:23], 1.0 op_sel_hi:[1,0]
	v_pk_mul_f32 v[8:9], v[12:13], v[8:9]
	s_nop 0
	v_cvt_pk_bf16_f32 v8, v8, v9
	v_rcp_f32_e32 v13, v19
	v_rcp_f32_e32 v12, v18
	s_nop 0
	v_pk_mul_f32 v[12:13], v[12:13], v[14:15]
	v_lshlrev_b32_e32 v14, 16, v40
	v_mul_f32_e32 v18, 0x3d372713, v14
	v_mul_f32_e32 v18, v18, v14
	v_mov_b32_e32 v19, v14
	v_and_b32_e32 v15, 0xffff0000, v40
	v_fmac_f32_e32 v19, v18, v19
	v_mul_f32_e32 v18, 0x3f4c422a, v19
	v_mul_f32_e32 v19, 0x3d372713, v15
	v_mul_f32_e32 v19, v19, v15
	v_mov_b32_e32 v20, v15
	v_fmac_f32_e32 v20, v19, v20
	v_mul_f32_e32 v19, 0x3f4c422a, v20
	v_add_f32_e32 v18, v18, v18
	v_add_f32_e32 v19, v19, v19
	v_mul_f32_e32 v18, 0xbfb8aa3b, v18
	v_mul_f32_e32 v19, 0xbfb8aa3b, v19
	v_exp_f32_e32 v18, v18
	v_exp_f32_e32 v19, v19
	v_pk_mul_f32 v[10:11], v[12:13], v[10:11]
	v_pk_add_f32 v[12:13], v[18:19], 1.0 op_sel_hi:[1,0]
	s_nop 0
	v_cvt_pk_bf16_f32 v9, v10, v11
	v_lshl_add_u64 v[10:11], v[16:17], 0, v[30:31]
	flat_store_dwordx2 v[10:11], v[8:9]
	v_rcp_f32_e32 v9, v13
	v_lshlrev_b32_e32 v10, 16, v41
	v_mul_f32_e32 v18, 0x3d372713, v10
	v_mul_f32_e32 v18, v18, v10
	v_mov_b32_e32 v19, v10
	v_and_b32_e32 v11, 0xffff0000, v41
	v_fmac_f32_e32 v19, v18, v19
	v_mul_f32_e32 v18, 0x3f4c422a, v19
	v_mul_f32_e32 v19, 0x3d372713, v11
	v_mul_f32_e32 v19, v19, v11
	v_mov_b32_e32 v21, v11
	v_fmac_f32_e32 v21, v19, v21
	v_mul_f32_e32 v19, 0x3f4c422a, v21
	v_add_f32_e32 v18, v18, v18
	v_add_f32_e32 v19, v19, v19
	v_mul_f32_e32 v18, 0xbfb8aa3b, v18
	v_mul_f32_e32 v19, 0xbfb8aa3b, v19
	v_exp_f32_e32 v18, v18
	v_exp_f32_e32 v19, v19
	v_rcp_f32_e32 v8, v12
	s_nop 0
	v_pk_mul_f32 v[8:9], v[8:9], v[14:15]
	v_pk_add_f32 v[12:13], v[18:19], 1.0 op_sel_hi:[1,0]
	v_pk_mul_f32 v[4:5], v[8:9], v[4:5]
	s_nop 0
	v_cvt_pk_bf16_f32 v4, v4, v5
	v_rcp_f32_e32 v9, v13
	v_rcp_f32_e32 v8, v12
	s_nop 0
	v_pk_mul_f32 v[8:9], v[8:9], v[10:11]
	v_lshlrev_b32_e32 v10, 16, v38
	v_mul_f32_e32 v12, 0x3d372713, v10
	v_mul_f32_e32 v12, v12, v10
	v_mov_b32_e32 v13, v10
	v_and_b32_e32 v11, 0xffff0000, v38
	v_fmac_f32_e32 v13, v12, v13
	v_mul_f32_e32 v12, 0x3f4c422a, v13
	v_mul_f32_e32 v13, 0x3d372713, v11
	v_mul_f32_e32 v13, v13, v11
	v_mov_b32_e32 v14, v11
	v_fmac_f32_e32 v14, v13, v14
	v_mul_f32_e32 v13, 0x3f4c422a, v14
	v_add_f32_e32 v12, v12, v12
	v_add_f32_e32 v13, v13, v13
	v_mul_f32_e32 v12, 0xbfb8aa3b, v12
	v_mul_f32_e32 v13, 0xbfb8aa3b, v13
	v_exp_f32_e32 v12, v12
	v_exp_f32_e32 v13, v13
	v_pk_mul_f32 v[6:7], v[8:9], v[6:7]
	v_pk_add_f32 v[8:9], v[12:13], 1.0 op_sel_hi:[1,0]
	s_nop 0
	v_cvt_pk_bf16_f32 v5, v6, v7
	v_lshl_add_u64 v[6:7], v[16:17], 0, v[34:35]
	flat_store_dwordx2 v[6:7], v[4:5]
	v_rcp_f32_e32 v5, v9
	v_lshlrev_b32_e32 v6, 16, v39
	v_mul_f32_e32 v12, 0x3d372713, v6
	v_mul_f32_e32 v12, v12, v6
	v_mov_b32_e32 v13, v6
	v_and_b32_e32 v7, 0xffff0000, v39
	v_fmac_f32_e32 v13, v12, v13
	v_mul_f32_e32 v12, 0x3f4c422a, v13
	v_mul_f32_e32 v13, 0x3d372713, v7
	v_mul_f32_e32 v13, v13, v7
	v_mov_b32_e32 v15, v7
	v_fmac_f32_e32 v15, v13, v15
	v_mul_f32_e32 v13, 0x3f4c422a, v15
	v_add_f32_e32 v12, v12, v12
	v_add_f32_e32 v13, v13, v13
	v_mul_f32_e32 v12, 0xbfb8aa3b, v12
	v_mul_f32_e32 v13, 0xbfb8aa3b, v13
	v_exp_f32_e32 v12, v12
	v_exp_f32_e32 v13, v13
	v_rcp_f32_e32 v4, v8
	s_nop 0
	v_pk_mul_f32 v[4:5], v[4:5], v[10:11]
	v_pk_add_f32 v[8:9], v[12:13], 1.0 op_sel_hi:[1,0]
	v_pk_mul_f32 v[0:1], v[4:5], v[0:1]
	s_nop 0
	v_cvt_pk_bf16_f32 v0, v0, v1
	v_rcp_f32_e32 v5, v9
	v_rcp_f32_e32 v4, v8
	s_nop 0
	v_pk_mul_f32 v[4:5], v[4:5], v[6:7]
	s_nop 0
	v_pk_mul_f32 v[2:3], v[4:5], v[2:3]
	s_nop 0
	v_cvt_pk_bf16_f32 v1, v2, v3
	v_lshl_add_u64 v[2:3], v[16:17], 0, v[66:67]
	flat_store_dwordx2 v[2:3], v[0:1]
	s_waitcnt lgkmcnt(0)
	s_barrier

.LBB0_862:
	s_add_u32 s2, s6, 0xfffc0080
	s_addc_u32 s3, s7, -1
	s_add_i32 s56, 0, 0x10000
	v_add_u32_e32 v150, s56, v159
	ds_read_b128 v[138:141], v150
	ds_read_b128 v[142:145], v150 offset:1024
	ds_read_b128 v[146:149], v150 offset:2048
	ds_read_b128 v[150:153], v150 offset:3072
	s_cmp_eq_u32 s41, 12
	s_cselect_b32 s21, s17, s3
	s_cselect_b32 s20, s39, s2
	s_cselect_b32 s3, s15, s23
	s_cselect_b32 s2, s40, s22
	v_lshl_add_u64 v[154:155], s[6:7], 0, v[136:137]
	s_add_i32 m0, s28, 0xc000
	ds_read_b128 v[162:165], v161
	ds_read_b128 v[166:169], v161 offset:1024
	ds_read_b128 v[170:173], v161 offset:2048
	ds_read_b128 v[174:177], v161 offset:3072
	ds_read_b128 v[178:181], v161 offset:4096
	ds_read_b128 v[182:185], v161 offset:5120
	ds_read_b128 v[186:189], v161 offset:6144
	ds_read_b128 v[206:209], v161 offset:7168
	global_load_lds_dwordx4 v[154:155], off
	v_lshl_add_u64 v[154:155], s[6:7], 0, v[134:135]
	s_add_i32 m0, s28, 0xe000
	s_nop 0
	global_load_lds_dwordx4 v[154:155], off
	s_waitcnt lgkmcnt(8)
	s_barrier
	s_waitcnt lgkmcnt(0)
	s_setprio 1
	s_waitcnt lgkmcnt(0)
	v_mfma_f32_16x16x32_bf16 v[120:123], v[138:141], v[162:165], v[120:123]
	v_mfma_f32_16x16x32_bf16 v[112:115], v[146:149], v[162:165], v[112:115]
	v_mfma_f32_16x16x32_bf16 v[104:107], v[138:141], v[170:173], v[104:107]
	v_mfma_f32_16x16x32_bf16 v[96:99], v[146:149], v[170:173], v[96:99]
	v_mfma_f32_16x16x32_bf16 v[88:91], v[138:141], v[178:181], v[88:91]
	v_mfma_f32_16x16x32_bf16 v[80:83], v[146:149], v[178:181], v[80:83]
	v_mfma_f32_16x16x32_bf16 v[72:75], v[138:141], v[186:189], v[72:75]
	v_mfma_f32_16x16x32_bf16 v[64:67], v[146:149], v[186:189], v[64:67]
	v_mfma_f32_16x16x32_bf16 v[120:123], v[142:145], v[166:169], v[120:123]
	v_mfma_f32_16x16x32_bf16 v[112:115], v[150:153], v[166:169], v[112:115]
	v_mfma_f32_16x16x32_bf16 v[104:107], v[142:145], v[174:177], v[104:107]
	v_mfma_f32_16x16x32_bf16 v[96:99], v[150:153], v[174:177], v[96:99]
	v_mfma_f32_16x16x32_bf16 v[88:91], v[142:145], v[182:185], v[88:91]
	v_mfma_f32_16x16x32_bf16 v[80:83], v[150:153], v[182:185], v[80:83]
	v_mfma_f32_16x16x32_bf16 v[72:75], v[142:145], v[206:209], v[72:75]
	v_mfma_f32_16x16x32_bf16 v[64:67], v[150:153], v[206:209], v[64:67]
	s_setprio 0
	s_barrier
	s_add_i32 s58, 0, 0x14000
	v_add_u32_e32 v154, s58, v159
	s_add_i32 s56, s56, s27
	ds_read_b128 v[210:213], v154
	ds_read_b128 v[214:217], v154 offset:1024
	ds_read_b128 v[218:221], v154 offset:2048
	ds_read_b128 v[222:225], v154 offset:3072
	v_lshl_add_u64 v[154:155], s[2:3], 0, v[194:195]
	s_mov_b32 m0, s56
	v_lshl_add_u64 v[190:191], s[2:3], 0, v[128:129]
	global_load_lds_dwordx4 v[154:155], off
	s_add_i32 m0, s56, 0x2000
	s_nop 0
	global_load_lds_dwordx4 v[190:191], off
	s_barrier
	s_waitcnt lgkmcnt(0)
	s_setprio 1
	s_waitcnt lgkmcnt(0)
	v_mfma_f32_16x16x32_bf16 v[124:127], v[210:213], v[162:165], v[124:127]
	v_mfma_f32_16x16x32_bf16 v[116:119], v[218:221], v[162:165], v[116:119]
	v_mfma_f32_16x16x32_bf16 v[108:111], v[210:213], v[170:173], v[108:111]
	v_mfma_f32_16x16x32_bf16 v[100:103], v[218:221], v[170:173], v[100:103]
	v_mfma_f32_16x16x32_bf16 v[92:95], v[210:213], v[178:181], v[92:95]
	v_mfma_f32_16x16x32_bf16 v[84:87], v[218:221], v[178:181], v[84:87]
	v_mfma_f32_16x16x32_bf16 v[76:79], v[210:213], v[186:189], v[76:79]
	v_mfma_f32_16x16x32_bf16 v[68:71], v[218:221], v[186:189], v[68:71]
	v_mfma_f32_16x16x32_bf16 v[124:127], v[214:217], v[166:169], v[124:127]
	v_mfma_f32_16x16x32_bf16 v[116:119], v[222:225], v[166:169], v[116:119]
	v_mfma_f32_16x16x32_bf16 v[108:111], v[214:217], v[174:177], v[108:111]
	v_mfma_f32_16x16x32_bf16 v[100:103], v[222:225], v[174:177], v[100:103]
	v_mfma_f32_16x16x32_bf16 v[92:95], v[214:217], v[182:185], v[92:95]
	v_mfma_f32_16x16x32_bf16 v[84:87], v[222:225], v[182:185], v[84:87]
	v_mfma_f32_16x16x32_bf16 v[76:79], v[214:217], v[206:209], v[76:79]
	v_mfma_f32_16x16x32_bf16 v[68:71], v[222:225], v[206:209], v[68:71]
	s_setprio 0
	s_mov_b32 m0, s28
	v_lshl_add_u64 v[202:203], s[20:21], 0, v[132:133]
	s_barrier
	ds_read_b128 v[162:165], v161 offset:16384
	ds_read_b128 v[166:169], v161 offset:17408
	ds_read_b128 v[170:173], v161 offset:18432
	ds_read_b128 v[174:177], v161 offset:19456
	ds_read_b128 v[178:181], v161 offset:20480
	ds_read_b128 v[182:185], v161 offset:21504
	ds_read_b128 v[186:189], v161 offset:22528
	ds_read_b128 v[206:209], v161 offset:23552
	global_load_lds_dwordx4 v[202:203], off
	v_lshl_add_u64 v[226:227], s[20:21], 0, v[130:131]
	s_mov_b32 m0, s29
	s_nop 0
	global_load_lds_dwordx4 v[226:227], off
	s_barrier
	s_waitcnt lgkmcnt(0)
	s_setprio 1
	s_waitcnt lgkmcnt(0)
	v_mfma_f32_16x16x32_bf16 v[56:59], v[138:141], v[162:165], v[56:59]
	v_mfma_f32_16x16x32_bf16 v[48:51], v[146:149], v[162:165], v[48:51]
	v_mfma_f32_16x16x32_bf16 v[40:43], v[138:141], v[170:173], v[40:43]
	v_mfma_f32_16x16x32_bf16 v[32:35], v[146:149], v[170:173], v[32:35]
	v_mfma_f32_16x16x32_bf16 v[24:27], v[138:141], v[178:181], v[24:27]
	v_mfma_f32_16x16x32_bf16 v[16:19], v[146:149], v[178:181], v[16:19]
	v_mfma_f32_16x16x32_bf16 v[8:11], v[138:141], v[186:189], v[8:11]
	v_mfma_f32_16x16x32_bf16 v[0:3], v[146:149], v[186:189], v[0:3]
	v_mfma_f32_16x16x32_bf16 v[56:59], v[142:145], v[166:169], v[56:59]
	v_mfma_f32_16x16x32_bf16 v[48:51], v[150:153], v[166:169], v[48:51]
	v_mfma_f32_16x16x32_bf16 v[40:43], v[142:145], v[174:177], v[40:43]
	v_mfma_f32_16x16x32_bf16 v[32:35], v[150:153], v[174:177], v[32:35]
	v_mfma_f32_16x16x32_bf16 v[24:27], v[142:145], v[182:185], v[24:27]
	v_mfma_f32_16x16x32_bf16 v[16:19], v[150:153], v[182:185], v[16:19]
	v_mfma_f32_16x16x32_bf16 v[8:11], v[142:145], v[206:209], v[8:11]
	v_mfma_f32_16x16x32_bf16 v[0:3], v[150:153], v[206:209], v[0:3]
	s_setprio 0
	s_barrier
	s_add_u32 s56, s2, 0x40000
	s_addc_u32 s57, s3, 0
	s_add_i32 s58, s58, s27
	v_lshl_add_u64 v[138:139], s[56:57], 0, v[194:195]
	s_mov_b32 m0, s58
	s_nop 0
	global_load_lds_dwordx4 v[138:139], off
	v_lshl_add_u64 v[138:139], s[56:57], 0, v[128:129]
	s_add_i32 m0, s58, 0x2000
	s_nop 0
	global_load_lds_dwordx4 v[138:139], off
	s_waitcnt vmcnt(6)
	s_barrier
	s_setprio 1
	v_mfma_f32_16x16x32_bf16 v[60:63], v[210:213], v[162:165], v[60:63]
	v_mfma_f32_16x16x32_bf16 v[52:55], v[218:221], v[162:165], v[52:55]
	v_mfma_f32_16x16x32_bf16 v[44:47], v[210:213], v[170:173], v[44:47]
	v_mfma_f32_16x16x32_bf16 v[36:39], v[218:221], v[170:173], v[36:39]
	v_mfma_f32_16x16x32_bf16 v[28:31], v[210:213], v[178:181], v[28:31]
	v_mfma_f32_16x16x32_bf16 v[20:23], v[218:221], v[178:181], v[20:23]
	v_mfma_f32_16x16x32_bf16 v[12:15], v[210:213], v[186:189], v[12:15]
	v_mfma_f32_16x16x32_bf16 v[4:7], v[218:221], v[186:189], v[4:7]
	v_mfma_f32_16x16x32_bf16 v[60:63], v[214:217], v[166:169], v[60:63]
	v_mfma_f32_16x16x32_bf16 v[52:55], v[222:225], v[166:169], v[52:55]
	v_mfma_f32_16x16x32_bf16 v[44:47], v[214:217], v[174:177], v[44:47]
	v_mfma_f32_16x16x32_bf16 v[36:39], v[222:225], v[174:177], v[36:39]
	v_mfma_f32_16x16x32_bf16 v[28:31], v[214:217], v[182:185], v[28:31]
	v_mfma_f32_16x16x32_bf16 v[20:23], v[222:225], v[182:185], v[20:23]
	v_mfma_f32_16x16x32_bf16 v[12:15], v[214:217], v[206:209], v[12:15]
	v_mfma_f32_16x16x32_bf16 v[4:7], v[222:225], v[206:209], v[4:7]
	s_setprio 0
	s_add_i32 s56, 0, 0x18000
	v_add_u32_e32 v150, s56, v159
	s_barrier
	ds_read_b128 v[138:141], v150
	ds_read_b128 v[142:145], v150 offset:1024
	ds_read_b128 v[146:149], v150 offset:2048
	ds_read_b128 v[150:153], v150 offset:3072
	s_add_u32 s20, s20, 0x40000
	s_addc_u32 s21, s21, 0
	s_mov_b32 m0, s30
	v_lshl_add_u64 v[210:211], s[20:21], 0, v[132:133]
	ds_read_b128 v[162:165], v161 offset:32768
	ds_read_b128 v[166:169], v161 offset:33792
	ds_read_b128 v[170:173], v161 offset:34816
	ds_read_b128 v[174:177], v161 offset:35840
	ds_read_b128 v[178:181], v161 offset:36864
	ds_read_b128 v[182:185], v161 offset:37888
	ds_read_b128 v[186:189], v161 offset:38912
	ds_read_b128 v[206:209], v161 offset:39936
	global_load_lds_dwordx4 v[210:211], off
	v_lshl_add_u64 v[210:211], s[20:21], 0, v[130:131]
	s_mov_b32 m0, s31
	s_nop 0
	global_load_lds_dwordx4 v[210:211], off
	s_waitcnt lgkmcnt(8)
	s_barrier
	s_waitcnt lgkmcnt(0)
	s_setprio 1
	s_waitcnt lgkmcnt(0)
	v_mfma_f32_16x16x32_bf16 v[120:123], v[138:141], v[162:165], v[120:123]
	v_mfma_f32_16x16x32_bf16 v[112:115], v[146:149], v[162:165], v[112:115]
	v_mfma_f32_16x16x32_bf16 v[104:107], v[138:141], v[170:173], v[104:107]
	v_mfma_f32_16x16x32_bf16 v[96:99], v[146:149], v[170:173], v[96:99]
	v_mfma_f32_16x16x32_bf16 v[88:91], v[138:141], v[178:181], v[88:91]
	v_mfma_f32_16x16x32_bf16 v[80:83], v[146:149], v[178:181], v[80:83]
	v_mfma_f32_16x16x32_bf16 v[72:75], v[138:141], v[186:189], v[72:75]
	v_mfma_f32_16x16x32_bf16 v[64:67], v[146:149], v[186:189], v[64:67]
	v_mfma_f32_16x16x32_bf16 v[120:123], v[142:145], v[166:169], v[120:123]
	v_mfma_f32_16x16x32_bf16 v[112:115], v[150:153], v[166:169], v[112:115]
	v_mfma_f32_16x16x32_bf16 v[104:107], v[142:145], v[174:177], v[104:107]
	v_mfma_f32_16x16x32_bf16 v[96:99], v[150:153], v[174:177], v[96:99]
	v_mfma_f32_16x16x32_bf16 v[88:91], v[142:145], v[182:185], v[88:91]
	v_mfma_f32_16x16x32_bf16 v[80:83], v[150:153], v[182:185], v[80:83]
	v_mfma_f32_16x16x32_bf16 v[72:75], v[142:145], v[206:209], v[72:75]
	v_mfma_f32_16x16x32_bf16 v[64:67], v[150:153], v[206:209], v[64:67]
	s_setprio 0
	s_barrier
	s_add_i32 s20, 0, 0x1c000
	s_add_i32 s21, s56, s27
	v_add_u32_e32 v156, s20, v159
	v_lshl_add_u64 v[154:155], v[154:155], 0, s[70:71]
	s_mov_b32 m0, s21
	ds_read_b128 v[210:213], v156
	ds_read_b128 v[214:217], v156 offset:1024
	ds_read_b128 v[218:221], v156 offset:2048
	ds_read_b128 v[222:225], v156 offset:3072
	global_load_lds_dwordx4 v[154:155], off
	v_lshl_add_u64 v[154:155], v[190:191], 0, s[70:71]
	s_add_i32 m0, s21, 0x2000
	s_nop 0
	global_load_lds_dwordx4 v[154:155], off
	s_barrier
	s_waitcnt lgkmcnt(0)
	s_setprio 1
	s_waitcnt lgkmcnt(0)
	v_mfma_f32_16x16x32_bf16 v[124:127], v[210:213], v[162:165], v[124:127]
	v_mfma_f32_16x16x32_bf16 v[116:119], v[218:221], v[162:165], v[116:119]
	v_mfma_f32_16x16x32_bf16 v[108:111], v[210:213], v[170:173], v[108:111]
	v_mfma_f32_16x16x32_bf16 v[100:103], v[218:221], v[170:173], v[100:103]
	v_mfma_f32_16x16x32_bf16 v[92:95], v[210:213], v[178:181], v[92:95]
	v_mfma_f32_16x16x32_bf16 v[84:87], v[218:221], v[178:181], v[84:87]
	v_mfma_f32_16x16x32_bf16 v[76:79], v[210:213], v[186:189], v[76:79]
	v_mfma_f32_16x16x32_bf16 v[68:71], v[218:221], v[186:189], v[68:71]
	v_mfma_f32_16x16x32_bf16 v[124:127], v[214:217], v[166:169], v[124:127]
	v_mfma_f32_16x16x32_bf16 v[116:119], v[222:225], v[166:169], v[116:119]
	v_mfma_f32_16x16x32_bf16 v[108:111], v[214:217], v[174:177], v[108:111]
	v_mfma_f32_16x16x32_bf16 v[100:103], v[222:225], v[174:177], v[100:103]
	v_mfma_f32_16x16x32_bf16 v[92:95], v[214:217], v[182:185], v[92:95]
	v_mfma_f32_16x16x32_bf16 v[84:87], v[222:225], v[182:185], v[84:87]
	v_mfma_f32_16x16x32_bf16 v[76:79], v[214:217], v[206:209], v[76:79]
	v_mfma_f32_16x16x32_bf16 v[68:71], v[222:225], v[206:209], v[68:71]
	s_setprio 0
	s_mov_b32 m0, s34
	v_lshl_add_u64 v[154:155], v[202:203], 0, s[70:71]
	s_barrier
	ds_read_b128 v[162:165], v161 offset:49152
	ds_read_b128 v[166:169], v161 offset:50176
	ds_read_b128 v[170:173], v161 offset:51200
	ds_read_b128 v[174:177], v161 offset:52224
	ds_read_b128 v[178:181], v161 offset:53248
	ds_read_b128 v[182:185], v161 offset:54272
	ds_read_b128 v[186:189], v161 offset:55296
	ds_read_b128 v[206:209], v161 offset:56320
	global_load_lds_dwordx4 v[154:155], off
	v_lshl_add_u64 v[154:155], v[226:227], 0, s[70:71]
	s_mov_b32 m0, s35
	s_nop 0
	global_load_lds_dwordx4 v[154:155], off
	s_barrier
	s_waitcnt lgkmcnt(0)
	s_setprio 1
	s_waitcnt lgkmcnt(0)
	v_mfma_f32_16x16x32_bf16 v[56:59], v[138:141], v[162:165], v[56:59]
	v_mfma_f32_16x16x32_bf16 v[48:51], v[146:149], v[162:165], v[48:51]
	v_mfma_f32_16x16x32_bf16 v[40:43], v[138:141], v[170:173], v[40:43]
	v_mfma_f32_16x16x32_bf16 v[32:35], v[146:149], v[170:173], v[32:35]
	v_mfma_f32_16x16x32_bf16 v[24:27], v[138:141], v[178:181], v[24:27]
	v_mfma_f32_16x16x32_bf16 v[16:19], v[146:149], v[178:181], v[16:19]
	v_mfma_f32_16x16x32_bf16 v[8:11], v[138:141], v[186:189], v[8:11]
	v_mfma_f32_16x16x32_bf16 v[0:3], v[146:149], v[186:189], v[0:3]
	v_mfma_f32_16x16x32_bf16 v[56:59], v[142:145], v[166:169], v[56:59]
	v_mfma_f32_16x16x32_bf16 v[48:51], v[150:153], v[166:169], v[48:51]
	v_mfma_f32_16x16x32_bf16 v[40:43], v[142:145], v[174:177], v[40:43]
	v_mfma_f32_16x16x32_bf16 v[32:35], v[150:153], v[174:177], v[32:35]
	v_mfma_f32_16x16x32_bf16 v[24:27], v[142:145], v[182:185], v[24:27]
	v_mfma_f32_16x16x32_bf16 v[16:19], v[150:153], v[182:185], v[16:19]
	v_mfma_f32_16x16x32_bf16 v[8:11], v[142:145], v[206:209], v[8:11]
	v_mfma_f32_16x16x32_bf16 v[0:3], v[150:153], v[206:209], v[0:3]
	s_setprio 0
	s_barrier
	s_add_u32 s2, s2, 0x40080
	s_addc_u32 s3, s3, 0
	s_add_i32 s20, s20, s27
	v_lshl_add_u64 v[138:139], s[2:3], 0, v[194:195]
	s_mov_b32 m0, s20
	s_nop 0
	global_load_lds_dwordx4 v[138:139], off
	v_lshl_add_u64 v[138:139], s[2:3], 0, v[128:129]
	s_add_i32 m0, s20, 0x2000
	s_nop 0
	global_load_lds_dwordx4 v[138:139], off
	s_waitcnt vmcnt(6)
	s_barrier
	s_setprio 1
	v_mfma_f32_16x16x32_bf16 v[60:63], v[210:213], v[162:165], v[60:63]
	v_mfma_f32_16x16x32_bf16 v[52:55], v[218:221], v[162:165], v[52:55]
	v_mfma_f32_16x16x32_bf16 v[44:47], v[210:213], v[170:173], v[44:47]
	v_mfma_f32_16x16x32_bf16 v[36:39], v[218:221], v[170:173], v[36:39]
	v_mfma_f32_16x16x32_bf16 v[28:31], v[210:213], v[178:181], v[28:31]
	v_mfma_f32_16x16x32_bf16 v[20:23], v[218:221], v[178:181], v[20:23]
	v_mfma_f32_16x16x32_bf16 v[12:15], v[210:213], v[186:189], v[12:15]
	v_mfma_f32_16x16x32_bf16 v[4:7], v[218:221], v[186:189], v[4:7]
	v_mfma_f32_16x16x32_bf16 v[60:63], v[214:217], v[166:169], v[60:63]
	v_mfma_f32_16x16x32_bf16 v[52:55], v[222:225], v[166:169], v[52:55]
	v_mfma_f32_16x16x32_bf16 v[44:47], v[214:217], v[174:177], v[44:47]
	v_mfma_f32_16x16x32_bf16 v[36:39], v[222:225], v[174:177], v[36:39]
	v_mfma_f32_16x16x32_bf16 v[28:31], v[214:217], v[182:185], v[28:31]
	v_mfma_f32_16x16x32_bf16 v[20:23], v[222:225], v[182:185], v[20:23]
	v_mfma_f32_16x16x32_bf16 v[12:15], v[214:217], v[206:209], v[12:15]
	v_mfma_f32_16x16x32_bf16 v[4:7], v[222:225], v[206:209], v[4:7]
	s_setprio 0
	s_add_i32 s41, s41, 2
	s_add_u32 s22, s22, 0x100
	s_addc_u32 s23, s23, 0
	s_add_u32 s6, s6, 0x100
	s_addc_u32 s7, s7, 0
	s_cmp_gt_u32 s41, 13
	s_barrier
	s_cbranch_scc0 .LBB0_862
	v_lshl_add_u32 v138, s38, 8, v158
	v_ashrrev_i32_e32 v139, 31, v138
	v_lshl_add_u64 v[140:141], v[138:139], 3, s[12:13]
	flat_load_dwordx2 v[162:163], v[140:141]
	flat_load_dwordx2 v[152:153], v[140:141] offset:128
	flat_load_dwordx2 v[150:151], v[140:141] offset:256
	flat_load_dwordx2 v[148:149], v[140:141] offset:384
	s_mov_b32 s20, 0x800000
	v_lshl_or_b32 v154, s37, 7, v160
	v_ashrrev_i32_e32 v155, 31, v154
	s_movk_i32 s6, 0x1600
	flat_load_dwordx2 v[146:147], v[140:141] offset:1024
	flat_load_dwordx2 v[144:145], v[140:141] offset:1152
	flat_load_dwordx2 v[142:143], v[140:141] offset:1280
	s_nop 0
	flat_load_dwordx2 v[140:141], v[140:141] offset:1408
	v_add_u32_e32 v139, 0x80, v138
	s_waitcnt vmcnt(0) lgkmcnt(0)
	v_ffbh_u32_e32 v156, v163
	v_min_u32_e32 v156, 32, v156
	v_lshlrev_b64 v[162:163], v156, v[162:163]
	v_min_u32_e32 v162, 1, v162
	v_or_b32_e32 v162, v163, v162
	v_cvt_f32_u32_e32 v162, v162
	v_sub_u32_e32 v156, 32, v156
	v_ldexp_f32 v156, v162, v156
	v_fmamk_f32 v156, v156, 0x2e800000, v236
	v_cmp_gt_f32_e32 vcc, s20, v156
	v_mul_f32_e32 v162, 0x4b800000, v156
	s_nop 0
	v_cndmask_b32_e32 v156, v156, v162, vcc
	v_rsq_f32_e32 v156, v156
	s_nop 0
	v_mul_f32_e32 v162, 0x45800000, v156
	v_cndmask_b32_e32 v156, v156, v162, vcc
	v_pk_mul_f32 v[120:121], v[120:121], v[156:157] op_sel_hi:[1,0]
	v_pk_mul_f32 v[124:125], v[124:125], v[156:157] op_sel_hi:[1,0]
	v_mul_f32_e32 v162, 0xbfb8aa3b, v120
	v_mul_f32_e32 v163, 0xbfb8aa3b, v121
	v_exp_f32_e32 v162, v162
	v_exp_f32_e32 v163, v163
	v_pk_mul_f32 v[122:123], v[122:123], v[156:157] op_sel_hi:[1,0]
	v_pk_mul_f32 v[112:113], v[112:113], v[156:157] op_sel_hi:[1,0]
	v_pk_mul_f32 v[126:127], v[126:127], v[156:157] op_sel_hi:[1,0]
	v_pk_add_f32 v[162:163], v[162:163], 1.0 op_sel_hi:[1,0]
	v_pk_mul_f32 v[116:117], v[116:117], v[156:157] op_sel_hi:[1,0]
	v_pk_mul_f32 v[114:115], v[114:115], v[156:157] op_sel_hi:[1,0]
	v_pk_mul_f32 v[118:119], v[118:119], v[156:157] op_sel_hi:[1,0]
	v_rcp_f32_e32 v163, v163
	v_rcp_f32_e32 v162, v162
	s_nop 0
	v_pk_mul_f32 v[120:121], v[120:121], v[162:163]
	s_nop 0
	v_pk_mul_f32 v[120:121], v[124:125], v[120:121]
	v_mul_f32_e32 v124, 0xbfb8aa3b, v122
	v_mul_f32_e32 v125, 0xbfb8aa3b, v123
	v_exp_f32_e32 v124, v124
	v_exp_f32_e32 v125, v125
	s_nop 0
	v_pk_add_f32 v[124:125], v[124:125], 1.0 op_sel_hi:[1,0]
	s_nop 0
	v_rcp_f32_e32 v125, v125
	v_rcp_f32_e32 v124, v124
	s_nop 0
	v_pk_mul_f32 v[122:123], v[122:123], v[124:125]
	v_mul_f32_e32 v124, 0xbfb8aa3b, v112
	v_mul_f32_e32 v125, 0xbfb8aa3b, v113
	v_exp_f32_e32 v124, v124
	v_exp_f32_e32 v125, v125
	v_pk_mul_f32 v[122:123], v[126:127], v[122:123]
	v_pk_add_f32 v[124:125], v[124:125], 1.0 op_sel_hi:[1,0]
	s_nop 0
	v_rcp_f32_e32 v125, v125
	v_rcp_f32_e32 v124, v124
	s_nop 0
	v_pk_mul_f32 v[112:113], v[112:113], v[124:125]
	s_nop 0
	v_pk_mul_f32 v[112:113], v[116:117], v[112:113]
	v_mul_f32_e32 v116, 0xbfb8aa3b, v114
	v_mul_f32_e32 v117, 0xbfb8aa3b, v115
	v_exp_f32_e32 v116, v116
	v_exp_f32_e32 v117, v117
	s_nop 0
	v_pk_add_f32 v[116:117], v[116:117], 1.0 op_sel_hi:[1,0]
	s_nop 0
	v_rcp_f32_e32 v117, v117
	v_rcp_f32_e32 v116, v116
	s_nop 0
	v_pk_mul_f32 v[114:115], v[114:115], v[116:117]
	v_cvt_pk_bf16_f32 v116, v120, v121
	v_pk_mul_f32 v[114:115], v[118:119], v[114:115]
	v_cvt_pk_bf16_f32 v118, v112, v113
	v_mov_b64_e32 v[112:113], s[10:11]
	v_cvt_pk_bf16_f32 v119, v114, v115
	v_mad_i64_i32 v[120:121], s[2:3], v138, s6, v[112:113]
	v_lshlrev_b64 v[114:115], 1, v[154:155]
	v_cvt_pk_bf16_f32 v117, v122, v123
	v_lshl_add_u64 v[120:121], v[120:121], 0, v[114:115]
	flat_store_dwordx4 v[120:121], v[116:119]
	s_nop 1
	v_ffbh_u32_e32 v116, v153
	v_min_u32_e32 v118, 32, v116
	v_lshlrev_b64 v[116:117], v118, v[152:153]
	v_min_u32_e32 v116, 1, v116
	v_or_b32_e32 v116, v117, v116
	v_cvt_f32_u32_e32 v116, v116
	v_sub_u32_e32 v117, 32, v118
	v_ldexp_f32 v116, v116, v117
	v_fmamk_f32 v116, v116, 0x2e800000, v236
	v_cmp_gt_f32_e32 vcc, s20, v116
	v_mul_f32_e32 v117, 0x4b800000, v116
	s_nop 0
	v_cndmask_b32_e32 v116, v116, v117, vcc
	v_rsq_f32_e32 v116, v116
	s_nop 0
	v_mul_f32_e32 v117, 0x45800000, v116
	v_cndmask_b32_e32 v116, v116, v117, vcc
	v_pk_mul_f32 v[104:105], v[104:105], v[116:117] op_sel_hi:[1,0]
	s_nop 0
	v_mul_f32_e32 v117, 0xbfb8aa3b, v104
	v_exp_f32_e32 v118, v117
	v_pk_mul_f32 v[108:109], v[108:109], v[116:117] op_sel_hi:[1,0]
	v_mul_f32_e32 v117, 0xbfb8aa3b, v105
	v_exp_f32_e32 v119, v117
	s_nop 0
	v_pk_add_f32 v[118:119], v[118:119], 1.0 op_sel_hi:[1,0]
	s_nop 0
	v_rcp_f32_e32 v119, v119
	v_rcp_f32_e32 v118, v118
	s_nop 0
	v_pk_mul_f32 v[104:105], v[104:105], v[118:119]
	v_pk_mul_f32 v[106:107], v[106:107], v[116:117] op_sel_hi:[1,0]
	v_pk_mul_f32 v[104:105], v[108:109], v[104:105]
	v_mul_f32_e32 v108, 0xbfb8aa3b, v106
	v_mul_f32_e32 v109, 0xbfb8aa3b, v107
	v_exp_f32_e32 v108, v108
	v_exp_f32_e32 v109, v109
	v_pk_mul_f32 v[110:111], v[110:111], v[116:117] op_sel_hi:[1,0]
	v_pk_add_f32 v[108:109], v[108:109], 1.0 op_sel_hi:[1,0]
	s_nop 0
	v_rcp_f32_e32 v109, v109
	v_rcp_f32_e32 v108, v108
	v_pk_mul_f32 v[96:97], v[96:97], v[116:117] op_sel_hi:[1,0]
	v_pk_mul_f32 v[106:107], v[106:107], v[108:109]
	v_mul_f32_e32 v108, 0xbfb8aa3b, v96
	v_mul_f32_e32 v109, 0xbfb8aa3b, v97
	v_exp_f32_e32 v108, v108
	v_exp_f32_e32 v109, v109
	v_pk_mul_f32 v[106:107], v[110:111], v[106:107]
	v_pk_mul_f32 v[100:101], v[100:101], v[116:117] op_sel_hi:[1,0]
	v_pk_add_f32 v[108:109], v[108:109], 1.0 op_sel_hi:[1,0]
	s_nop 0
	v_rcp_f32_e32 v109, v109
	v_rcp_f32_e32 v108, v108
	s_nop 0
	v_pk_mul_f32 v[96:97], v[96:97], v[108:109]
	v_pk_mul_f32 v[102:103], v[102:103], v[116:117] op_sel_hi:[1,0]
	v_pk_mul_f32 v[100:101], v[100:101], v[96:97]
	v_pk_mul_f32 v[96:97], v[98:99], v[116:117] op_sel_hi:[1,0]
	s_nop 0
	v_mul_f32_e32 v98, 0xbfb8aa3b, v96
	v_mul_f32_e32 v99, 0xbfb8aa3b, v97
	v_exp_f32_e32 v98, v98
	v_exp_f32_e32 v99, v99
	s_nop 0
	v_pk_add_f32 v[98:99], v[98:99], 1.0 op_sel_hi:[1,0]
	s_nop 0
	v_rcp_f32_e32 v99, v99
	v_rcp_f32_e32 v98, v98
	s_nop 0
	v_pk_mul_f32 v[96:97], v[96:97], v[98:99]
	v_or_b32_e32 v108, 16, v138
	v_pk_mul_f32 v[102:103], v[102:103], v[96:97]
	v_cvt_pk_bf16_f32 v98, v100, v101
	v_mad_i64_i32 v[100:101], s[2:3], v108, s6, v[112:113]
	v_cvt_pk_bf16_f32 v96, v104, v105
	v_cvt_pk_bf16_f32 v97, v106, v107
	v_cvt_pk_bf16_f32 v99, v102, v103
	v_lshl_add_u64 v[100:101], v[100:101], 0, v[114:115]
	flat_store_dwordx4 v[100:101], v[96:99]
	s_nop 1
	v_ffbh_u32_e32 v96, v151
	v_min_u32_e32 v98, 32, v96
	v_lshlrev_b64 v[96:97], v98, v[150:151]
	v_min_u32_e32 v96, 1, v96
	v_or_b32_e32 v96, v97, v96
	v_cvt_f32_u32_e32 v96, v96
	v_sub_u32_e32 v97, 32, v98
	v_ldexp_f32 v96, v96, v97
	v_fmamk_f32 v96, v96, 0x2e800000, v236
	v_cmp_gt_f32_e32 vcc, s20, v96
	v_mul_f32_e32 v97, 0x4b800000, v96
	s_nop 0
	v_cndmask_b32_e32 v96, v96, v97, vcc
	v_rsq_f32_e32 v96, v96
	s_nop 0
	v_mul_f32_e32 v97, 0x45800000, v96
	v_cndmask_b32_e32 v96, v96, v97, vcc
	v_pk_mul_f32 v[88:89], v[88:89], v[96:97] op_sel_hi:[1,0]
	s_nop 0
	v_mul_f32_e32 v97, 0xbfb8aa3b, v88
	v_exp_f32_e32 v98, v97
	v_pk_mul_f32 v[92:93], v[92:93], v[96:97] op_sel_hi:[1,0]
	v_mul_f32_e32 v97, 0xbfb8aa3b, v89
	v_exp_f32_e32 v99, v97
	s_nop 0
	v_pk_add_f32 v[98:99], v[98:99], 1.0 op_sel_hi:[1,0]
	s_nop 0
	v_rcp_f32_e32 v99, v99
	v_rcp_f32_e32 v98, v98
	s_nop 0
	v_pk_mul_f32 v[88:89], v[88:89], v[98:99]
	v_pk_mul_f32 v[90:91], v[90:91], v[96:97] op_sel_hi:[1,0]
	v_pk_mul_f32 v[88:89], v[92:93], v[88:89]
	v_mul_f32_e32 v92, 0xbfb8aa3b, v90
	v_mul_f32_e32 v93, 0xbfb8aa3b, v91
	v_exp_f32_e32 v92, v92
	v_exp_f32_e32 v93, v93
	v_pk_mul_f32 v[94:95], v[94:95], v[96:97] op_sel_hi:[1,0]
	v_pk_add_f32 v[92:93], v[92:93], 1.0 op_sel_hi:[1,0]
	s_nop 0
	v_rcp_f32_e32 v93, v93
	v_rcp_f32_e32 v92, v92
	v_pk_mul_f32 v[80:81], v[80:81], v[96:97] op_sel_hi:[1,0]
	v_pk_mul_f32 v[90:91], v[90:91], v[92:93]
	v_mul_f32_e32 v92, 0xbfb8aa3b, v80
	v_mul_f32_e32 v93, 0xbfb8aa3b, v81
	v_exp_f32_e32 v92, v92
	v_exp_f32_e32 v93, v93
	v_pk_mul_f32 v[90:91], v[94:95], v[90:91]
	v_pk_mul_f32 v[84:85], v[84:85], v[96:97] op_sel_hi:[1,0]
	v_pk_add_f32 v[92:93], v[92:93], 1.0 op_sel_hi:[1,0]
	s_nop 0
	v_rcp_f32_e32 v93, v93
	v_rcp_f32_e32 v92, v92
	s_nop 0
	v_pk_mul_f32 v[80:81], v[80:81], v[92:93]
	v_pk_mul_f32 v[86:87], v[86:87], v[96:97] op_sel_hi:[1,0]
	v_pk_mul_f32 v[84:85], v[84:85], v[80:81]
	v_pk_mul_f32 v[80:81], v[82:83], v[96:97] op_sel_hi:[1,0]
	s_nop 0
	v_mul_f32_e32 v82, 0xbfb8aa3b, v80
	v_mul_f32_e32 v83, 0xbfb8aa3b, v81
	v_exp_f32_e32 v82, v82
	v_exp_f32_e32 v83, v83
	s_nop 0
	v_pk_add_f32 v[82:83], v[82:83], 1.0 op_sel_hi:[1,0]
	s_nop 0
	v_rcp_f32_e32 v83, v83
	v_rcp_f32_e32 v82, v82
	s_nop 0
	v_pk_mul_f32 v[80:81], v[80:81], v[82:83]
	v_or_b32_e32 v92, 32, v138
	v_pk_mul_f32 v[86:87], v[86:87], v[80:81]
	v_cvt_pk_bf16_f32 v82, v84, v85
	v_mad_i64_i32 v[84:85], s[2:3], v92, s6, v[112:113]
	v_cvt_pk_bf16_f32 v80, v88, v89
	v_cvt_pk_bf16_f32 v81, v90, v91
	v_cvt_pk_bf16_f32 v83, v86, v87
	v_lshl_add_u64 v[84:85], v[84:85], 0, v[114:115]
	flat_store_dwordx4 v[84:85], v[80:83]
	s_nop 1
	v_ffbh_u32_e32 v80, v149
	v_min_u32_e32 v82, 32, v80
	v_lshlrev_b64 v[80:81], v82, v[148:149]
	v_min_u32_e32 v80, 1, v80
	v_or_b32_e32 v80, v81, v80
	v_cvt_f32_u32_e32 v80, v80
	v_sub_u32_e32 v81, 32, v82
	v_ldexp_f32 v80, v80, v81
	v_fmamk_f32 v80, v80, 0x2e800000, v236
	v_cmp_gt_f32_e32 vcc, s20, v80
	v_mul_f32_e32 v81, 0x4b800000, v80
	s_nop 0
	v_cndmask_b32_e32 v80, v80, v81, vcc
	v_rsq_f32_e32 v80, v80
	s_nop 0
	v_mul_f32_e32 v81, 0x45800000, v80
	v_cndmask_b32_e32 v80, v80, v81, vcc
	v_pk_mul_f32 v[72:73], v[72:73], v[80:81] op_sel_hi:[1,0]
	s_nop 0
	v_mul_f32_e32 v81, 0xbfb8aa3b, v72
	v_exp_f32_e32 v82, v81
	v_pk_mul_f32 v[76:77], v[76:77], v[80:81] op_sel_hi:[1,0]
	v_mul_f32_e32 v81, 0xbfb8aa3b, v73
	v_exp_f32_e32 v83, v81
	s_nop 0
	v_pk_add_f32 v[82:83], v[82:83], 1.0 op_sel_hi:[1,0]
	s_nop 0
	v_rcp_f32_e32 v83, v83
	v_rcp_f32_e32 v82, v82
	s_nop 0
	v_pk_mul_f32 v[72:73], v[72:73], v[82:83]
	v_pk_mul_f32 v[74:75], v[74:75], v[80:81] op_sel_hi:[1,0]
	v_pk_mul_f32 v[72:73], v[76:77], v[72:73]
	v_mul_f32_e32 v76, 0xbfb8aa3b, v74
	v_mul_f32_e32 v77, 0xbfb8aa3b, v75
	v_exp_f32_e32 v76, v76
	v_exp_f32_e32 v77, v77
	v_pk_mul_f32 v[78:79], v[78:79], v[80:81] op_sel_hi:[1,0]
	v_pk_add_f32 v[76:77], v[76:77], 1.0 op_sel_hi:[1,0]
	s_nop 0
	v_rcp_f32_e32 v77, v77
	v_rcp_f32_e32 v76, v76
	v_pk_mul_f32 v[64:65], v[64:65], v[80:81] op_sel_hi:[1,0]
	v_pk_mul_f32 v[74:75], v[74:75], v[76:77]
	v_mul_f32_e32 v76, 0xbfb8aa3b, v64
	v_mul_f32_e32 v77, 0xbfb8aa3b, v65
	v_exp_f32_e32 v76, v76
	v_exp_f32_e32 v77, v77
	v_pk_mul_f32 v[74:75], v[78:79], v[74:75]
	v_pk_mul_f32 v[68:69], v[68:69], v[80:81] op_sel_hi:[1,0]
	v_pk_add_f32 v[76:77], v[76:77], 1.0 op_sel_hi:[1,0]
	s_nop 0
	v_rcp_f32_e32 v77, v77
	v_rcp_f32_e32 v76, v76
	s_nop 0
	v_pk_mul_f32 v[64:65], v[64:65], v[76:77]
	v_pk_mul_f32 v[70:71], v[70:71], v[80:81] op_sel_hi:[1,0]
	v_pk_mul_f32 v[68:69], v[68:69], v[64:65]
	v_pk_mul_f32 v[64:65], v[66:67], v[80:81] op_sel_hi:[1,0]
	s_nop 0
	v_mul_f32_e32 v66, 0xbfb8aa3b, v64
	v_mul_f32_e32 v67, 0xbfb8aa3b, v65
	v_exp_f32_e32 v66, v66
	v_exp_f32_e32 v67, v67
	s_nop 0
	v_pk_add_f32 v[66:67], v[66:67], 1.0 op_sel_hi:[1,0]
	s_nop 0
	v_rcp_f32_e32 v67, v67
	v_rcp_f32_e32 v66, v66
	s_nop 0
	v_pk_mul_f32 v[64:65], v[64:65], v[66:67]
	v_or_b32_e32 v76, 48, v138
	v_pk_mul_f32 v[70:71], v[70:71], v[64:65]
	v_cvt_pk_bf16_f32 v66, v68, v69
	v_mad_i64_i32 v[68:69], s[2:3], v76, s6, v[112:113]
	v_cvt_pk_bf16_f32 v64, v72, v73
	v_cvt_pk_bf16_f32 v65, v74, v75
	v_cvt_pk_bf16_f32 v67, v70, v71
	v_lshl_add_u64 v[68:69], v[68:69], 0, v[114:115]
	flat_store_dwordx4 v[68:69], v[64:67]
	s_nop 1
	v_ffbh_u32_e32 v64, v147
	v_min_u32_e32 v66, 32, v64
	v_lshlrev_b64 v[64:65], v66, v[146:147]
	v_min_u32_e32 v64, 1, v64
	v_or_b32_e32 v64, v65, v64
	v_cvt_f32_u32_e32 v64, v64
	v_sub_u32_e32 v65, 32, v66
	v_ldexp_f32 v64, v64, v65
	v_fmamk_f32 v64, v64, 0x2e800000, v236
	v_cmp_gt_f32_e32 vcc, s20, v64
	v_mul_f32_e32 v65, 0x4b800000, v64
	s_nop 0
	v_cndmask_b32_e32 v64, v64, v65, vcc
	v_rsq_f32_e32 v64, v64
	s_nop 0
	v_mul_f32_e32 v65, 0x45800000, v64
	v_cndmask_b32_e32 v64, v64, v65, vcc
	v_pk_mul_f32 v[56:57], v[56:57], v[64:65] op_sel_hi:[1,0]
	s_nop 0
	v_mul_f32_e32 v65, 0xbfb8aa3b, v56
	v_exp_f32_e32 v66, v65
	v_pk_mul_f32 v[60:61], v[60:61], v[64:65] op_sel_hi:[1,0]
	v_mul_f32_e32 v65, 0xbfb8aa3b, v57
	v_exp_f32_e32 v67, v65
	s_nop 0
	v_pk_add_f32 v[66:67], v[66:67], 1.0 op_sel_hi:[1,0]
	s_nop 0
	v_rcp_f32_e32 v67, v67
	v_rcp_f32_e32 v66, v66
	s_nop 0
	v_pk_mul_f32 v[56:57], v[56:57], v[66:67]
	v_pk_mul_f32 v[58:59], v[58:59], v[64:65] op_sel_hi:[1,0]
	v_pk_mul_f32 v[56:57], v[60:61], v[56:57]
	v_mul_f32_e32 v60, 0xbfb8aa3b, v58
	v_mul_f32_e32 v61, 0xbfb8aa3b, v59
	v_exp_f32_e32 v60, v60
	v_exp_f32_e32 v61, v61
	v_pk_mul_f32 v[62:63], v[62:63], v[64:65] op_sel_hi:[1,0]
	v_pk_add_f32 v[60:61], v[60:61], 1.0 op_sel_hi:[1,0]
	s_nop 0
	v_rcp_f32_e32 v61, v61
	v_rcp_f32_e32 v60, v60
	v_pk_mul_f32 v[48:49], v[48:49], v[64:65] op_sel_hi:[1,0]
	v_pk_mul_f32 v[58:59], v[58:59], v[60:61]
	v_mul_f32_e32 v60, 0xbfb8aa3b, v48
	v_mul_f32_e32 v61, 0xbfb8aa3b, v49
	v_exp_f32_e32 v60, v60
	v_exp_f32_e32 v61, v61
	v_pk_mul_f32 v[58:59], v[62:63], v[58:59]
	v_pk_mul_f32 v[52:53], v[52:53], v[64:65] op_sel_hi:[1,0]
	v_pk_add_f32 v[60:61], v[60:61], 1.0 op_sel_hi:[1,0]
	s_nop 0
	v_rcp_f32_e32 v61, v61
	v_rcp_f32_e32 v60, v60
	s_nop 0
	v_pk_mul_f32 v[48:49], v[48:49], v[60:61]
	v_pk_mul_f32 v[54:55], v[54:55], v[64:65] op_sel_hi:[1,0]
	v_pk_mul_f32 v[52:53], v[52:53], v[48:49]
	v_pk_mul_f32 v[48:49], v[50:51], v[64:65] op_sel_hi:[1,0]
	s_nop 0
	v_mul_f32_e32 v50, 0xbfb8aa3b, v48
	v_mul_f32_e32 v51, 0xbfb8aa3b, v49
	v_exp_f32_e32 v50, v50
	v_exp_f32_e32 v51, v51
	s_nop 0
	v_pk_add_f32 v[50:51], v[50:51], 1.0 op_sel_hi:[1,0]
	s_nop 0
	v_rcp_f32_e32 v51, v51
	v_rcp_f32_e32 v50, v50
	s_nop 0
	v_pk_mul_f32 v[48:49], v[48:49], v[50:51]
	v_cvt_pk_bf16_f32 v50, v52, v53
	v_pk_mul_f32 v[54:55], v[54:55], v[48:49]
	v_mad_i64_i32 v[52:53], s[2:3], v139, s6, v[112:113]
	v_cvt_pk_bf16_f32 v48, v56, v57
	v_cvt_pk_bf16_f32 v49, v58, v59
	v_cvt_pk_bf16_f32 v51, v54, v55
	v_lshl_add_u64 v[52:53], v[52:53], 0, v[114:115]
	flat_store_dwordx4 v[52:53], v[48:51]
	s_nop 1
	v_ffbh_u32_e32 v48, v145
	v_min_u32_e32 v50, 32, v48
	v_lshlrev_b64 v[48:49], v50, v[144:145]
	v_min_u32_e32 v48, 1, v48
	v_or_b32_e32 v48, v49, v48
	v_cvt_f32_u32_e32 v48, v48
	v_sub_u32_e32 v49, 32, v50
	v_ldexp_f32 v48, v48, v49
	v_fmamk_f32 v48, v48, 0x2e800000, v236
	v_cmp_gt_f32_e32 vcc, s20, v48
	v_mul_f32_e32 v49, 0x4b800000, v48
	s_nop 0
	v_cndmask_b32_e32 v48, v48, v49, vcc
	v_rsq_f32_e32 v48, v48
	s_nop 0
	v_mul_f32_e32 v49, 0x45800000, v48
	v_cndmask_b32_e32 v48, v48, v49, vcc
	v_pk_mul_f32 v[40:41], v[40:41], v[48:49] op_sel_hi:[1,0]
	s_nop 0
	v_mul_f32_e32 v49, 0xbfb8aa3b, v40
	v_exp_f32_e32 v50, v49
	v_pk_mul_f32 v[44:45], v[44:45], v[48:49] op_sel_hi:[1,0]
	v_mul_f32_e32 v49, 0xbfb8aa3b, v41
	v_exp_f32_e32 v51, v49
	s_nop 0
	v_pk_add_f32 v[50:51], v[50:51], 1.0 op_sel_hi:[1,0]
	s_nop 0
	v_rcp_f32_e32 v51, v51
	v_rcp_f32_e32 v50, v50
	s_nop 0
	v_pk_mul_f32 v[40:41], v[40:41], v[50:51]
	v_pk_mul_f32 v[42:43], v[42:43], v[48:49] op_sel_hi:[1,0]
	v_pk_mul_f32 v[40:41], v[44:45], v[40:41]
	v_mul_f32_e32 v44, 0xbfb8aa3b, v42
	v_mul_f32_e32 v45, 0xbfb8aa3b, v43
	v_exp_f32_e32 v44, v44
	v_exp_f32_e32 v45, v45
	v_pk_mul_f32 v[46:47], v[46:47], v[48:49] op_sel_hi:[1,0]
	v_pk_add_f32 v[44:45], v[44:45], 1.0 op_sel_hi:[1,0]
	s_nop 0
	v_rcp_f32_e32 v45, v45
	v_rcp_f32_e32 v44, v44
	v_pk_mul_f32 v[32:33], v[32:33], v[48:49] op_sel_hi:[1,0]
	v_pk_mul_f32 v[42:43], v[42:43], v[44:45]
	v_mul_f32_e32 v44, 0xbfb8aa3b, v32
	v_mul_f32_e32 v45, 0xbfb8aa3b, v33
	v_exp_f32_e32 v44, v44
	v_exp_f32_e32 v45, v45
	v_pk_mul_f32 v[42:43], v[46:47], v[42:43]
	v_pk_mul_f32 v[36:37], v[36:37], v[48:49] op_sel_hi:[1,0]
	v_pk_add_f32 v[44:45], v[44:45], 1.0 op_sel_hi:[1,0]
	s_nop 0
	v_rcp_f32_e32 v45, v45
	v_rcp_f32_e32 v44, v44
	s_nop 0
	v_pk_mul_f32 v[32:33], v[32:33], v[44:45]
	v_pk_mul_f32 v[38:39], v[38:39], v[48:49] op_sel_hi:[1,0]
	v_pk_mul_f32 v[36:37], v[36:37], v[32:33]
	v_pk_mul_f32 v[32:33], v[34:35], v[48:49] op_sel_hi:[1,0]
	s_nop 0
	v_mul_f32_e32 v34, 0xbfb8aa3b, v32
	v_mul_f32_e32 v35, 0xbfb8aa3b, v33
	v_exp_f32_e32 v34, v34
	v_exp_f32_e32 v35, v35
	s_nop 0
	v_pk_add_f32 v[34:35], v[34:35], 1.0 op_sel_hi:[1,0]
	s_nop 0
	v_rcp_f32_e32 v35, v35
	v_rcp_f32_e32 v34, v34
	s_nop 0
	v_pk_mul_f32 v[32:33], v[32:33], v[34:35]
	v_add_u32_e32 v44, 0x90, v138
	v_pk_mul_f32 v[38:39], v[38:39], v[32:33]
	v_cvt_pk_bf16_f32 v34, v36, v37
	v_mad_i64_i32 v[36:37], s[2:3], v44, s6, v[112:113]
	v_cvt_pk_bf16_f32 v32, v40, v41
	v_cvt_pk_bf16_f32 v33, v42, v43
	v_cvt_pk_bf16_f32 v35, v38, v39
	v_lshl_add_u64 v[36:37], v[36:37], 0, v[114:115]
	flat_store_dwordx4 v[36:37], v[32:35]
	s_nop 1
	v_ffbh_u32_e32 v32, v143
	v_min_u32_e32 v34, 32, v32
	v_lshlrev_b64 v[32:33], v34, v[142:143]
	v_min_u32_e32 v32, 1, v32
	v_or_b32_e32 v32, v33, v32
	v_cvt_f32_u32_e32 v32, v32
	v_sub_u32_e32 v33, 32, v34
	v_ldexp_f32 v32, v32, v33
	v_fmamk_f32 v32, v32, 0x2e800000, v236
	v_cmp_gt_f32_e32 vcc, s20, v32
	v_mul_f32_e32 v33, 0x4b800000, v32
	s_nop 0
	v_cndmask_b32_e32 v32, v32, v33, vcc
	v_rsq_f32_e32 v32, v32
	s_nop 0
	v_mul_f32_e32 v33, 0x45800000, v32
	v_cndmask_b32_e32 v32, v32, v33, vcc
	v_pk_mul_f32 v[24:25], v[24:25], v[32:33] op_sel_hi:[1,0]
	s_nop 0
	v_mul_f32_e32 v33, 0xbfb8aa3b, v24
	v_exp_f32_e32 v34, v33
	v_pk_mul_f32 v[28:29], v[28:29], v[32:33] op_sel_hi:[1,0]
	v_mul_f32_e32 v33, 0xbfb8aa3b, v25
	v_exp_f32_e32 v35, v33
	s_nop 0
	v_pk_add_f32 v[34:35], v[34:35], 1.0 op_sel_hi:[1,0]
	s_nop 0
	v_rcp_f32_e32 v35, v35
	v_rcp_f32_e32 v34, v34
	s_nop 0
	v_pk_mul_f32 v[24:25], v[24:25], v[34:35]
	v_pk_mul_f32 v[26:27], v[26:27], v[32:33] op_sel_hi:[1,0]
	v_pk_mul_f32 v[24:25], v[28:29], v[24:25]
	v_mul_f32_e32 v28, 0xbfb8aa3b, v26
	v_mul_f32_e32 v29, 0xbfb8aa3b, v27
	v_exp_f32_e32 v28, v28
	v_exp_f32_e32 v29, v29
	v_pk_mul_f32 v[30:31], v[30:31], v[32:33] op_sel_hi:[1,0]
	v_pk_add_f32 v[28:29], v[28:29], 1.0 op_sel_hi:[1,0]
	s_nop 0
	v_rcp_f32_e32 v29, v29
	v_rcp_f32_e32 v28, v28
	v_pk_mul_f32 v[16:17], v[16:17], v[32:33] op_sel_hi:[1,0]
	v_pk_mul_f32 v[26:27], v[26:27], v[28:29]
	v_mul_f32_e32 v28, 0xbfb8aa3b, v16
	v_mul_f32_e32 v29, 0xbfb8aa3b, v17
	v_exp_f32_e32 v28, v28
	v_exp_f32_e32 v29, v29
	v_pk_mul_f32 v[26:27], v[30:31], v[26:27]
	v_pk_mul_f32 v[20:21], v[20:21], v[32:33] op_sel_hi:[1,0]
	v_pk_add_f32 v[28:29], v[28:29], 1.0 op_sel_hi:[1,0]
	s_nop 0
	v_rcp_f32_e32 v29, v29
	v_rcp_f32_e32 v28, v28
	s_nop 0
	v_pk_mul_f32 v[16:17], v[16:17], v[28:29]
	v_pk_mul_f32 v[22:23], v[22:23], v[32:33] op_sel_hi:[1,0]
	v_pk_mul_f32 v[20:21], v[20:21], v[16:17]
	v_pk_mul_f32 v[16:17], v[18:19], v[32:33] op_sel_hi:[1,0]
	s_nop 0
	v_mul_f32_e32 v18, 0xbfb8aa3b, v16
	v_mul_f32_e32 v19, 0xbfb8aa3b, v17
	v_exp_f32_e32 v18, v18
	v_exp_f32_e32 v19, v19
	s_nop 0
	v_pk_add_f32 v[18:19], v[18:19], 1.0 op_sel_hi:[1,0]
	s_nop 0
	v_rcp_f32_e32 v19, v19
	v_rcp_f32_e32 v18, v18
	s_nop 0
	v_pk_mul_f32 v[16:17], v[16:17], v[18:19]
	v_add_u32_e32 v28, 0xa0, v138
	v_pk_mul_f32 v[22:23], v[22:23], v[16:17]
	v_cvt_pk_bf16_f32 v18, v20, v21
	v_mad_i64_i32 v[20:21], s[2:3], v28, s6, v[112:113]
	v_cvt_pk_bf16_f32 v16, v24, v25
	v_cvt_pk_bf16_f32 v17, v26, v27
	v_cvt_pk_bf16_f32 v19, v22, v23
	v_lshl_add_u64 v[20:21], v[20:21], 0, v[114:115]
	flat_store_dwordx4 v[20:21], v[16:19]
	s_nop 1
	v_ffbh_u32_e32 v16, v141
	v_min_u32_e32 v18, 32, v16
	v_lshlrev_b64 v[16:17], v18, v[140:141]
	v_min_u32_e32 v16, 1, v16
	v_or_b32_e32 v16, v17, v16
	v_cvt_f32_u32_e32 v16, v16
	v_sub_u32_e32 v17, 32, v18
	v_ldexp_f32 v16, v16, v17
	v_fmamk_f32 v16, v16, 0x2e800000, v236
	v_cmp_gt_f32_e32 vcc, s20, v16
	v_mul_f32_e32 v17, 0x4b800000, v16
	s_nop 0
	v_cndmask_b32_e32 v16, v16, v17, vcc
	v_rsq_f32_e32 v16, v16
	s_nop 0
	v_mul_f32_e32 v17, 0x45800000, v16
	v_cndmask_b32_e32 v16, v16, v17, vcc
	v_pk_mul_f32 v[8:9], v[8:9], v[16:17] op_sel_hi:[1,0]
	s_nop 0
	v_mul_f32_e32 v17, 0xbfb8aa3b, v8
	v_exp_f32_e32 v18, v17
	v_pk_mul_f32 v[12:13], v[12:13], v[16:17] op_sel_hi:[1,0]
	v_mul_f32_e32 v17, 0xbfb8aa3b, v9
	v_exp_f32_e32 v19, v17
	s_nop 0
	v_pk_add_f32 v[18:19], v[18:19], 1.0 op_sel_hi:[1,0]
	s_nop 0
	v_rcp_f32_e32 v19, v19
	v_rcp_f32_e32 v18, v18
	s_nop 0
	v_pk_mul_f32 v[8:9], v[8:9], v[18:19]
	v_pk_mul_f32 v[10:11], v[10:11], v[16:17] op_sel_hi:[1,0]
	v_pk_mul_f32 v[8:9], v[12:13], v[8:9]
	v_mul_f32_e32 v12, 0xbfb8aa3b, v10
	v_mul_f32_e32 v13, 0xbfb8aa3b, v11
	v_exp_f32_e32 v12, v12
	v_exp_f32_e32 v13, v13
	v_pk_mul_f32 v[14:15], v[14:15], v[16:17] op_sel_hi:[1,0]
	v_pk_add_f32 v[12:13], v[12:13], 1.0 op_sel_hi:[1,0]
	s_nop 0
	v_rcp_f32_e32 v13, v13
	v_rcp_f32_e32 v12, v12
	v_pk_mul_f32 v[0:1], v[0:1], v[16:17] op_sel_hi:[1,0]
	v_pk_mul_f32 v[10:11], v[10:11], v[12:13]
	v_mul_f32_e32 v12, 0xbfb8aa3b, v0
	v_mul_f32_e32 v13, 0xbfb8aa3b, v1
	v_exp_f32_e32 v12, v12
	v_exp_f32_e32 v13, v13
	v_pk_mul_f32 v[10:11], v[14:15], v[10:11]
	v_pk_mul_f32 v[4:5], v[4:5], v[16:17] op_sel_hi:[1,0]
	v_pk_add_f32 v[12:13], v[12:13], 1.0 op_sel_hi:[1,0]
	s_nop 0
	v_rcp_f32_e32 v13, v13
	v_rcp_f32_e32 v12, v12
	s_nop 0
	v_pk_mul_f32 v[0:1], v[0:1], v[12:13]
	v_pk_mul_f32 v[6:7], v[6:7], v[16:17] op_sel_hi:[1,0]
	v_pk_mul_f32 v[4:5], v[4:5], v[0:1]
	v_pk_mul_f32 v[0:1], v[2:3], v[16:17] op_sel_hi:[1,0]
	s_nop 0
	v_mul_f32_e32 v2, 0xbfb8aa3b, v0
	v_mul_f32_e32 v3, 0xbfb8aa3b, v1
	v_exp_f32_e32 v2, v2
	v_exp_f32_e32 v3, v3
	s_nop 0
	v_pk_add_f32 v[2:3], v[2:3], 1.0 op_sel_hi:[1,0]
	s_nop 0
	v_rcp_f32_e32 v3, v3
	v_rcp_f32_e32 v2, v2
	s_nop 0
	v_pk_mul_f32 v[0:1], v[0:1], v[2:3]
	v_add_u32_e32 v12, 0xb0, v138
	v_pk_mul_f32 v[6:7], v[6:7], v[0:1]
	v_cvt_pk_bf16_f32 v2, v4, v5
	v_mad_i64_i32 v[4:5], s[2:3], v12, s6, v[112:113]
	v_cvt_pk_bf16_f32 v0, v8, v9
	v_cvt_pk_bf16_f32 v1, v10, v11
	v_cvt_pk_bf16_f32 v3, v6, v7
	v_lshl_add_u64 v[4:5], v[4:5], 0, v[114:115]
	s_mov_b64 s[2:3], -1
	s_andn2_b64 vcc, exec, s[8:9]
	flat_store_dwordx4 v[4:5], v[0:3]
	s_cbranch_vccnz .LBB0_858
	v_mov_b32_e32 v120, v192
	v_mov_b32_e32 v112, v192
	v_mov_b32_e32 v104, v192
	v_mov_b32_e32 v96, v192
	v_mov_b32_e32 v88, v192
	v_mov_b32_e32 v80, v192
	v_mov_b32_e32 v72, v192
	v_mov_b32_e32 v64, v192
	v_mov_b32_e32 v124, v192
	v_mov_b32_e32 v116, v192
	v_mov_b32_e32 v108, v192
	v_mov_b32_e32 v100, v192
	v_mov_b32_e32 v92, v192
	v_mov_b32_e32 v84, v192
	v_mov_b32_e32 v76, v192
	v_mov_b32_e32 v68, v192
	v_mov_b32_e32 v56, v192
	v_mov_b32_e32 v48, v192
	v_mov_b32_e32 v40, v192
	v_mov_b32_e32 v32, v192
	v_mov_b32_e32 v24, v192
	v_mov_b32_e32 v16, v192
	v_mov_b32_e32 v8, v192
	v_mov_b32_e32 v0, v192
	v_mov_b32_e32 v60, v192
	v_mov_b32_e32 v52, v192
	v_mov_b32_e32 v44, v192
	v_mov_b32_e32 v36, v192
	v_mov_b32_e32 v28, v192
	v_mov_b32_e32 v20, v192
	v_mov_b32_e32 v12, v192
	v_mov_b32_e32 v4, v195
	s_nop 0
	v_mov_b32_e32 v121, v120
	v_mov_b32_e32 v122, v120
	v_mov_b32_e32 v123, v120
	v_mov_b32_e32 v113, v112
	v_mov_b32_e32 v114, v112
	v_mov_b32_e32 v115, v112
	v_mov_b32_e32 v105, v104
	v_mov_b32_e32 v106, v104
	v_mov_b32_e32 v107, v104
	v_mov_b32_e32 v97, v96
	v_mov_b32_e32 v98, v96
	v_mov_b32_e32 v99, v96
	v_mov_b32_e32 v89, v88
	v_mov_b32_e32 v90, v88
	v_mov_b32_e32 v91, v88
	v_mov_b32_e32 v81, v80
	v_mov_b32_e32 v82, v80
	v_mov_b32_e32 v83, v80
	s_nop 0
	v_mov_b32_e32 v73, v72
	v_mov_b32_e32 v74, v72
	v_mov_b32_e32 v75, v72
	v_mov_b32_e32 v65, v64
	v_mov_b32_e32 v66, v64
	v_mov_b32_e32 v67, v64
	v_mov_b32_e32 v125, v124
	v_mov_b32_e32 v126, v124
	v_mov_b32_e32 v127, v124
	v_mov_b32_e32 v117, v116
	v_mov_b32_e32 v118, v116
	v_mov_b32_e32 v119, v116
	v_mov_b32_e32 v109, v108
	v_mov_b32_e32 v110, v108
	v_mov_b32_e32 v111, v108
	v_mov_b32_e32 v101, v100
	v_mov_b32_e32 v102, v100
	v_mov_b32_e32 v103, v100
	s_nop 0
	v_mov_b32_e32 v93, v92
	v_mov_b32_e32 v94, v92
	v_mov_b32_e32 v95, v92
	v_mov_b32_e32 v85, v84
	v_mov_b32_e32 v86, v84
	v_mov_b32_e32 v87, v84
	v_mov_b32_e32 v77, v76
	v_mov_b32_e32 v78, v76
	v_mov_b32_e32 v79, v76
	v_mov_b32_e32 v69, v68
	v_mov_b32_e32 v70, v68
	v_mov_b32_e32 v71, v68
	v_mov_b32_e32 v57, v56
	v_mov_b32_e32 v58, v56
	v_mov_b32_e32 v59, v56
	v_mov_b32_e32 v49, v48
	v_mov_b32_e32 v50, v48
	v_mov_b32_e32 v51, v48
	s_nop 0
	v_mov_b32_e32 v41, v40
	v_mov_b32_e32 v42, v40
	v_mov_b32_e32 v43, v40
	v_mov_b32_e32 v33, v32
	v_mov_b32_e32 v34, v32
	v_mov_b32_e32 v35, v32
	v_mov_b32_e32 v25, v24
	v_mov_b32_e32 v26, v24
	v_mov_b32_e32 v27, v24
	v_mov_b32_e32 v17, v16
	v_mov_b32_e32 v18, v16
	v_mov_b32_e32 v19, v16
	v_mov_b32_e32 v9, v8
	v_mov_b32_e32 v10, v8
	v_mov_b32_e32 v11, v8
	v_mov_b32_e32 v1, v0
	v_mov_b32_e32 v2, v0
	v_mov_b32_e32 v3, v0
	s_nop 0
	v_mov_b32_e32 v61, v60
	v_mov_b32_e32 v62, v60
	v_mov_b32_e32 v63, v60
	v_mov_b32_e32 v53, v52
	v_mov_b32_e32 v54, v52
	v_mov_b32_e32 v55, v52
	v_mov_b32_e32 v45, v44
	v_mov_b32_e32 v46, v44
	v_mov_b32_e32 v47, v44
	v_mov_b32_e32 v37, v36
	v_mov_b32_e32 v38, v36
	v_mov_b32_e32 v39, v36
	v_mov_b32_e32 v29, v28
	v_mov_b32_e32 v30, v28
	v_mov_b32_e32 v31, v28
	v_mov_b32_e32 v21, v20
	v_mov_b32_e32 v22, v20
	v_mov_b32_e32 v23, v20
	s_mov_b64 s[2:3], 0
	v_mov_b32_e32 v13, v12
	v_mov_b32_e32 v14, v12
	v_mov_b32_e32 v15, v12
	v_mov_b32_e32 v5, v4
	v_mov_b32_e32 v6, v4
	v_mov_b32_e32 v7, v4
	s_branch .LBB0_858

.LBB0_871:
	s_ashr_i32 s1, s3, 3
	s_and_b32 s0, s6, 0x70
	v_or_b32_e32 v6, s0, v12
	s_lshl_b32 s0, s1, 4
	s_lshl_b32 s1, s1, 5
	s_and_b32 s7, s1, 0xffffff00
	s_and_b32 s8, s0, 0x70
	s_or_b32 s7, s8, s7
	v_lshlrev_b32_e32 v194, 11, v6
	v_or_b32_e32 v13, 0x4000, v6
	v_or_b32_e32 v6, s7, v12
	v_ashrrev_i32_e32 v7, 31, v6
	v_or_b32_e32 v22, 0x80, v6
	v_lshlrev_b64 v[6:7], 11, v[6:7]
	v_lshl_add_u64 v[78:79], v[0:1], 0, v[194:195]
	v_ashrrev_i32_e32 v23, 31, v22
	v_lshl_add_u64 v[8:9], v[2:3], 0, v[6:7]
	flat_load_dwordx4 v[14:17], v[78:79]
	flat_load_dwordx4 v[18:21], v[78:79] offset:64
	v_lshlrev_b64 v[6:7], 11, v[22:23]
	flat_load_dwordx4 v[22:25], v[8:9]
	v_lshl_add_u64 v[6:7], v[2:3], 0, v[6:7]
	flat_load_dwordx4 v[26:29], v[8:9] offset:64
	flat_load_dwordx4 v[30:33], v[6:7]
	flat_load_dwordx4 v[34:37], v[6:7] offset:64
	v_lshlrev_b32_e32 v194, 3, v13
	v_mul_u32_u24_e32 v13, 0xb00, v13
	s_ashr_i32 s1, s0, 31
	v_mov_b32_e32 v5, v195
	s_add_i32 s3, s3, s80
	s_add_i32 s6, s6, s64
	s_cmpk_gt_i32 s3, 0x57f
	s_waitcnt vmcnt(0) lgkmcnt(0)
	v_mfma_f32_16x16x32_bf16 v[22:25], v[22:25], v[14:17], 0
	v_mfma_f32_16x16x32_bf16 v[14:17], v[30:33], v[14:17], 0
	flat_load_dwordx4 v[30:33], v[78:79] offset:128
	flat_load_dwordx4 v[38:41], v[78:79] offset:192
	v_mfma_f32_16x16x32_bf16 v[22:25], v[26:29], v[18:21], v[22:25]
	flat_load_dwordx4 v[26:29], v[8:9] offset:128
	flat_load_dwordx4 v[42:45], v[8:9] offset:192
	v_mfma_f32_16x16x32_bf16 v[14:17], v[34:37], v[18:21], v[14:17]
	flat_load_dwordx4 v[18:21], v[6:7] offset:128
	s_waitcnt vmcnt(0) lgkmcnt(0)
	v_mfma_f32_16x16x32_bf16 v[22:25], v[26:29], v[30:33], v[22:25]
	flat_load_dwordx4 v[26:29], v[6:7] offset:192
	v_mfma_f32_16x16x32_bf16 v[14:17], v[18:21], v[30:33], v[14:17]
	flat_load_dwordx4 v[18:21], v[78:79] offset:256
	flat_load_dwordx4 v[30:33], v[78:79] offset:320
	v_mfma_f32_16x16x32_bf16 v[22:25], v[42:45], v[38:41], v[22:25]
	flat_load_dwordx4 v[34:37], v[8:9] offset:256
	flat_load_dwordx4 v[42:45], v[8:9] offset:320
	s_waitcnt vmcnt(0) lgkmcnt(0)
	v_mfma_f32_16x16x32_bf16 v[14:17], v[26:29], v[38:41], v[14:17]
	flat_load_dwordx4 v[26:29], v[6:7] offset:256
	v_mfma_f32_16x16x32_bf16 v[22:25], v[34:37], v[18:21], v[22:25]
	flat_load_dwordx4 v[34:37], v[6:7] offset:320
	v_mfma_f32_16x16x32_bf16 v[22:25], v[42:45], v[30:33], v[22:25]
	s_waitcnt vmcnt(0) lgkmcnt(0)
	v_mfma_f32_16x16x32_bf16 v[14:17], v[26:29], v[18:21], v[14:17]
	flat_load_dwordx4 v[18:21], v[78:79] offset:384
	flat_load_dwordx4 v[26:29], v[78:79] offset:448
	flat_load_dwordx4 v[38:41], v[78:79] offset:512
	flat_load_dwordx4 v[42:45], v[8:9] offset:384
	flat_load_dwordx4 v[46:49], v[8:9] offset:448
	v_mfma_f32_16x16x32_bf16 v[14:17], v[34:37], v[30:33], v[14:17]
	flat_load_dwordx4 v[30:33], v[6:7] offset:384
	flat_load_dwordx4 v[34:37], v[6:7] offset:448
	s_waitcnt vmcnt(0) lgkmcnt(0)
	v_mfma_f32_16x16x32_bf16 v[22:25], v[42:45], v[18:21], v[22:25]
	v_mfma_f32_16x16x32_bf16 v[14:17], v[30:33], v[18:21], v[14:17]
	flat_load_dwordx4 v[18:21], v[78:79] offset:576
	flat_load_dwordx4 v[30:33], v[78:79] offset:640
	flat_load_dwordx4 v[42:45], v[78:79] offset:704
	v_mfma_f32_16x16x32_bf16 v[22:25], v[46:49], v[26:29], v[22:25]
	flat_load_dwordx4 v[46:49], v[8:9] offset:512
	flat_load_dwordx4 v[50:53], v[8:9] offset:576
	v_mfma_f32_16x16x32_bf16 v[14:17], v[34:37], v[26:29], v[14:17]
	flat_load_dwordx4 v[26:29], v[6:7] offset:512
	flat_load_dwordx4 v[34:37], v[6:7] offset:576
	s_waitcnt vmcnt(0) lgkmcnt(0)
	v_mfma_f32_16x16x32_bf16 v[22:25], v[46:49], v[38:41], v[22:25]
	v_mfma_f32_16x16x32_bf16 v[14:17], v[26:29], v[38:41], v[14:17]
	flat_load_dwordx4 v[26:29], v[78:79] offset:768
	flat_load_dwordx4 v[38:41], v[78:79] offset:832
	flat_load_dwordx4 v[46:49], v[78:79] offset:896
	v_mfma_f32_16x16x32_bf16 v[22:25], v[50:53], v[18:21], v[22:25]
	flat_load_dwordx4 v[50:53], v[8:9] offset:640
	flat_load_dwordx4 v[54:57], v[8:9] offset:704
	v_mfma_f32_16x16x32_bf16 v[14:17], v[34:37], v[18:21], v[14:17]
	flat_load_dwordx4 v[18:21], v[6:7] offset:640
	flat_load_dwordx4 v[34:37], v[6:7] offset:704
	s_waitcnt vmcnt(0) lgkmcnt(0)
	v_mfma_f32_16x16x32_bf16 v[22:25], v[50:53], v[30:33], v[22:25]
	v_mfma_f32_16x16x32_bf16 v[14:17], v[18:21], v[30:33], v[14:17]
	flat_load_dwordx4 v[18:21], v[78:79] offset:960
	flat_load_dwordx4 v[30:33], v[78:79] offset:1024
	flat_load_dwordx4 v[50:53], v[78:79] offset:1088
	v_mfma_f32_16x16x32_bf16 v[22:25], v[54:57], v[42:45], v[22:25]
	flat_load_dwordx4 v[54:57], v[8:9] offset:768
	flat_load_dwordx4 v[58:61], v[8:9] offset:832
	v_mfma_f32_16x16x32_bf16 v[14:17], v[34:37], v[42:45], v[14:17]
	flat_load_dwordx4 v[34:37], v[6:7] offset:768
	flat_load_dwordx4 v[42:45], v[6:7] offset:832
	s_waitcnt vmcnt(0) lgkmcnt(0)
	v_mfma_f32_16x16x32_bf16 v[22:25], v[54:57], v[26:29], v[22:25]
	v_mfma_f32_16x16x32_bf16 v[14:17], v[34:37], v[26:29], v[14:17]
	flat_load_dwordx4 v[26:29], v[78:79] offset:1152
	flat_load_dwordx4 v[34:37], v[78:79] offset:1216
	flat_load_dwordx4 v[54:57], v[78:79] offset:1280
	v_mfma_f32_16x16x32_bf16 v[22:25], v[58:61], v[38:41], v[22:25]
	flat_load_dwordx4 v[58:61], v[8:9] offset:896
	flat_load_dwordx4 v[62:65], v[8:9] offset:960
	v_mfma_f32_16x16x32_bf16 v[14:17], v[42:45], v[38:41], v[14:17]
	flat_load_dwordx4 v[38:41], v[6:7] offset:896
	flat_load_dwordx4 v[42:45], v[6:7] offset:960
	s_waitcnt vmcnt(0) lgkmcnt(0)
	v_mfma_f32_16x16x32_bf16 v[22:25], v[58:61], v[46:49], v[22:25]
	v_mfma_f32_16x16x32_bf16 v[14:17], v[38:41], v[46:49], v[14:17]
	flat_load_dwordx4 v[38:41], v[78:79] offset:1344
	flat_load_dwordx4 v[46:49], v[78:79] offset:1408
	flat_load_dwordx4 v[58:61], v[78:79] offset:1472
	v_mfma_f32_16x16x32_bf16 v[22:25], v[62:65], v[18:21], v[22:25]
	flat_load_dwordx4 v[62:65], v[8:9] offset:1024
	flat_load_dwordx4 v[66:69], v[8:9] offset:1088
	v_mfma_f32_16x16x32_bf16 v[14:17], v[42:45], v[18:21], v[14:17]
	flat_load_dwordx4 v[18:21], v[6:7] offset:1024
	flat_load_dwordx4 v[42:45], v[6:7] offset:1088
	s_waitcnt vmcnt(0) lgkmcnt(0)
	v_mfma_f32_16x16x32_bf16 v[22:25], v[62:65], v[30:33], v[22:25]
	v_mfma_f32_16x16x32_bf16 v[14:17], v[18:21], v[30:33], v[14:17]
	flat_load_dwordx4 v[18:21], v[78:79] offset:1536
	flat_load_dwordx4 v[30:33], v[78:79] offset:1600
	flat_load_dwordx4 v[62:65], v[78:79] offset:1664
	v_mfma_f32_16x16x32_bf16 v[22:25], v[66:69], v[50:53], v[22:25]
	flat_load_dwordx4 v[66:69], v[8:9] offset:1152
	flat_load_dwordx4 v[70:73], v[8:9] offset:1216
	v_mfma_f32_16x16x32_bf16 v[14:17], v[42:45], v[50:53], v[14:17]
	flat_load_dwordx4 v[42:45], v[6:7] offset:1152
	flat_load_dwordx4 v[50:53], v[6:7] offset:1216
	s_waitcnt vmcnt(0) lgkmcnt(0)
	v_mfma_f32_16x16x32_bf16 v[22:25], v[66:69], v[26:29], v[22:25]
	v_mfma_f32_16x16x32_bf16 v[14:17], v[42:45], v[26:29], v[14:17]
	flat_load_dwordx4 v[26:29], v[78:79] offset:1728
	flat_load_dwordx4 v[42:45], v[78:79] offset:1792
	flat_load_dwordx4 v[66:69], v[78:79] offset:1856
	v_mfma_f32_16x16x32_bf16 v[22:25], v[70:73], v[34:37], v[22:25]
	flat_load_dwordx4 v[70:73], v[8:9] offset:1280
	flat_load_dwordx4 v[74:77], v[8:9] offset:1344
	v_mfma_f32_16x16x32_bf16 v[14:17], v[50:53], v[34:37], v[14:17]
	flat_load_dwordx4 v[34:37], v[6:7] offset:1280
	flat_load_dwordx4 v[50:53], v[6:7] offset:1344
	s_waitcnt vmcnt(0) lgkmcnt(0)
	v_mfma_f32_16x16x32_bf16 v[22:25], v[70:73], v[54:57], v[22:25]
	v_mfma_f32_16x16x32_bf16 v[14:17], v[34:37], v[54:57], v[14:17]
	flat_load_dwordx4 v[34:37], v[78:79] offset:1920
	flat_load_dwordx4 v[54:57], v[78:79] offset:1984
	v_lshl_add_u64 v[78:79], s[14:15], 0, v[194:195]
	v_lshlrev_b32_e32 v194, 1, v13
	v_mfma_f32_16x16x32_bf16 v[22:25], v[74:77], v[38:41], v[22:25]
	flat_load_dwordx4 v[70:73], v[8:9] offset:1408
	flat_load_dwordx4 v[74:77], v[8:9] offset:1472
	v_mfma_f32_16x16x32_bf16 v[14:17], v[50:53], v[38:41], v[14:17]
	flat_load_dwordx4 v[38:41], v[6:7] offset:1408
	flat_load_dwordx4 v[50:53], v[6:7] offset:1472
	s_waitcnt vmcnt(0) lgkmcnt(0)
	v_mfma_f32_16x16x32_bf16 v[22:25], v[70:73], v[46:49], v[22:25]
	flat_load_dwordx2 v[70:71], v[78:79]
	v_mfma_f32_16x16x32_bf16 v[14:17], v[38:41], v[46:49], v[14:17]
	flat_load_dwordx4 v[38:41], v[8:9] offset:1536
	flat_load_dwordx4 v[46:49], v[8:9] offset:1600
	v_mfma_f32_16x16x32_bf16 v[14:17], v[50:53], v[58:61], v[14:17]
	flat_load_dwordx4 v[50:53], v[6:7] offset:1536
	v_mfma_f32_16x16x32_bf16 v[22:25], v[74:77], v[58:61], v[22:25]
	s_waitcnt vmcnt(0) lgkmcnt(0)
	v_mfma_f32_16x16x32_bf16 v[22:25], v[38:41], v[18:21], v[22:25]
	flat_load_dwordx4 v[38:41], v[6:7] offset:1600
	v_mfma_f32_16x16x32_bf16 v[14:17], v[50:53], v[18:21], v[14:17]
	v_lshl_add_u64 v[18:19], s[12:13], 0, v[194:195]
	v_lshl_add_u64 v[18:19], s[0:1], 1, v[18:19]
	v_lshl_add_u64 v[72:73], v[18:19], 0, v[4:5]
	v_mfma_f32_16x16x32_bf16 v[18:21], v[46:49], v[30:33], v[22:25]
	s_nop 2
	flat_load_dwordx4 v[22:25], v[8:9] offset:1664
	flat_load_dwordx4 v[46:49], v[8:9] offset:1728
	flat_load_dwordx4 v[50:53], v[8:9] offset:1792
	v_ffbh_u32_e32 v5, v71
	v_min_u32_e32 v5, 32, v5
	s_waitcnt vmcnt(0) lgkmcnt(0)
	v_mfma_f32_16x16x32_bf16 v[14:17], v[38:41], v[30:33], v[14:17]
	flat_load_dwordx4 v[30:33], v[6:7] offset:1664
	v_mfma_f32_16x16x32_bf16 v[18:21], v[22:25], v[62:65], v[18:21]
	flat_load_dwordx4 v[22:25], v[6:7] offset:1728
	v_mfma_f32_16x16x32_bf16 v[18:21], v[46:49], v[26:29], v[18:21]
	v_mfma_f32_16x16x32_bf16 v[18:21], v[50:53], v[42:45], v[18:21]
	s_waitcnt vmcnt(0) lgkmcnt(0)
	v_mfma_f32_16x16x32_bf16 v[14:17], v[30:33], v[62:65], v[14:17]
	flat_load_dwordx4 v[30:33], v[8:9] offset:1856
	flat_load_dwordx4 v[38:41], v[8:9] offset:1920
	flat_load_dwordx4 v[58:61], v[8:9] offset:1984
	flat_load_dwordx4 v[46:49], v[6:7] offset:1792
	v_mfma_f32_16x16x32_bf16 v[14:17], v[22:25], v[26:29], v[14:17]
	flat_load_dwordx4 v[22:25], v[6:7] offset:1856
	flat_load_dwordx4 v[26:29], v[6:7] offset:1920
	s_nop 0
	flat_load_dwordx4 v[6:9], v[6:7] offset:1984
	s_waitcnt vmcnt(0) lgkmcnt(0)
	v_mfma_f32_16x16x32_bf16 v[18:21], v[30:33], v[66:69], v[18:21]
	v_lshlrev_b64 v[30:31], v5, v[70:71]
	v_min_u32_e32 v13, 1, v30
	v_or_b32_e32 v13, v31, v13
	v_cvt_f32_u32_e32 v13, v13
	v_mfma_f32_16x16x32_bf16 v[14:17], v[46:49], v[42:45], v[14:17]
	v_sub_u32_e32 v5, 32, v5
	v_ldexp_f32 v5, v13, v5
	v_fmamk_f32 v5, v5, 0x2e800000, v236
	v_mfma_f32_16x16x32_bf16 v[14:17], v[22:25], v[66:69], v[14:17]
	v_mul_f32_e32 v13, 0x4b800000, v5
	v_cmp_gt_f32_e32 vcc, s20, v5
	v_mfma_f32_16x16x32_bf16 v[18:21], v[38:41], v[34:37], v[18:21]
	s_nop 0
	v_cndmask_b32_e32 v5, v5, v13, vcc
	v_rsq_f32_e32 v5, v5
	v_mfma_f32_16x16x32_bf16 v[14:17], v[26:29], v[34:37], v[14:17]
	v_mul_f32_e32 v13, 0x45800000, v5
	v_cndmask_b32_e32 v22, v5, v13, vcc
	v_mfma_f32_16x16x32_bf16 v[18:21], v[58:61], v[54:57], v[18:21]
	v_mfma_f32_16x16x32_bf16 v[6:9], v[6:9], v[54:57], v[14:17]
	s_nop 6
	v_mul_f32_e64 v14, v18, v22
	v_mul_f32_e64 v15, v19, v22
	v_pk_mul_f32 v[16:17], v[20:21], v[22:23] op_sel_hi:[1,0]
	v_mul_f32_e32 v5, 0xbfb8aa3b, v14
	v_mul_f32_e32 v13, 0xbfb8aa3b, v15
	v_exp_f32_e32 v18, v5
	v_exp_f32_e32 v19, v13
	v_mul_f32_e32 v20, 0xbfb8aa3b, v16
	v_mul_f32_e32 v21, 0xbfb8aa3b, v17
	v_exp_f32_e32 v20, v20
	v_exp_f32_e32 v21, v21
	v_pk_add_f32 v[18:19], v[18:19], 1.0 op_sel_hi:[1,0]
	v_pk_mul_f32 v[6:7], v[6:7], v[22:23] op_sel_hi:[1,0]
	v_pk_mul_f32 v[8:9], v[8:9], v[22:23] op_sel_hi:[1,0]
	v_pk_add_f32 v[20:21], v[20:21], 1.0 op_sel_hi:[1,0]
	v_div_scale_f32 v22, s[0:1], v18, v18, 1.0
	v_div_scale_f32 v24, s[8:9], v21, v21, 1.0
	v_rcp_f32_e32 v29, v22
	v_div_scale_f32 v26, s[10:11], v20, v20, 1.0
	v_rcp_f32_e32 v30, v24
	v_rcp_f32_e32 v31, v26
	v_fma_f32 v33, -v22, v29, 1.0
	v_div_scale_f32 v23, s[0:1], 1.0, v18, 1.0
	v_fma_f32 v34, -v24, v30, 1.0
	v_fmac_f32_e32 v29, v33, v29
	v_div_scale_f32 v25, s[8:9], 1.0, v21, 1.0
	v_fma_f32 v35, -v26, v31, 1.0
	v_fmac_f32_e32 v30, v34, v30
	v_mul_f32_e32 v33, v23, v29
	v_div_scale_f32 v27, s[10:11], 1.0, v20, 1.0
	v_fmac_f32_e32 v31, v35, v31
	v_mul_f32_e32 v34, v25, v30
	v_fma_f32 v37, -v22, v33, v23
	v_mul_f32_e32 v35, v27, v31
	v_fma_f32 v38, -v24, v34, v25
	v_fmac_f32_e32 v33, v37, v29
	v_fma_f32 v39, -v26, v35, v27
	v_fmac_f32_e32 v34, v38, v30
	v_fma_f32 v13, -v22, v33, v23
	s_mov_b64 vcc, s[0:1]
	v_fmac_f32_e32 v35, v39, v31
	v_fma_f32 v22, -v24, v34, v25
	v_rcp_f32_e32 v19, v19
	v_div_fmas_f32 v5, v13, v29, v33
	s_mov_b64 vcc, s[8:9]
	v_fma_f32 v23, -v26, v35, v27
	v_div_fixup_f32 v18, v5, v18, 1.0
	v_div_fmas_f32 v5, v22, v30, v34
	s_mov_b64 vcc, s[10:11]
	v_pk_mul_f32 v[14:15], v[14:15], v[18:19]
	v_div_fixup_f32 v19, v5, v21, 1.0
	v_div_fmas_f32 v5, v23, v31, v35
	v_div_fixup_f32 v18, v5, v20, 1.0
	v_pk_mul_f32 v[6:7], v[6:7], v[14:15]
	v_pk_mul_f32 v[14:15], v[16:17], v[18:19]
	v_cvt_pk_bf16_f32 v6, v6, v7
	v_pk_mul_f32 v[8:9], v[8:9], v[14:15]
	s_nop 0
	v_cvt_pk_bf16_f32 v7, v8, v9
	flat_store_dwordx2 v[72:73], v[6:7]
	s_cbranch_scc0 .LBB0_871

.LBB0_877:
	s_ashr_i32 s1, s2, 3
	s_and_b32 s0, s3, 0x70
	v_or_b32_e32 v6, s0, v11
	s_lshl_b32 s0, s1, 4
	s_lshl_b32 s1, s1, 5
	s_and_b32 s4, s1, 0xffffff00
	s_and_b32 s5, s0, 0x70
	s_or_b32 s4, s5, s4
	v_lshlrev_b32_e32 v194, 11, v6
	v_or_b32_e32 v10, 0x4000, v6
	v_or_b32_e32 v6, s4, v11
	v_ashrrev_i32_e32 v7, 31, v6
	v_or_b32_e32 v20, 0x80, v6
	v_lshlrev_b64 v[6:7], 11, v[6:7]
	v_lshl_add_u64 v[76:77], v[0:1], 0, v[194:195]
	v_ashrrev_i32_e32 v21, 31, v20
	v_lshl_add_u64 v[8:9], v[2:3], 0, v[6:7]
	flat_load_dwordx4 v[12:15], v[76:77]
	flat_load_dwordx4 v[16:19], v[76:77] offset:64
	v_lshlrev_b64 v[6:7], 11, v[20:21]
	flat_load_dwordx4 v[20:23], v[8:9]
	v_lshl_add_u64 v[6:7], v[2:3], 0, v[6:7]
	flat_load_dwordx4 v[24:27], v[8:9] offset:64
	flat_load_dwordx4 v[28:31], v[6:7]
	flat_load_dwordx4 v[32:35], v[6:7] offset:64
	v_lshlrev_b32_e32 v194, 3, v10
	v_mul_u32_u24_e32 v10, 0xb00, v10
	s_ashr_i32 s1, s0, 31
	v_mov_b32_e32 v5, v195
	s_add_i32 s2, s2, s18
	s_add_i32 s3, s3, s19
	s_cmpk_gt_i32 s2, 0x57f
	s_waitcnt vmcnt(0) lgkmcnt(0)
	v_mfma_f32_16x16x32_bf16 v[20:23], v[20:23], v[12:15], 0
	v_mfma_f32_16x16x32_bf16 v[12:15], v[28:31], v[12:15], 0
	flat_load_dwordx4 v[28:31], v[76:77] offset:128
	flat_load_dwordx4 v[36:39], v[76:77] offset:192
	v_mfma_f32_16x16x32_bf16 v[20:23], v[24:27], v[16:19], v[20:23]
	flat_load_dwordx4 v[24:27], v[8:9] offset:128
	flat_load_dwordx4 v[40:43], v[8:9] offset:192
	v_mfma_f32_16x16x32_bf16 v[12:15], v[32:35], v[16:19], v[12:15]
	flat_load_dwordx4 v[16:19], v[6:7] offset:128
	s_waitcnt vmcnt(0) lgkmcnt(0)
	v_mfma_f32_16x16x32_bf16 v[20:23], v[24:27], v[28:31], v[20:23]
	flat_load_dwordx4 v[24:27], v[6:7] offset:192
	v_mfma_f32_16x16x32_bf16 v[12:15], v[16:19], v[28:31], v[12:15]
	flat_load_dwordx4 v[16:19], v[76:77] offset:256
	flat_load_dwordx4 v[28:31], v[76:77] offset:320
	v_mfma_f32_16x16x32_bf16 v[20:23], v[40:43], v[36:39], v[20:23]
	flat_load_dwordx4 v[32:35], v[8:9] offset:256
	flat_load_dwordx4 v[40:43], v[8:9] offset:320
	s_waitcnt vmcnt(0) lgkmcnt(0)
	v_mfma_f32_16x16x32_bf16 v[12:15], v[24:27], v[36:39], v[12:15]
	flat_load_dwordx4 v[24:27], v[6:7] offset:256
	v_mfma_f32_16x16x32_bf16 v[20:23], v[32:35], v[16:19], v[20:23]
	flat_load_dwordx4 v[32:35], v[6:7] offset:320
	v_mfma_f32_16x16x32_bf16 v[20:23], v[40:43], v[28:31], v[20:23]
	s_waitcnt vmcnt(0) lgkmcnt(0)
	v_mfma_f32_16x16x32_bf16 v[12:15], v[24:27], v[16:19], v[12:15]
	flat_load_dwordx4 v[16:19], v[76:77] offset:384
	flat_load_dwordx4 v[24:27], v[76:77] offset:448
	flat_load_dwordx4 v[36:39], v[76:77] offset:512
	flat_load_dwordx4 v[40:43], v[8:9] offset:384
	flat_load_dwordx4 v[44:47], v[8:9] offset:448
	v_mfma_f32_16x16x32_bf16 v[12:15], v[32:35], v[28:31], v[12:15]
	flat_load_dwordx4 v[28:31], v[6:7] offset:384
	flat_load_dwordx4 v[32:35], v[6:7] offset:448
	s_waitcnt vmcnt(0) lgkmcnt(0)
	v_mfma_f32_16x16x32_bf16 v[20:23], v[40:43], v[16:19], v[20:23]
	v_mfma_f32_16x16x32_bf16 v[12:15], v[28:31], v[16:19], v[12:15]
	flat_load_dwordx4 v[16:19], v[76:77] offset:576
	flat_load_dwordx4 v[28:31], v[76:77] offset:640
	flat_load_dwordx4 v[40:43], v[76:77] offset:704
	v_mfma_f32_16x16x32_bf16 v[20:23], v[44:47], v[24:27], v[20:23]
	flat_load_dwordx4 v[44:47], v[8:9] offset:512
	flat_load_dwordx4 v[48:51], v[8:9] offset:576
	v_mfma_f32_16x16x32_bf16 v[12:15], v[32:35], v[24:27], v[12:15]
	flat_load_dwordx4 v[24:27], v[6:7] offset:512
	flat_load_dwordx4 v[32:35], v[6:7] offset:576
	s_waitcnt vmcnt(0) lgkmcnt(0)
	v_mfma_f32_16x16x32_bf16 v[20:23], v[44:47], v[36:39], v[20:23]
	v_mfma_f32_16x16x32_bf16 v[12:15], v[24:27], v[36:39], v[12:15]
	flat_load_dwordx4 v[24:27], v[76:77] offset:768
	flat_load_dwordx4 v[36:39], v[76:77] offset:832
	flat_load_dwordx4 v[44:47], v[76:77] offset:896
	v_mfma_f32_16x16x32_bf16 v[20:23], v[48:51], v[16:19], v[20:23]
	flat_load_dwordx4 v[48:51], v[8:9] offset:640
	flat_load_dwordx4 v[52:55], v[8:9] offset:704
	v_mfma_f32_16x16x32_bf16 v[12:15], v[32:35], v[16:19], v[12:15]
	flat_load_dwordx4 v[16:19], v[6:7] offset:640
	flat_load_dwordx4 v[32:35], v[6:7] offset:704
	s_waitcnt vmcnt(0) lgkmcnt(0)
	v_mfma_f32_16x16x32_bf16 v[20:23], v[48:51], v[28:31], v[20:23]
	v_mfma_f32_16x16x32_bf16 v[12:15], v[16:19], v[28:31], v[12:15]
	flat_load_dwordx4 v[16:19], v[76:77] offset:960
	flat_load_dwordx4 v[28:31], v[76:77] offset:1024
	flat_load_dwordx4 v[48:51], v[76:77] offset:1088
	v_mfma_f32_16x16x32_bf16 v[20:23], v[52:55], v[40:43], v[20:23]
	flat_load_dwordx4 v[52:55], v[8:9] offset:768
	flat_load_dwordx4 v[56:59], v[8:9] offset:832
	v_mfma_f32_16x16x32_bf16 v[12:15], v[32:35], v[40:43], v[12:15]
	flat_load_dwordx4 v[32:35], v[6:7] offset:768
	flat_load_dwordx4 v[40:43], v[6:7] offset:832
	s_waitcnt vmcnt(0) lgkmcnt(0)
	v_mfma_f32_16x16x32_bf16 v[20:23], v[52:55], v[24:27], v[20:23]
	v_mfma_f32_16x16x32_bf16 v[12:15], v[32:35], v[24:27], v[12:15]
	flat_load_dwordx4 v[24:27], v[76:77] offset:1152
	flat_load_dwordx4 v[32:35], v[76:77] offset:1216
	flat_load_dwordx4 v[52:55], v[76:77] offset:1280
	v_mfma_f32_16x16x32_bf16 v[20:23], v[56:59], v[36:39], v[20:23]
	flat_load_dwordx4 v[56:59], v[8:9] offset:896
	flat_load_dwordx4 v[60:63], v[8:9] offset:960
	v_mfma_f32_16x16x32_bf16 v[12:15], v[40:43], v[36:39], v[12:15]
	flat_load_dwordx4 v[36:39], v[6:7] offset:896
	flat_load_dwordx4 v[40:43], v[6:7] offset:960
	s_waitcnt vmcnt(0) lgkmcnt(0)
	v_mfma_f32_16x16x32_bf16 v[20:23], v[56:59], v[44:47], v[20:23]
	v_mfma_f32_16x16x32_bf16 v[12:15], v[36:39], v[44:47], v[12:15]
	flat_load_dwordx4 v[36:39], v[76:77] offset:1344
	flat_load_dwordx4 v[44:47], v[76:77] offset:1408
	flat_load_dwordx4 v[56:59], v[76:77] offset:1472
	v_mfma_f32_16x16x32_bf16 v[20:23], v[60:63], v[16:19], v[20:23]
	flat_load_dwordx4 v[60:63], v[8:9] offset:1024
	flat_load_dwordx4 v[64:67], v[8:9] offset:1088
	v_mfma_f32_16x16x32_bf16 v[12:15], v[40:43], v[16:19], v[12:15]
	flat_load_dwordx4 v[16:19], v[6:7] offset:1024
	flat_load_dwordx4 v[40:43], v[6:7] offset:1088
	s_waitcnt vmcnt(0) lgkmcnt(0)
	v_mfma_f32_16x16x32_bf16 v[20:23], v[60:63], v[28:31], v[20:23]
	v_mfma_f32_16x16x32_bf16 v[12:15], v[16:19], v[28:31], v[12:15]
	flat_load_dwordx4 v[16:19], v[76:77] offset:1536
	flat_load_dwordx4 v[28:31], v[76:77] offset:1600
	flat_load_dwordx4 v[60:63], v[76:77] offset:1664
	v_mfma_f32_16x16x32_bf16 v[20:23], v[64:67], v[48:51], v[20:23]
	flat_load_dwordx4 v[64:67], v[8:9] offset:1152
	flat_load_dwordx4 v[68:71], v[8:9] offset:1216
	v_mfma_f32_16x16x32_bf16 v[12:15], v[40:43], v[48:51], v[12:15]
	flat_load_dwordx4 v[40:43], v[6:7] offset:1152
	flat_load_dwordx4 v[48:51], v[6:7] offset:1216
	s_waitcnt vmcnt(0) lgkmcnt(0)
	v_mfma_f32_16x16x32_bf16 v[20:23], v[64:67], v[24:27], v[20:23]
	v_mfma_f32_16x16x32_bf16 v[12:15], v[40:43], v[24:27], v[12:15]
	flat_load_dwordx4 v[24:27], v[76:77] offset:1728
	flat_load_dwordx4 v[40:43], v[76:77] offset:1792
	flat_load_dwordx4 v[64:67], v[76:77] offset:1856
	v_mfma_f32_16x16x32_bf16 v[20:23], v[68:71], v[32:35], v[20:23]
	flat_load_dwordx4 v[68:71], v[8:9] offset:1280
	flat_load_dwordx4 v[72:75], v[8:9] offset:1344
	v_mfma_f32_16x16x32_bf16 v[12:15], v[48:51], v[32:35], v[12:15]
	flat_load_dwordx4 v[32:35], v[6:7] offset:1280
	flat_load_dwordx4 v[48:51], v[6:7] offset:1344
	s_waitcnt vmcnt(0) lgkmcnt(0)
	v_mfma_f32_16x16x32_bf16 v[20:23], v[68:71], v[52:55], v[20:23]
	v_mfma_f32_16x16x32_bf16 v[12:15], v[32:35], v[52:55], v[12:15]
	flat_load_dwordx4 v[32:35], v[76:77] offset:1920
	flat_load_dwordx4 v[52:55], v[76:77] offset:1984
	v_lshl_add_u64 v[76:77], s[14:15], 0, v[194:195]
	v_lshlrev_b32_e32 v194, 1, v10
	v_mfma_f32_16x16x32_bf16 v[20:23], v[72:75], v[36:39], v[20:23]
	flat_load_dwordx4 v[68:71], v[8:9] offset:1408
	flat_load_dwordx4 v[72:75], v[8:9] offset:1472
	v_mfma_f32_16x16x32_bf16 v[12:15], v[48:51], v[36:39], v[12:15]
	flat_load_dwordx4 v[36:39], v[6:7] offset:1408
	flat_load_dwordx4 v[48:51], v[6:7] offset:1472
	s_waitcnt vmcnt(0) lgkmcnt(0)
	v_mfma_f32_16x16x32_bf16 v[20:23], v[68:71], v[44:47], v[20:23]
	flat_load_dwordx2 v[68:69], v[76:77]
	v_mfma_f32_16x16x32_bf16 v[12:15], v[36:39], v[44:47], v[12:15]
	flat_load_dwordx4 v[36:39], v[8:9] offset:1536
	flat_load_dwordx4 v[44:47], v[8:9] offset:1600
	v_mfma_f32_16x16x32_bf16 v[12:15], v[48:51], v[56:59], v[12:15]
	flat_load_dwordx4 v[48:51], v[6:7] offset:1536
	v_mfma_f32_16x16x32_bf16 v[20:23], v[72:75], v[56:59], v[20:23]
	s_waitcnt vmcnt(0) lgkmcnt(0)
	v_mfma_f32_16x16x32_bf16 v[20:23], v[36:39], v[16:19], v[20:23]
	flat_load_dwordx4 v[36:39], v[6:7] offset:1600
	v_mfma_f32_16x16x32_bf16 v[12:15], v[48:51], v[16:19], v[12:15]
	v_lshl_add_u64 v[16:17], s[12:13], 0, v[194:195]
	v_lshl_add_u64 v[16:17], s[0:1], 1, v[16:17]
	v_lshl_add_u64 v[70:71], v[16:17], 0, v[4:5]
	v_mfma_f32_16x16x32_bf16 v[16:19], v[44:47], v[28:31], v[20:23]
	s_nop 2
	flat_load_dwordx4 v[20:23], v[8:9] offset:1664
	flat_load_dwordx4 v[44:47], v[8:9] offset:1728
	flat_load_dwordx4 v[48:51], v[8:9] offset:1792
	v_ffbh_u32_e32 v5, v69
	v_min_u32_e32 v5, 32, v5
	s_waitcnt vmcnt(0) lgkmcnt(0)
	v_mfma_f32_16x16x32_bf16 v[12:15], v[36:39], v[28:31], v[12:15]
	flat_load_dwordx4 v[28:31], v[6:7] offset:1664
	v_mfma_f32_16x16x32_bf16 v[16:19], v[20:23], v[60:63], v[16:19]
	flat_load_dwordx4 v[20:23], v[6:7] offset:1728
	v_mfma_f32_16x16x32_bf16 v[16:19], v[44:47], v[24:27], v[16:19]
	v_mfma_f32_16x16x32_bf16 v[16:19], v[48:51], v[40:43], v[16:19]
	s_waitcnt vmcnt(0) lgkmcnt(0)
	v_mfma_f32_16x16x32_bf16 v[12:15], v[28:31], v[60:63], v[12:15]
	flat_load_dwordx4 v[28:31], v[8:9] offset:1856
	flat_load_dwordx4 v[36:39], v[8:9] offset:1920
	flat_load_dwordx4 v[56:59], v[8:9] offset:1984
	flat_load_dwordx4 v[44:47], v[6:7] offset:1792
	v_mfma_f32_16x16x32_bf16 v[12:15], v[20:23], v[24:27], v[12:15]
	flat_load_dwordx4 v[20:23], v[6:7] offset:1856
	flat_load_dwordx4 v[24:27], v[6:7] offset:1920
	s_nop 0
	flat_load_dwordx4 v[6:9], v[6:7] offset:1984
	s_waitcnt vmcnt(0) lgkmcnt(0)
	v_mfma_f32_16x16x32_bf16 v[16:19], v[28:31], v[64:67], v[16:19]
	v_lshlrev_b64 v[28:29], v5, v[68:69]
	v_min_u32_e32 v10, 1, v28
	v_or_b32_e32 v10, v29, v10
	v_cvt_f32_u32_e32 v10, v10
	v_mfma_f32_16x16x32_bf16 v[12:15], v[44:47], v[40:43], v[12:15]
	v_sub_u32_e32 v5, 32, v5
	v_ldexp_f32 v5, v10, v5
	v_fmamk_f32 v5, v5, 0x2e800000, v236
	v_mfma_f32_16x16x32_bf16 v[12:15], v[20:23], v[64:67], v[12:15]
	v_mul_f32_e32 v10, 0x4b800000, v5
	v_cmp_gt_f32_e32 vcc, s20, v5
	v_mfma_f32_16x16x32_bf16 v[16:19], v[36:39], v[32:35], v[16:19]
	s_nop 0
	v_cndmask_b32_e32 v5, v5, v10, vcc
	v_rsq_f32_e32 v5, v5
	v_mfma_f32_16x16x32_bf16 v[12:15], v[24:27], v[32:35], v[12:15]
	v_mul_f32_e32 v10, 0x45800000, v5
	v_cndmask_b32_e32 v10, v5, v10, vcc
	v_mfma_f32_16x16x32_bf16 v[16:19], v[56:59], v[52:55], v[16:19]
	v_mfma_f32_16x16x32_bf16 v[6:9], v[6:9], v[52:55], v[12:15]
	s_nop 6
	v_mul_f32_e64 v12, v16, v10
	v_mul_f32_e64 v13, v17, v10
	v_pk_mul_f32 v[14:15], v[18:19], v[10:11] op_sel_hi:[1,0]
	v_mul_f32_e32 v5, 0xbfb8aa3b, v12
	v_mul_f32_e32 v17, 0xbfb8aa3b, v13
	v_exp_f32_e32 v16, v5
	v_exp_f32_e32 v17, v17
	v_pk_mul_f32 v[6:7], v[6:7], v[10:11] op_sel_hi:[1,0]
	v_mul_f32_e32 v18, 0xbfb8aa3b, v14
	v_pk_mul_f32 v[8:9], v[8:9], v[10:11] op_sel_hi:[1,0]
	v_mul_f32_e32 v10, 0xbfb8aa3b, v15
	v_exp_f32_e32 v18, v18
	v_exp_f32_e32 v19, v10
	v_pk_add_f32 v[16:17], v[16:17], 1.0 op_sel_hi:[1,0]
	v_pk_add_f32 v[18:19], v[18:19], 1.0 op_sel_hi:[1,0]
	v_div_scale_f32 v20, s[0:1], v16, v16, 1.0
	v_div_scale_f32 v22, s[4:5], v19, v19, 1.0
	v_rcp_f32_e32 v27, v20
	v_div_scale_f32 v24, s[4:5], v18, v18, 1.0
	v_rcp_f32_e32 v28, v22
	v_rcp_f32_e32 v29, v24
	v_fma_f32 v31, -v20, v27, 1.0
	v_div_scale_f32 v21, s[0:1], 1.0, v16, 1.0
	v_fma_f32 v32, -v22, v28, 1.0
	v_fmac_f32_e32 v27, v31, v27
	v_div_scale_f32 v23, s[8:9], 1.0, v19, 1.0
	v_fma_f32 v33, -v24, v29, 1.0
	v_fmac_f32_e32 v28, v32, v28
	v_mul_f32_e32 v31, v21, v27
	v_div_scale_f32 v25, s[10:11], 1.0, v18, 1.0
	v_fmac_f32_e32 v29, v33, v29
	v_mul_f32_e32 v32, v23, v28
	v_fma_f32 v35, -v20, v31, v21
	v_mul_f32_e32 v33, v25, v29
	v_fma_f32 v36, -v22, v32, v23
	v_fmac_f32_e32 v31, v35, v27
	v_fma_f32 v37, -v24, v33, v25
	v_fmac_f32_e32 v32, v36, v28
	v_fma_f32 v10, -v20, v31, v21
	s_mov_b64 vcc, s[0:1]
	v_fmac_f32_e32 v33, v37, v29
	v_fma_f32 v20, -v22, v32, v23
	v_rcp_f32_e32 v17, v17
	v_div_fmas_f32 v5, v10, v27, v31
	s_mov_b64 vcc, s[8:9]
	v_fma_f32 v21, -v24, v33, v25
	v_div_fixup_f32 v16, v5, v16, 1.0
	v_div_fmas_f32 v5, v20, v28, v32
	s_mov_b64 vcc, s[10:11]
	v_pk_mul_f32 v[12:13], v[12:13], v[16:17]
	v_div_fixup_f32 v17, v5, v19, 1.0
	v_div_fmas_f32 v5, v21, v29, v33
	v_div_fixup_f32 v16, v5, v18, 1.0
	v_pk_mul_f32 v[6:7], v[6:7], v[12:13]
	v_pk_mul_f32 v[12:13], v[14:15], v[16:17]
	v_cvt_pk_bf16_f32 v6, v6, v7
	v_pk_mul_f32 v[8:9], v[8:9], v[12:13]
	s_nop 0
	v_cvt_pk_bf16_f32 v7, v8, v9
	flat_store_dwordx2 v[70:71], v[6:7]
	s_cbranch_scc0 .LBB0_877
